# unit-boundary priority: a wave group runs at s_setprio 1 from GEMM loop exit (epilogue, next-unit set-up, first load segment) until it closes that load segment; reset at phase end
# speedup vs baseline: 1.0119x; 1.0038x over previous
.LBB0_30:
	s_add_u32 s10, s52, 0x100
	s_addc_u32 s11, s53, 0
	s_mov_b32 s12, -2
	s_waitcnt lgkmcnt(0)
	s_add_u32 s46, s50, 0x100
	s_addc_u32 s47, s51, 0
	s_add_i32 s6, 0, 0x10000
	v_add_u32_e32 v146, s6, v206
	ds_read_b128 v[128:131], v146
	ds_read_b128 v[132:135], v146 offset:1024
	ds_read_b128 v[136:139], v146 offset:2048
	ds_read_b128 v[146:149], v146 offset:3072
	s_cmp_eq_u32 s12, 40
	s_cselect_b32 s53, s31, s47
	s_cselect_b32 s52, s30, s46
	s_cselect_b32 s49, s35, s11
	s_cselect_b32 s48, s34, s10
	v_lshl_add_u64 v[214:215], s[50:51], 0, v[158:159]
	s_add_i32 m0, s58, 0xc000
	ds_read_b128 v[162:165], v208
	ds_read_b128 v[166:169], v208 offset:1024
	ds_read_b128 v[170:173], v208 offset:2048
	ds_read_b128 v[174:177], v208 offset:3072
	ds_read_b128 v[178:181], v208 offset:4096
	ds_read_b128 v[182:185], v208 offset:5120
	ds_read_b128 v[194:197], v208 offset:6144
	ds_read_b128 v[210:213], v208 offset:7168
	global_load_lds_dwordx4 v[214:215], off
	v_lshl_add_u64 v[214:215], s[50:51], 0, v[160:161]
	s_add_i32 m0, s58, 0xe000
	s_nop 0
	global_load_lds_dwordx4 v[214:215], off
	s_add_i32 s19, 0, 0x14000
	v_add_u32_e32 v192, s19, v206
	ds_read_b128 v[214:217], v192
	ds_read_b128 v[218:221], v192 offset:1024
	ds_read_b128 v[222:225], v192 offset:2048
	ds_read_b128 v[226:229], v192 offset:3072
	s_setprio 0
	s_waitcnt vmcnt(40)
	s_cmp_lg_u32 s100, 0
	s_cbranch_scc1 .Lm4ap_31
	s_waitcnt vmcnt(8)

.LBB0_31:
	s_add_u32 s46, s50, 0x100
	s_addc_u32 s47, s51, 0
	s_add_i32 s6, 0, 0x10000
	v_add_u32_e32 v146, s6, v206
	ds_read_b128 v[128:131], v146
	ds_read_b128 v[132:135], v146 offset:1024
	ds_read_b128 v[136:139], v146 offset:2048
	ds_read_b128 v[146:149], v146 offset:3072
	s_cmp_eq_u32 s12, 40
	s_cselect_b32 s53, s31, s47
	s_cselect_b32 s52, s30, s46
	s_cselect_b32 s49, s35, s11
	s_cselect_b32 s48, s34, s10
	v_lshl_add_u64 v[214:215], s[50:51], 0, v[158:159]
	s_add_i32 m0, s58, 0xc000
	ds_read_b128 v[162:165], v208
	ds_read_b128 v[166:169], v208 offset:1024
	ds_read_b128 v[170:173], v208 offset:2048
	ds_read_b128 v[174:177], v208 offset:3072
	ds_read_b128 v[178:181], v208 offset:4096
	ds_read_b128 v[182:185], v208 offset:5120
	ds_read_b128 v[194:197], v208 offset:6144
	ds_read_b128 v[210:213], v208 offset:7168
	global_load_lds_dwordx4 v[214:215], off
	v_lshl_add_u64 v[214:215], s[50:51], 0, v[160:161]
	s_add_i32 m0, s58, 0xe000
	s_nop 0
	global_load_lds_dwordx4 v[214:215], off
	s_add_i32 s19, 0, 0x14000
	v_add_u32_e32 v192, s19, v206
	ds_read_b128 v[214:217], v192
	ds_read_b128 v[218:221], v192 offset:1024
	ds_read_b128 v[222:225], v192 offset:2048
	ds_read_b128 v[226:229], v192 offset:3072
	s_nop 0
	s_waitcnt vmcnt(8)
	s_waitcnt lgkmcnt(0)
	s_barrier
	v_mfma_f32_16x16x32_bf16 v[124:127], v[128:131], v[162:165], v[124:127]
	v_mfma_f32_16x16x32_bf16 v[120:123], v[136:139], v[162:165], v[120:123]
	v_mfma_f32_16x16x32_bf16 v[108:111], v[128:131], v[170:173], v[108:111]
	v_mfma_f32_16x16x32_bf16 v[104:107], v[136:139], v[170:173], v[104:107]
	v_mfma_f32_16x16x32_bf16 v[96:99], v[128:131], v[178:181], v[96:99]
	v_mfma_f32_16x16x32_bf16 v[88:91], v[136:139], v[178:181], v[88:91]
	v_mfma_f32_16x16x32_bf16 v[84:87], v[128:131], v[194:197], v[84:87]
	v_mfma_f32_16x16x32_bf16 v[80:83], v[136:139], v[194:197], v[80:83]
	v_mfma_f32_16x16x32_bf16 v[124:127], v[132:135], v[166:169], v[124:127]
	v_mfma_f32_16x16x32_bf16 v[120:123], v[146:149], v[166:169], v[120:123]
	v_mfma_f32_16x16x32_bf16 v[108:111], v[132:135], v[174:177], v[108:111]
	v_mfma_f32_16x16x32_bf16 v[104:107], v[146:149], v[174:177], v[104:107]
	v_mfma_f32_16x16x32_bf16 v[96:99], v[132:135], v[182:185], v[96:99]
	v_mfma_f32_16x16x32_bf16 v[88:91], v[146:149], v[182:185], v[88:91]
	v_mfma_f32_16x16x32_bf16 v[84:87], v[132:135], v[210:213], v[84:87]
	v_mfma_f32_16x16x32_bf16 v[80:83], v[146:149], v[210:213], v[80:83]
	v_mfma_f32_16x16x32_bf16 v[116:119], v[214:217], v[162:165], v[116:119]
	v_mfma_f32_16x16x32_bf16 v[112:115], v[222:225], v[162:165], v[112:115]
	v_mfma_f32_16x16x32_bf16 v[100:103], v[214:217], v[170:173], v[100:103]
	v_mfma_f32_16x16x32_bf16 v[92:95], v[222:225], v[170:173], v[92:95]
	v_mfma_f32_16x16x32_bf16 v[76:79], v[214:217], v[178:181], v[76:79]
	v_mfma_f32_16x16x32_bf16 v[72:75], v[222:225], v[178:181], v[72:75]
	v_mfma_f32_16x16x32_bf16 v[68:71], v[214:217], v[194:197], v[68:71]
	v_mfma_f32_16x16x32_bf16 v[64:67], v[222:225], v[194:197], v[64:67]
	v_mfma_f32_16x16x32_bf16 v[116:119], v[218:221], v[166:169], v[116:119]
	v_mfma_f32_16x16x32_bf16 v[112:115], v[226:229], v[166:169], v[112:115]
	v_mfma_f32_16x16x32_bf16 v[100:103], v[218:221], v[174:177], v[100:103]
	v_mfma_f32_16x16x32_bf16 v[92:95], v[226:229], v[174:177], v[92:95]
	v_mfma_f32_16x16x32_bf16 v[76:79], v[218:221], v[182:185], v[76:79]
	v_mfma_f32_16x16x32_bf16 v[72:75], v[226:229], v[182:185], v[72:75]
	v_mfma_f32_16x16x32_bf16 v[68:71], v[218:221], v[210:213], v[68:71]
	v_mfma_f32_16x16x32_bf16 v[64:67], v[226:229], v[210:213], v[64:67]
	s_barrier
	s_add_i32 s6, s6, s57
	v_lshl_add_u64 v[230:231], s[48:49], 0, v[140:141]
	s_mov_b32 m0, s6
	s_nop 0
	global_load_lds_dwordx4 v[230:231], off
	v_lshl_add_u64 v[232:233], s[48:49], 0, v[150:151]
	s_add_i32 m0, s6, 0x2000
	s_nop 0
	global_load_lds_dwordx4 v[232:233], off
	s_mov_b32 m0, s58
	v_lshl_add_u64 v[234:235], s[52:53], 0, v[154:155]
	ds_read_b128 v[162:165], v208 offset:16384
	ds_read_b128 v[166:169], v208 offset:17408
	ds_read_b128 v[170:173], v208 offset:18432
	ds_read_b128 v[174:177], v208 offset:19456
	ds_read_b128 v[178:181], v208 offset:20480
	ds_read_b128 v[182:185], v208 offset:21504
	ds_read_b128 v[194:197], v208 offset:22528
	ds_read_b128 v[210:213], v208 offset:23552
	global_load_lds_dwordx4 v[234:235], off
	v_lshl_add_u64 v[236:237], s[52:53], 0, v[152:153]
	s_mov_b32 m0, s59
	s_nop 0
	global_load_lds_dwordx4 v[236:237], off
	s_add_u32 s50, s48, 0xb0000
	s_addc_u32 s51, s49, 0
	s_add_i32 s6, s19, s57
	v_lshl_add_u64 v[250:251], s[50:51], 0, v[140:141]
	s_mov_b32 m0, s6
	s_nop 0
	global_load_lds_dwordx4 v[250:251], off
	v_lshl_add_u64 v[250:251], s[50:51], 0, v[150:151]
	s_add_i32 m0, s6, 0x2000
	s_nop 0
	global_load_lds_dwordx4 v[250:251], off
	s_waitcnt vmcnt(8)
	s_waitcnt lgkmcnt(0)
	s_barrier
	v_mfma_f32_16x16x32_bf16 v[60:63], v[128:131], v[162:165], v[60:63]
	v_mfma_f32_16x16x32_bf16 v[56:59], v[136:139], v[162:165], v[56:59]
	v_mfma_f32_16x16x32_bf16 v[48:51], v[128:131], v[170:173], v[48:51]
	v_mfma_f32_16x16x32_bf16 v[40:43], v[136:139], v[170:173], v[40:43]
	v_mfma_f32_16x16x32_bf16 v[32:35], v[128:131], v[178:181], v[32:35]
	v_mfma_f32_16x16x32_bf16 v[24:27], v[136:139], v[178:181], v[24:27]
	v_mfma_f32_16x16x32_bf16 v[16:19], v[128:131], v[194:197], v[16:19]
	v_mfma_f32_16x16x32_bf16 v[8:11], v[136:139], v[194:197], v[8:11]
	v_mfma_f32_16x16x32_bf16 v[60:63], v[132:135], v[166:169], v[60:63]
	v_mfma_f32_16x16x32_bf16 v[56:59], v[146:149], v[166:169], v[56:59]
	v_mfma_f32_16x16x32_bf16 v[48:51], v[132:135], v[174:177], v[48:51]
	v_mfma_f32_16x16x32_bf16 v[40:43], v[146:149], v[174:177], v[40:43]
	v_mfma_f32_16x16x32_bf16 v[32:35], v[132:135], v[182:185], v[32:35]
	v_mfma_f32_16x16x32_bf16 v[24:27], v[146:149], v[182:185], v[24:27]
	v_mfma_f32_16x16x32_bf16 v[16:19], v[132:135], v[210:213], v[16:19]
	v_mfma_f32_16x16x32_bf16 v[8:11], v[146:149], v[210:213], v[8:11]
	v_mfma_f32_16x16x32_bf16 v[52:55], v[214:217], v[162:165], v[52:55]
	v_mfma_f32_16x16x32_bf16 v[44:47], v[222:225], v[162:165], v[44:47]
	v_mfma_f32_16x16x32_bf16 v[36:39], v[214:217], v[170:173], v[36:39]
	v_mfma_f32_16x16x32_bf16 v[28:31], v[222:225], v[170:173], v[28:31]
	v_mfma_f32_16x16x32_bf16 v[20:23], v[214:217], v[178:181], v[20:23]
	v_mfma_f32_16x16x32_bf16 v[12:15], v[222:225], v[178:181], v[12:15]
	v_mfma_f32_16x16x32_bf16 v[4:7], v[214:217], v[194:197], v[4:7]
	v_mfma_f32_16x16x32_bf16 v[0:3], v[222:225], v[194:197], v[0:3]
	v_mfma_f32_16x16x32_bf16 v[52:55], v[218:221], v[166:169], v[52:55]
	v_mfma_f32_16x16x32_bf16 v[44:47], v[226:229], v[166:169], v[44:47]
	v_mfma_f32_16x16x32_bf16 v[36:39], v[218:221], v[174:177], v[36:39]
	v_mfma_f32_16x16x32_bf16 v[28:31], v[226:229], v[174:177], v[28:31]
	v_mfma_f32_16x16x32_bf16 v[20:23], v[218:221], v[182:185], v[20:23]
	v_mfma_f32_16x16x32_bf16 v[12:15], v[226:229], v[182:185], v[12:15]
	v_mfma_f32_16x16x32_bf16 v[4:7], v[218:221], v[210:213], v[4:7]
	v_mfma_f32_16x16x32_bf16 v[0:3], v[226:229], v[210:213], v[0:3]
	s_barrier
	s_add_i32 s6, 0, 0x18000
	v_add_u32_e32 v146, s6, v206
	ds_read_b128 v[128:131], v146
	ds_read_b128 v[132:135], v146 offset:1024
	ds_read_b128 v[136:139], v146 offset:2048
	ds_read_b128 v[146:149], v146 offset:3072
	s_add_u32 s50, s52, 0xb0000
	s_addc_u32 s51, s53, 0
	s_mov_b32 m0, s68
	v_lshl_add_u64 v[214:215], s[50:51], 0, v[154:155]
	ds_read_b128 v[162:165], v208 offset:32768
	ds_read_b128 v[166:169], v208 offset:33792
	ds_read_b128 v[170:173], v208 offset:34816
	ds_read_b128 v[174:177], v208 offset:35840
	ds_read_b128 v[178:181], v208 offset:36864
	ds_read_b128 v[182:185], v208 offset:37888
	ds_read_b128 v[194:197], v208 offset:38912
	ds_read_b128 v[210:213], v208 offset:39936
	global_load_lds_dwordx4 v[214:215], off
	v_lshl_add_u64 v[214:215], s[50:51], 0, v[152:153]
	s_mov_b32 m0, s69
	s_nop 0
	global_load_lds_dwordx4 v[214:215], off
	s_add_i32 s19, 0, 0x1c000
	v_add_u32_e32 v192, s19, v206
	ds_read_b128 v[214:217], v192
	ds_read_b128 v[218:221], v192 offset:1024
	ds_read_b128 v[222:225], v192 offset:2048
	ds_read_b128 v[226:229], v192 offset:3072
	s_waitcnt vmcnt(8)
	s_waitcnt lgkmcnt(0)
	s_barrier
	v_mfma_f32_16x16x32_bf16 v[124:127], v[128:131], v[162:165], v[124:127]
	v_mfma_f32_16x16x32_bf16 v[120:123], v[136:139], v[162:165], v[120:123]
	v_mfma_f32_16x16x32_bf16 v[108:111], v[128:131], v[170:173], v[108:111]
	v_mfma_f32_16x16x32_bf16 v[104:107], v[136:139], v[170:173], v[104:107]
	v_mfma_f32_16x16x32_bf16 v[96:99], v[128:131], v[178:181], v[96:99]
	v_mfma_f32_16x16x32_bf16 v[88:91], v[136:139], v[178:181], v[88:91]
	v_mfma_f32_16x16x32_bf16 v[84:87], v[128:131], v[194:197], v[84:87]
	v_mfma_f32_16x16x32_bf16 v[80:83], v[136:139], v[194:197], v[80:83]
	v_mfma_f32_16x16x32_bf16 v[124:127], v[132:135], v[166:169], v[124:127]
	v_mfma_f32_16x16x32_bf16 v[120:123], v[146:149], v[166:169], v[120:123]
	v_mfma_f32_16x16x32_bf16 v[108:111], v[132:135], v[174:177], v[108:111]
	v_mfma_f32_16x16x32_bf16 v[104:107], v[146:149], v[174:177], v[104:107]
	v_mfma_f32_16x16x32_bf16 v[96:99], v[132:135], v[182:185], v[96:99]
	v_mfma_f32_16x16x32_bf16 v[88:91], v[146:149], v[182:185], v[88:91]
	v_mfma_f32_16x16x32_bf16 v[84:87], v[132:135], v[210:213], v[84:87]
	v_mfma_f32_16x16x32_bf16 v[80:83], v[146:149], v[210:213], v[80:83]
	v_mfma_f32_16x16x32_bf16 v[116:119], v[214:217], v[162:165], v[116:119]
	v_mfma_f32_16x16x32_bf16 v[112:115], v[222:225], v[162:165], v[112:115]
	v_mfma_f32_16x16x32_bf16 v[100:103], v[214:217], v[170:173], v[100:103]
	v_mfma_f32_16x16x32_bf16 v[92:95], v[222:225], v[170:173], v[92:95]
	v_mfma_f32_16x16x32_bf16 v[76:79], v[214:217], v[178:181], v[76:79]
	v_mfma_f32_16x16x32_bf16 v[72:75], v[222:225], v[178:181], v[72:75]
	v_mfma_f32_16x16x32_bf16 v[68:71], v[214:217], v[194:197], v[68:71]
	v_mfma_f32_16x16x32_bf16 v[64:67], v[222:225], v[194:197], v[64:67]
	v_mfma_f32_16x16x32_bf16 v[116:119], v[218:221], v[166:169], v[116:119]
	v_mfma_f32_16x16x32_bf16 v[112:115], v[226:229], v[166:169], v[112:115]
	v_mfma_f32_16x16x32_bf16 v[100:103], v[218:221], v[174:177], v[100:103]
	v_mfma_f32_16x16x32_bf16 v[92:95], v[226:229], v[174:177], v[92:95]
	v_mfma_f32_16x16x32_bf16 v[76:79], v[218:221], v[182:185], v[76:79]
	v_mfma_f32_16x16x32_bf16 v[72:75], v[226:229], v[182:185], v[72:75]
	v_mfma_f32_16x16x32_bf16 v[68:71], v[218:221], v[210:213], v[68:71]
	v_mfma_f32_16x16x32_bf16 v[64:67], v[226:229], v[210:213], v[64:67]
	s_barrier
	s_add_i32 s6, s6, s57
	v_lshl_add_u64 v[230:231], v[230:231], 0, s[36:37]
	s_mov_b32 m0, s6
	s_nop 0
	global_load_lds_dwordx4 v[230:231], off
	v_lshl_add_u64 v[230:231], v[232:233], 0, s[36:37]
	s_add_i32 m0, s6, 0x2000
	s_nop 0
	global_load_lds_dwordx4 v[230:231], off
	s_mov_b32 m0, s70
	v_lshl_add_u64 v[230:231], v[234:235], 0, s[36:37]
	ds_read_b128 v[162:165], v208 offset:49152
	ds_read_b128 v[166:169], v208 offset:50176
	ds_read_b128 v[170:173], v208 offset:51200
	ds_read_b128 v[174:177], v208 offset:52224
	ds_read_b128 v[178:181], v208 offset:53248
	ds_read_b128 v[182:185], v208 offset:54272
	ds_read_b128 v[194:197], v208 offset:55296
	ds_read_b128 v[210:213], v208 offset:56320
	global_load_lds_dwordx4 v[230:231], off
	v_lshl_add_u64 v[230:231], v[236:237], 0, s[36:37]
	s_mov_b32 m0, s71
	s_nop 0
	global_load_lds_dwordx4 v[230:231], off
	s_add_u32 s48, s48, 0xb0080
	s_addc_u32 s49, s49, 0
	s_add_i32 s6, s19, s57
	v_lshl_add_u64 v[250:251], s[48:49], 0, v[140:141]
	s_mov_b32 m0, s6
	s_nop 0
	global_load_lds_dwordx4 v[250:251], off
	v_lshl_add_u64 v[250:251], s[48:49], 0, v[150:151]
	s_add_i32 m0, s6, 0x2000
	s_nop 0
	global_load_lds_dwordx4 v[250:251], off
	s_add_i32 s12, s12, 2
	s_add_u32 s10, s10, 0x100
	s_addc_u32 s11, s11, 0
	s_cmp_gt_u32 s12, 41
	s_mov_b64 s[50:51], s[46:47]
	s_waitcnt vmcnt(8)
	s_waitcnt lgkmcnt(0)
	s_barrier
	v_mfma_f32_16x16x32_bf16 v[60:63], v[128:131], v[162:165], v[60:63]
	v_mfma_f32_16x16x32_bf16 v[56:59], v[136:139], v[162:165], v[56:59]
	v_mfma_f32_16x16x32_bf16 v[48:51], v[128:131], v[170:173], v[48:51]
	v_mfma_f32_16x16x32_bf16 v[40:43], v[136:139], v[170:173], v[40:43]
	v_mfma_f32_16x16x32_bf16 v[32:35], v[128:131], v[178:181], v[32:35]
	v_mfma_f32_16x16x32_bf16 v[24:27], v[136:139], v[178:181], v[24:27]
	v_mfma_f32_16x16x32_bf16 v[16:19], v[128:131], v[194:197], v[16:19]
	v_mfma_f32_16x16x32_bf16 v[8:11], v[136:139], v[194:197], v[8:11]
	v_mfma_f32_16x16x32_bf16 v[60:63], v[132:135], v[166:169], v[60:63]
	v_mfma_f32_16x16x32_bf16 v[56:59], v[146:149], v[166:169], v[56:59]
	v_mfma_f32_16x16x32_bf16 v[48:51], v[132:135], v[174:177], v[48:51]
	v_mfma_f32_16x16x32_bf16 v[40:43], v[146:149], v[174:177], v[40:43]
	v_mfma_f32_16x16x32_bf16 v[32:35], v[132:135], v[182:185], v[32:35]
	v_mfma_f32_16x16x32_bf16 v[24:27], v[146:149], v[182:185], v[24:27]
	v_mfma_f32_16x16x32_bf16 v[16:19], v[132:135], v[210:213], v[16:19]
	v_mfma_f32_16x16x32_bf16 v[8:11], v[146:149], v[210:213], v[8:11]
	v_mfma_f32_16x16x32_bf16 v[52:55], v[214:217], v[162:165], v[52:55]
	v_mfma_f32_16x16x32_bf16 v[44:47], v[222:225], v[162:165], v[44:47]
	v_mfma_f32_16x16x32_bf16 v[36:39], v[214:217], v[170:173], v[36:39]
	v_mfma_f32_16x16x32_bf16 v[28:31], v[222:225], v[170:173], v[28:31]
	v_mfma_f32_16x16x32_bf16 v[20:23], v[214:217], v[178:181], v[20:23]
	v_mfma_f32_16x16x32_bf16 v[12:15], v[222:225], v[178:181], v[12:15]
	v_mfma_f32_16x16x32_bf16 v[4:7], v[214:217], v[194:197], v[4:7]
	v_mfma_f32_16x16x32_bf16 v[0:3], v[222:225], v[194:197], v[0:3]
	v_mfma_f32_16x16x32_bf16 v[52:55], v[218:221], v[166:169], v[52:55]
	v_mfma_f32_16x16x32_bf16 v[44:47], v[226:229], v[166:169], v[44:47]
	v_mfma_f32_16x16x32_bf16 v[36:39], v[218:221], v[174:177], v[36:39]
	v_mfma_f32_16x16x32_bf16 v[28:31], v[226:229], v[174:177], v[28:31]
	v_mfma_f32_16x16x32_bf16 v[20:23], v[218:221], v[182:185], v[20:23]
	v_mfma_f32_16x16x32_bf16 v[12:15], v[226:229], v[182:185], v[12:15]
	v_mfma_f32_16x16x32_bf16 v[4:7], v[218:221], v[210:213], v[4:7]
	v_mfma_f32_16x16x32_bf16 v[0:3], v[226:229], v[210:213], v[0:3]
	s_barrier
	s_cbranch_scc0 .LBB0_31
	s_mov_b32 s100, 1
	s_setprio 1
	s_ashr_i32 s39, s38, 31
	v_lshl_or_b32 v128, s81, 8, v207
	s_lshl_b64 s[10:11], s[38:39], 8
	v_ashrrev_i32_e32 v129, 31, v128
	v_lshl_add_u64 v[168:169], s[10:11], 0, v[156:157]
	v_lshlrev_b64 v[170:171], 1, v[128:129]
	v_lshl_add_u64 v[174:175], s[4:5], 0, v[170:171]
	v_lshlrev_b64 v[172:173], 11, v[168:169]
	v_lshl_add_u64 v[128:129], v[174:175], 0, v[172:173]
	global_load_dwordx4 v[146:149], v[128:129], off
	global_load_dwordx4 v[182:185], v[128:129], off offset:256
	v_or_b32_e32 v166, 16, v168
	v_mov_b32_e32 v167, v169
	v_lshlrev_b64 v[176:177], 11, v[166:167]
	v_lshl_add_u64 v[128:129], v[174:175], 0, v[176:177]
	global_load_dwordx4 v[194:197], v[128:129], off
	global_load_dwordx4 v[210:213], v[128:129], off offset:256
	v_or_b32_e32 v164, 32, v168
	v_mov_b32_e32 v165, v169
	v_or_b32_e32 v162, 48, v168
	v_mov_b32_e32 v163, v169
	v_lshlrev_b64 v[180:181], 11, v[164:165]
	v_lshlrev_b64 v[178:179], 11, v[162:163]
	v_lshl_add_u64 v[128:129], v[174:175], 0, v[180:181]
	v_lshl_add_u64 v[130:131], v[174:175], 0, v[178:179]
	global_load_dwordx4 v[214:217], v[128:129], off
	global_load_dwordx4 v[136:139], v[128:129], off offset:256
	global_load_dwordx4 v[132:135], v[130:131], off
	s_nop 0
	global_load_dwordx4 v[128:131], v[130:131], off offset:256
	s_mov_b64 s[10:11], 0x90
	v_lshl_add_u64 v[172:173], s[28:29], 0, v[172:173]
	v_lshl_add_u64 v[172:173], v[172:173], 0, v[170:171]
	s_waitcnt vmcnt(0)
	v_lshlrev_b32_e32 v218, 16, v146
	v_and_b32_e32 v219, 0xffff0000, v146
	v_lshlrev_b32_e32 v220, 16, v148
	v_and_b32_e32 v221, 0xffff0000, v148
	v_lshlrev_b32_e32 v146, 16, v147
	v_and_b32_e32 v147, 0xffff0000, v147
	v_lshlrev_b32_e32 v222, 16, v182
	v_and_b32_e32 v223, 0xffff0000, v182
	v_lshlrev_b32_e32 v224, 16, v184
	v_and_b32_e32 v225, 0xffff0000, v184
	v_lshlrev_b32_e32 v182, 16, v183
	v_and_b32_e32 v183, 0xffff0000, v183
	v_pk_fma_f32 v[124:125], v[124:125], 0.5, v[218:219] op_sel_hi:[1,0,1]
	v_pk_fma_f32 v[120:121], v[120:121], 0.5, v[220:221] op_sel_hi:[1,0,1]
	v_pk_fma_f32 v[126:127], v[126:127], 0.5, v[146:147] op_sel_hi:[1,0,1]
	v_pk_fma_f32 v[116:117], v[116:117], 0.5, v[222:223] op_sel_hi:[1,0,1]
	v_pk_fma_f32 v[146:147], v[112:113], 0.5, v[224:225] op_sel_hi:[1,0,1]
	v_pk_fma_f32 v[118:119], v[118:119], 0.5, v[182:183] op_sel_hi:[1,0,1]
	v_pk_mul_f32 v[220:221], v[124:125], v[124:125]
	v_pk_mul_f32 v[222:223], v[126:127], v[126:127]
	v_cvt_pk_bf16_f32 v112, v124, v125
	v_cvt_pk_bf16_f32 v113, v126, v127
	v_pk_mul_f32 v[124:125], v[116:117], v[116:117]
	v_pk_mul_f32 v[126:127], v[118:119], v[118:119]
	v_pk_mul_f32 v[228:229], v[146:147], v[146:147]
	v_cvt_pk_bf16_f32 v116, v116, v117
	v_cvt_pk_bf16_f32 v117, v118, v119
	v_cvt_pk_bf16_f32 v118, v146, v147
	v_add_f32_e32 v146, v220, v221
	v_add_f32_e32 v146, v222, v146
	v_lshlrev_b32_e32 v148, 16, v149
	v_and_b32_e32 v149, 0xffff0000, v149
	v_pk_mul_f32 v[224:225], v[120:121], v[120:121]
	v_add_f32_e32 v146, v223, v146
	v_pk_fma_f32 v[122:123], v[122:123], 0.5, v[148:149] op_sel_hi:[1,0,1]
	v_add_f32_e32 v146, v224, v146
	v_pk_mul_f32 v[226:227], v[122:123], v[122:123]
	v_add_f32_e32 v146, v225, v146
	v_add_f32_e32 v146, v226, v146
	v_add_f32_e32 v146, v227, v146
	v_add_f32_e32 v124, v124, v146
	v_add_f32_e32 v124, v125, v124
	v_add_f32_e32 v124, v126, v124
	v_lshlrev_b32_e32 v184, 16, v185
	v_and_b32_e32 v185, 0xffff0000, v185
	v_add_f32_e32 v124, v127, v124
	v_pk_fma_f32 v[148:149], v[114:115], 0.5, v[184:185] op_sel_hi:[1,0,1]
	v_add_f32_e32 v124, v228, v124
	v_pk_mul_f32 v[230:231], v[148:149], v[148:149]
	v_add_f32_e32 v124, v229, v124
	v_add_f32_e32 v124, v230, v124
	v_add_f32_e32 v209, v231, v124
	v_lshlrev_b32_e32 v124, 16, v212
	v_and_b32_e32 v125, 0xffff0000, v212
	v_pk_fma_f32 v[124:125], v[92:93], 0.5, v[124:125] op_sel_hi:[1,0,1]
	v_lshlrev_b32_e32 v92, 16, v211
	v_and_b32_e32 v93, 0xffff0000, v211
	v_pk_fma_f32 v[102:103], v[102:103], 0.5, v[92:93] op_sel_hi:[1,0,1]
	v_lshlrev_b32_e32 v92, 16, v213
	v_and_b32_e32 v93, 0xffff0000, v213
	v_pk_fma_f32 v[126:127], v[94:95], 0.5, v[92:93] op_sel_hi:[1,0,1]
	v_lshlrev_b32_e32 v92, 16, v214
	v_and_b32_e32 v93, 0xffff0000, v214
	v_pk_fma_f32 v[92:93], v[96:97], 0.5, v[92:93] op_sel_hi:[1,0,1]
	v_lshlrev_b32_e32 v96, 16, v217
	v_and_b32_e32 v97, 0xffff0000, v217
	v_lshlrev_b32_e32 v94, 16, v216
	v_and_b32_e32 v95, 0xffff0000, v216
	v_pk_fma_f32 v[90:91], v[90:91], 0.5, v[96:97] op_sel_hi:[1,0,1]
	v_lshlrev_b32_e32 v96, 16, v136
	v_and_b32_e32 v97, 0xffff0000, v136
	v_lshlrev_b32_e32 v182, 16, v194
	v_and_b32_e32 v183, 0xffff0000, v194
	v_pk_fma_f32 v[88:89], v[88:89], 0.5, v[94:95] op_sel_hi:[1,0,1]
	v_lshlrev_b32_e32 v94, 16, v215
	v_and_b32_e32 v95, 0xffff0000, v215
	v_pk_fma_f32 v[96:97], v[76:77], 0.5, v[96:97] op_sel_hi:[1,0,1]
	v_lshl_add_u64 v[76:77], v[168:169], 0, s[36:37]
	v_lshlrev_b32_e32 v184, 16, v196
	v_and_b32_e32 v185, 0xffff0000, v196
	v_cvt_pk_bf16_f32 v114, v120, v121
	v_pk_fma_f32 v[120:121], v[108:109], 0.5, v[182:183] op_sel_hi:[1,0,1]
	v_pk_fma_f32 v[94:95], v[98:99], 0.5, v[94:95] op_sel_hi:[1,0,1]
	v_lshlrev_b64 v[182:183], 11, v[76:77]
	v_lshlrev_b32_e32 v98, 16, v138
	v_and_b32_e32 v99, 0xffff0000, v138
	v_pk_fma_f32 v[108:109], v[104:105], 0.5, v[184:185] op_sel_hi:[1,0,1]
	v_lshl_add_u64 v[184:185], v[174:175], 0, v[182:183]
	v_pk_fma_f32 v[98:99], v[72:73], 0.5, v[98:99] op_sel_hi:[1,0,1]
	v_lshlrev_b32_e32 v72, 16, v137
	v_and_b32_e32 v73, 0xffff0000, v137
	v_lshlrev_b32_e32 v218, 16, v210
	v_and_b32_e32 v219, 0xffff0000, v210
	global_load_dwordx4 v[210:213], v[184:185], off
	v_pk_fma_f32 v[136:137], v[78:79], 0.5, v[72:73] op_sel_hi:[1,0,1]
	v_lshlrev_b32_e32 v72, 16, v139
	v_and_b32_e32 v73, 0xffff0000, v139
	v_pk_fma_f32 v[138:139], v[74:75], 0.5, v[72:73] op_sel_hi:[1,0,1]
	v_lshlrev_b32_e32 v72, 16, v132
	v_and_b32_e32 v73, 0xffff0000, v132
	v_pk_fma_f32 v[74:75], v[84:85], 0.5, v[72:73] op_sel_hi:[1,0,1]
	v_lshlrev_b32_e32 v72, 16, v134
	v_and_b32_e32 v73, 0xffff0000, v134
	v_pk_fma_f32 v[78:79], v[80:81], 0.5, v[72:73] op_sel_hi:[1,0,1]
	v_lshlrev_b32_e32 v72, 16, v133
	v_and_b32_e32 v73, 0xffff0000, v133
	v_pk_fma_f32 v[100:101], v[100:101], 0.5, v[218:219] op_sel_hi:[1,0,1]
	global_load_dwordx4 v[218:221], v[184:185], off offset:256
	v_pk_fma_f32 v[80:81], v[86:87], 0.5, v[72:73] op_sel_hi:[1,0,1]
	v_lshlrev_b32_e32 v72, 16, v135
	v_and_b32_e32 v73, 0xffff0000, v135
	v_pk_fma_f32 v[82:83], v[82:83], 0.5, v[72:73] op_sel_hi:[1,0,1]
	v_lshl_add_u64 v[72:73], v[168:169], 0, s[10:11]
	v_lshlrev_b64 v[132:133], 11, v[72:73]
	v_lshl_add_u64 v[134:135], v[174:175], 0, v[132:133]
	v_lshlrev_b32_e32 v84, 16, v128
	v_and_b32_e32 v85, 0xffff0000, v128
	global_load_dwordx4 v[226:229], v[134:135], off
	global_load_dwordx4 v[234:237], v[134:135], off offset:256
	v_pk_fma_f32 v[84:85], v[68:69], 0.5, v[84:85] op_sel_hi:[1,0,1]
	v_lshlrev_b32_e32 v68, 16, v130
	v_and_b32_e32 v69, 0xffff0000, v130
	v_pk_fma_f32 v[86:87], v[64:65], 0.5, v[68:69] op_sel_hi:[1,0,1]
	v_lshlrev_b32_e32 v64, 16, v129
	v_and_b32_e32 v65, 0xffff0000, v129
	s_mov_b64 s[10:11], 0xa0
	v_pk_fma_f32 v[128:129], v[70:71], 0.5, v[64:65] op_sel_hi:[1,0,1]
	v_lshl_add_u64 v[70:71], v[168:169], 0, s[10:11]
	s_mov_b64 s[10:11], 0xb0
	v_lshlrev_b32_e32 v64, 16, v131
	v_and_b32_e32 v65, 0xffff0000, v131
	v_lshlrev_b64 v[134:135], 11, v[70:71]
	v_lshl_add_u64 v[68:69], v[168:169], 0, s[10:11]
	v_pk_fma_f32 v[130:131], v[66:67], 0.5, v[64:65] op_sel_hi:[1,0,1]
	v_lshl_add_u64 v[64:65], v[174:175], 0, v[134:135]
	v_lshlrev_b64 v[184:185], 11, v[68:69]
	global_load_dwordx4 v[238:241], v[64:65], off
	global_load_dwordx4 v[242:245], v[64:65], off offset:256
	v_lshl_add_u64 v[64:65], v[174:175], 0, v[184:185]
	global_load_dwordx4 v[246:249], v[64:65], off
	s_nop 0
	global_load_dwordx4 v[64:67], v[64:65], off offset:256
	v_lshlrev_b32_e32 v194, 16, v195
	v_and_b32_e32 v195, 0xffff0000, v195
	v_lshlrev_b32_e32 v196, 16, v197
	v_and_b32_e32 v197, 0xffff0000, v197
	v_cvt_pk_bf16_f32 v115, v122, v123
	v_cvt_pk_bf16_f32 v119, v148, v149
	v_pk_fma_f32 v[122:123], v[110:111], 0.5, v[194:195] op_sel_hi:[1,0,1]
	v_pk_fma_f32 v[110:111], v[106:107], 0.5, v[196:197] op_sel_hi:[1,0,1]
	global_store_dwordx4 v[172:173], v[112:115], off
	global_store_dwordx4 v[172:173], v[116:119], off offset:256
	v_cvt_pk_bf16_f32 v104, v120, v121
	v_lshl_add_u64 v[112:113], s[28:29], 0, v[176:177]
	v_cvt_pk_bf16_f32 v105, v122, v123
	v_cvt_pk_bf16_f32 v106, v108, v109
	v_cvt_pk_bf16_f32 v107, v110, v111
	v_lshl_add_u64 v[112:113], v[112:113], 0, v[170:171]
	v_cvt_pk_bf16_f32 v146, v100, v101
	v_cvt_pk_bf16_f32 v147, v102, v103
	v_cvt_pk_bf16_f32 v148, v124, v125
	v_cvt_pk_bf16_f32 v149, v126, v127
	global_store_dwordx4 v[112:113], v[104:107], off
	global_store_dwordx4 v[112:113], v[146:149], off offset:256
	v_cvt_pk_bf16_f32 v194, v92, v93
	v_lshl_add_u64 v[104:105], s[28:29], 0, v[180:181]
	v_cvt_pk_bf16_f32 v195, v94, v95
	v_cvt_pk_bf16_f32 v196, v88, v89
	v_cvt_pk_bf16_f32 v197, v90, v91
	v_lshl_add_u64 v[104:105], v[104:105], 0, v[170:171]
	v_cvt_pk_bf16_f32 v214, v96, v97
	v_cvt_pk_bf16_f32 v215, v136, v137
	v_cvt_pk_bf16_f32 v216, v98, v99
	v_cvt_pk_bf16_f32 v217, v138, v139
	global_store_dwordx4 v[104:105], v[194:197], off
	global_store_dwordx4 v[104:105], v[214:217], off offset:256
	v_lshl_add_u64 v[104:105], s[28:29], 0, v[178:179]
	v_cvt_pk_bf16_f32 v222, v74, v75
	v_cvt_pk_bf16_f32 v223, v80, v81
	v_cvt_pk_bf16_f32 v224, v78, v79
	v_cvt_pk_bf16_f32 v225, v82, v83
	v_lshl_add_u64 v[104:105], v[104:105], 0, v[170:171]
	v_cvt_pk_bf16_f32 v230, v84, v85
	v_cvt_pk_bf16_f32 v231, v128, v129
	v_cvt_pk_bf16_f32 v232, v86, v87
	v_cvt_pk_bf16_f32 v233, v130, v131
	global_store_dwordx4 v[104:105], v[222:225], off
	global_store_dwordx4 v[104:105], v[230:233], off offset:256
	s_waitcnt vmcnt(8)
	v_lshlrev_b32_e32 v104, 16, v210
	v_and_b32_e32 v105, 0xffff0000, v210
	v_pk_fma_f32 v[60:61], v[60:61], 0.5, v[104:105] op_sel_hi:[1,0,1]
	v_lshlrev_b32_e32 v104, 16, v212
	v_and_b32_e32 v105, 0xffff0000, v212
	v_pk_fma_f32 v[56:57], v[56:57], 0.5, v[104:105] op_sel_hi:[1,0,1]
	v_lshlrev_b32_e32 v104, 16, v211
	v_and_b32_e32 v105, 0xffff0000, v211
	v_pk_fma_f32 v[62:63], v[62:63], 0.5, v[104:105] op_sel_hi:[1,0,1]
	v_lshlrev_b32_e32 v104, 16, v213
	v_and_b32_e32 v105, 0xffff0000, v213
	v_pk_fma_f32 v[58:59], v[58:59], 0.5, v[104:105] op_sel_hi:[1,0,1]
	v_lshlrev_b32_e32 v104, 16, v218
	v_and_b32_e32 v105, 0xffff0000, v218
	v_pk_fma_f32 v[52:53], v[52:53], 0.5, v[104:105] op_sel_hi:[1,0,1]
	v_lshlrev_b32_e32 v104, 16, v220
	v_and_b32_e32 v105, 0xffff0000, v220
	v_pk_fma_f32 v[104:105], v[44:45], 0.5, v[104:105] op_sel_hi:[1,0,1]
	v_lshlrev_b32_e32 v44, 16, v219
	v_and_b32_e32 v45, 0xffff0000, v219
	v_pk_fma_f32 v[54:55], v[54:55], 0.5, v[44:45] op_sel_hi:[1,0,1]
	v_lshlrev_b32_e32 v44, 16, v221
	v_and_b32_e32 v45, 0xffff0000, v221
	v_pk_fma_f32 v[106:107], v[46:47], 0.5, v[44:45] op_sel_hi:[1,0,1]
	v_lshlrev_b32_e32 v44, 16, v226
	v_and_b32_e32 v45, 0xffff0000, v226
	v_pk_fma_f32 v[44:45], v[48:49], 0.5, v[44:45] op_sel_hi:[1,0,1]
	v_lshlrev_b32_e32 v48, 16, v229
	v_and_b32_e32 v49, 0xffff0000, v229
	v_pk_fma_f32 v[42:43], v[42:43], 0.5, v[48:49] op_sel_hi:[1,0,1]
	v_lshlrev_b32_e32 v48, 16, v234
	v_and_b32_e32 v49, 0xffff0000, v234
	v_pk_fma_f32 v[36:37], v[36:37], 0.5, v[48:49] op_sel_hi:[1,0,1]
	v_lshlrev_b32_e32 v48, 16, v236
	v_and_b32_e32 v49, 0xffff0000, v236
	v_lshlrev_b32_e32 v46, 16, v228
	v_and_b32_e32 v47, 0xffff0000, v228
	v_pk_fma_f32 v[48:49], v[28:29], 0.5, v[48:49] op_sel_hi:[1,0,1]
	v_lshlrev_b32_e32 v28, 16, v235
	v_and_b32_e32 v29, 0xffff0000, v235
	v_pk_fma_f32 v[40:41], v[40:41], 0.5, v[46:47] op_sel_hi:[1,0,1]
	v_lshlrev_b32_e32 v46, 16, v227
	v_and_b32_e32 v47, 0xffff0000, v227
	v_pk_fma_f32 v[38:39], v[38:39], 0.5, v[28:29] op_sel_hi:[1,0,1]
	v_lshlrev_b32_e32 v28, 16, v237
	v_and_b32_e32 v29, 0xffff0000, v237
	v_pk_fma_f32 v[46:47], v[50:51], 0.5, v[46:47] op_sel_hi:[1,0,1]
	v_pk_fma_f32 v[50:51], v[30:31], 0.5, v[28:29] op_sel_hi:[1,0,1]
	v_lshlrev_b32_e32 v28, 16, v238
	v_and_b32_e32 v29, 0xffff0000, v238
	v_lshlrev_b32_e32 v180, 16, v64
	v_and_b32_e32 v181, 0xffff0000, v64
	v_pk_fma_f32 v[28:29], v[32:33], 0.5, v[28:29] op_sel_hi:[1,0,1]
	v_lshlrev_b32_e32 v32, 16, v241
	v_and_b32_e32 v33, 0xffff0000, v241
	v_pk_fma_f32 v[4:5], v[4:5], 0.5, v[180:181] op_sel_hi:[1,0,1]
	v_lshlrev_b32_e32 v180, 16, v66
	v_and_b32_e32 v181, 0xffff0000, v66
	v_pk_fma_f32 v[26:27], v[26:27], 0.5, v[32:33] op_sel_hi:[1,0,1]
	v_lshlrev_b32_e32 v32, 16, v242
	v_and_b32_e32 v33, 0xffff0000, v242
	v_pk_fma_f32 v[0:1], v[0:1], 0.5, v[180:181] op_sel_hi:[1,0,1]
	v_lshl_add_u64 v[180:181], s[28:29], 0, v[182:183]
	v_cvt_pk_bf16_f32 v112, v60, v61
	v_cvt_pk_bf16_f32 v113, v62, v63
	v_cvt_pk_bf16_f32 v114, v56, v57
	v_cvt_pk_bf16_f32 v115, v58, v59
	v_pk_fma_f32 v[20:21], v[20:21], 0.5, v[32:33] op_sel_hi:[1,0,1]
	v_lshlrev_b32_e32 v32, 16, v244
	v_and_b32_e32 v33, 0xffff0000, v244
	v_lshl_add_u64 v[180:181], v[180:181], 0, v[170:171]
	v_cvt_pk_bf16_f32 v116, v52, v53
	v_cvt_pk_bf16_f32 v117, v54, v55
	v_cvt_pk_bf16_f32 v118, v104, v105
	v_cvt_pk_bf16_f32 v119, v106, v107
	v_lshlrev_b32_e32 v30, 16, v240
	v_and_b32_e32 v31, 0xffff0000, v240
	v_pk_fma_f32 v[32:33], v[12:13], 0.5, v[32:33] op_sel_hi:[1,0,1]
	v_lshlrev_b32_e32 v12, 16, v243
	v_and_b32_e32 v13, 0xffff0000, v243
	global_store_dwordx4 v[180:181], v[112:115], off
	global_store_dwordx4 v[180:181], v[116:119], off offset:256
	v_cvt_pk_bf16_f32 v146, v44, v45
	v_lshl_add_u64 v[112:113], s[28:29], 0, v[132:133]
	v_cvt_pk_bf16_f32 v147, v46, v47
	v_cvt_pk_bf16_f32 v148, v40, v41
	v_cvt_pk_bf16_f32 v149, v42, v43
	v_pk_fma_f32 v[24:25], v[24:25], 0.5, v[30:31] op_sel_hi:[1,0,1]
	v_lshlrev_b32_e32 v30, 16, v239
	v_and_b32_e32 v31, 0xffff0000, v239
	v_pk_fma_f32 v[22:23], v[22:23], 0.5, v[12:13] op_sel_hi:[1,0,1]
	v_lshlrev_b32_e32 v12, 16, v245
	v_and_b32_e32 v13, 0xffff0000, v245
	v_lshl_add_u64 v[112:113], v[112:113], 0, v[170:171]
	v_cvt_pk_bf16_f32 v172, v36, v37
	v_cvt_pk_bf16_f32 v173, v38, v39
	v_cvt_pk_bf16_f32 v174, v48, v49
	v_cvt_pk_bf16_f32 v175, v50, v51
	v_pk_fma_f32 v[30:31], v[34:35], 0.5, v[30:31] op_sel_hi:[1,0,1]
	v_pk_fma_f32 v[34:35], v[14:15], 0.5, v[12:13] op_sel_hi:[1,0,1]
	v_lshlrev_b32_e32 v12, 16, v246
	v_and_b32_e32 v13, 0xffff0000, v246
	v_lshlrev_b32_e32 v14, 16, v248
	v_and_b32_e32 v15, 0xffff0000, v248
	global_store_dwordx4 v[112:113], v[146:149], off
	global_store_dwordx4 v[112:113], v[172:175], off offset:256
	v_lshl_add_u64 v[112:113], s[28:29], 0, v[134:135]
	v_cvt_pk_bf16_f32 v176, v28, v29
	v_cvt_pk_bf16_f32 v177, v30, v31
	v_cvt_pk_bf16_f32 v178, v24, v25
	v_cvt_pk_bf16_f32 v179, v26, v27
	v_pk_fma_f32 v[12:13], v[16:17], 0.5, v[12:13] op_sel_hi:[1,0,1]
	v_pk_fma_f32 v[8:9], v[8:9], 0.5, v[14:15] op_sel_hi:[1,0,1]
	v_lshlrev_b32_e32 v14, 16, v247
	v_and_b32_e32 v15, 0xffff0000, v247
	v_lshlrev_b32_e32 v16, 16, v249
	v_and_b32_e32 v17, 0xffff0000, v249
	v_lshlrev_b32_e32 v64, 16, v65
	v_and_b32_e32 v65, 0xffff0000, v65
	v_lshl_add_u64 v[112:113], v[112:113], 0, v[170:171]
	v_cvt_pk_bf16_f32 v194, v20, v21
	v_cvt_pk_bf16_f32 v195, v22, v23
	v_cvt_pk_bf16_f32 v196, v32, v33
	v_cvt_pk_bf16_f32 v197, v34, v35
	v_pk_fma_f32 v[14:15], v[18:19], 0.5, v[14:15] op_sel_hi:[1,0,1]
	v_pk_fma_f32 v[10:11], v[10:11], 0.5, v[16:17] op_sel_hi:[1,0,1]
	v_pk_fma_f32 v[6:7], v[6:7], 0.5, v[64:65] op_sel_hi:[1,0,1]
	v_lshlrev_b32_e32 v64, 16, v67
	v_and_b32_e32 v65, 0xffff0000, v67
	global_store_dwordx4 v[112:113], v[176:179], off
	global_store_dwordx4 v[112:113], v[194:197], off offset:256
	v_lshl_add_u64 v[112:113], s[28:29], 0, v[184:185]
	v_cvt_pk_bf16_f32 v16, v12, v13
	v_cvt_pk_bf16_f32 v17, v14, v15
	v_cvt_pk_bf16_f32 v18, v8, v9
	v_cvt_pk_bf16_f32 v19, v10, v11
	v_pk_fma_f32 v[2:3], v[2:3], 0.5, v[64:65] op_sel_hi:[1,0,1]
	v_lshl_add_u64 v[112:113], v[112:113], 0, v[170:171]
	v_cvt_pk_bf16_f32 v64, v4, v5
	v_cvt_pk_bf16_f32 v65, v6, v7
	v_cvt_pk_bf16_f32 v66, v0, v1
	v_cvt_pk_bf16_f32 v67, v2, v3
	global_store_dwordx4 v[112:113], v[16:19], off
	global_store_dwordx4 v[112:113], v[64:67], off offset:256
	s_lshl_b32 s10, s81, 2
	v_and_b32_e32 v17, 64, v188
	v_xor_b32_e32 v16, 16, v188
	v_add_u32_e32 v17, 64, v17
	v_cmp_lt_i32_e32 vcc, v16, v17
	v_xor_b32_e32 v18, 32, v188
	s_ashr_i32 s11, s10, 31
	v_cndmask_b32_e32 v16, v188, v16, vcc
	v_lshlrev_b32_e32 v16, 2, v16
	v_mov_b32_e32 v132, v209
	v_cmp_lt_i32_e32 vcc, v18, v17
	s_lshl_b64 s[10:11], s[10:11], 2
	s_add_u32 s38, s73, s10
	v_cndmask_b32_e32 v17, v188, v18, vcc
	v_lshlrev_b32_e32 v17, 2, v17
	s_addc_u32 s39, s74, s11
	v_pk_mul_f32 v[18:19], v[120:121], v[120:121]
	v_pk_mul_f32 v[64:65], v[122:123], v[122:123]
	v_add_f32_e32 v18, v18, v19
	v_add_f32_e32 v18, v64, v18
	v_pk_mul_f32 v[66:67], v[108:109], v[108:109]
	v_add_f32_e32 v18, v65, v18
	v_add_f32_e32 v18, v66, v18
	v_pk_mul_f32 v[108:109], v[110:111], v[110:111]
	v_add_f32_e32 v18, v67, v18
	v_add_f32_e32 v18, v108, v18
	v_pk_mul_f32 v[100:101], v[100:101], v[100:101]
	v_add_f32_e32 v18, v109, v18
	v_add_f32_e32 v18, v100, v18
	v_pk_mul_f32 v[102:103], v[102:103], v[102:103]
	v_add_f32_e32 v18, v101, v18
	v_add_f32_e32 v18, v102, v18
	v_pk_mul_f32 v[110:111], v[124:125], v[124:125]
	v_add_f32_e32 v18, v103, v18
	v_add_f32_e32 v18, v110, v18
	v_pk_mul_f32 v[112:113], v[126:127], v[126:127]
	v_add_f32_e32 v18, v111, v18
	v_add_f32_e32 v18, v112, v18
	v_add_f32_e32 v18, v113, v18
	v_mov_b32_e32 v133, v18
	v_pk_mul_f32 v[18:19], v[92:93], v[92:93]
	v_pk_mul_f32 v[64:65], v[94:95], v[94:95]
	v_add_f32_e32 v18, v18, v19
	v_add_f32_e32 v18, v64, v18
	v_pk_mul_f32 v[66:67], v[88:89], v[88:89]
	v_add_f32_e32 v18, v65, v18
	v_add_f32_e32 v18, v66, v18
	v_pk_mul_f32 v[88:89], v[90:91], v[90:91]
	v_add_f32_e32 v18, v67, v18
	v_add_f32_e32 v18, v88, v18
	v_pk_mul_f32 v[90:91], v[96:97], v[96:97]
	v_add_f32_e32 v18, v89, v18
	v_add_f32_e32 v18, v90, v18
	v_pk_mul_f32 v[92:93], v[136:137], v[136:137]
	v_add_f32_e32 v18, v91, v18
	v_add_f32_e32 v18, v92, v18
	v_pk_mul_f32 v[94:95], v[98:99], v[98:99]
	v_add_f32_e32 v18, v93, v18
	v_add_f32_e32 v18, v94, v18
	v_pk_mul_f32 v[96:97], v[138:139], v[138:139]
	v_add_f32_e32 v18, v95, v18
	v_add_f32_e32 v18, v96, v18
	v_add_f32_e32 v18, v97, v18
	v_mov_b32_e32 v134, v18
	v_pk_mul_f32 v[18:19], v[74:75], v[74:75]
	v_pk_mul_f32 v[210:211], v[60:61], v[60:61]
	v_pk_mul_f32 v[64:65], v[80:81], v[80:81]
	v_pk_mul_f32 v[60:61], v[62:63], v[62:63]
	v_add_f32_e32 v18, v18, v19
	v_add_f32_e32 v210, v210, v211
	v_add_f32_e32 v18, v64, v18
	v_add_f32_e32 v210, v60, v210
	v_pk_mul_f32 v[66:67], v[78:79], v[78:79]
	v_pk_mul_f32 v[56:57], v[56:57], v[56:57]
	v_add_f32_e32 v18, v65, v18
	v_add_f32_e32 v210, v61, v210
	v_add_f32_e32 v18, v66, v18
	v_add_f32_e32 v210, v56, v210
	v_pk_mul_f32 v[74:75], v[82:83], v[82:83]
	v_pk_mul_f32 v[58:59], v[58:59], v[58:59]
	v_add_f32_e32 v18, v67, v18
	v_add_f32_e32 v210, v57, v210
	v_add_f32_e32 v18, v74, v18
	v_add_f32_e32 v210, v58, v210
	v_pk_mul_f32 v[78:79], v[84:85], v[84:85]
	v_pk_mul_f32 v[52:53], v[52:53], v[52:53]
	v_add_f32_e32 v18, v75, v18
	v_add_f32_e32 v210, v59, v210
	v_add_f32_e32 v18, v78, v18
	v_add_f32_e32 v210, v52, v210
	v_pk_mul_f32 v[80:81], v[128:129], v[128:129]
	v_pk_mul_f32 v[54:55], v[54:55], v[54:55]
	v_add_f32_e32 v18, v79, v18
	v_add_f32_e32 v210, v53, v210
	v_add_f32_e32 v18, v80, v18
	v_add_f32_e32 v210, v54, v210
	v_pk_mul_f32 v[82:83], v[86:87], v[86:87]
	v_pk_mul_f32 v[62:63], v[104:105], v[104:105]
	v_add_f32_e32 v18, v81, v18
	v_add_f32_e32 v210, v55, v210
	v_add_f32_e32 v18, v82, v18
	v_add_f32_e32 v210, v62, v210
	v_pk_mul_f32 v[84:85], v[130:131], v[130:131]
	v_pk_mul_f32 v[212:213], v[106:107], v[106:107]
	v_add_f32_e32 v18, v83, v18
	v_add_f32_e32 v210, v63, v210
	v_add_f32_e32 v18, v84, v18
	v_add_f32_e32 v210, v212, v210
	v_add_f32_e32 v18, v85, v18
	v_add_f32_e32 v210, v213, v210
	v_mov_b32_e32 v135, v18
	v_mov_b32_e32 v146, v210
	v_pk_mul_f32 v[18:19], v[44:45], v[44:45]
	v_pk_mul_f32 v[210:211], v[28:29], v[28:29]
	v_pk_mul_f32 v[44:45], v[46:47], v[46:47]
	v_pk_mul_f32 v[28:29], v[30:31], v[30:31]
	v_add_f32_e32 v18, v18, v19
	v_add_f32_e32 v210, v210, v211
	v_add_f32_e32 v18, v44, v18
	v_add_f32_e32 v210, v28, v210
	v_pk_mul_f32 v[40:41], v[40:41], v[40:41]
	v_pk_mul_f32 v[24:25], v[24:25], v[24:25]
	v_add_f32_e32 v18, v45, v18
	v_add_f32_e32 v210, v29, v210
	v_add_f32_e32 v18, v40, v18
	v_add_f32_e32 v210, v24, v210
	v_pk_mul_f32 v[42:43], v[42:43], v[42:43]
	v_pk_mul_f32 v[26:27], v[26:27], v[26:27]
	v_add_f32_e32 v18, v41, v18
	v_add_f32_e32 v210, v25, v210
	v_add_f32_e32 v18, v42, v18
	v_add_f32_e32 v210, v26, v210
	v_pk_mul_f32 v[36:37], v[36:37], v[36:37]
	v_pk_mul_f32 v[20:21], v[20:21], v[20:21]
	v_add_f32_e32 v18, v43, v18
	v_add_f32_e32 v210, v27, v210
	v_add_f32_e32 v18, v36, v18
	v_add_f32_e32 v210, v20, v210
	v_pk_mul_f32 v[38:39], v[38:39], v[38:39]
	v_pk_mul_f32 v[22:23], v[22:23], v[22:23]
	v_add_f32_e32 v18, v37, v18
	v_add_f32_e32 v210, v21, v210
	v_add_f32_e32 v18, v38, v18
	v_add_f32_e32 v210, v22, v210
	v_pk_mul_f32 v[46:47], v[48:49], v[48:49]
	v_pk_mul_f32 v[30:31], v[32:33], v[32:33]
	v_add_f32_e32 v18, v39, v18
	v_add_f32_e32 v210, v23, v210
	v_add_f32_e32 v18, v46, v18
	v_add_f32_e32 v210, v30, v210
	v_pk_mul_f32 v[48:49], v[50:51], v[50:51]
	v_pk_mul_f32 v[32:33], v[34:35], v[34:35]
	v_add_f32_e32 v18, v47, v18
	v_add_f32_e32 v210, v31, v210
	v_add_f32_e32 v18, v48, v18
	v_add_f32_e32 v210, v32, v210
	v_add_f32_e32 v18, v49, v18
	v_add_f32_e32 v210, v33, v210
	v_mov_b32_e32 v147, v18
	v_mov_b32_e32 v148, v210
	v_pk_mul_f32 v[12:13], v[12:13], v[12:13]
	v_pk_mul_f32 v[14:15], v[14:15], v[14:15]
	v_add_f32_e32 v12, v12, v13
	v_add_f32_e32 v12, v14, v12
	v_pk_mul_f32 v[8:9], v[8:9], v[8:9]
	v_add_f32_e32 v12, v15, v12
	v_add_f32_e32 v8, v8, v12
	v_pk_mul_f32 v[10:11], v[10:11], v[10:11]
	v_add_f32_e32 v8, v9, v8
	v_add_f32_e32 v8, v10, v8
	v_pk_mul_f32 v[4:5], v[4:5], v[4:5]
	v_add_f32_e32 v8, v11, v8
	v_add_f32_e32 v4, v4, v8
	v_pk_mul_f32 v[6:7], v[6:7], v[6:7]
	v_add_f32_e32 v4, v5, v4
	v_add_f32_e32 v4, v6, v4
	v_pk_mul_f32 v[0:1], v[0:1], v[0:1]
	v_add_f32_e32 v4, v7, v4
	v_add_f32_e32 v0, v0, v4
	v_pk_mul_f32 v[2:3], v[2:3], v[2:3]
	v_add_f32_e32 v0, v1, v0
	v_add_f32_e32 v0, v2, v0
	v_add_f32_e32 v0, v3, v0
	v_mov_b32_e32 v149, v0
	ds_bpermute_b32 v172, v16, v132
	ds_bpermute_b32 v173, v16, v133
	ds_bpermute_b32 v174, v16, v134
	ds_bpermute_b32 v175, v16, v135
	ds_bpermute_b32 v180, v16, v146
	ds_bpermute_b32 v181, v16, v147
	ds_bpermute_b32 v182, v16, v148
	ds_bpermute_b32 v183, v16, v149
	s_waitcnt lgkmcnt(0)
	v_add_f32_e32 v132, v132, v172
	v_add_f32_e32 v133, v133, v173
	v_add_f32_e32 v134, v134, v174
	v_add_f32_e32 v135, v135, v175
	v_add_f32_e32 v146, v146, v180
	v_add_f32_e32 v147, v147, v181
	v_add_f32_e32 v148, v148, v182
	v_add_f32_e32 v149, v149, v183
	ds_bpermute_b32 v172, v17, v132
	ds_bpermute_b32 v173, v17, v133
	ds_bpermute_b32 v174, v17, v134
	ds_bpermute_b32 v175, v17, v135
	ds_bpermute_b32 v180, v17, v146
	ds_bpermute_b32 v181, v17, v147
	ds_bpermute_b32 v182, v17, v148
	ds_bpermute_b32 v183, v17, v149
	s_and_saveexec_b64 s[46:47], s[42:43]
	s_cbranch_execz .LBB0_19
	s_waitcnt lgkmcnt(0)
	v_add_f32_e32 v132, v132, v172
	v_lshlrev_b64 v[18:19], 6, v[168:169]
	v_lshl_add_u64 v[18:19], s[38:39], 0, v[18:19]
	global_store_dword v[18:19], v132, off
	v_add_f32_e32 v133, v133, v173
	v_lshlrev_b64 v[18:19], 6, v[166:167]
	v_lshl_add_u64 v[18:19], s[38:39], 0, v[18:19]
	global_store_dword v[18:19], v133, off
	v_add_f32_e32 v134, v134, v174
	v_lshlrev_b64 v[18:19], 6, v[164:165]
	v_lshl_add_u64 v[18:19], s[38:39], 0, v[18:19]
	global_store_dword v[18:19], v134, off
	v_add_f32_e32 v135, v135, v175
	v_lshlrev_b64 v[18:19], 6, v[162:163]
	v_lshl_add_u64 v[18:19], s[38:39], 0, v[18:19]
	global_store_dword v[18:19], v135, off
	v_add_f32_e32 v146, v146, v180
	v_lshlrev_b64 v[18:19], 6, v[76:77]
	v_lshl_add_u64 v[18:19], s[38:39], 0, v[18:19]
	global_store_dword v[18:19], v146, off
	v_add_f32_e32 v147, v147, v181
	v_lshlrev_b64 v[18:19], 6, v[72:73]
	v_lshl_add_u64 v[18:19], s[38:39], 0, v[18:19]
	global_store_dword v[18:19], v147, off
	v_add_f32_e32 v148, v148, v182
	v_lshlrev_b64 v[18:19], 6, v[70:71]
	v_lshl_add_u64 v[18:19], s[38:39], 0, v[18:19]
	global_store_dword v[18:19], v148, off
	v_add_f32_e32 v149, v149, v183
	v_lshlrev_b64 v[18:19], 6, v[68:69]
	v_lshl_add_u64 v[18:19], s[38:39], 0, v[18:19]
	global_store_dword v[18:19], v149, off
	s_branch .LBB0_19
.LBB0_48:
	s_waitcnt vmcnt(0)
	s_setprio 0
	s_cmpk_gt_u32 s9, 0xff
	s_cbranch_scc1 .LBB0_50
	s_barrier

.LBB0_76:
	s_add_u32 s10, s50, 0x100
	s_addc_u32 s11, s51, 0
	s_ashr_i32 s35, s34, 31
	s_lshl_b64 s[46:47], s[34:35], 19
	s_add_u32 s48, s33, s46
	s_addc_u32 s49, s41, s47
	s_and_b64 s[46:47], s[44:45], exec
	s_cselect_b32 s12, s49, s27
	s_cselect_b32 s31, s48, s26
	s_ashr_i32 s39, s38, 31
	s_lshl_b64 s[46:47], s[38:39], 19
	s_add_u32 s46, s57, s46
	s_addc_u32 s47, s58, s47
	s_and_b64 s[52:53], s[44:45], exec
	s_cselect_b32 s35, s47, s51
	s_cselect_b32 s39, s46, s50
	s_add_u32 s50, s26, 0x40080
	s_addc_u32 s51, s27, 0
	v_lshl_add_u64 v[150:151], s[50:51], 0, v[136:137]
	v_lshl_add_u64 v[152:153], s[50:51], 0, v[138:139]
	s_mov_b32 s81, -2
	s_mov_b64 s[50:51], 0
	s_add_u32 s6, s26, s50
	s_addc_u32 s19, s27, s51
	s_add_u32 s6, s6, 0x100
	s_addc_u32 s19, s19, 0
	s_add_u32 s23, s10, s50
	s_addc_u32 s52, s11, s51
	s_add_i32 s82, 0, 0x10000
	v_add_u32_e32 v146, s82, v154
	ds_read_b128 v[158:161], v146
	ds_read_b128 v[162:165], v146 offset:1024
	ds_read_b128 v[166:169], v146 offset:2048
	ds_read_b128 v[170:173], v146 offset:3072
	s_cmpk_eq_i32 s50, 0x700
	s_cselect_b32 s55, s12, s19
	s_cselect_b32 s54, s31, s6
	s_cselect_b32 s53, s35, s52
	s_cselect_b32 s52, s39, s23
	v_lshl_add_u64 v[146:147], v[150:151], 0, s[50:51]
	s_add_i32 m0, s68, 0xc000
	ds_read_b128 v[174:177], v157
	ds_read_b128 v[178:181], v157 offset:1024
	ds_read_b128 v[182:185], v157 offset:2048
	ds_read_b128 v[206:209], v157 offset:3072
	ds_read_b128 v[210:213], v157 offset:4096
	ds_read_b128 v[214:217], v157 offset:5120
	ds_read_b128 v[218:221], v157 offset:6144
	ds_read_b128 v[222:225], v157 offset:7168
	global_load_lds_dwordx4 v[146:147], off
	v_lshl_add_u64 v[146:147], v[152:153], 0, s[50:51]
	s_add_i32 m0, s68, 0xe000
	s_nop 0
	global_load_lds_dwordx4 v[146:147], off
	s_add_i32 s6, 0, 0x14000
	v_add_u32_e32 v146, s6, v154
	ds_read_b128 v[226:229], v146
	ds_read_b128 v[230:233], v146 offset:1024
	ds_read_b128 v[234:237], v146 offset:2048
	ds_read_b128 v[238:241], v146 offset:3072
	s_setprio 0
	s_waitcnt vmcnt(16)
	s_cmp_lg_u32 s100, 0
	s_cbranch_scc1 .Lm4ap_77
	s_waitcnt vmcnt(8)

.LBB0_77:
	s_add_u32 s6, s26, s50
	s_addc_u32 s19, s27, s51
	s_add_u32 s6, s6, 0x100
	s_addc_u32 s19, s19, 0
	s_add_u32 s23, s10, s50
	s_addc_u32 s52, s11, s51
	s_add_i32 s82, 0, 0x10000
	v_add_u32_e32 v146, s82, v154
	ds_read_b128 v[158:161], v146
	ds_read_b128 v[162:165], v146 offset:1024
	ds_read_b128 v[166:169], v146 offset:2048
	ds_read_b128 v[170:173], v146 offset:3072
	s_cmpk_eq_i32 s50, 0x700
	s_cselect_b32 s55, s12, s19
	s_cselect_b32 s54, s31, s6
	s_cselect_b32 s53, s35, s52
	s_cselect_b32 s52, s39, s23
	v_lshl_add_u64 v[146:147], v[150:151], 0, s[50:51]
	s_add_i32 m0, s68, 0xc000
	ds_read_b128 v[174:177], v157
	ds_read_b128 v[178:181], v157 offset:1024
	ds_read_b128 v[182:185], v157 offset:2048
	ds_read_b128 v[206:209], v157 offset:3072
	ds_read_b128 v[210:213], v157 offset:4096
	ds_read_b128 v[214:217], v157 offset:5120
	ds_read_b128 v[218:221], v157 offset:6144
	ds_read_b128 v[222:225], v157 offset:7168
	global_load_lds_dwordx4 v[146:147], off
	v_lshl_add_u64 v[146:147], v[152:153], 0, s[50:51]
	s_add_i32 m0, s68, 0xe000
	s_nop 0
	global_load_lds_dwordx4 v[146:147], off
	s_add_i32 s6, 0, 0x14000
	v_add_u32_e32 v146, s6, v154
	ds_read_b128 v[226:229], v146
	ds_read_b128 v[230:233], v146 offset:1024
	ds_read_b128 v[234:237], v146 offset:2048
	ds_read_b128 v[238:241], v146 offset:3072
	s_nop 0
	s_waitcnt vmcnt(8)
	s_waitcnt lgkmcnt(0)
	s_barrier
	v_mfma_f32_16x16x32_bf16 v[124:127], v[158:161], v[174:177], v[124:127]
	v_mfma_f32_16x16x32_bf16 v[120:123], v[166:169], v[174:177], v[120:123]
	v_mfma_f32_16x16x32_bf16 v[116:119], v[158:161], v[182:185], v[116:119]
	v_mfma_f32_16x16x32_bf16 v[112:115], v[166:169], v[182:185], v[112:115]
	v_mfma_f32_16x16x32_bf16 v[108:111], v[158:161], v[210:213], v[108:111]
	v_mfma_f32_16x16x32_bf16 v[104:107], v[166:169], v[210:213], v[104:107]
	v_mfma_f32_16x16x32_bf16 v[100:103], v[158:161], v[218:221], v[100:103]
	v_mfma_f32_16x16x32_bf16 v[96:99], v[166:169], v[218:221], v[96:99]
	v_mfma_f32_16x16x32_bf16 v[124:127], v[162:165], v[178:181], v[124:127]
	v_mfma_f32_16x16x32_bf16 v[120:123], v[170:173], v[178:181], v[120:123]
	v_mfma_f32_16x16x32_bf16 v[116:119], v[162:165], v[206:209], v[116:119]
	v_mfma_f32_16x16x32_bf16 v[112:115], v[170:173], v[206:209], v[112:115]
	v_mfma_f32_16x16x32_bf16 v[108:111], v[162:165], v[214:217], v[108:111]
	v_mfma_f32_16x16x32_bf16 v[104:107], v[170:173], v[214:217], v[104:107]
	v_mfma_f32_16x16x32_bf16 v[100:103], v[162:165], v[222:225], v[100:103]
	v_mfma_f32_16x16x32_bf16 v[96:99], v[170:173], v[222:225], v[96:99]
	v_mfma_f32_16x16x32_bf16 v[92:95], v[226:229], v[174:177], v[92:95]
	v_mfma_f32_16x16x32_bf16 v[88:91], v[234:237], v[174:177], v[88:91]
	v_mfma_f32_16x16x32_bf16 v[84:87], v[226:229], v[182:185], v[84:87]
	v_mfma_f32_16x16x32_bf16 v[80:83], v[234:237], v[182:185], v[80:83]
	v_mfma_f32_16x16x32_bf16 v[76:79], v[226:229], v[210:213], v[76:79]
	v_mfma_f32_16x16x32_bf16 v[72:75], v[234:237], v[210:213], v[72:75]
	v_mfma_f32_16x16x32_bf16 v[68:71], v[226:229], v[218:221], v[68:71]
	v_mfma_f32_16x16x32_bf16 v[64:67], v[234:237], v[218:221], v[64:67]
	v_mfma_f32_16x16x32_bf16 v[92:95], v[230:233], v[178:181], v[92:95]
	v_mfma_f32_16x16x32_bf16 v[88:91], v[238:241], v[178:181], v[88:91]
	v_mfma_f32_16x16x32_bf16 v[84:87], v[230:233], v[206:209], v[84:87]
	v_mfma_f32_16x16x32_bf16 v[80:83], v[238:241], v[206:209], v[80:83]
	v_mfma_f32_16x16x32_bf16 v[76:79], v[230:233], v[214:217], v[76:79]
	v_mfma_f32_16x16x32_bf16 v[72:75], v[238:241], v[214:217], v[72:75]
	v_mfma_f32_16x16x32_bf16 v[68:71], v[230:233], v[222:225], v[68:71]
	v_mfma_f32_16x16x32_bf16 v[64:67], v[238:241], v[222:225], v[64:67]
	s_barrier
	s_add_i32 s19, s82, s59
	v_lshl_add_u64 v[146:147], s[52:53], 0, v[140:141]
	s_mov_b32 m0, s19
	v_lshl_add_u64 v[148:149], s[52:53], 0, v[132:133]
	global_load_lds_dwordx4 v[146:147], off
	s_add_i32 m0, s19, 0x2000
	s_nop 0
	global_load_lds_dwordx4 v[148:149], off
	s_mov_b32 m0, s68
	v_lshl_add_u64 v[194:195], s[54:55], 0, v[128:129]
	ds_read_b128 v[174:177], v157 offset:16384
	ds_read_b128 v[178:181], v157 offset:17408
	ds_read_b128 v[182:185], v157 offset:18432
	ds_read_b128 v[206:209], v157 offset:19456
	ds_read_b128 v[210:213], v157 offset:20480
	ds_read_b128 v[214:217], v157 offset:21504
	ds_read_b128 v[218:221], v157 offset:22528
	ds_read_b128 v[222:225], v157 offset:23552
	global_load_lds_dwordx4 v[194:195], off
	v_lshl_add_u64 v[196:197], s[54:55], 0, v[130:131]
	s_mov_b32 m0, s69
	s_nop 0
	global_load_lds_dwordx4 v[196:197], off
	s_add_u32 s82, s52, 0x40000
	s_addc_u32 s83, s53, 0
	s_add_i32 s6, s6, s59
	v_lshl_add_u64 v[250:251], s[82:83], 0, v[140:141]
	s_mov_b32 m0, s6
	s_nop 0
	global_load_lds_dwordx4 v[250:251], off
	v_lshl_add_u64 v[250:251], s[82:83], 0, v[132:133]
	s_add_i32 m0, s6, 0x2000
	s_nop 0
	global_load_lds_dwordx4 v[250:251], off
	s_nop 0
	s_waitcnt vmcnt(8)
	s_waitcnt lgkmcnt(0)
	s_barrier
	v_mfma_f32_16x16x32_bf16 v[60:63], v[158:161], v[174:177], v[60:63]
	v_mfma_f32_16x16x32_bf16 v[56:59], v[166:169], v[174:177], v[56:59]
	v_mfma_f32_16x16x32_bf16 v[52:55], v[158:161], v[182:185], v[52:55]
	v_mfma_f32_16x16x32_bf16 v[48:51], v[166:169], v[182:185], v[48:51]
	v_mfma_f32_16x16x32_bf16 v[44:47], v[158:161], v[210:213], v[44:47]
	v_mfma_f32_16x16x32_bf16 v[40:43], v[166:169], v[210:213], v[40:43]
	v_mfma_f32_16x16x32_bf16 v[36:39], v[158:161], v[218:221], v[36:39]
	v_mfma_f32_16x16x32_bf16 v[32:35], v[166:169], v[218:221], v[32:35]
	v_mfma_f32_16x16x32_bf16 v[60:63], v[162:165], v[178:181], v[60:63]
	v_mfma_f32_16x16x32_bf16 v[56:59], v[170:173], v[178:181], v[56:59]
	v_mfma_f32_16x16x32_bf16 v[52:55], v[162:165], v[206:209], v[52:55]
	v_mfma_f32_16x16x32_bf16 v[48:51], v[170:173], v[206:209], v[48:51]
	v_mfma_f32_16x16x32_bf16 v[44:47], v[162:165], v[214:217], v[44:47]
	v_mfma_f32_16x16x32_bf16 v[40:43], v[170:173], v[214:217], v[40:43]
	v_mfma_f32_16x16x32_bf16 v[36:39], v[162:165], v[222:225], v[36:39]
	v_mfma_f32_16x16x32_bf16 v[32:35], v[170:173], v[222:225], v[32:35]
	v_mfma_f32_16x16x32_bf16 v[28:31], v[226:229], v[174:177], v[28:31]
	v_mfma_f32_16x16x32_bf16 v[24:27], v[234:237], v[174:177], v[24:27]
	v_mfma_f32_16x16x32_bf16 v[20:23], v[226:229], v[182:185], v[20:23]
	v_mfma_f32_16x16x32_bf16 v[16:19], v[234:237], v[182:185], v[16:19]
	v_mfma_f32_16x16x32_bf16 v[12:15], v[226:229], v[210:213], v[12:15]
	v_mfma_f32_16x16x32_bf16 v[8:11], v[234:237], v[210:213], v[8:11]
	v_mfma_f32_16x16x32_bf16 v[4:7], v[226:229], v[218:221], v[4:7]
	v_mfma_f32_16x16x32_bf16 v[0:3], v[234:237], v[218:221], v[0:3]
	v_mfma_f32_16x16x32_bf16 v[28:31], v[230:233], v[178:181], v[28:31]
	v_mfma_f32_16x16x32_bf16 v[24:27], v[238:241], v[178:181], v[24:27]
	v_mfma_f32_16x16x32_bf16 v[20:23], v[230:233], v[206:209], v[20:23]
	v_mfma_f32_16x16x32_bf16 v[16:19], v[238:241], v[206:209], v[16:19]
	v_mfma_f32_16x16x32_bf16 v[12:15], v[230:233], v[214:217], v[12:15]
	v_mfma_f32_16x16x32_bf16 v[8:11], v[238:241], v[214:217], v[8:11]
	v_mfma_f32_16x16x32_bf16 v[4:7], v[230:233], v[222:225], v[4:7]
	v_mfma_f32_16x16x32_bf16 v[0:3], v[238:241], v[222:225], v[0:3]
	s_barrier
	s_add_i32 s6, 0, 0x18000
	v_add_u32_e32 v170, s6, v154
	ds_read_b128 v[158:161], v170
	ds_read_b128 v[162:165], v170 offset:1024
	ds_read_b128 v[166:169], v170 offset:2048
	ds_read_b128 v[170:173], v170 offset:3072
	s_add_u32 s54, s54, 0x40000
	s_addc_u32 s55, s55, 0
	s_mov_b32 m0, s70
	v_lshl_add_u64 v[226:227], s[54:55], 0, v[128:129]
	ds_read_b128 v[174:177], v157 offset:32768
	ds_read_b128 v[178:181], v157 offset:33792
	ds_read_b128 v[182:185], v157 offset:34816
	ds_read_b128 v[206:209], v157 offset:35840
	ds_read_b128 v[210:213], v157 offset:36864
	ds_read_b128 v[214:217], v157 offset:37888
	ds_read_b128 v[218:221], v157 offset:38912
	ds_read_b128 v[222:225], v157 offset:39936
	global_load_lds_dwordx4 v[226:227], off
	v_lshl_add_u64 v[226:227], s[54:55], 0, v[130:131]
	s_mov_b32 m0, s71
	s_nop 0
	global_load_lds_dwordx4 v[226:227], off
	s_add_i32 s19, 0, 0x1c000
	v_add_u32_e32 v192, s19, v154
	ds_read_b128 v[226:229], v192
	ds_read_b128 v[230:233], v192 offset:1024
	ds_read_b128 v[234:237], v192 offset:2048
	ds_read_b128 v[238:241], v192 offset:3072
	s_waitcnt vmcnt(8)
	s_waitcnt lgkmcnt(0)
	s_barrier
	v_mfma_f32_16x16x32_bf16 v[124:127], v[158:161], v[174:177], v[124:127]
	v_mfma_f32_16x16x32_bf16 v[120:123], v[166:169], v[174:177], v[120:123]
	v_mfma_f32_16x16x32_bf16 v[116:119], v[158:161], v[182:185], v[116:119]
	v_mfma_f32_16x16x32_bf16 v[112:115], v[166:169], v[182:185], v[112:115]
	v_mfma_f32_16x16x32_bf16 v[108:111], v[158:161], v[210:213], v[108:111]
	v_mfma_f32_16x16x32_bf16 v[104:107], v[166:169], v[210:213], v[104:107]
	v_mfma_f32_16x16x32_bf16 v[100:103], v[158:161], v[218:221], v[100:103]
	v_mfma_f32_16x16x32_bf16 v[96:99], v[166:169], v[218:221], v[96:99]
	v_mfma_f32_16x16x32_bf16 v[124:127], v[162:165], v[178:181], v[124:127]
	v_mfma_f32_16x16x32_bf16 v[120:123], v[170:173], v[178:181], v[120:123]
	v_mfma_f32_16x16x32_bf16 v[116:119], v[162:165], v[206:209], v[116:119]
	v_mfma_f32_16x16x32_bf16 v[112:115], v[170:173], v[206:209], v[112:115]
	v_mfma_f32_16x16x32_bf16 v[108:111], v[162:165], v[214:217], v[108:111]
	v_mfma_f32_16x16x32_bf16 v[104:107], v[170:173], v[214:217], v[104:107]
	v_mfma_f32_16x16x32_bf16 v[100:103], v[162:165], v[222:225], v[100:103]
	v_mfma_f32_16x16x32_bf16 v[96:99], v[170:173], v[222:225], v[96:99]
	v_mfma_f32_16x16x32_bf16 v[92:95], v[226:229], v[174:177], v[92:95]
	v_mfma_f32_16x16x32_bf16 v[88:91], v[234:237], v[174:177], v[88:91]
	v_mfma_f32_16x16x32_bf16 v[84:87], v[226:229], v[182:185], v[84:87]
	v_mfma_f32_16x16x32_bf16 v[80:83], v[234:237], v[182:185], v[80:83]
	v_mfma_f32_16x16x32_bf16 v[76:79], v[226:229], v[210:213], v[76:79]
	v_mfma_f32_16x16x32_bf16 v[72:75], v[234:237], v[210:213], v[72:75]
	v_mfma_f32_16x16x32_bf16 v[68:71], v[226:229], v[218:221], v[68:71]
	v_mfma_f32_16x16x32_bf16 v[64:67], v[234:237], v[218:221], v[64:67]
	v_mfma_f32_16x16x32_bf16 v[92:95], v[230:233], v[178:181], v[92:95]
	v_mfma_f32_16x16x32_bf16 v[88:91], v[238:241], v[178:181], v[88:91]
	v_mfma_f32_16x16x32_bf16 v[84:87], v[230:233], v[206:209], v[84:87]
	v_mfma_f32_16x16x32_bf16 v[80:83], v[238:241], v[206:209], v[80:83]
	v_mfma_f32_16x16x32_bf16 v[76:79], v[230:233], v[214:217], v[76:79]
	v_mfma_f32_16x16x32_bf16 v[72:75], v[238:241], v[214:217], v[72:75]
	v_mfma_f32_16x16x32_bf16 v[68:71], v[230:233], v[222:225], v[68:71]
	v_mfma_f32_16x16x32_bf16 v[64:67], v[238:241], v[222:225], v[64:67]
	s_barrier
	s_add_i32 s6, s6, s59
	v_lshl_add_u64 v[146:147], v[146:147], 0, s[36:37]
	s_mov_b32 m0, s6
	s_nop 0
	global_load_lds_dwordx4 v[146:147], off
	v_lshl_add_u64 v[146:147], v[148:149], 0, s[36:37]
	s_add_i32 m0, s6, 0x2000
	s_nop 0
	global_load_lds_dwordx4 v[146:147], off
	s_mov_b32 m0, s72
	v_lshl_add_u64 v[146:147], v[194:195], 0, s[36:37]
	ds_read_b128 v[174:177], v157 offset:49152
	ds_read_b128 v[178:181], v157 offset:50176
	ds_read_b128 v[182:185], v157 offset:51200
	ds_read_b128 v[206:209], v157 offset:52224
	ds_read_b128 v[210:213], v157 offset:53248
	ds_read_b128 v[214:217], v157 offset:54272
	ds_read_b128 v[218:221], v157 offset:55296
	ds_read_b128 v[222:225], v157 offset:56320
	global_load_lds_dwordx4 v[146:147], off
	v_lshl_add_u64 v[146:147], v[196:197], 0, s[36:37]
	s_mov_b32 m0, s73
	s_nop 0
	global_load_lds_dwordx4 v[146:147], off
	s_add_u32 s52, s52, 0x40080
	s_addc_u32 s53, s53, 0
	s_add_i32 s6, s19, s59
	v_lshl_add_u64 v[146:147], s[52:53], 0, v[140:141]
	s_mov_b32 m0, s6
	s_nop 0
	global_load_lds_dwordx4 v[146:147], off
	v_lshl_add_u64 v[146:147], s[52:53], 0, v[132:133]
	s_add_i32 m0, s6, 0x2000
	s_nop 0
	global_load_lds_dwordx4 v[146:147], off
	s_add_i32 s81, s81, 2
	s_add_u32 s50, s50, 0x100
	s_addc_u32 s51, s51, 0
	s_cmp_gt_u32 s81, 13
	s_nop 0
	s_waitcnt vmcnt(8)
	s_waitcnt lgkmcnt(0)
	s_barrier
	v_mfma_f32_16x16x32_bf16 v[60:63], v[158:161], v[174:177], v[60:63]
	v_mfma_f32_16x16x32_bf16 v[56:59], v[166:169], v[174:177], v[56:59]
	v_mfma_f32_16x16x32_bf16 v[52:55], v[158:161], v[182:185], v[52:55]
	v_mfma_f32_16x16x32_bf16 v[48:51], v[166:169], v[182:185], v[48:51]
	v_mfma_f32_16x16x32_bf16 v[44:47], v[158:161], v[210:213], v[44:47]
	v_mfma_f32_16x16x32_bf16 v[40:43], v[166:169], v[210:213], v[40:43]
	v_mfma_f32_16x16x32_bf16 v[36:39], v[158:161], v[218:221], v[36:39]
	v_mfma_f32_16x16x32_bf16 v[32:35], v[166:169], v[218:221], v[32:35]
	v_mfma_f32_16x16x32_bf16 v[60:63], v[162:165], v[178:181], v[60:63]
	v_mfma_f32_16x16x32_bf16 v[56:59], v[170:173], v[178:181], v[56:59]
	v_mfma_f32_16x16x32_bf16 v[52:55], v[162:165], v[206:209], v[52:55]
	v_mfma_f32_16x16x32_bf16 v[48:51], v[170:173], v[206:209], v[48:51]
	v_mfma_f32_16x16x32_bf16 v[44:47], v[162:165], v[214:217], v[44:47]
	v_mfma_f32_16x16x32_bf16 v[40:43], v[170:173], v[214:217], v[40:43]
	v_mfma_f32_16x16x32_bf16 v[36:39], v[162:165], v[222:225], v[36:39]
	v_mfma_f32_16x16x32_bf16 v[32:35], v[170:173], v[222:225], v[32:35]
	v_mfma_f32_16x16x32_bf16 v[28:31], v[226:229], v[174:177], v[28:31]
	v_mfma_f32_16x16x32_bf16 v[24:27], v[234:237], v[174:177], v[24:27]
	v_mfma_f32_16x16x32_bf16 v[20:23], v[226:229], v[182:185], v[20:23]
	v_mfma_f32_16x16x32_bf16 v[16:19], v[234:237], v[182:185], v[16:19]
	v_mfma_f32_16x16x32_bf16 v[12:15], v[226:229], v[210:213], v[12:15]
	v_mfma_f32_16x16x32_bf16 v[8:11], v[234:237], v[210:213], v[8:11]
	v_mfma_f32_16x16x32_bf16 v[4:7], v[226:229], v[218:221], v[4:7]
	v_mfma_f32_16x16x32_bf16 v[0:3], v[234:237], v[218:221], v[0:3]
	v_mfma_f32_16x16x32_bf16 v[28:31], v[230:233], v[178:181], v[28:31]
	v_mfma_f32_16x16x32_bf16 v[24:27], v[238:241], v[178:181], v[24:27]
	v_mfma_f32_16x16x32_bf16 v[20:23], v[230:233], v[206:209], v[20:23]
	v_mfma_f32_16x16x32_bf16 v[16:19], v[238:241], v[206:209], v[16:19]
	v_mfma_f32_16x16x32_bf16 v[12:15], v[230:233], v[214:217], v[12:15]
	v_mfma_f32_16x16x32_bf16 v[8:11], v[238:241], v[214:217], v[8:11]
	v_mfma_f32_16x16x32_bf16 v[4:7], v[230:233], v[222:225], v[4:7]
	v_mfma_f32_16x16x32_bf16 v[0:3], v[238:241], v[222:225], v[0:3]
	s_barrier
	s_cbranch_scc0 .LBB0_77
	s_mov_b32 s100, 1
	s_setprio 1
	v_lshl_add_u32 v158, s75, 10, v155
	ds_read2_b32 v[146:147], v158 offset1:16
	ds_read2_b32 v[208:209], v158 offset0:32 offset1:48
	ds_read2_b32 v[210:211], v158 offset0:128 offset1:144
	ds_read2_b32 v[212:213], v158 offset0:160 offset1:176
	s_add_u32 s50, s10, 0xffffff00
	s_addc_u32 s51, s11, -1
	s_ashr_i32 s31, s30, 31
	s_lshl_b64 s[10:11], s[30:31], 8
	s_waitcnt lgkmcnt(0)
	v_mul_f32_e32 v184, 0xbfb8aa3b, v146
	v_mul_f32_e32 v206, v146, v146
	v_pk_mul_f32 v[168:169], v[124:125], v[184:185] op_sel_hi:[1,0]
	v_pk_mul_f32 v[170:171], v[126:127], v[184:185] op_sel_hi:[1,0]
	v_pk_mul_f32 v[172:173], v[120:121], v[184:185] op_sel_hi:[1,0]
	v_pk_mul_f32 v[174:175], v[122:123], v[184:185] op_sel_hi:[1,0]
	v_exp_f32_e32 v168, v168
	v_exp_f32_e32 v169, v169
	v_exp_f32_e32 v170, v170
	v_exp_f32_e32 v171, v171
	v_exp_f32_e32 v172, v172
	v_exp_f32_e32 v173, v173
	v_exp_f32_e32 v174, v174
	v_exp_f32_e32 v175, v175
	v_pk_mul_f32 v[176:177], v[124:125], v[92:93]
	v_pk_mul_f32 v[178:179], v[126:127], v[94:95]
	v_pk_mul_f32 v[180:181], v[120:121], v[88:89]
	v_pk_mul_f32 v[182:183], v[122:123], v[90:91]
	v_pk_add_f32 v[168:169], v[168:169], 1.0 op_sel_hi:[1,0]
	v_pk_add_f32 v[170:171], v[170:171], 1.0 op_sel_hi:[1,0]
	v_pk_add_f32 v[172:173], v[172:173], 1.0 op_sel_hi:[1,0]
	v_pk_add_f32 v[174:175], v[174:175], 1.0 op_sel_hi:[1,0]
	v_rcp_f32_e32 v168, v168
	v_rcp_f32_e32 v169, v169
	v_rcp_f32_e32 v170, v170
	v_rcp_f32_e32 v171, v171
	v_rcp_f32_e32 v172, v172
	v_rcp_f32_e32 v173, v173
	v_rcp_f32_e32 v174, v174
	v_rcp_f32_e32 v175, v175
	v_pk_mul_f32 v[176:177], v[176:177], v[206:207] op_sel_hi:[1,0]
	v_pk_mul_f32 v[178:179], v[178:179], v[206:207] op_sel_hi:[1,0]
	v_pk_mul_f32 v[180:181], v[180:181], v[206:207] op_sel_hi:[1,0]
	v_pk_mul_f32 v[182:183], v[182:183], v[206:207] op_sel_hi:[1,0]
	v_pk_mul_f32 v[176:177], v[176:177], v[168:169]
	v_pk_mul_f32 v[178:179], v[178:179], v[170:171]
	v_pk_mul_f32 v[180:181], v[180:181], v[172:173]
	v_pk_mul_f32 v[182:183], v[182:183], v[174:175]
	v_cvt_pk_bf16_f32 v160, v176, v177
	v_cvt_pk_bf16_f32 v161, v178, v179
	v_cvt_pk_bf16_f32 v162, v180, v181
	v_cvt_pk_bf16_f32 v163, v182, v183
	v_lshl_add_u64 v[152:153], v[134:135], 0, s[10:11]
	s_movk_i32 s6, 0x1600
	v_lshl_or_b32 v150, s74, 7, v156
	v_ashrrev_i32_e32 v151, 31, v150
	s_nop 1
	v_mov_b64_e32 v[148:149], s[28:29]
	v_mad_u64_u32 v[148:149], s[10:11], v152, s6, v[148:149]
	v_mov_b32_e32 v146, v149
	v_mad_u64_u32 v[152:153], s[10:11], v153, s6, v[146:147]
	v_mov_b32_e32 v149, v152
	v_mov_b32_e32 v146, v147
	v_lshl_add_u64 v[150:151], v[150:151], 1, v[148:149]
	global_store_dwordx4 v[150:151], v[160:163], off
	v_mul_f32_e32 v184, 0xbfb8aa3b, v146
	v_mul_f32_e32 v206, v146, v146
	v_pk_mul_f32 v[168:169], v[116:117], v[184:185] op_sel_hi:[1,0]
	v_pk_mul_f32 v[170:171], v[118:119], v[184:185] op_sel_hi:[1,0]
	v_pk_mul_f32 v[172:173], v[112:113], v[184:185] op_sel_hi:[1,0]
	v_pk_mul_f32 v[174:175], v[114:115], v[184:185] op_sel_hi:[1,0]
	v_exp_f32_e32 v168, v168
	v_exp_f32_e32 v169, v169
	v_exp_f32_e32 v170, v170
	v_exp_f32_e32 v171, v171
	v_exp_f32_e32 v172, v172
	v_exp_f32_e32 v173, v173
	v_exp_f32_e32 v174, v174
	v_exp_f32_e32 v175, v175
	v_pk_mul_f32 v[176:177], v[116:117], v[84:85]
	v_pk_mul_f32 v[178:179], v[118:119], v[86:87]
	v_pk_mul_f32 v[180:181], v[112:113], v[80:81]
	v_pk_mul_f32 v[182:183], v[114:115], v[82:83]
	v_pk_add_f32 v[168:169], v[168:169], 1.0 op_sel_hi:[1,0]
	v_pk_add_f32 v[170:171], v[170:171], 1.0 op_sel_hi:[1,0]
	v_pk_add_f32 v[172:173], v[172:173], 1.0 op_sel_hi:[1,0]
	v_pk_add_f32 v[174:175], v[174:175], 1.0 op_sel_hi:[1,0]
	v_rcp_f32_e32 v168, v168
	v_rcp_f32_e32 v169, v169
	v_rcp_f32_e32 v170, v170
	v_rcp_f32_e32 v171, v171
	v_rcp_f32_e32 v172, v172
	v_rcp_f32_e32 v173, v173
	v_rcp_f32_e32 v174, v174
	v_rcp_f32_e32 v175, v175
	v_pk_mul_f32 v[176:177], v[176:177], v[206:207] op_sel_hi:[1,0]
	v_pk_mul_f32 v[178:179], v[178:179], v[206:207] op_sel_hi:[1,0]
	v_pk_mul_f32 v[180:181], v[180:181], v[206:207] op_sel_hi:[1,0]
	v_pk_mul_f32 v[182:183], v[182:183], v[206:207] op_sel_hi:[1,0]
	v_pk_mul_f32 v[176:177], v[176:177], v[168:169]
	v_pk_mul_f32 v[178:179], v[178:179], v[170:171]
	v_pk_mul_f32 v[180:181], v[180:181], v[172:173]
	v_pk_mul_f32 v[182:183], v[182:183], v[174:175]
	v_cvt_pk_bf16_f32 v160, v176, v177
	v_cvt_pk_bf16_f32 v161, v178, v179
	v_cvt_pk_bf16_f32 v162, v180, v181
	v_cvt_pk_bf16_f32 v163, v182, v183
	s_mov_b32 s6, 0x16000
	s_nop 1
	v_add_co_u32_e32 v146, vcc, s6, v150
	s_nop 0
	v_addc_co_u32_e32 v147, vcc, 0, v151, vcc
	global_store_dwordx4 v[146:147], v[160:163], off
	v_mov_b32_e32 v146, v208
	v_mov_b32_e32 v147, v209
	s_mov_b32 s6, 0x2c000
	s_waitcnt lgkmcnt(0)
	v_mul_f32_e32 v184, 0xbfb8aa3b, v146
	v_mul_f32_e32 v206, v146, v146
	v_pk_mul_f32 v[168:169], v[108:109], v[184:185] op_sel_hi:[1,0]
	v_pk_mul_f32 v[170:171], v[110:111], v[184:185] op_sel_hi:[1,0]
	v_pk_mul_f32 v[172:173], v[104:105], v[184:185] op_sel_hi:[1,0]
	v_pk_mul_f32 v[174:175], v[106:107], v[184:185] op_sel_hi:[1,0]
	v_exp_f32_e32 v168, v168
	v_exp_f32_e32 v169, v169
	v_exp_f32_e32 v170, v170
	v_exp_f32_e32 v171, v171
	v_exp_f32_e32 v172, v172
	v_exp_f32_e32 v173, v173
	v_exp_f32_e32 v174, v174
	v_exp_f32_e32 v175, v175
	v_pk_mul_f32 v[176:177], v[108:109], v[76:77]
	v_pk_mul_f32 v[178:179], v[110:111], v[78:79]
	v_pk_mul_f32 v[180:181], v[104:105], v[72:73]
	v_pk_mul_f32 v[182:183], v[106:107], v[74:75]
	v_pk_add_f32 v[168:169], v[168:169], 1.0 op_sel_hi:[1,0]
	v_pk_add_f32 v[170:171], v[170:171], 1.0 op_sel_hi:[1,0]
	v_pk_add_f32 v[172:173], v[172:173], 1.0 op_sel_hi:[1,0]
	v_pk_add_f32 v[174:175], v[174:175], 1.0 op_sel_hi:[1,0]
	v_rcp_f32_e32 v168, v168
	v_rcp_f32_e32 v169, v169
	v_rcp_f32_e32 v170, v170
	v_rcp_f32_e32 v171, v171
	v_rcp_f32_e32 v172, v172
	v_rcp_f32_e32 v173, v173
	v_rcp_f32_e32 v174, v174
	v_rcp_f32_e32 v175, v175
	v_pk_mul_f32 v[176:177], v[176:177], v[206:207] op_sel_hi:[1,0]
	v_pk_mul_f32 v[178:179], v[178:179], v[206:207] op_sel_hi:[1,0]
	v_pk_mul_f32 v[180:181], v[180:181], v[206:207] op_sel_hi:[1,0]
	v_pk_mul_f32 v[182:183], v[182:183], v[206:207] op_sel_hi:[1,0]
	v_pk_mul_f32 v[176:177], v[176:177], v[168:169]
	v_pk_mul_f32 v[178:179], v[178:179], v[170:171]
	v_pk_mul_f32 v[180:181], v[180:181], v[172:173]
	v_pk_mul_f32 v[182:183], v[182:183], v[174:175]
	v_cvt_pk_bf16_f32 v160, v176, v177
	v_cvt_pk_bf16_f32 v161, v178, v179
	v_cvt_pk_bf16_f32 v162, v180, v181
	v_cvt_pk_bf16_f32 v163, v182, v183
	s_nop 1
	v_mov_b32_e32 v146, v147
	v_add_co_u32_e32 v148, vcc, s6, v150
	v_addc_co_u32_e32 v149, vcc, 0, v151, vcc
	global_store_dwordx4 v[148:149], v[160:163], off
	v_mul_f32_e32 v184, 0xbfb8aa3b, v146
	v_mul_f32_e32 v206, v146, v146
	v_pk_mul_f32 v[168:169], v[100:101], v[184:185] op_sel_hi:[1,0]
	v_pk_mul_f32 v[170:171], v[102:103], v[184:185] op_sel_hi:[1,0]
	v_pk_mul_f32 v[172:173], v[96:97], v[184:185] op_sel_hi:[1,0]
	v_pk_mul_f32 v[174:175], v[98:99], v[184:185] op_sel_hi:[1,0]
	v_exp_f32_e32 v168, v168
	v_exp_f32_e32 v169, v169
	v_exp_f32_e32 v170, v170
	v_exp_f32_e32 v171, v171
	v_exp_f32_e32 v172, v172
	v_exp_f32_e32 v173, v173
	v_exp_f32_e32 v174, v174
	v_exp_f32_e32 v175, v175
	v_pk_mul_f32 v[176:177], v[100:101], v[68:69]
	v_pk_mul_f32 v[178:179], v[102:103], v[70:71]
	v_pk_mul_f32 v[180:181], v[96:97], v[64:65]
	v_pk_mul_f32 v[182:183], v[98:99], v[66:67]
	v_pk_add_f32 v[168:169], v[168:169], 1.0 op_sel_hi:[1,0]
	v_pk_add_f32 v[170:171], v[170:171], 1.0 op_sel_hi:[1,0]
	v_pk_add_f32 v[172:173], v[172:173], 1.0 op_sel_hi:[1,0]
	v_pk_add_f32 v[174:175], v[174:175], 1.0 op_sel_hi:[1,0]
	v_rcp_f32_e32 v168, v168
	v_rcp_f32_e32 v169, v169
	v_rcp_f32_e32 v170, v170
	v_rcp_f32_e32 v171, v171
	v_rcp_f32_e32 v172, v172
	v_rcp_f32_e32 v173, v173
	v_rcp_f32_e32 v174, v174
	v_rcp_f32_e32 v175, v175
	v_pk_mul_f32 v[176:177], v[176:177], v[206:207] op_sel_hi:[1,0]
	v_pk_mul_f32 v[178:179], v[178:179], v[206:207] op_sel_hi:[1,0]
	v_pk_mul_f32 v[180:181], v[180:181], v[206:207] op_sel_hi:[1,0]
	v_pk_mul_f32 v[182:183], v[182:183], v[206:207] op_sel_hi:[1,0]
	v_pk_mul_f32 v[176:177], v[176:177], v[168:169]
	v_pk_mul_f32 v[178:179], v[178:179], v[170:171]
	v_pk_mul_f32 v[180:181], v[180:181], v[172:173]
	v_pk_mul_f32 v[182:183], v[182:183], v[174:175]
	v_cvt_pk_bf16_f32 v160, v176, v177
	v_cvt_pk_bf16_f32 v161, v178, v179
	v_cvt_pk_bf16_f32 v162, v180, v181
	v_cvt_pk_bf16_f32 v163, v182, v183
	s_mov_b32 s6, 0x42000
	s_nop 1
	v_add_co_u32_e32 v146, vcc, s6, v150
	s_nop 0
	v_addc_co_u32_e32 v147, vcc, 0, v151, vcc
	global_store_dwordx4 v[146:147], v[160:163], off
	v_mov_b32_e32 v146, v210
	v_mov_b32_e32 v147, v211
	s_mov_b32 s6, 0xb0000
	s_waitcnt lgkmcnt(0)
	v_mul_f32_e32 v184, 0xbfb8aa3b, v146
	v_mul_f32_e32 v206, v146, v146
	v_pk_mul_f32 v[168:169], v[60:61], v[184:185] op_sel_hi:[1,0]
	v_pk_mul_f32 v[170:171], v[62:63], v[184:185] op_sel_hi:[1,0]
	v_pk_mul_f32 v[172:173], v[56:57], v[184:185] op_sel_hi:[1,0]
	v_pk_mul_f32 v[174:175], v[58:59], v[184:185] op_sel_hi:[1,0]
	v_exp_f32_e32 v168, v168
	v_exp_f32_e32 v169, v169
	v_exp_f32_e32 v170, v170
	v_exp_f32_e32 v171, v171
	v_exp_f32_e32 v172, v172
	v_exp_f32_e32 v173, v173
	v_exp_f32_e32 v174, v174
	v_exp_f32_e32 v175, v175
	v_pk_mul_f32 v[176:177], v[60:61], v[28:29]
	v_pk_mul_f32 v[178:179], v[62:63], v[30:31]
	v_pk_mul_f32 v[180:181], v[56:57], v[24:25]
	v_pk_mul_f32 v[182:183], v[58:59], v[26:27]
	v_pk_add_f32 v[168:169], v[168:169], 1.0 op_sel_hi:[1,0]
	v_pk_add_f32 v[170:171], v[170:171], 1.0 op_sel_hi:[1,0]
	v_pk_add_f32 v[172:173], v[172:173], 1.0 op_sel_hi:[1,0]
	v_pk_add_f32 v[174:175], v[174:175], 1.0 op_sel_hi:[1,0]
	v_rcp_f32_e32 v168, v168
	v_rcp_f32_e32 v169, v169
	v_rcp_f32_e32 v170, v170
	v_rcp_f32_e32 v171, v171
	v_rcp_f32_e32 v172, v172
	v_rcp_f32_e32 v173, v173
	v_rcp_f32_e32 v174, v174
	v_rcp_f32_e32 v175, v175
	v_pk_mul_f32 v[176:177], v[176:177], v[206:207] op_sel_hi:[1,0]
	v_pk_mul_f32 v[178:179], v[178:179], v[206:207] op_sel_hi:[1,0]
	v_pk_mul_f32 v[180:181], v[180:181], v[206:207] op_sel_hi:[1,0]
	v_pk_mul_f32 v[182:183], v[182:183], v[206:207] op_sel_hi:[1,0]
	v_pk_mul_f32 v[176:177], v[176:177], v[168:169]
	v_pk_mul_f32 v[178:179], v[178:179], v[170:171]
	v_pk_mul_f32 v[180:181], v[180:181], v[172:173]
	v_pk_mul_f32 v[182:183], v[182:183], v[174:175]
	v_cvt_pk_bf16_f32 v160, v176, v177
	v_cvt_pk_bf16_f32 v161, v178, v179
	v_cvt_pk_bf16_f32 v162, v180, v181
	v_cvt_pk_bf16_f32 v163, v182, v183
	s_nop 1
	v_mov_b32_e32 v146, v147
	v_add_co_u32_e32 v148, vcc, s6, v150
	v_addc_co_u32_e32 v149, vcc, 0, v151, vcc
	global_store_dwordx4 v[148:149], v[160:163], off
	v_mul_f32_e32 v184, 0xbfb8aa3b, v146
	v_mul_f32_e32 v206, v146, v146
	v_pk_mul_f32 v[168:169], v[52:53], v[184:185] op_sel_hi:[1,0]
	v_pk_mul_f32 v[170:171], v[54:55], v[184:185] op_sel_hi:[1,0]
	v_pk_mul_f32 v[172:173], v[48:49], v[184:185] op_sel_hi:[1,0]
	v_pk_mul_f32 v[174:175], v[50:51], v[184:185] op_sel_hi:[1,0]
	v_exp_f32_e32 v168, v168
	v_exp_f32_e32 v169, v169
	v_exp_f32_e32 v170, v170
	v_exp_f32_e32 v171, v171
	v_exp_f32_e32 v172, v172
	v_exp_f32_e32 v173, v173
	v_exp_f32_e32 v174, v174
	v_exp_f32_e32 v175, v175
	v_pk_mul_f32 v[176:177], v[52:53], v[20:21]
	v_pk_mul_f32 v[178:179], v[54:55], v[22:23]
	v_pk_mul_f32 v[180:181], v[48:49], v[16:17]
	v_pk_mul_f32 v[182:183], v[50:51], v[18:19]
	v_pk_add_f32 v[168:169], v[168:169], 1.0 op_sel_hi:[1,0]
	v_pk_add_f32 v[170:171], v[170:171], 1.0 op_sel_hi:[1,0]
	v_pk_add_f32 v[172:173], v[172:173], 1.0 op_sel_hi:[1,0]
	v_pk_add_f32 v[174:175], v[174:175], 1.0 op_sel_hi:[1,0]
	v_rcp_f32_e32 v168, v168
	v_rcp_f32_e32 v169, v169
	v_rcp_f32_e32 v170, v170
	v_rcp_f32_e32 v171, v171
	v_rcp_f32_e32 v172, v172
	v_rcp_f32_e32 v173, v173
	v_rcp_f32_e32 v174, v174
	v_rcp_f32_e32 v175, v175
	v_pk_mul_f32 v[176:177], v[176:177], v[206:207] op_sel_hi:[1,0]
	v_pk_mul_f32 v[178:179], v[178:179], v[206:207] op_sel_hi:[1,0]
	v_pk_mul_f32 v[180:181], v[180:181], v[206:207] op_sel_hi:[1,0]
	v_pk_mul_f32 v[182:183], v[182:183], v[206:207] op_sel_hi:[1,0]
	v_pk_mul_f32 v[176:177], v[176:177], v[168:169]
	v_pk_mul_f32 v[178:179], v[178:179], v[170:171]
	v_pk_mul_f32 v[180:181], v[180:181], v[172:173]
	v_pk_mul_f32 v[182:183], v[182:183], v[174:175]
	v_cvt_pk_bf16_f32 v160, v176, v177
	v_cvt_pk_bf16_f32 v161, v178, v179
	v_cvt_pk_bf16_f32 v162, v180, v181
	v_cvt_pk_bf16_f32 v163, v182, v183
	s_mov_b32 s6, 0xc6000
	s_nop 1
	v_add_co_u32_e32 v146, vcc, s6, v150
	s_nop 0
	v_addc_co_u32_e32 v147, vcc, 0, v151, vcc
	global_store_dwordx4 v[146:147], v[160:163], off
	v_mov_b32_e32 v146, v212
	v_mov_b32_e32 v147, v213
	s_mov_b32 s6, 0xdc000
	s_waitcnt lgkmcnt(0)
	v_mul_f32_e32 v184, 0xbfb8aa3b, v146
	v_mul_f32_e32 v206, v146, v146
	v_pk_mul_f32 v[168:169], v[44:45], v[184:185] op_sel_hi:[1,0]
	v_pk_mul_f32 v[170:171], v[46:47], v[184:185] op_sel_hi:[1,0]
	v_pk_mul_f32 v[172:173], v[40:41], v[184:185] op_sel_hi:[1,0]
	v_pk_mul_f32 v[174:175], v[42:43], v[184:185] op_sel_hi:[1,0]
	v_exp_f32_e32 v168, v168
	v_exp_f32_e32 v169, v169
	v_exp_f32_e32 v170, v170
	v_exp_f32_e32 v171, v171
	v_exp_f32_e32 v172, v172
	v_exp_f32_e32 v173, v173
	v_exp_f32_e32 v174, v174
	v_exp_f32_e32 v175, v175
	v_pk_mul_f32 v[176:177], v[44:45], v[12:13]
	v_pk_mul_f32 v[178:179], v[46:47], v[14:15]
	v_pk_mul_f32 v[180:181], v[40:41], v[8:9]
	v_pk_mul_f32 v[182:183], v[42:43], v[10:11]
	v_pk_add_f32 v[168:169], v[168:169], 1.0 op_sel_hi:[1,0]
	v_pk_add_f32 v[170:171], v[170:171], 1.0 op_sel_hi:[1,0]
	v_pk_add_f32 v[172:173], v[172:173], 1.0 op_sel_hi:[1,0]
	v_pk_add_f32 v[174:175], v[174:175], 1.0 op_sel_hi:[1,0]
	v_rcp_f32_e32 v168, v168
	v_rcp_f32_e32 v169, v169
	v_rcp_f32_e32 v170, v170
	v_rcp_f32_e32 v171, v171
	v_rcp_f32_e32 v172, v172
	v_rcp_f32_e32 v173, v173
	v_rcp_f32_e32 v174, v174
	v_rcp_f32_e32 v175, v175
	v_pk_mul_f32 v[176:177], v[176:177], v[206:207] op_sel_hi:[1,0]
	v_pk_mul_f32 v[178:179], v[178:179], v[206:207] op_sel_hi:[1,0]
	v_pk_mul_f32 v[180:181], v[180:181], v[206:207] op_sel_hi:[1,0]
	v_pk_mul_f32 v[182:183], v[182:183], v[206:207] op_sel_hi:[1,0]
	v_pk_mul_f32 v[176:177], v[176:177], v[168:169]
	v_pk_mul_f32 v[178:179], v[178:179], v[170:171]
	v_pk_mul_f32 v[180:181], v[180:181], v[172:173]
	v_pk_mul_f32 v[182:183], v[182:183], v[174:175]
	v_cvt_pk_bf16_f32 v158, v176, v177
	v_cvt_pk_bf16_f32 v159, v178, v179
	v_cvt_pk_bf16_f32 v160, v180, v181
	v_cvt_pk_bf16_f32 v161, v182, v183
	s_nop 1
	v_mov_b32_e32 v146, v147
	v_add_co_u32_e32 v148, vcc, s6, v150
	v_addc_co_u32_e32 v149, vcc, 0, v151, vcc
	global_store_dwordx4 v[148:149], v[158:161], off
	v_mul_f32_e32 v184, 0xbfb8aa3b, v146
	v_mul_f32_e32 v206, v146, v146
	v_pk_mul_f32 v[168:169], v[36:37], v[184:185] op_sel_hi:[1,0]
	v_pk_mul_f32 v[170:171], v[38:39], v[184:185] op_sel_hi:[1,0]
	v_pk_mul_f32 v[172:173], v[32:33], v[184:185] op_sel_hi:[1,0]
	v_pk_mul_f32 v[174:175], v[34:35], v[184:185] op_sel_hi:[1,0]
	v_exp_f32_e32 v168, v168
	v_exp_f32_e32 v169, v169
	v_exp_f32_e32 v170, v170
	v_exp_f32_e32 v171, v171
	v_exp_f32_e32 v172, v172
	v_exp_f32_e32 v173, v173
	v_exp_f32_e32 v174, v174
	v_exp_f32_e32 v175, v175
	v_pk_mul_f32 v[176:177], v[36:37], v[4:5]
	v_pk_mul_f32 v[178:179], v[38:39], v[6:7]
	v_pk_mul_f32 v[180:181], v[32:33], v[0:1]
	v_pk_mul_f32 v[182:183], v[34:35], v[2:3]
	v_pk_add_f32 v[168:169], v[168:169], 1.0 op_sel_hi:[1,0]
	v_pk_add_f32 v[170:171], v[170:171], 1.0 op_sel_hi:[1,0]
	v_pk_add_f32 v[172:173], v[172:173], 1.0 op_sel_hi:[1,0]
	v_pk_add_f32 v[174:175], v[174:175], 1.0 op_sel_hi:[1,0]
	v_rcp_f32_e32 v168, v168
	v_rcp_f32_e32 v169, v169
	v_rcp_f32_e32 v170, v170
	v_rcp_f32_e32 v171, v171
	v_rcp_f32_e32 v172, v172
	v_rcp_f32_e32 v173, v173
	v_rcp_f32_e32 v174, v174
	v_rcp_f32_e32 v175, v175
	v_pk_mul_f32 v[176:177], v[176:177], v[206:207] op_sel_hi:[1,0]
	v_pk_mul_f32 v[178:179], v[178:179], v[206:207] op_sel_hi:[1,0]
	v_pk_mul_f32 v[180:181], v[180:181], v[206:207] op_sel_hi:[1,0]
	v_pk_mul_f32 v[182:183], v[182:183], v[206:207] op_sel_hi:[1,0]
	v_pk_mul_f32 v[176:177], v[176:177], v[168:169]
	v_pk_mul_f32 v[178:179], v[178:179], v[170:171]
	v_pk_mul_f32 v[180:181], v[180:181], v[172:173]
	v_pk_mul_f32 v[182:183], v[182:183], v[174:175]
	v_cvt_pk_bf16_f32 v158, v176, v177
	v_cvt_pk_bf16_f32 v159, v178, v179
	v_cvt_pk_bf16_f32 v160, v180, v181
	v_cvt_pk_bf16_f32 v161, v182, v183
	s_nop 1
	v_add_co_u32_e32 v146, vcc, 0xf2000, v150
	s_nop 0
	v_addc_co_u32_e32 v147, vcc, 0, v151, vcc
	s_andn2_b64 vcc, exec, s[44:45]
	global_store_dwordx4 v[146:147], v[158:161], off
	s_cbranch_vccz .LBB0_73
	s_mov_b64 s[46:47], s[50:51]
	s_andn2_b64 vcc, exec, s[42:43]
	s_mov_b64 s[50:51], s[46:47]
	s_cbranch_vccnz .LBB0_74

.LBB0_102:
	s_add_u32 s54, s54, 0x40080
	s_addc_u32 s55, s55, 0
	s_add_u32 s10, s58, 0x100
	s_addc_u32 s11, s59, 0
	s_mov_b32 s12, -2
	s_waitcnt lgkmcnt(0)
	s_add_u32 s6, s54, 0xfffc0080
	s_addc_u32 s19, s55, -1
	s_add_i32 s23, 0, 0x10000
	v_add_u32_e32 v146, s23, v206
	ds_read_b128 v[128:131], v146
	ds_read_b128 v[132:135], v146 offset:1024
	ds_read_b128 v[136:139], v146 offset:2048
	ds_read_b128 v[146:149], v146 offset:3072
	s_cmp_eq_u32 s12, 12
	s_cselect_b32 s69, s47, s19
	s_cselect_b32 s68, s46, s6
	s_cselect_b32 s59, s49, s11
	s_cselect_b32 s58, s48, s10
	v_lshl_add_u64 v[192:193], s[54:55], 0, v[158:159]
	s_add_i32 m0, s72, 0xc000
	ds_read_b128 v[162:165], v208
	ds_read_b128 v[166:169], v208 offset:1024
	ds_read_b128 v[170:173], v208 offset:2048
	ds_read_b128 v[174:177], v208 offset:3072
	ds_read_b128 v[178:181], v208 offset:4096
	ds_read_b128 v[182:185], v208 offset:5120
	ds_read_b128 v[194:197], v208 offset:6144
	ds_read_b128 v[210:213], v208 offset:7168
	global_load_lds_dwordx4 v[192:193], off
	v_lshl_add_u64 v[192:193], s[54:55], 0, v[160:161]
	s_add_i32 m0, s72, 0xe000
	s_nop 0
	global_load_lds_dwordx4 v[192:193], off
	s_add_i32 s6, 0, 0x14000
	v_add_u32_e32 v192, s6, v206
	ds_read_b128 v[214:217], v192
	ds_read_b128 v[218:221], v192 offset:1024
	ds_read_b128 v[222:225], v192 offset:2048
	ds_read_b128 v[226:229], v192 offset:3072
	s_setprio 0
	s_waitcnt vmcnt(40)
	s_cmp_lg_u32 s100, 0
	s_cbranch_scc1 .Lm4ap_103
	s_waitcnt vmcnt(8)

.LBB0_103:
	s_add_u32 s6, s54, 0xfffc0080
	s_addc_u32 s19, s55, -1
	s_add_i32 s23, 0, 0x10000
	v_add_u32_e32 v146, s23, v206
	ds_read_b128 v[128:131], v146
	ds_read_b128 v[132:135], v146 offset:1024
	ds_read_b128 v[136:139], v146 offset:2048
	ds_read_b128 v[146:149], v146 offset:3072
	s_cmp_eq_u32 s12, 12
	s_cselect_b32 s69, s47, s19
	s_cselect_b32 s68, s46, s6
	s_cselect_b32 s59, s49, s11
	s_cselect_b32 s58, s48, s10
	v_lshl_add_u64 v[192:193], s[54:55], 0, v[158:159]
	s_add_i32 m0, s72, 0xc000
	ds_read_b128 v[162:165], v208
	ds_read_b128 v[166:169], v208 offset:1024
	ds_read_b128 v[170:173], v208 offset:2048
	ds_read_b128 v[174:177], v208 offset:3072
	ds_read_b128 v[178:181], v208 offset:4096
	ds_read_b128 v[182:185], v208 offset:5120
	ds_read_b128 v[194:197], v208 offset:6144
	ds_read_b128 v[210:213], v208 offset:7168
	global_load_lds_dwordx4 v[192:193], off
	v_lshl_add_u64 v[192:193], s[54:55], 0, v[160:161]
	s_add_i32 m0, s72, 0xe000
	s_nop 0
	global_load_lds_dwordx4 v[192:193], off
	s_add_i32 s6, 0, 0x14000
	v_add_u32_e32 v192, s6, v206
	ds_read_b128 v[214:217], v192
	ds_read_b128 v[218:221], v192 offset:1024
	ds_read_b128 v[222:225], v192 offset:2048
	ds_read_b128 v[226:229], v192 offset:3072
	s_nop 0
	s_waitcnt vmcnt(8)
	s_waitcnt lgkmcnt(0)
	s_barrier
	v_mfma_f32_16x16x32_bf16 v[124:127], v[128:131], v[162:165], v[124:127]
	v_mfma_f32_16x16x32_bf16 v[120:123], v[136:139], v[162:165], v[120:123]
	v_mfma_f32_16x16x32_bf16 v[108:111], v[128:131], v[170:173], v[108:111]
	v_mfma_f32_16x16x32_bf16 v[104:107], v[136:139], v[170:173], v[104:107]
	v_mfma_f32_16x16x32_bf16 v[96:99], v[128:131], v[178:181], v[96:99]
	v_mfma_f32_16x16x32_bf16 v[88:91], v[136:139], v[178:181], v[88:91]
	v_mfma_f32_16x16x32_bf16 v[84:87], v[128:131], v[194:197], v[84:87]
	v_mfma_f32_16x16x32_bf16 v[80:83], v[136:139], v[194:197], v[80:83]
	v_mfma_f32_16x16x32_bf16 v[124:127], v[132:135], v[166:169], v[124:127]
	v_mfma_f32_16x16x32_bf16 v[120:123], v[146:149], v[166:169], v[120:123]
	v_mfma_f32_16x16x32_bf16 v[108:111], v[132:135], v[174:177], v[108:111]
	v_mfma_f32_16x16x32_bf16 v[104:107], v[146:149], v[174:177], v[104:107]
	v_mfma_f32_16x16x32_bf16 v[96:99], v[132:135], v[182:185], v[96:99]
	v_mfma_f32_16x16x32_bf16 v[88:91], v[146:149], v[182:185], v[88:91]
	v_mfma_f32_16x16x32_bf16 v[84:87], v[132:135], v[210:213], v[84:87]
	v_mfma_f32_16x16x32_bf16 v[80:83], v[146:149], v[210:213], v[80:83]
	v_mfma_f32_16x16x32_bf16 v[116:119], v[214:217], v[162:165], v[116:119]
	v_mfma_f32_16x16x32_bf16 v[112:115], v[222:225], v[162:165], v[112:115]
	v_mfma_f32_16x16x32_bf16 v[100:103], v[214:217], v[170:173], v[100:103]
	v_mfma_f32_16x16x32_bf16 v[92:95], v[222:225], v[170:173], v[92:95]
	v_mfma_f32_16x16x32_bf16 v[76:79], v[214:217], v[178:181], v[76:79]
	v_mfma_f32_16x16x32_bf16 v[72:75], v[222:225], v[178:181], v[72:75]
	v_mfma_f32_16x16x32_bf16 v[68:71], v[214:217], v[194:197], v[68:71]
	v_mfma_f32_16x16x32_bf16 v[64:67], v[222:225], v[194:197], v[64:67]
	v_mfma_f32_16x16x32_bf16 v[116:119], v[218:221], v[166:169], v[116:119]
	v_mfma_f32_16x16x32_bf16 v[112:115], v[226:229], v[166:169], v[112:115]
	v_mfma_f32_16x16x32_bf16 v[100:103], v[218:221], v[174:177], v[100:103]
	v_mfma_f32_16x16x32_bf16 v[92:95], v[226:229], v[174:177], v[92:95]
	v_mfma_f32_16x16x32_bf16 v[76:79], v[218:221], v[182:185], v[76:79]
	v_mfma_f32_16x16x32_bf16 v[72:75], v[226:229], v[182:185], v[72:75]
	v_mfma_f32_16x16x32_bf16 v[68:71], v[218:221], v[210:213], v[68:71]
	v_mfma_f32_16x16x32_bf16 v[64:67], v[226:229], v[210:213], v[64:67]
	s_barrier
	s_add_i32 s19, s23, s71
	v_lshl_add_u64 v[192:193], s[58:59], 0, v[140:141]
	s_mov_b32 m0, s19
	v_lshl_add_u64 v[230:231], s[58:59], 0, v[150:151]
	global_load_lds_dwordx4 v[192:193], off
	s_add_i32 m0, s19, 0x2000
	s_nop 0
	global_load_lds_dwordx4 v[230:231], off
	s_mov_b32 m0, s72
	v_lshl_add_u64 v[232:233], s[68:69], 0, v[154:155]
	ds_read_b128 v[162:165], v208 offset:16384
	ds_read_b128 v[166:169], v208 offset:17408
	ds_read_b128 v[170:173], v208 offset:18432
	ds_read_b128 v[174:177], v208 offset:19456
	ds_read_b128 v[178:181], v208 offset:20480
	ds_read_b128 v[182:185], v208 offset:21504
	ds_read_b128 v[194:197], v208 offset:22528
	ds_read_b128 v[210:213], v208 offset:23552
	global_load_lds_dwordx4 v[232:233], off
	v_lshl_add_u64 v[234:235], s[68:69], 0, v[152:153]
	s_mov_b32 m0, s73
	s_nop 0
	global_load_lds_dwordx4 v[234:235], off
	s_add_u32 s86, s58, 0x40000
	s_addc_u32 s87, s59, 0
	s_add_i32 s6, s6, s71
	v_lshl_add_u64 v[250:251], s[86:87], 0, v[140:141]
	s_mov_b32 m0, s6
	s_nop 0
	global_load_lds_dwordx4 v[250:251], off
	v_lshl_add_u64 v[250:251], s[86:87], 0, v[150:151]
	s_add_i32 m0, s6, 0x2000
	s_nop 0
	global_load_lds_dwordx4 v[250:251], off
	s_nop 0
	s_waitcnt vmcnt(8)
	s_waitcnt lgkmcnt(0)
	s_barrier
	v_mfma_f32_16x16x32_bf16 v[60:63], v[128:131], v[162:165], v[60:63]
	v_mfma_f32_16x16x32_bf16 v[56:59], v[136:139], v[162:165], v[56:59]
	v_mfma_f32_16x16x32_bf16 v[48:51], v[128:131], v[170:173], v[48:51]
	v_mfma_f32_16x16x32_bf16 v[40:43], v[136:139], v[170:173], v[40:43]
	v_mfma_f32_16x16x32_bf16 v[32:35], v[128:131], v[178:181], v[32:35]
	v_mfma_f32_16x16x32_bf16 v[24:27], v[136:139], v[178:181], v[24:27]
	v_mfma_f32_16x16x32_bf16 v[16:19], v[128:131], v[194:197], v[16:19]
	v_mfma_f32_16x16x32_bf16 v[8:11], v[136:139], v[194:197], v[8:11]
	v_mfma_f32_16x16x32_bf16 v[60:63], v[132:135], v[166:169], v[60:63]
	v_mfma_f32_16x16x32_bf16 v[56:59], v[146:149], v[166:169], v[56:59]
	v_mfma_f32_16x16x32_bf16 v[48:51], v[132:135], v[174:177], v[48:51]
	v_mfma_f32_16x16x32_bf16 v[40:43], v[146:149], v[174:177], v[40:43]
	v_mfma_f32_16x16x32_bf16 v[32:35], v[132:135], v[182:185], v[32:35]
	v_mfma_f32_16x16x32_bf16 v[24:27], v[146:149], v[182:185], v[24:27]
	v_mfma_f32_16x16x32_bf16 v[16:19], v[132:135], v[210:213], v[16:19]
	v_mfma_f32_16x16x32_bf16 v[8:11], v[146:149], v[210:213], v[8:11]
	v_mfma_f32_16x16x32_bf16 v[52:55], v[214:217], v[162:165], v[52:55]
	v_mfma_f32_16x16x32_bf16 v[44:47], v[222:225], v[162:165], v[44:47]
	v_mfma_f32_16x16x32_bf16 v[36:39], v[214:217], v[170:173], v[36:39]
	v_mfma_f32_16x16x32_bf16 v[28:31], v[222:225], v[170:173], v[28:31]
	v_mfma_f32_16x16x32_bf16 v[20:23], v[214:217], v[178:181], v[20:23]
	v_mfma_f32_16x16x32_bf16 v[12:15], v[222:225], v[178:181], v[12:15]
	v_mfma_f32_16x16x32_bf16 v[4:7], v[214:217], v[194:197], v[4:7]
	v_mfma_f32_16x16x32_bf16 v[0:3], v[222:225], v[194:197], v[0:3]
	v_mfma_f32_16x16x32_bf16 v[52:55], v[218:221], v[166:169], v[52:55]
	v_mfma_f32_16x16x32_bf16 v[44:47], v[226:229], v[166:169], v[44:47]
	v_mfma_f32_16x16x32_bf16 v[36:39], v[218:221], v[174:177], v[36:39]
	v_mfma_f32_16x16x32_bf16 v[28:31], v[226:229], v[174:177], v[28:31]
	v_mfma_f32_16x16x32_bf16 v[20:23], v[218:221], v[182:185], v[20:23]
	v_mfma_f32_16x16x32_bf16 v[12:15], v[226:229], v[182:185], v[12:15]
	v_mfma_f32_16x16x32_bf16 v[4:7], v[218:221], v[210:213], v[4:7]
	v_mfma_f32_16x16x32_bf16 v[0:3], v[226:229], v[210:213], v[0:3]
	s_barrier
	s_add_i32 s6, 0, 0x18000
	v_add_u32_e32 v146, s6, v206
	ds_read_b128 v[128:131], v146
	ds_read_b128 v[132:135], v146 offset:1024
	ds_read_b128 v[136:139], v146 offset:2048
	ds_read_b128 v[146:149], v146 offset:3072
	s_add_u32 s68, s68, 0x40000
	s_addc_u32 s69, s69, 0
	s_mov_b32 m0, s74
	v_lshl_add_u64 v[214:215], s[68:69], 0, v[154:155]
	ds_read_b128 v[162:165], v208 offset:32768
	ds_read_b128 v[166:169], v208 offset:33792
	ds_read_b128 v[170:173], v208 offset:34816
	ds_read_b128 v[174:177], v208 offset:35840
	ds_read_b128 v[178:181], v208 offset:36864
	ds_read_b128 v[182:185], v208 offset:37888
	ds_read_b128 v[194:197], v208 offset:38912
	ds_read_b128 v[210:213], v208 offset:39936
	global_load_lds_dwordx4 v[214:215], off
	v_lshl_add_u64 v[214:215], s[68:69], 0, v[152:153]
	s_mov_b32 m0, s75
	s_nop 0
	global_load_lds_dwordx4 v[214:215], off
	s_add_i32 s19, 0, 0x1c000
	v_add_u32_e32 v209, s19, v206
	ds_read_b128 v[214:217], v209
	ds_read_b128 v[218:221], v209 offset:1024
	ds_read_b128 v[222:225], v209 offset:2048
	ds_read_b128 v[226:229], v209 offset:3072
	s_waitcnt vmcnt(8)
	s_waitcnt lgkmcnt(0)
	s_barrier
	v_mfma_f32_16x16x32_bf16 v[124:127], v[128:131], v[162:165], v[124:127]
	v_mfma_f32_16x16x32_bf16 v[120:123], v[136:139], v[162:165], v[120:123]
	v_mfma_f32_16x16x32_bf16 v[108:111], v[128:131], v[170:173], v[108:111]
	v_mfma_f32_16x16x32_bf16 v[104:107], v[136:139], v[170:173], v[104:107]
	v_mfma_f32_16x16x32_bf16 v[96:99], v[128:131], v[178:181], v[96:99]
	v_mfma_f32_16x16x32_bf16 v[88:91], v[136:139], v[178:181], v[88:91]
	v_mfma_f32_16x16x32_bf16 v[84:87], v[128:131], v[194:197], v[84:87]
	v_mfma_f32_16x16x32_bf16 v[80:83], v[136:139], v[194:197], v[80:83]
	v_mfma_f32_16x16x32_bf16 v[124:127], v[132:135], v[166:169], v[124:127]
	v_mfma_f32_16x16x32_bf16 v[120:123], v[146:149], v[166:169], v[120:123]
	v_mfma_f32_16x16x32_bf16 v[108:111], v[132:135], v[174:177], v[108:111]
	v_mfma_f32_16x16x32_bf16 v[104:107], v[146:149], v[174:177], v[104:107]
	v_mfma_f32_16x16x32_bf16 v[96:99], v[132:135], v[182:185], v[96:99]
	v_mfma_f32_16x16x32_bf16 v[88:91], v[146:149], v[182:185], v[88:91]
	v_mfma_f32_16x16x32_bf16 v[84:87], v[132:135], v[210:213], v[84:87]
	v_mfma_f32_16x16x32_bf16 v[80:83], v[146:149], v[210:213], v[80:83]
	v_mfma_f32_16x16x32_bf16 v[116:119], v[214:217], v[162:165], v[116:119]
	v_mfma_f32_16x16x32_bf16 v[112:115], v[222:225], v[162:165], v[112:115]
	v_mfma_f32_16x16x32_bf16 v[100:103], v[214:217], v[170:173], v[100:103]
	v_mfma_f32_16x16x32_bf16 v[92:95], v[222:225], v[170:173], v[92:95]
	v_mfma_f32_16x16x32_bf16 v[76:79], v[214:217], v[178:181], v[76:79]
	v_mfma_f32_16x16x32_bf16 v[72:75], v[222:225], v[178:181], v[72:75]
	v_mfma_f32_16x16x32_bf16 v[68:71], v[214:217], v[194:197], v[68:71]
	v_mfma_f32_16x16x32_bf16 v[64:67], v[222:225], v[194:197], v[64:67]
	v_mfma_f32_16x16x32_bf16 v[116:119], v[218:221], v[166:169], v[116:119]
	v_mfma_f32_16x16x32_bf16 v[112:115], v[226:229], v[166:169], v[112:115]
	v_mfma_f32_16x16x32_bf16 v[100:103], v[218:221], v[174:177], v[100:103]
	v_mfma_f32_16x16x32_bf16 v[92:95], v[226:229], v[174:177], v[92:95]
	v_mfma_f32_16x16x32_bf16 v[76:79], v[218:221], v[182:185], v[76:79]
	v_mfma_f32_16x16x32_bf16 v[72:75], v[226:229], v[182:185], v[72:75]
	v_mfma_f32_16x16x32_bf16 v[68:71], v[218:221], v[210:213], v[68:71]
	v_mfma_f32_16x16x32_bf16 v[64:67], v[226:229], v[210:213], v[64:67]
	s_barrier
	s_add_i32 s6, s6, s71
	v_lshl_add_u64 v[192:193], v[192:193], 0, s[36:37]
	s_mov_b32 m0, s6
	s_nop 0
	global_load_lds_dwordx4 v[192:193], off
	v_lshl_add_u64 v[192:193], v[230:231], 0, s[36:37]
	s_add_i32 m0, s6, 0x2000
	s_nop 0
	global_load_lds_dwordx4 v[192:193], off
	s_mov_b32 m0, s80
	v_lshl_add_u64 v[192:193], v[232:233], 0, s[36:37]
	ds_read_b128 v[162:165], v208 offset:49152
	ds_read_b128 v[166:169], v208 offset:50176
	ds_read_b128 v[170:173], v208 offset:51200
	ds_read_b128 v[174:177], v208 offset:52224
	ds_read_b128 v[178:181], v208 offset:53248
	ds_read_b128 v[182:185], v208 offset:54272
	ds_read_b128 v[194:197], v208 offset:55296
	ds_read_b128 v[210:213], v208 offset:56320
	global_load_lds_dwordx4 v[192:193], off
	v_lshl_add_u64 v[192:193], v[234:235], 0, s[36:37]
	s_mov_b32 m0, s81
	s_nop 0
	global_load_lds_dwordx4 v[192:193], off
	s_add_u32 s58, s58, 0x40080
	s_addc_u32 s59, s59, 0
	s_add_i32 s6, s19, s71
	v_lshl_add_u64 v[250:251], s[58:59], 0, v[140:141]
	s_mov_b32 m0, s6
	s_nop 0
	global_load_lds_dwordx4 v[250:251], off
	v_lshl_add_u64 v[250:251], s[58:59], 0, v[150:151]
	s_add_i32 m0, s6, 0x2000
	s_nop 0
	global_load_lds_dwordx4 v[250:251], off
	s_add_i32 s12, s12, 2
	s_add_u32 s54, s54, 0x100
	s_addc_u32 s55, s55, 0
	s_add_u32 s10, s10, 0x100
	s_addc_u32 s11, s11, 0
	s_cmp_gt_u32 s12, 13
	s_waitcnt vmcnt(8)
	s_waitcnt lgkmcnt(0)
	s_barrier
	v_mfma_f32_16x16x32_bf16 v[60:63], v[128:131], v[162:165], v[60:63]
	v_mfma_f32_16x16x32_bf16 v[56:59], v[136:139], v[162:165], v[56:59]
	v_mfma_f32_16x16x32_bf16 v[48:51], v[128:131], v[170:173], v[48:51]
	v_mfma_f32_16x16x32_bf16 v[40:43], v[136:139], v[170:173], v[40:43]
	v_mfma_f32_16x16x32_bf16 v[32:35], v[128:131], v[178:181], v[32:35]
	v_mfma_f32_16x16x32_bf16 v[24:27], v[136:139], v[178:181], v[24:27]
	v_mfma_f32_16x16x32_bf16 v[16:19], v[128:131], v[194:197], v[16:19]
	v_mfma_f32_16x16x32_bf16 v[8:11], v[136:139], v[194:197], v[8:11]
	v_mfma_f32_16x16x32_bf16 v[60:63], v[132:135], v[166:169], v[60:63]
	v_mfma_f32_16x16x32_bf16 v[56:59], v[146:149], v[166:169], v[56:59]
	v_mfma_f32_16x16x32_bf16 v[48:51], v[132:135], v[174:177], v[48:51]
	v_mfma_f32_16x16x32_bf16 v[40:43], v[146:149], v[174:177], v[40:43]
	v_mfma_f32_16x16x32_bf16 v[32:35], v[132:135], v[182:185], v[32:35]
	v_mfma_f32_16x16x32_bf16 v[24:27], v[146:149], v[182:185], v[24:27]
	v_mfma_f32_16x16x32_bf16 v[16:19], v[132:135], v[210:213], v[16:19]
	v_mfma_f32_16x16x32_bf16 v[8:11], v[146:149], v[210:213], v[8:11]
	v_mfma_f32_16x16x32_bf16 v[52:55], v[214:217], v[162:165], v[52:55]
	v_mfma_f32_16x16x32_bf16 v[44:47], v[222:225], v[162:165], v[44:47]
	v_mfma_f32_16x16x32_bf16 v[36:39], v[214:217], v[170:173], v[36:39]
	v_mfma_f32_16x16x32_bf16 v[28:31], v[222:225], v[170:173], v[28:31]
	v_mfma_f32_16x16x32_bf16 v[20:23], v[214:217], v[178:181], v[20:23]
	v_mfma_f32_16x16x32_bf16 v[12:15], v[222:225], v[178:181], v[12:15]
	v_mfma_f32_16x16x32_bf16 v[4:7], v[214:217], v[194:197], v[4:7]
	v_mfma_f32_16x16x32_bf16 v[0:3], v[222:225], v[194:197], v[0:3]
	v_mfma_f32_16x16x32_bf16 v[52:55], v[218:221], v[166:169], v[52:55]
	v_mfma_f32_16x16x32_bf16 v[44:47], v[226:229], v[166:169], v[44:47]
	v_mfma_f32_16x16x32_bf16 v[36:39], v[218:221], v[174:177], v[36:39]
	v_mfma_f32_16x16x32_bf16 v[28:31], v[226:229], v[174:177], v[28:31]
	v_mfma_f32_16x16x32_bf16 v[20:23], v[218:221], v[182:185], v[20:23]
	v_mfma_f32_16x16x32_bf16 v[12:15], v[226:229], v[182:185], v[12:15]
	v_mfma_f32_16x16x32_bf16 v[4:7], v[218:221], v[210:213], v[4:7]
	v_mfma_f32_16x16x32_bf16 v[0:3], v[226:229], v[210:213], v[0:3]
	s_barrier
	s_cbranch_scc0 .LBB0_103
	s_mov_b32 s100, 1
	s_setprio 1
	s_ashr_i32 s51, s50, 31
	s_ashr_i32 s53, s52, 31
	s_lshl_b64 s[10:11], s[50:51], 13
	s_lshl_b64 s[50:51], s[52:53], 8
	s_add_u32 s10, s50, s10
	v_lshl_or_b32 v128, s85, 8, v207
	s_addc_u32 s11, s51, s11
	v_ashrrev_i32_e32 v129, 31, v128
	v_lshl_add_u64 v[168:169], s[10:11], 0, v[156:157]
	v_lshlrev_b64 v[170:171], 1, v[128:129]
	v_lshl_add_u64 v[174:175], s[26:27], 0, v[170:171]
	v_lshlrev_b64 v[172:173], 11, v[168:169]
	v_or_b32_e32 v166, 16, v168
	v_mov_b32_e32 v167, v169
	v_lshl_add_u64 v[128:129], v[174:175], 0, v[172:173]
	v_lshlrev_b64 v[176:177], 11, v[166:167]
	global_load_dwordx4 v[146:149], v[128:129], off
	global_load_dwordx4 v[182:185], v[128:129], off offset:256
	v_lshl_add_u64 v[128:129], v[174:175], 0, v[176:177]
	global_load_dwordx4 v[194:197], v[128:129], off
	global_load_dwordx4 v[210:213], v[128:129], off offset:256
	v_or_b32_e32 v164, 32, v168
	v_mov_b32_e32 v165, v169
	v_or_b32_e32 v162, 48, v168
	v_mov_b32_e32 v163, v169
	v_lshlrev_b64 v[180:181], 11, v[164:165]
	v_lshlrev_b64 v[178:179], 11, v[162:163]
	v_lshl_add_u64 v[128:129], v[174:175], 0, v[180:181]
	v_lshl_add_u64 v[130:131], v[174:175], 0, v[178:179]
	global_load_dwordx4 v[214:217], v[128:129], off
	global_load_dwordx4 v[136:139], v[128:129], off offset:256
	global_load_dwordx4 v[132:135], v[130:131], off
	s_nop 0
	global_load_dwordx4 v[128:131], v[130:131], off offset:256
	s_mov_b64 s[10:11], 0x90
	v_lshl_add_u64 v[172:173], s[28:29], 0, v[172:173]
	v_lshl_add_u64 v[172:173], v[172:173], 0, v[170:171]
	s_waitcnt vmcnt(0)
	v_lshlrev_b32_e32 v192, 16, v146
	v_and_b32_e32 v193, 0xffff0000, v146
	v_lshlrev_b32_e32 v218, 16, v148
	v_and_b32_e32 v219, 0xffff0000, v148
	v_lshlrev_b32_e32 v146, 16, v147
	v_and_b32_e32 v147, 0xffff0000, v147
	v_lshlrev_b32_e32 v148, 16, v149
	v_and_b32_e32 v149, 0xffff0000, v149
	v_lshlrev_b32_e32 v220, 16, v182
	v_and_b32_e32 v221, 0xffff0000, v182
	v_lshlrev_b32_e32 v222, 16, v184
	v_and_b32_e32 v223, 0xffff0000, v184
	v_lshlrev_b32_e32 v182, 16, v183
	v_and_b32_e32 v183, 0xffff0000, v183
	v_lshlrev_b32_e32 v184, 16, v185
	v_and_b32_e32 v185, 0xffff0000, v185
	v_pk_add_f32 v[124:125], v[124:125], v[192:193]
	v_pk_add_f32 v[126:127], v[126:127], v[146:147]
	v_pk_add_f32 v[122:123], v[122:123], v[148:149]
	v_pk_add_f32 v[116:117], v[116:117], v[220:221]
	v_pk_add_f32 v[146:147], v[112:113], v[222:223]
	v_pk_add_f32 v[118:119], v[118:119], v[182:183]
	v_pk_add_f32 v[148:149], v[114:115], v[184:185]
	v_lshlrev_b32_e32 v182, 16, v194
	v_and_b32_e32 v183, 0xffff0000, v194
	v_lshlrev_b32_e32 v184, 16, v196
	v_and_b32_e32 v185, 0xffff0000, v196
	v_lshlrev_b32_e32 v192, 16, v195
	v_and_b32_e32 v193, 0xffff0000, v195
	v_lshlrev_b32_e32 v194, 16, v197
	v_and_b32_e32 v195, 0xffff0000, v197
	v_pk_mul_f32 v[196:197], v[124:125], v[124:125]
	v_pk_add_f32 v[120:121], v[120:121], v[218:219]
	v_pk_mul_f32 v[218:219], v[126:127], v[126:127]
	v_cvt_pk_bf16_f32 v112, v124, v125
	v_cvt_pk_bf16_f32 v113, v126, v127
	v_pk_mul_f32 v[124:125], v[116:117], v[116:117]
	v_pk_mul_f32 v[126:127], v[118:119], v[118:119]
	v_pk_mul_f32 v[224:225], v[146:147], v[146:147]
	v_cvt_pk_bf16_f32 v116, v116, v117
	v_cvt_pk_bf16_f32 v117, v118, v119
	v_cvt_pk_bf16_f32 v118, v146, v147
	v_add_f32_e32 v146, v196, v197
	v_add_f32_e32 v146, v218, v146
	v_pk_mul_f32 v[220:221], v[120:121], v[120:121]
	v_add_f32_e32 v146, v219, v146
	v_add_f32_e32 v146, v220, v146
	v_pk_mul_f32 v[222:223], v[122:123], v[122:123]
	v_add_f32_e32 v146, v221, v146
	v_add_f32_e32 v146, v222, v146
	v_add_f32_e32 v146, v223, v146
	v_add_f32_e32 v124, v124, v146
	v_add_f32_e32 v124, v125, v124
	v_add_f32_e32 v124, v126, v124
	v_add_f32_e32 v124, v127, v124
	v_add_f32_e32 v124, v224, v124
	v_pk_mul_f32 v[226:227], v[148:149], v[148:149]
	v_add_f32_e32 v124, v225, v124
	v_add_f32_e32 v124, v226, v124
	v_add_f32_e32 v209, v227, v124
	v_lshlrev_b32_e32 v124, 16, v210
	v_and_b32_e32 v125, 0xffff0000, v210
	v_pk_add_f32 v[100:101], v[100:101], v[124:125]
	v_lshlrev_b32_e32 v124, 16, v212
	v_and_b32_e32 v125, 0xffff0000, v212
	v_pk_add_f32 v[124:125], v[92:93], v[124:125]
	v_lshlrev_b32_e32 v92, 16, v211
	v_and_b32_e32 v93, 0xffff0000, v211
	v_pk_add_f32 v[102:103], v[102:103], v[92:93]
	v_lshlrev_b32_e32 v92, 16, v213
	v_and_b32_e32 v93, 0xffff0000, v213
	v_pk_add_f32 v[126:127], v[94:95], v[92:93]
	v_lshlrev_b32_e32 v92, 16, v214
	v_and_b32_e32 v93, 0xffff0000, v214
	v_pk_add_f32 v[92:93], v[96:97], v[92:93]
	v_lshlrev_b32_e32 v96, 16, v217
	v_and_b32_e32 v97, 0xffff0000, v217
	v_lshlrev_b32_e32 v94, 16, v216
	v_and_b32_e32 v95, 0xffff0000, v216
	v_pk_add_f32 v[90:91], v[90:91], v[96:97]
	v_lshlrev_b32_e32 v96, 16, v136
	v_and_b32_e32 v97, 0xffff0000, v136
	v_pk_add_f32 v[88:89], v[88:89], v[94:95]
	v_lshlrev_b32_e32 v94, 16, v215
	v_and_b32_e32 v95, 0xffff0000, v215
	v_pk_add_f32 v[96:97], v[76:77], v[96:97]
	v_lshl_add_u64 v[76:77], v[168:169], 0, s[36:37]
	v_cvt_pk_bf16_f32 v114, v120, v121
	v_pk_add_f32 v[120:121], v[108:109], v[182:183]
	v_pk_add_f32 v[94:95], v[98:99], v[94:95]
	v_lshlrev_b64 v[182:183], 11, v[76:77]
	v_lshlrev_b32_e32 v98, 16, v138
	v_and_b32_e32 v99, 0xffff0000, v138
	v_pk_add_f32 v[108:109], v[104:105], v[184:185]
	v_lshl_add_u64 v[184:185], v[174:175], 0, v[182:183]
	v_pk_add_f32 v[98:99], v[72:73], v[98:99]
	v_lshlrev_b32_e32 v72, 16, v137
	v_and_b32_e32 v73, 0xffff0000, v137
	global_load_dwordx4 v[210:213], v[184:185], off
	global_load_dwordx4 v[218:221], v[184:185], off offset:256
	v_pk_add_f32 v[136:137], v[78:79], v[72:73]
	v_lshlrev_b32_e32 v72, 16, v139
	v_and_b32_e32 v73, 0xffff0000, v139
	v_pk_add_f32 v[138:139], v[74:75], v[72:73]
	v_lshlrev_b32_e32 v72, 16, v132
	v_and_b32_e32 v73, 0xffff0000, v132
	v_pk_add_f32 v[74:75], v[84:85], v[72:73]
	v_lshlrev_b32_e32 v72, 16, v134
	v_and_b32_e32 v73, 0xffff0000, v134
	v_pk_add_f32 v[78:79], v[80:81], v[72:73]
	v_lshlrev_b32_e32 v72, 16, v133
	v_and_b32_e32 v73, 0xffff0000, v133
	v_pk_add_f32 v[80:81], v[86:87], v[72:73]
	v_lshlrev_b32_e32 v72, 16, v135
	v_and_b32_e32 v73, 0xffff0000, v135
	v_pk_add_f32 v[82:83], v[82:83], v[72:73]
	v_lshl_add_u64 v[72:73], v[168:169], 0, s[10:11]
	v_lshlrev_b64 v[132:133], 11, v[72:73]
	v_lshl_add_u64 v[134:135], v[174:175], 0, v[132:133]
	v_lshlrev_b32_e32 v84, 16, v128
	v_and_b32_e32 v85, 0xffff0000, v128
	global_load_dwordx4 v[226:229], v[134:135], off
	global_load_dwordx4 v[234:237], v[134:135], off offset:256
	v_pk_add_f32 v[84:85], v[68:69], v[84:85]
	v_lshlrev_b32_e32 v68, 16, v130
	v_and_b32_e32 v69, 0xffff0000, v130
	v_pk_add_f32 v[86:87], v[64:65], v[68:69]
	v_lshlrev_b32_e32 v64, 16, v129
	v_and_b32_e32 v65, 0xffff0000, v129
	s_mov_b64 s[10:11], 0xa0
	v_pk_add_f32 v[128:129], v[70:71], v[64:65]
	v_lshl_add_u64 v[70:71], v[168:169], 0, s[10:11]
	s_mov_b64 s[10:11], 0xb0
	v_lshlrev_b32_e32 v64, 16, v131
	v_and_b32_e32 v65, 0xffff0000, v131
	v_lshlrev_b64 v[134:135], 11, v[70:71]
	v_lshl_add_u64 v[68:69], v[168:169], 0, s[10:11]
	v_pk_add_f32 v[130:131], v[66:67], v[64:65]
	v_lshl_add_u64 v[64:65], v[174:175], 0, v[134:135]
	v_lshlrev_b64 v[184:185], 11, v[68:69]
	global_load_dwordx4 v[238:241], v[64:65], off
	global_load_dwordx4 v[242:245], v[64:65], off offset:256
	v_lshl_add_u64 v[64:65], v[174:175], 0, v[184:185]
	global_load_dwordx4 v[246:249], v[64:65], off
	s_nop 0
	global_load_dwordx4 v[64:67], v[64:65], off offset:256
	v_cvt_pk_bf16_f32 v115, v122, v123
	v_cvt_pk_bf16_f32 v119, v148, v149
	v_pk_add_f32 v[110:111], v[110:111], v[192:193]
	v_pk_add_f32 v[122:123], v[106:107], v[194:195]
	global_store_dwordx4 v[172:173], v[112:115], off
	global_store_dwordx4 v[172:173], v[116:119], off offset:256
	v_cvt_pk_bf16_f32 v104, v120, v121
	v_lshl_add_u64 v[112:113], s[28:29], 0, v[176:177]
	v_cvt_pk_bf16_f32 v105, v110, v111
	v_cvt_pk_bf16_f32 v106, v108, v109
	v_cvt_pk_bf16_f32 v107, v122, v123
	v_lshl_add_u64 v[112:113], v[112:113], 0, v[170:171]
	v_cvt_pk_bf16_f32 v146, v100, v101
	v_cvt_pk_bf16_f32 v147, v102, v103
	v_cvt_pk_bf16_f32 v148, v124, v125
	v_cvt_pk_bf16_f32 v149, v126, v127
	global_store_dwordx4 v[112:113], v[104:107], off
	global_store_dwordx4 v[112:113], v[146:149], off offset:256
	v_cvt_pk_bf16_f32 v194, v92, v93
	v_lshl_add_u64 v[104:105], s[28:29], 0, v[180:181]
	v_cvt_pk_bf16_f32 v195, v94, v95
	v_cvt_pk_bf16_f32 v196, v88, v89
	v_cvt_pk_bf16_f32 v197, v90, v91
	v_lshl_add_u64 v[104:105], v[104:105], 0, v[170:171]
	v_cvt_pk_bf16_f32 v214, v96, v97
	v_cvt_pk_bf16_f32 v215, v136, v137
	v_cvt_pk_bf16_f32 v216, v98, v99
	v_cvt_pk_bf16_f32 v217, v138, v139
	global_store_dwordx4 v[104:105], v[194:197], off
	global_store_dwordx4 v[104:105], v[214:217], off offset:256
	v_lshl_add_u64 v[104:105], s[28:29], 0, v[178:179]
	v_cvt_pk_bf16_f32 v222, v74, v75
	v_cvt_pk_bf16_f32 v223, v80, v81
	v_cvt_pk_bf16_f32 v224, v78, v79
	v_cvt_pk_bf16_f32 v225, v82, v83
	v_lshl_add_u64 v[104:105], v[104:105], 0, v[170:171]
	v_cvt_pk_bf16_f32 v230, v84, v85
	v_cvt_pk_bf16_f32 v231, v128, v129
	v_cvt_pk_bf16_f32 v232, v86, v87
	v_cvt_pk_bf16_f32 v233, v130, v131
	global_store_dwordx4 v[104:105], v[222:225], off
	global_store_dwordx4 v[104:105], v[230:233], off offset:256
	s_waitcnt vmcnt(8)
	v_lshlrev_b32_e32 v104, 16, v210
	v_and_b32_e32 v105, 0xffff0000, v210
	v_pk_add_f32 v[60:61], v[60:61], v[104:105]
	v_lshlrev_b32_e32 v104, 16, v212
	v_and_b32_e32 v105, 0xffff0000, v212
	v_pk_add_f32 v[56:57], v[56:57], v[104:105]
	v_lshlrev_b32_e32 v104, 16, v211
	v_and_b32_e32 v105, 0xffff0000, v211
	v_pk_add_f32 v[62:63], v[62:63], v[104:105]
	v_lshlrev_b32_e32 v104, 16, v213
	v_and_b32_e32 v105, 0xffff0000, v213
	v_pk_add_f32 v[58:59], v[58:59], v[104:105]
	v_lshlrev_b32_e32 v104, 16, v218
	v_and_b32_e32 v105, 0xffff0000, v218
	v_pk_add_f32 v[52:53], v[52:53], v[104:105]
	v_lshlrev_b32_e32 v104, 16, v220
	v_and_b32_e32 v105, 0xffff0000, v220
	v_pk_add_f32 v[104:105], v[44:45], v[104:105]
	v_lshlrev_b32_e32 v44, 16, v219
	v_and_b32_e32 v45, 0xffff0000, v219
	v_pk_add_f32 v[54:55], v[54:55], v[44:45]
	v_lshlrev_b32_e32 v44, 16, v221
	v_and_b32_e32 v45, 0xffff0000, v221
	v_pk_add_f32 v[106:107], v[46:47], v[44:45]
	v_lshlrev_b32_e32 v44, 16, v226
	v_and_b32_e32 v45, 0xffff0000, v226
	v_pk_add_f32 v[44:45], v[48:49], v[44:45]
	v_lshlrev_b32_e32 v48, 16, v229
	v_and_b32_e32 v49, 0xffff0000, v229
	v_pk_add_f32 v[42:43], v[42:43], v[48:49]
	v_lshlrev_b32_e32 v48, 16, v234
	v_and_b32_e32 v49, 0xffff0000, v234
	v_pk_add_f32 v[36:37], v[36:37], v[48:49]
	v_lshlrev_b32_e32 v48, 16, v236
	v_and_b32_e32 v49, 0xffff0000, v236
	v_lshlrev_b32_e32 v46, 16, v228
	v_and_b32_e32 v47, 0xffff0000, v228
	v_pk_add_f32 v[48:49], v[28:29], v[48:49]
	v_lshlrev_b32_e32 v28, 16, v235
	v_and_b32_e32 v29, 0xffff0000, v235
	v_pk_add_f32 v[40:41], v[40:41], v[46:47]
	v_lshlrev_b32_e32 v46, 16, v227
	v_and_b32_e32 v47, 0xffff0000, v227
	v_pk_add_f32 v[38:39], v[38:39], v[28:29]
	v_lshlrev_b32_e32 v28, 16, v237
	v_and_b32_e32 v29, 0xffff0000, v237
	v_pk_add_f32 v[46:47], v[50:51], v[46:47]
	v_pk_add_f32 v[50:51], v[30:31], v[28:29]
	v_lshlrev_b32_e32 v28, 16, v238
	v_and_b32_e32 v29, 0xffff0000, v238
	v_lshlrev_b32_e32 v180, 16, v64
	v_and_b32_e32 v181, 0xffff0000, v64
	v_pk_add_f32 v[28:29], v[32:33], v[28:29]
	v_lshlrev_b32_e32 v32, 16, v241
	v_and_b32_e32 v33, 0xffff0000, v241
	v_pk_add_f32 v[4:5], v[4:5], v[180:181]
	v_lshlrev_b32_e32 v180, 16, v66
	v_and_b32_e32 v181, 0xffff0000, v66
	v_pk_add_f32 v[26:27], v[26:27], v[32:33]
	v_lshlrev_b32_e32 v32, 16, v242
	v_and_b32_e32 v33, 0xffff0000, v242
	v_pk_add_f32 v[0:1], v[0:1], v[180:181]
	v_lshl_add_u64 v[180:181], s[28:29], 0, v[182:183]
	v_cvt_pk_bf16_f32 v112, v60, v61
	v_cvt_pk_bf16_f32 v113, v62, v63
	v_cvt_pk_bf16_f32 v114, v56, v57
	v_cvt_pk_bf16_f32 v115, v58, v59
	v_pk_add_f32 v[20:21], v[20:21], v[32:33]
	v_lshlrev_b32_e32 v32, 16, v244
	v_and_b32_e32 v33, 0xffff0000, v244
	v_lshl_add_u64 v[180:181], v[180:181], 0, v[170:171]
	v_cvt_pk_bf16_f32 v116, v52, v53
	v_cvt_pk_bf16_f32 v117, v54, v55
	v_cvt_pk_bf16_f32 v118, v104, v105
	v_cvt_pk_bf16_f32 v119, v106, v107
	v_lshlrev_b32_e32 v30, 16, v240
	v_and_b32_e32 v31, 0xffff0000, v240
	v_pk_add_f32 v[32:33], v[12:13], v[32:33]
	v_lshlrev_b32_e32 v12, 16, v243
	v_and_b32_e32 v13, 0xffff0000, v243
	global_store_dwordx4 v[180:181], v[112:115], off
	global_store_dwordx4 v[180:181], v[116:119], off offset:256
	v_cvt_pk_bf16_f32 v146, v44, v45
	v_lshl_add_u64 v[112:113], s[28:29], 0, v[132:133]
	v_cvt_pk_bf16_f32 v147, v46, v47
	v_cvt_pk_bf16_f32 v148, v40, v41
	v_cvt_pk_bf16_f32 v149, v42, v43
	v_pk_add_f32 v[24:25], v[24:25], v[30:31]
	v_lshlrev_b32_e32 v30, 16, v239
	v_and_b32_e32 v31, 0xffff0000, v239
	v_pk_add_f32 v[22:23], v[22:23], v[12:13]
	v_lshlrev_b32_e32 v12, 16, v245
	v_and_b32_e32 v13, 0xffff0000, v245
	v_lshl_add_u64 v[112:113], v[112:113], 0, v[170:171]
	v_cvt_pk_bf16_f32 v172, v36, v37
	v_cvt_pk_bf16_f32 v173, v38, v39
	v_cvt_pk_bf16_f32 v174, v48, v49
	v_cvt_pk_bf16_f32 v175, v50, v51
	v_pk_add_f32 v[30:31], v[34:35], v[30:31]
	v_pk_add_f32 v[34:35], v[14:15], v[12:13]
	v_lshlrev_b32_e32 v12, 16, v246
	v_and_b32_e32 v13, 0xffff0000, v246
	v_lshlrev_b32_e32 v14, 16, v248
	v_and_b32_e32 v15, 0xffff0000, v248
	global_store_dwordx4 v[112:113], v[146:149], off
	global_store_dwordx4 v[112:113], v[172:175], off offset:256
	v_lshl_add_u64 v[112:113], s[28:29], 0, v[134:135]
	v_cvt_pk_bf16_f32 v176, v28, v29
	v_cvt_pk_bf16_f32 v177, v30, v31
	v_cvt_pk_bf16_f32 v178, v24, v25
	v_cvt_pk_bf16_f32 v179, v26, v27
	v_pk_add_f32 v[12:13], v[16:17], v[12:13]
	v_pk_add_f32 v[8:9], v[8:9], v[14:15]
	v_lshlrev_b32_e32 v14, 16, v247
	v_and_b32_e32 v15, 0xffff0000, v247
	v_lshlrev_b32_e32 v16, 16, v249
	v_and_b32_e32 v17, 0xffff0000, v249
	v_lshlrev_b32_e32 v64, 16, v65
	v_and_b32_e32 v65, 0xffff0000, v65
	v_lshl_add_u64 v[112:113], v[112:113], 0, v[170:171]
	v_cvt_pk_bf16_f32 v194, v20, v21
	v_cvt_pk_bf16_f32 v195, v22, v23
	v_cvt_pk_bf16_f32 v196, v32, v33
	v_cvt_pk_bf16_f32 v197, v34, v35
	v_pk_add_f32 v[14:15], v[18:19], v[14:15]
	v_pk_add_f32 v[10:11], v[10:11], v[16:17]
	v_pk_add_f32 v[6:7], v[6:7], v[64:65]
	v_lshlrev_b32_e32 v64, 16, v67
	v_and_b32_e32 v65, 0xffff0000, v67
	global_store_dwordx4 v[112:113], v[176:179], off
	global_store_dwordx4 v[112:113], v[194:197], off offset:256
	v_lshl_add_u64 v[112:113], s[28:29], 0, v[184:185]
	v_cvt_pk_bf16_f32 v16, v12, v13
	v_cvt_pk_bf16_f32 v17, v14, v15
	v_cvt_pk_bf16_f32 v18, v8, v9
	v_cvt_pk_bf16_f32 v19, v10, v11
	v_pk_add_f32 v[2:3], v[2:3], v[64:65]
	v_lshl_add_u64 v[112:113], v[112:113], 0, v[170:171]
	v_cvt_pk_bf16_f32 v64, v4, v5
	v_cvt_pk_bf16_f32 v65, v6, v7
	v_cvt_pk_bf16_f32 v66, v0, v1
	v_cvt_pk_bf16_f32 v67, v2, v3
	global_store_dwordx4 v[112:113], v[16:19], off
	global_store_dwordx4 v[112:113], v[64:67], off offset:256
	s_lshl_b32 s10, s85, 2
	v_and_b32_e32 v17, 64, v188
	v_xor_b32_e32 v16, 16, v188
	v_add_u32_e32 v17, 64, v17
	v_cmp_lt_i32_e32 vcc, v16, v17
	v_xor_b32_e32 v18, 32, v188
	s_ashr_i32 s11, s10, 31
	v_cndmask_b32_e32 v16, v188, v16, vcc
	v_lshlrev_b32_e32 v16, 2, v16
	v_mov_b32_e32 v132, v209
	v_cmp_lt_i32_e32 vcc, v18, v17
	s_lshl_b64 s[10:11], s[10:11], 2
	s_add_u32 s50, s83, s10
	v_cndmask_b32_e32 v17, v188, v18, vcc
	v_lshlrev_b32_e32 v17, 2, v17
	s_addc_u32 s51, s84, s11
	v_pk_mul_f32 v[18:19], v[120:121], v[120:121]
	v_pk_mul_f32 v[64:65], v[110:111], v[110:111]
	v_add_f32_e32 v18, v18, v19
	v_add_f32_e32 v18, v64, v18
	v_pk_mul_f32 v[66:67], v[108:109], v[108:109]
	v_add_f32_e32 v18, v65, v18
	v_add_f32_e32 v18, v66, v18
	v_pk_mul_f32 v[108:109], v[122:123], v[122:123]
	v_add_f32_e32 v18, v67, v18
	v_add_f32_e32 v18, v108, v18
	v_pk_mul_f32 v[100:101], v[100:101], v[100:101]
	v_add_f32_e32 v18, v109, v18
	v_add_f32_e32 v18, v100, v18
	v_pk_mul_f32 v[102:103], v[102:103], v[102:103]
	v_add_f32_e32 v18, v101, v18
	v_add_f32_e32 v18, v102, v18
	v_pk_mul_f32 v[110:111], v[124:125], v[124:125]
	v_add_f32_e32 v18, v103, v18
	v_add_f32_e32 v18, v110, v18
	v_pk_mul_f32 v[112:113], v[126:127], v[126:127]
	v_add_f32_e32 v18, v111, v18
	v_add_f32_e32 v18, v112, v18
	v_add_f32_e32 v18, v113, v18
	v_mov_b32_e32 v133, v18
	v_pk_mul_f32 v[18:19], v[92:93], v[92:93]
	v_pk_mul_f32 v[64:65], v[94:95], v[94:95]
	v_add_f32_e32 v18, v18, v19
	v_add_f32_e32 v18, v64, v18
	v_pk_mul_f32 v[66:67], v[88:89], v[88:89]
	v_add_f32_e32 v18, v65, v18
	v_add_f32_e32 v18, v66, v18
	v_pk_mul_f32 v[88:89], v[90:91], v[90:91]
	v_add_f32_e32 v18, v67, v18
	v_add_f32_e32 v18, v88, v18
	v_pk_mul_f32 v[90:91], v[96:97], v[96:97]
	v_add_f32_e32 v18, v89, v18
	v_add_f32_e32 v18, v90, v18
	v_pk_mul_f32 v[92:93], v[136:137], v[136:137]
	v_add_f32_e32 v18, v91, v18
	v_add_f32_e32 v18, v92, v18
	v_pk_mul_f32 v[94:95], v[98:99], v[98:99]
	v_add_f32_e32 v18, v93, v18
	v_add_f32_e32 v18, v94, v18
	v_pk_mul_f32 v[96:97], v[138:139], v[138:139]
	v_add_f32_e32 v18, v95, v18
	v_add_f32_e32 v18, v96, v18
	v_add_f32_e32 v18, v97, v18
	v_mov_b32_e32 v134, v18
	v_pk_mul_f32 v[18:19], v[74:75], v[74:75]
	v_pk_mul_f32 v[192:193], v[60:61], v[60:61]
	v_pk_mul_f32 v[64:65], v[80:81], v[80:81]
	v_pk_mul_f32 v[60:61], v[62:63], v[62:63]
	v_add_f32_e32 v18, v18, v19
	v_add_f32_e32 v192, v192, v193
	v_add_f32_e32 v18, v64, v18
	v_add_f32_e32 v192, v60, v192
	v_pk_mul_f32 v[66:67], v[78:79], v[78:79]
	v_pk_mul_f32 v[56:57], v[56:57], v[56:57]
	v_add_f32_e32 v18, v65, v18
	v_add_f32_e32 v192, v61, v192
	v_add_f32_e32 v18, v66, v18
	v_add_f32_e32 v192, v56, v192
	v_pk_mul_f32 v[74:75], v[82:83], v[82:83]
	v_pk_mul_f32 v[58:59], v[58:59], v[58:59]
	v_add_f32_e32 v18, v67, v18
	v_add_f32_e32 v192, v57, v192
	v_add_f32_e32 v18, v74, v18
	v_add_f32_e32 v192, v58, v192
	v_pk_mul_f32 v[78:79], v[84:85], v[84:85]
	v_pk_mul_f32 v[52:53], v[52:53], v[52:53]
	v_add_f32_e32 v18, v75, v18
	v_add_f32_e32 v192, v59, v192
	v_add_f32_e32 v18, v78, v18
	v_add_f32_e32 v192, v52, v192
	v_pk_mul_f32 v[80:81], v[128:129], v[128:129]
	v_pk_mul_f32 v[54:55], v[54:55], v[54:55]
	v_add_f32_e32 v18, v79, v18
	v_add_f32_e32 v192, v53, v192
	v_add_f32_e32 v18, v80, v18
	v_add_f32_e32 v192, v54, v192
	v_pk_mul_f32 v[82:83], v[86:87], v[86:87]
	v_pk_mul_f32 v[62:63], v[104:105], v[104:105]
	v_add_f32_e32 v18, v81, v18
	v_add_f32_e32 v192, v55, v192
	v_add_f32_e32 v18, v82, v18
	v_add_f32_e32 v192, v62, v192
	v_pk_mul_f32 v[84:85], v[130:131], v[130:131]
	v_pk_mul_f32 v[210:211], v[106:107], v[106:107]
	v_add_f32_e32 v18, v83, v18
	v_add_f32_e32 v192, v63, v192
	v_add_f32_e32 v18, v84, v18
	v_add_f32_e32 v192, v210, v192
	v_add_f32_e32 v18, v85, v18
	v_add_f32_e32 v192, v211, v192
	v_mov_b32_e32 v135, v18
	v_mov_b32_e32 v146, v192
	v_pk_mul_f32 v[18:19], v[44:45], v[44:45]
	v_pk_mul_f32 v[192:193], v[28:29], v[28:29]
	v_pk_mul_f32 v[44:45], v[46:47], v[46:47]
	v_pk_mul_f32 v[28:29], v[30:31], v[30:31]
	v_add_f32_e32 v18, v18, v19
	v_add_f32_e32 v192, v192, v193
	v_add_f32_e32 v18, v44, v18
	v_add_f32_e32 v192, v28, v192
	v_pk_mul_f32 v[40:41], v[40:41], v[40:41]
	v_pk_mul_f32 v[24:25], v[24:25], v[24:25]
	v_add_f32_e32 v18, v45, v18
	v_add_f32_e32 v192, v29, v192
	v_add_f32_e32 v18, v40, v18
	v_add_f32_e32 v192, v24, v192
	v_pk_mul_f32 v[42:43], v[42:43], v[42:43]
	v_pk_mul_f32 v[26:27], v[26:27], v[26:27]
	v_add_f32_e32 v18, v41, v18
	v_add_f32_e32 v192, v25, v192
	v_add_f32_e32 v18, v42, v18
	v_add_f32_e32 v192, v26, v192
	v_pk_mul_f32 v[36:37], v[36:37], v[36:37]
	v_pk_mul_f32 v[20:21], v[20:21], v[20:21]
	v_add_f32_e32 v18, v43, v18
	v_add_f32_e32 v192, v27, v192
	v_add_f32_e32 v18, v36, v18
	v_add_f32_e32 v192, v20, v192
	v_pk_mul_f32 v[38:39], v[38:39], v[38:39]
	v_pk_mul_f32 v[22:23], v[22:23], v[22:23]
	v_add_f32_e32 v18, v37, v18
	v_add_f32_e32 v192, v21, v192
	v_add_f32_e32 v18, v38, v18
	v_add_f32_e32 v192, v22, v192
	v_pk_mul_f32 v[46:47], v[48:49], v[48:49]
	v_pk_mul_f32 v[30:31], v[32:33], v[32:33]
	v_add_f32_e32 v18, v39, v18
	v_add_f32_e32 v192, v23, v192
	v_add_f32_e32 v18, v46, v18
	v_add_f32_e32 v192, v30, v192
	v_pk_mul_f32 v[48:49], v[50:51], v[50:51]
	v_pk_mul_f32 v[32:33], v[34:35], v[34:35]
	v_add_f32_e32 v18, v47, v18
	v_add_f32_e32 v192, v31, v192
	v_add_f32_e32 v18, v48, v18
	v_add_f32_e32 v192, v32, v192
	v_add_f32_e32 v18, v49, v18
	v_add_f32_e32 v192, v33, v192
	v_mov_b32_e32 v147, v18
	v_mov_b32_e32 v148, v192
	v_pk_mul_f32 v[12:13], v[12:13], v[12:13]
	v_pk_mul_f32 v[14:15], v[14:15], v[14:15]
	v_add_f32_e32 v12, v12, v13
	v_add_f32_e32 v12, v14, v12
	v_pk_mul_f32 v[8:9], v[8:9], v[8:9]
	v_add_f32_e32 v12, v15, v12
	v_add_f32_e32 v8, v8, v12
	v_pk_mul_f32 v[10:11], v[10:11], v[10:11]
	v_add_f32_e32 v8, v9, v8
	v_add_f32_e32 v8, v10, v8
	v_pk_mul_f32 v[4:5], v[4:5], v[4:5]
	v_add_f32_e32 v8, v11, v8
	v_add_f32_e32 v4, v4, v8
	v_pk_mul_f32 v[6:7], v[6:7], v[6:7]
	v_add_f32_e32 v4, v5, v4
	v_add_f32_e32 v4, v6, v4
	v_pk_mul_f32 v[0:1], v[0:1], v[0:1]
	v_add_f32_e32 v4, v7, v4
	v_add_f32_e32 v0, v0, v4
	v_pk_mul_f32 v[2:3], v[2:3], v[2:3]
	v_add_f32_e32 v0, v1, v0
	v_add_f32_e32 v0, v2, v0
	v_add_f32_e32 v0, v3, v0
	v_mov_b32_e32 v149, v0
	ds_bpermute_b32 v172, v16, v132
	ds_bpermute_b32 v173, v16, v133
	ds_bpermute_b32 v174, v16, v134
	ds_bpermute_b32 v175, v16, v135
	ds_bpermute_b32 v180, v16, v146
	ds_bpermute_b32 v181, v16, v147
	ds_bpermute_b32 v182, v16, v148
	ds_bpermute_b32 v183, v16, v149
	s_waitcnt lgkmcnt(0)
	v_add_f32_e32 v132, v132, v172
	v_add_f32_e32 v133, v133, v173
	v_add_f32_e32 v134, v134, v174
	v_add_f32_e32 v135, v135, v175
	v_add_f32_e32 v146, v146, v180
	v_add_f32_e32 v147, v147, v181
	v_add_f32_e32 v148, v148, v182
	v_add_f32_e32 v149, v149, v183
	ds_bpermute_b32 v172, v17, v132
	ds_bpermute_b32 v173, v17, v133
	ds_bpermute_b32 v174, v17, v134
	ds_bpermute_b32 v175, v17, v135
	ds_bpermute_b32 v180, v17, v146
	ds_bpermute_b32 v181, v17, v147
	ds_bpermute_b32 v182, v17, v148
	ds_bpermute_b32 v183, v17, v149
	s_and_saveexec_b64 s[52:53], s[42:43]
	s_cbranch_execz .LBB0_91
	s_waitcnt lgkmcnt(0)
	v_add_f32_e32 v132, v132, v172
	v_lshlrev_b64 v[18:19], 6, v[168:169]
	v_lshl_add_u64 v[18:19], s[50:51], 0, v[18:19]
	global_store_dword v[18:19], v132, off
	v_add_f32_e32 v133, v133, v173
	v_lshlrev_b64 v[18:19], 6, v[166:167]
	v_lshl_add_u64 v[18:19], s[50:51], 0, v[18:19]
	global_store_dword v[18:19], v133, off
	v_add_f32_e32 v134, v134, v174
	v_lshlrev_b64 v[18:19], 6, v[164:165]
	v_lshl_add_u64 v[18:19], s[50:51], 0, v[18:19]
	global_store_dword v[18:19], v134, off
	v_add_f32_e32 v135, v135, v175
	v_lshlrev_b64 v[18:19], 6, v[162:163]
	v_lshl_add_u64 v[18:19], s[50:51], 0, v[18:19]
	global_store_dword v[18:19], v135, off
	v_add_f32_e32 v146, v146, v180
	v_lshlrev_b64 v[18:19], 6, v[76:77]
	v_lshl_add_u64 v[18:19], s[50:51], 0, v[18:19]
	global_store_dword v[18:19], v146, off
	v_add_f32_e32 v147, v147, v181
	v_lshlrev_b64 v[18:19], 6, v[72:73]
	v_lshl_add_u64 v[18:19], s[50:51], 0, v[18:19]
	global_store_dword v[18:19], v147, off
	v_add_f32_e32 v148, v148, v182
	v_lshlrev_b64 v[18:19], 6, v[70:71]
	v_lshl_add_u64 v[18:19], s[50:51], 0, v[18:19]
	global_store_dword v[18:19], v148, off
	v_add_f32_e32 v149, v149, v183
	v_lshlrev_b64 v[18:19], 6, v[68:69]
	v_lshl_add_u64 v[18:19], s[50:51], 0, v[18:19]
	global_store_dword v[18:19], v149, off
	s_branch .LBB0_91

.LBB0_247:
	s_ashr_i32 s35, s34, 31
	s_lshl_b64 s[10:11], s[34:35], 19
	v_cmp_lt_i64_e32 vcc, s[46:47], v[142:143]
	s_add_u32 s46, s26, s10
	s_addc_u32 s47, s27, s11
	s_and_b64 s[10:11], vcc, exec
	s_cselect_b32 s10, s47, s53
	s_cselect_b32 s11, s46, s52
	s_ashr_i32 s39, s38, 31
	s_lshl_b64 s[48:49], s[38:39], 19
	s_add_u32 s48, s33, s48
	s_addc_u32 s49, s41, s49
	s_and_b64 s[58:59], vcc, exec
	s_cselect_b32 s12, s49, s55
	s_cselect_b32 s35, s48, s54
	s_add_u32 s52, s52, 0x40080
	s_addc_u32 s53, s53, 0
	s_add_u32 s39, s54, 0x100
	s_addc_u32 s51, s55, 0
	s_mov_b32 s82, -2
	s_waitcnt lgkmcnt(0)
	s_add_u32 s6, s52, 0xfffc0080
	s_addc_u32 s19, s53, -1
	s_add_i32 s23, 0, 0x10000
	v_add_u32_e32 v146, s23, v206
	ds_read_b128 v[128:131], v146
	ds_read_b128 v[132:135], v146 offset:1024
	ds_read_b128 v[136:139], v146 offset:2048
	ds_read_b128 v[146:149], v146 offset:3072
	s_cmp_eq_u32 s82, 12
	s_cselect_b32 s59, s10, s19
	s_cselect_b32 s58, s11, s6
	s_cselect_b32 s55, s12, s51
	s_cselect_b32 s54, s35, s39
	v_lshl_add_u64 v[214:215], s[52:53], 0, v[158:159]
	s_add_i32 m0, s68, 0xc000
	ds_read_b128 v[162:165], v208
	ds_read_b128 v[166:169], v208 offset:1024
	ds_read_b128 v[170:173], v208 offset:2048
	ds_read_b128 v[174:177], v208 offset:3072
	ds_read_b128 v[178:181], v208 offset:4096
	ds_read_b128 v[182:185], v208 offset:5120
	ds_read_b128 v[194:197], v208 offset:6144
	ds_read_b128 v[210:213], v208 offset:7168
	global_load_lds_dwordx4 v[214:215], off
	v_lshl_add_u64 v[214:215], s[52:53], 0, v[160:161]
	s_add_i32 m0, s68, 0xe000
	s_nop 0
	global_load_lds_dwordx4 v[214:215], off
	s_add_i32 s6, 0, 0x14000
	v_add_u32_e32 v192, s6, v206
	ds_read_b128 v[214:217], v192
	ds_read_b128 v[218:221], v192 offset:1024
	ds_read_b128 v[222:225], v192 offset:2048
	ds_read_b128 v[226:229], v192 offset:3072
	s_setprio 0
	s_waitcnt vmcnt(40)
	s_cmp_lg_u32 s100, 0
	s_cbranch_scc1 .Lm4ap_248
	s_waitcnt vmcnt(8)

.LBB0_248:
	s_add_u32 s6, s52, 0xfffc0080
	s_addc_u32 s19, s53, -1
	s_add_i32 s23, 0, 0x10000
	v_add_u32_e32 v146, s23, v206
	ds_read_b128 v[128:131], v146
	ds_read_b128 v[132:135], v146 offset:1024
	ds_read_b128 v[136:139], v146 offset:2048
	ds_read_b128 v[146:149], v146 offset:3072
	s_cmp_eq_u32 s82, 12
	s_cselect_b32 s59, s10, s19
	s_cselect_b32 s58, s11, s6
	s_cselect_b32 s55, s12, s51
	s_cselect_b32 s54, s35, s39
	v_lshl_add_u64 v[214:215], s[52:53], 0, v[158:159]
	s_add_i32 m0, s68, 0xc000
	ds_read_b128 v[162:165], v208
	ds_read_b128 v[166:169], v208 offset:1024
	ds_read_b128 v[170:173], v208 offset:2048
	ds_read_b128 v[174:177], v208 offset:3072
	ds_read_b128 v[178:181], v208 offset:4096
	ds_read_b128 v[182:185], v208 offset:5120
	ds_read_b128 v[194:197], v208 offset:6144
	ds_read_b128 v[210:213], v208 offset:7168
	global_load_lds_dwordx4 v[214:215], off
	v_lshl_add_u64 v[214:215], s[52:53], 0, v[160:161]
	s_add_i32 m0, s68, 0xe000
	s_nop 0
	global_load_lds_dwordx4 v[214:215], off
	s_add_i32 s6, 0, 0x14000
	v_add_u32_e32 v192, s6, v206
	ds_read_b128 v[214:217], v192
	ds_read_b128 v[218:221], v192 offset:1024
	ds_read_b128 v[222:225], v192 offset:2048
	ds_read_b128 v[226:229], v192 offset:3072
	s_nop 0
	s_waitcnt vmcnt(8)
	s_waitcnt lgkmcnt(0)
	s_barrier
	v_mfma_f32_16x16x32_bf16 v[124:127], v[128:131], v[162:165], v[124:127]
	v_mfma_f32_16x16x32_bf16 v[120:123], v[136:139], v[162:165], v[120:123]
	v_mfma_f32_16x16x32_bf16 v[108:111], v[128:131], v[170:173], v[108:111]
	v_mfma_f32_16x16x32_bf16 v[104:107], v[136:139], v[170:173], v[104:107]
	v_mfma_f32_16x16x32_bf16 v[96:99], v[128:131], v[178:181], v[96:99]
	v_mfma_f32_16x16x32_bf16 v[88:91], v[136:139], v[178:181], v[88:91]
	v_mfma_f32_16x16x32_bf16 v[84:87], v[128:131], v[194:197], v[84:87]
	v_mfma_f32_16x16x32_bf16 v[80:83], v[136:139], v[194:197], v[80:83]
	v_mfma_f32_16x16x32_bf16 v[124:127], v[132:135], v[166:169], v[124:127]
	v_mfma_f32_16x16x32_bf16 v[120:123], v[146:149], v[166:169], v[120:123]
	v_mfma_f32_16x16x32_bf16 v[108:111], v[132:135], v[174:177], v[108:111]
	v_mfma_f32_16x16x32_bf16 v[104:107], v[146:149], v[174:177], v[104:107]
	v_mfma_f32_16x16x32_bf16 v[96:99], v[132:135], v[182:185], v[96:99]
	v_mfma_f32_16x16x32_bf16 v[88:91], v[146:149], v[182:185], v[88:91]
	v_mfma_f32_16x16x32_bf16 v[84:87], v[132:135], v[210:213], v[84:87]
	v_mfma_f32_16x16x32_bf16 v[80:83], v[146:149], v[210:213], v[80:83]
	v_mfma_f32_16x16x32_bf16 v[116:119], v[214:217], v[162:165], v[116:119]
	v_mfma_f32_16x16x32_bf16 v[112:115], v[222:225], v[162:165], v[112:115]
	v_mfma_f32_16x16x32_bf16 v[100:103], v[214:217], v[170:173], v[100:103]
	v_mfma_f32_16x16x32_bf16 v[92:95], v[222:225], v[170:173], v[92:95]
	v_mfma_f32_16x16x32_bf16 v[76:79], v[214:217], v[178:181], v[76:79]
	v_mfma_f32_16x16x32_bf16 v[72:75], v[222:225], v[178:181], v[72:75]
	v_mfma_f32_16x16x32_bf16 v[68:71], v[214:217], v[194:197], v[68:71]
	v_mfma_f32_16x16x32_bf16 v[64:67], v[222:225], v[194:197], v[64:67]
	v_mfma_f32_16x16x32_bf16 v[116:119], v[218:221], v[166:169], v[116:119]
	v_mfma_f32_16x16x32_bf16 v[112:115], v[226:229], v[166:169], v[112:115]
	v_mfma_f32_16x16x32_bf16 v[100:103], v[218:221], v[174:177], v[100:103]
	v_mfma_f32_16x16x32_bf16 v[92:95], v[226:229], v[174:177], v[92:95]
	v_mfma_f32_16x16x32_bf16 v[76:79], v[218:221], v[182:185], v[76:79]
	v_mfma_f32_16x16x32_bf16 v[72:75], v[226:229], v[182:185], v[72:75]
	v_mfma_f32_16x16x32_bf16 v[68:71], v[218:221], v[210:213], v[68:71]
	v_mfma_f32_16x16x32_bf16 v[64:67], v[226:229], v[210:213], v[64:67]
	s_barrier
	s_add_i32 s19, s23, s57
	v_lshl_add_u64 v[230:231], s[54:55], 0, v[140:141]
	s_mov_b32 m0, s19
	s_nop 0
	global_load_lds_dwordx4 v[230:231], off
	v_lshl_add_u64 v[232:233], s[54:55], 0, v[150:151]
	s_add_i32 m0, s19, 0x2000
	s_nop 0
	global_load_lds_dwordx4 v[232:233], off
	s_mov_b32 m0, s68
	v_lshl_add_u64 v[234:235], s[58:59], 0, v[154:155]
	ds_read_b128 v[162:165], v208 offset:16384
	ds_read_b128 v[166:169], v208 offset:17408
	ds_read_b128 v[170:173], v208 offset:18432
	ds_read_b128 v[174:177], v208 offset:19456
	ds_read_b128 v[178:181], v208 offset:20480
	ds_read_b128 v[182:185], v208 offset:21504
	ds_read_b128 v[194:197], v208 offset:22528
	ds_read_b128 v[210:213], v208 offset:23552
	global_load_lds_dwordx4 v[234:235], off
	v_lshl_add_u64 v[236:237], s[58:59], 0, v[152:153]
	s_mov_b32 m0, s69
	s_nop 0
	global_load_lds_dwordx4 v[236:237], off
	s_add_u32 s84, s54, 0x40000
	s_addc_u32 s85, s55, 0
	s_add_i32 s6, s6, s57
	v_lshl_add_u64 v[250:251], s[84:85], 0, v[140:141]
	s_mov_b32 m0, s6
	s_nop 0
	global_load_lds_dwordx4 v[250:251], off
	v_lshl_add_u64 v[250:251], s[84:85], 0, v[150:151]
	s_add_i32 m0, s6, 0x2000
	s_nop 0
	global_load_lds_dwordx4 v[250:251], off
	s_waitcnt vmcnt(8)
	s_waitcnt lgkmcnt(0)
	s_barrier
	v_mfma_f32_16x16x32_bf16 v[60:63], v[128:131], v[162:165], v[60:63]
	v_mfma_f32_16x16x32_bf16 v[56:59], v[136:139], v[162:165], v[56:59]
	v_mfma_f32_16x16x32_bf16 v[48:51], v[128:131], v[170:173], v[48:51]
	v_mfma_f32_16x16x32_bf16 v[40:43], v[136:139], v[170:173], v[40:43]
	v_mfma_f32_16x16x32_bf16 v[32:35], v[128:131], v[178:181], v[32:35]
	v_mfma_f32_16x16x32_bf16 v[24:27], v[136:139], v[178:181], v[24:27]
	v_mfma_f32_16x16x32_bf16 v[16:19], v[128:131], v[194:197], v[16:19]
	v_mfma_f32_16x16x32_bf16 v[8:11], v[136:139], v[194:197], v[8:11]
	v_mfma_f32_16x16x32_bf16 v[60:63], v[132:135], v[166:169], v[60:63]
	v_mfma_f32_16x16x32_bf16 v[56:59], v[146:149], v[166:169], v[56:59]
	v_mfma_f32_16x16x32_bf16 v[48:51], v[132:135], v[174:177], v[48:51]
	v_mfma_f32_16x16x32_bf16 v[40:43], v[146:149], v[174:177], v[40:43]
	v_mfma_f32_16x16x32_bf16 v[32:35], v[132:135], v[182:185], v[32:35]
	v_mfma_f32_16x16x32_bf16 v[24:27], v[146:149], v[182:185], v[24:27]
	v_mfma_f32_16x16x32_bf16 v[16:19], v[132:135], v[210:213], v[16:19]
	v_mfma_f32_16x16x32_bf16 v[8:11], v[146:149], v[210:213], v[8:11]
	v_mfma_f32_16x16x32_bf16 v[52:55], v[214:217], v[162:165], v[52:55]
	v_mfma_f32_16x16x32_bf16 v[44:47], v[222:225], v[162:165], v[44:47]
	v_mfma_f32_16x16x32_bf16 v[36:39], v[214:217], v[170:173], v[36:39]
	v_mfma_f32_16x16x32_bf16 v[28:31], v[222:225], v[170:173], v[28:31]
	v_mfma_f32_16x16x32_bf16 v[20:23], v[214:217], v[178:181], v[20:23]
	v_mfma_f32_16x16x32_bf16 v[12:15], v[222:225], v[178:181], v[12:15]
	v_mfma_f32_16x16x32_bf16 v[4:7], v[214:217], v[194:197], v[4:7]
	v_mfma_f32_16x16x32_bf16 v[0:3], v[222:225], v[194:197], v[0:3]
	v_mfma_f32_16x16x32_bf16 v[52:55], v[218:221], v[166:169], v[52:55]
	v_mfma_f32_16x16x32_bf16 v[44:47], v[226:229], v[166:169], v[44:47]
	v_mfma_f32_16x16x32_bf16 v[36:39], v[218:221], v[174:177], v[36:39]
	v_mfma_f32_16x16x32_bf16 v[28:31], v[226:229], v[174:177], v[28:31]
	v_mfma_f32_16x16x32_bf16 v[20:23], v[218:221], v[182:185], v[20:23]
	v_mfma_f32_16x16x32_bf16 v[12:15], v[226:229], v[182:185], v[12:15]
	v_mfma_f32_16x16x32_bf16 v[4:7], v[218:221], v[210:213], v[4:7]
	v_mfma_f32_16x16x32_bf16 v[0:3], v[226:229], v[210:213], v[0:3]
	s_barrier
	s_add_i32 s6, 0, 0x18000
	v_add_u32_e32 v146, s6, v206
	ds_read_b128 v[128:131], v146
	ds_read_b128 v[132:135], v146 offset:1024
	ds_read_b128 v[136:139], v146 offset:2048
	ds_read_b128 v[146:149], v146 offset:3072
	s_add_u32 s58, s58, 0x40000
	s_addc_u32 s59, s59, 0
	s_mov_b32 m0, s70
	v_lshl_add_u64 v[214:215], s[58:59], 0, v[154:155]
	ds_read_b128 v[162:165], v208 offset:32768
	ds_read_b128 v[166:169], v208 offset:33792
	ds_read_b128 v[170:173], v208 offset:34816
	ds_read_b128 v[174:177], v208 offset:35840
	ds_read_b128 v[178:181], v208 offset:36864
	ds_read_b128 v[182:185], v208 offset:37888
	ds_read_b128 v[194:197], v208 offset:38912
	ds_read_b128 v[210:213], v208 offset:39936
	global_load_lds_dwordx4 v[214:215], off
	v_lshl_add_u64 v[214:215], s[58:59], 0, v[152:153]
	s_mov_b32 m0, s71
	s_nop 0
	global_load_lds_dwordx4 v[214:215], off
	s_add_i32 s19, 0, 0x1c000
	v_add_u32_e32 v192, s19, v206
	ds_read_b128 v[214:217], v192
	ds_read_b128 v[218:221], v192 offset:1024
	ds_read_b128 v[222:225], v192 offset:2048
	ds_read_b128 v[226:229], v192 offset:3072
	s_waitcnt vmcnt(8)
	s_waitcnt lgkmcnt(0)
	s_barrier
	v_mfma_f32_16x16x32_bf16 v[124:127], v[128:131], v[162:165], v[124:127]
	v_mfma_f32_16x16x32_bf16 v[120:123], v[136:139], v[162:165], v[120:123]
	v_mfma_f32_16x16x32_bf16 v[108:111], v[128:131], v[170:173], v[108:111]
	v_mfma_f32_16x16x32_bf16 v[104:107], v[136:139], v[170:173], v[104:107]
	v_mfma_f32_16x16x32_bf16 v[96:99], v[128:131], v[178:181], v[96:99]
	v_mfma_f32_16x16x32_bf16 v[88:91], v[136:139], v[178:181], v[88:91]
	v_mfma_f32_16x16x32_bf16 v[84:87], v[128:131], v[194:197], v[84:87]
	v_mfma_f32_16x16x32_bf16 v[80:83], v[136:139], v[194:197], v[80:83]
	v_mfma_f32_16x16x32_bf16 v[124:127], v[132:135], v[166:169], v[124:127]
	v_mfma_f32_16x16x32_bf16 v[120:123], v[146:149], v[166:169], v[120:123]
	v_mfma_f32_16x16x32_bf16 v[108:111], v[132:135], v[174:177], v[108:111]
	v_mfma_f32_16x16x32_bf16 v[104:107], v[146:149], v[174:177], v[104:107]
	v_mfma_f32_16x16x32_bf16 v[96:99], v[132:135], v[182:185], v[96:99]
	v_mfma_f32_16x16x32_bf16 v[88:91], v[146:149], v[182:185], v[88:91]
	v_mfma_f32_16x16x32_bf16 v[84:87], v[132:135], v[210:213], v[84:87]
	v_mfma_f32_16x16x32_bf16 v[80:83], v[146:149], v[210:213], v[80:83]
	v_mfma_f32_16x16x32_bf16 v[116:119], v[214:217], v[162:165], v[116:119]
	v_mfma_f32_16x16x32_bf16 v[112:115], v[222:225], v[162:165], v[112:115]
	v_mfma_f32_16x16x32_bf16 v[100:103], v[214:217], v[170:173], v[100:103]
	v_mfma_f32_16x16x32_bf16 v[92:95], v[222:225], v[170:173], v[92:95]
	v_mfma_f32_16x16x32_bf16 v[76:79], v[214:217], v[178:181], v[76:79]
	v_mfma_f32_16x16x32_bf16 v[72:75], v[222:225], v[178:181], v[72:75]
	v_mfma_f32_16x16x32_bf16 v[68:71], v[214:217], v[194:197], v[68:71]
	v_mfma_f32_16x16x32_bf16 v[64:67], v[222:225], v[194:197], v[64:67]
	v_mfma_f32_16x16x32_bf16 v[116:119], v[218:221], v[166:169], v[116:119]
	v_mfma_f32_16x16x32_bf16 v[112:115], v[226:229], v[166:169], v[112:115]
	v_mfma_f32_16x16x32_bf16 v[100:103], v[218:221], v[174:177], v[100:103]
	v_mfma_f32_16x16x32_bf16 v[92:95], v[226:229], v[174:177], v[92:95]
	v_mfma_f32_16x16x32_bf16 v[76:79], v[218:221], v[182:185], v[76:79]
	v_mfma_f32_16x16x32_bf16 v[72:75], v[226:229], v[182:185], v[72:75]
	v_mfma_f32_16x16x32_bf16 v[68:71], v[218:221], v[210:213], v[68:71]
	v_mfma_f32_16x16x32_bf16 v[64:67], v[226:229], v[210:213], v[64:67]
	s_barrier
	s_add_i32 s6, s6, s57
	v_lshl_add_u64 v[230:231], v[230:231], 0, s[36:37]
	s_mov_b32 m0, s6
	s_nop 0
	global_load_lds_dwordx4 v[230:231], off
	v_lshl_add_u64 v[230:231], v[232:233], 0, s[36:37]
	s_add_i32 m0, s6, 0x2000
	s_nop 0
	global_load_lds_dwordx4 v[230:231], off
	s_mov_b32 m0, s72
	v_lshl_add_u64 v[230:231], v[234:235], 0, s[36:37]
	ds_read_b128 v[162:165], v208 offset:49152
	ds_read_b128 v[166:169], v208 offset:50176
	ds_read_b128 v[170:173], v208 offset:51200
	ds_read_b128 v[174:177], v208 offset:52224
	ds_read_b128 v[178:181], v208 offset:53248
	ds_read_b128 v[182:185], v208 offset:54272
	ds_read_b128 v[194:197], v208 offset:55296
	ds_read_b128 v[210:213], v208 offset:56320
	global_load_lds_dwordx4 v[230:231], off
	v_lshl_add_u64 v[230:231], v[236:237], 0, s[36:37]
	s_mov_b32 m0, s73
	s_nop 0
	global_load_lds_dwordx4 v[230:231], off
	s_add_u32 s54, s54, 0x40080
	s_addc_u32 s55, s55, 0
	s_add_i32 s6, s19, s57
	v_lshl_add_u64 v[250:251], s[54:55], 0, v[140:141]
	s_mov_b32 m0, s6
	s_nop 0
	global_load_lds_dwordx4 v[250:251], off
	v_lshl_add_u64 v[250:251], s[54:55], 0, v[150:151]
	s_add_i32 m0, s6, 0x2000
	s_nop 0
	global_load_lds_dwordx4 v[250:251], off
	s_add_i32 s82, s82, 2
	s_add_u32 s52, s52, 0x100
	s_addc_u32 s53, s53, 0
	s_add_u32 s39, s39, 0x100
	s_addc_u32 s51, s51, 0
	s_cmp_gt_u32 s82, 13
	s_waitcnt vmcnt(8)
	s_waitcnt lgkmcnt(0)
	s_barrier
	v_mfma_f32_16x16x32_bf16 v[60:63], v[128:131], v[162:165], v[60:63]
	v_mfma_f32_16x16x32_bf16 v[56:59], v[136:139], v[162:165], v[56:59]
	v_mfma_f32_16x16x32_bf16 v[48:51], v[128:131], v[170:173], v[48:51]
	v_mfma_f32_16x16x32_bf16 v[40:43], v[136:139], v[170:173], v[40:43]
	v_mfma_f32_16x16x32_bf16 v[32:35], v[128:131], v[178:181], v[32:35]
	v_mfma_f32_16x16x32_bf16 v[24:27], v[136:139], v[178:181], v[24:27]
	v_mfma_f32_16x16x32_bf16 v[16:19], v[128:131], v[194:197], v[16:19]
	v_mfma_f32_16x16x32_bf16 v[8:11], v[136:139], v[194:197], v[8:11]
	v_mfma_f32_16x16x32_bf16 v[60:63], v[132:135], v[166:169], v[60:63]
	v_mfma_f32_16x16x32_bf16 v[56:59], v[146:149], v[166:169], v[56:59]
	v_mfma_f32_16x16x32_bf16 v[48:51], v[132:135], v[174:177], v[48:51]
	v_mfma_f32_16x16x32_bf16 v[40:43], v[146:149], v[174:177], v[40:43]
	v_mfma_f32_16x16x32_bf16 v[32:35], v[132:135], v[182:185], v[32:35]
	v_mfma_f32_16x16x32_bf16 v[24:27], v[146:149], v[182:185], v[24:27]
	v_mfma_f32_16x16x32_bf16 v[16:19], v[132:135], v[210:213], v[16:19]
	v_mfma_f32_16x16x32_bf16 v[8:11], v[146:149], v[210:213], v[8:11]
	v_mfma_f32_16x16x32_bf16 v[52:55], v[214:217], v[162:165], v[52:55]
	v_mfma_f32_16x16x32_bf16 v[44:47], v[222:225], v[162:165], v[44:47]
	v_mfma_f32_16x16x32_bf16 v[36:39], v[214:217], v[170:173], v[36:39]
	v_mfma_f32_16x16x32_bf16 v[28:31], v[222:225], v[170:173], v[28:31]
	v_mfma_f32_16x16x32_bf16 v[20:23], v[214:217], v[178:181], v[20:23]
	v_mfma_f32_16x16x32_bf16 v[12:15], v[222:225], v[178:181], v[12:15]
	v_mfma_f32_16x16x32_bf16 v[4:7], v[214:217], v[194:197], v[4:7]
	v_mfma_f32_16x16x32_bf16 v[0:3], v[222:225], v[194:197], v[0:3]
	v_mfma_f32_16x16x32_bf16 v[52:55], v[218:221], v[166:169], v[52:55]
	v_mfma_f32_16x16x32_bf16 v[44:47], v[226:229], v[166:169], v[44:47]
	v_mfma_f32_16x16x32_bf16 v[36:39], v[218:221], v[174:177], v[36:39]
	v_mfma_f32_16x16x32_bf16 v[28:31], v[226:229], v[174:177], v[28:31]
	v_mfma_f32_16x16x32_bf16 v[20:23], v[218:221], v[182:185], v[20:23]
	v_mfma_f32_16x16x32_bf16 v[12:15], v[226:229], v[182:185], v[12:15]
	v_mfma_f32_16x16x32_bf16 v[4:7], v[218:221], v[210:213], v[4:7]
	v_mfma_f32_16x16x32_bf16 v[0:3], v[226:229], v[210:213], v[0:3]
	s_barrier
	s_cbranch_scc0 .LBB0_248
	s_mov_b32 s100, 1
	s_setprio 1
	s_ashr_i32 s51, s50, 31
	v_lshl_or_b32 v128, s81, 8, v207
	s_lshl_b64 s[10:11], s[50:51], 8
	v_ashrrev_i32_e32 v129, 31, v128
	v_lshl_add_u64 v[168:169], s[10:11], 0, v[156:157]
	v_lshlrev_b64 v[170:171], 1, v[128:129]
	v_lshl_add_u64 v[174:175], s[28:29], 0, v[170:171]
	v_lshlrev_b64 v[172:173], 11, v[168:169]
	v_lshl_add_u64 v[128:129], v[174:175], 0, v[172:173]
	global_load_dwordx4 v[146:149], v[128:129], off
	global_load_dwordx4 v[182:185], v[128:129], off offset:256
	v_or_b32_e32 v166, 16, v168
	v_mov_b32_e32 v167, v169
	v_lshlrev_b64 v[176:177], 11, v[166:167]
	v_lshl_add_u64 v[128:129], v[174:175], 0, v[176:177]
	global_load_dwordx4 v[194:197], v[128:129], off
	global_load_dwordx4 v[210:213], v[128:129], off offset:256
	v_or_b32_e32 v164, 32, v168
	v_mov_b32_e32 v165, v169
	v_or_b32_e32 v162, 48, v168
	v_mov_b32_e32 v163, v169
	v_lshlrev_b64 v[180:181], 11, v[164:165]
	v_lshlrev_b64 v[178:179], 11, v[162:163]
	v_lshl_add_u64 v[128:129], v[174:175], 0, v[180:181]
	v_lshl_add_u64 v[130:131], v[174:175], 0, v[178:179]
	global_load_dwordx4 v[214:217], v[128:129], off
	global_load_dwordx4 v[136:139], v[128:129], off offset:256
	global_load_dwordx4 v[132:135], v[130:131], off
	s_nop 0
	global_load_dwordx4 v[128:131], v[130:131], off offset:256
	s_mov_b64 s[10:11], 0x90
	v_lshl_add_u64 v[172:173], s[30:31], 0, v[172:173]
	v_lshl_add_u64 v[172:173], v[172:173], 0, v[170:171]
	s_waitcnt vmcnt(0)
	v_lshlrev_b32_e32 v218, 16, v146
	v_and_b32_e32 v219, 0xffff0000, v146
	v_lshlrev_b32_e32 v220, 16, v148
	v_and_b32_e32 v221, 0xffff0000, v148
	v_lshlrev_b32_e32 v146, 16, v147
	v_and_b32_e32 v147, 0xffff0000, v147
	v_lshlrev_b32_e32 v222, 16, v182
	v_and_b32_e32 v223, 0xffff0000, v182
	v_lshlrev_b32_e32 v224, 16, v184
	v_and_b32_e32 v225, 0xffff0000, v184
	v_lshlrev_b32_e32 v182, 16, v183
	v_and_b32_e32 v183, 0xffff0000, v183
	v_pk_add_f32 v[124:125], v[124:125], v[218:219]
	v_pk_add_f32 v[120:121], v[120:121], v[220:221]
	v_pk_add_f32 v[126:127], v[126:127], v[146:147]
	v_pk_add_f32 v[116:117], v[116:117], v[222:223]
	v_pk_add_f32 v[146:147], v[112:113], v[224:225]
	v_pk_add_f32 v[118:119], v[118:119], v[182:183]
	v_pk_mul_f32 v[220:221], v[124:125], v[124:125]
	v_pk_mul_f32 v[222:223], v[126:127], v[126:127]
	v_cvt_pk_bf16_f32 v112, v124, v125
	v_cvt_pk_bf16_f32 v113, v126, v127
	v_pk_mul_f32 v[124:125], v[116:117], v[116:117]
	v_pk_mul_f32 v[126:127], v[118:119], v[118:119]
	v_pk_mul_f32 v[228:229], v[146:147], v[146:147]
	v_cvt_pk_bf16_f32 v116, v116, v117
	v_cvt_pk_bf16_f32 v117, v118, v119
	v_cvt_pk_bf16_f32 v118, v146, v147
	v_add_f32_e32 v146, v220, v221
	v_add_f32_e32 v146, v222, v146
	v_lshlrev_b32_e32 v148, 16, v149
	v_and_b32_e32 v149, 0xffff0000, v149
	v_pk_mul_f32 v[224:225], v[120:121], v[120:121]
	v_add_f32_e32 v146, v223, v146
	v_pk_add_f32 v[122:123], v[122:123], v[148:149]
	v_add_f32_e32 v146, v224, v146
	v_pk_mul_f32 v[226:227], v[122:123], v[122:123]
	v_add_f32_e32 v146, v225, v146
	v_add_f32_e32 v146, v226, v146
	v_add_f32_e32 v146, v227, v146
	v_add_f32_e32 v124, v124, v146
	v_add_f32_e32 v124, v125, v124
	v_add_f32_e32 v124, v126, v124
	v_lshlrev_b32_e32 v184, 16, v185
	v_and_b32_e32 v185, 0xffff0000, v185
	v_add_f32_e32 v124, v127, v124
	v_pk_add_f32 v[148:149], v[114:115], v[184:185]
	v_add_f32_e32 v124, v228, v124
	v_pk_mul_f32 v[230:231], v[148:149], v[148:149]
	v_add_f32_e32 v124, v229, v124
	v_add_f32_e32 v124, v230, v124
	v_add_f32_e32 v209, v231, v124
	v_lshlrev_b32_e32 v124, 16, v212
	v_and_b32_e32 v125, 0xffff0000, v212
	v_pk_add_f32 v[124:125], v[92:93], v[124:125]
	v_lshlrev_b32_e32 v92, 16, v211
	v_and_b32_e32 v93, 0xffff0000, v211
	v_pk_add_f32 v[102:103], v[102:103], v[92:93]
	v_lshlrev_b32_e32 v92, 16, v213
	v_and_b32_e32 v93, 0xffff0000, v213
	v_pk_add_f32 v[126:127], v[94:95], v[92:93]
	v_lshlrev_b32_e32 v92, 16, v214
	v_and_b32_e32 v93, 0xffff0000, v214
	v_pk_add_f32 v[92:93], v[96:97], v[92:93]
	v_lshlrev_b32_e32 v96, 16, v217
	v_and_b32_e32 v97, 0xffff0000, v217
	v_lshlrev_b32_e32 v94, 16, v216
	v_and_b32_e32 v95, 0xffff0000, v216
	v_pk_add_f32 v[90:91], v[90:91], v[96:97]
	v_lshlrev_b32_e32 v96, 16, v136
	v_and_b32_e32 v97, 0xffff0000, v136
	v_lshlrev_b32_e32 v182, 16, v194
	v_and_b32_e32 v183, 0xffff0000, v194
	v_pk_add_f32 v[88:89], v[88:89], v[94:95]
	v_lshlrev_b32_e32 v94, 16, v215
	v_and_b32_e32 v95, 0xffff0000, v215
	v_pk_add_f32 v[96:97], v[76:77], v[96:97]
	v_lshl_add_u64 v[76:77], v[168:169], 0, s[36:37]
	v_lshlrev_b32_e32 v184, 16, v196
	v_and_b32_e32 v185, 0xffff0000, v196
	v_cvt_pk_bf16_f32 v114, v120, v121
	v_pk_add_f32 v[120:121], v[108:109], v[182:183]
	v_pk_add_f32 v[94:95], v[98:99], v[94:95]
	v_lshlrev_b64 v[182:183], 11, v[76:77]
	v_lshlrev_b32_e32 v98, 16, v138
	v_and_b32_e32 v99, 0xffff0000, v138
	v_pk_add_f32 v[108:109], v[104:105], v[184:185]
	v_lshl_add_u64 v[184:185], v[174:175], 0, v[182:183]
	v_pk_add_f32 v[98:99], v[72:73], v[98:99]
	v_lshlrev_b32_e32 v72, 16, v137
	v_and_b32_e32 v73, 0xffff0000, v137
	v_lshlrev_b32_e32 v218, 16, v210
	v_and_b32_e32 v219, 0xffff0000, v210
	global_load_dwordx4 v[210:213], v[184:185], off
	v_pk_add_f32 v[136:137], v[78:79], v[72:73]
	v_lshlrev_b32_e32 v72, 16, v139
	v_and_b32_e32 v73, 0xffff0000, v139
	v_pk_add_f32 v[138:139], v[74:75], v[72:73]
	v_lshlrev_b32_e32 v72, 16, v132
	v_and_b32_e32 v73, 0xffff0000, v132
	v_pk_add_f32 v[74:75], v[84:85], v[72:73]
	v_lshlrev_b32_e32 v72, 16, v134
	v_and_b32_e32 v73, 0xffff0000, v134
	v_pk_add_f32 v[78:79], v[80:81], v[72:73]
	v_lshlrev_b32_e32 v72, 16, v133
	v_and_b32_e32 v73, 0xffff0000, v133
	v_pk_add_f32 v[100:101], v[100:101], v[218:219]
	global_load_dwordx4 v[218:221], v[184:185], off offset:256
	v_pk_add_f32 v[80:81], v[86:87], v[72:73]
	v_lshlrev_b32_e32 v72, 16, v135
	v_and_b32_e32 v73, 0xffff0000, v135
	v_pk_add_f32 v[82:83], v[82:83], v[72:73]
	v_lshl_add_u64 v[72:73], v[168:169], 0, s[10:11]
	v_lshlrev_b64 v[132:133], 11, v[72:73]
	v_lshl_add_u64 v[134:135], v[174:175], 0, v[132:133]
	v_lshlrev_b32_e32 v84, 16, v128
	v_and_b32_e32 v85, 0xffff0000, v128
	global_load_dwordx4 v[226:229], v[134:135], off
	global_load_dwordx4 v[234:237], v[134:135], off offset:256
	v_pk_add_f32 v[84:85], v[68:69], v[84:85]
	v_lshlrev_b32_e32 v68, 16, v130
	v_and_b32_e32 v69, 0xffff0000, v130
	v_pk_add_f32 v[86:87], v[64:65], v[68:69]
	v_lshlrev_b32_e32 v64, 16, v129
	v_and_b32_e32 v65, 0xffff0000, v129
	s_mov_b64 s[10:11], 0xa0
	v_pk_add_f32 v[128:129], v[70:71], v[64:65]
	v_lshl_add_u64 v[70:71], v[168:169], 0, s[10:11]
	s_mov_b64 s[10:11], 0xb0
	v_lshlrev_b32_e32 v64, 16, v131
	v_and_b32_e32 v65, 0xffff0000, v131
	v_lshlrev_b64 v[134:135], 11, v[70:71]
	v_lshl_add_u64 v[68:69], v[168:169], 0, s[10:11]
	v_pk_add_f32 v[130:131], v[66:67], v[64:65]
	v_lshl_add_u64 v[64:65], v[174:175], 0, v[134:135]
	v_lshlrev_b64 v[184:185], 11, v[68:69]
	global_load_dwordx4 v[238:241], v[64:65], off
	global_load_dwordx4 v[242:245], v[64:65], off offset:256
	v_lshl_add_u64 v[64:65], v[174:175], 0, v[184:185]
	global_load_dwordx4 v[246:249], v[64:65], off
	s_nop 0
	global_load_dwordx4 v[64:67], v[64:65], off offset:256
	v_lshlrev_b32_e32 v194, 16, v195
	v_and_b32_e32 v195, 0xffff0000, v195
	v_lshlrev_b32_e32 v196, 16, v197
	v_and_b32_e32 v197, 0xffff0000, v197
	v_cvt_pk_bf16_f32 v115, v122, v123
	v_cvt_pk_bf16_f32 v119, v148, v149
	v_pk_add_f32 v[122:123], v[110:111], v[194:195]
	v_pk_add_f32 v[110:111], v[106:107], v[196:197]
	global_store_dwordx4 v[172:173], v[112:115], off
	global_store_dwordx4 v[172:173], v[116:119], off offset:256
	v_cvt_pk_bf16_f32 v104, v120, v121
	v_lshl_add_u64 v[112:113], s[30:31], 0, v[176:177]
	v_cvt_pk_bf16_f32 v105, v122, v123
	v_cvt_pk_bf16_f32 v106, v108, v109
	v_cvt_pk_bf16_f32 v107, v110, v111
	v_lshl_add_u64 v[112:113], v[112:113], 0, v[170:171]
	v_cvt_pk_bf16_f32 v146, v100, v101
	v_cvt_pk_bf16_f32 v147, v102, v103
	v_cvt_pk_bf16_f32 v148, v124, v125
	v_cvt_pk_bf16_f32 v149, v126, v127
	global_store_dwordx4 v[112:113], v[104:107], off
	global_store_dwordx4 v[112:113], v[146:149], off offset:256
	v_cvt_pk_bf16_f32 v194, v92, v93
	v_lshl_add_u64 v[104:105], s[30:31], 0, v[180:181]
	v_cvt_pk_bf16_f32 v195, v94, v95
	v_cvt_pk_bf16_f32 v196, v88, v89
	v_cvt_pk_bf16_f32 v197, v90, v91
	v_lshl_add_u64 v[104:105], v[104:105], 0, v[170:171]
	v_cvt_pk_bf16_f32 v214, v96, v97
	v_cvt_pk_bf16_f32 v215, v136, v137
	v_cvt_pk_bf16_f32 v216, v98, v99
	v_cvt_pk_bf16_f32 v217, v138, v139
	global_store_dwordx4 v[104:105], v[194:197], off
	global_store_dwordx4 v[104:105], v[214:217], off offset:256
	v_lshl_add_u64 v[104:105], s[30:31], 0, v[178:179]
	v_cvt_pk_bf16_f32 v222, v74, v75
	v_cvt_pk_bf16_f32 v223, v80, v81
	v_cvt_pk_bf16_f32 v224, v78, v79
	v_cvt_pk_bf16_f32 v225, v82, v83
	v_lshl_add_u64 v[104:105], v[104:105], 0, v[170:171]
	v_cvt_pk_bf16_f32 v230, v84, v85
	v_cvt_pk_bf16_f32 v231, v128, v129
	v_cvt_pk_bf16_f32 v232, v86, v87
	v_cvt_pk_bf16_f32 v233, v130, v131
	global_store_dwordx4 v[104:105], v[222:225], off
	global_store_dwordx4 v[104:105], v[230:233], off offset:256
	s_waitcnt vmcnt(8)
	v_lshlrev_b32_e32 v104, 16, v210
	v_and_b32_e32 v105, 0xffff0000, v210
	v_pk_add_f32 v[60:61], v[60:61], v[104:105]
	v_lshlrev_b32_e32 v104, 16, v212
	v_and_b32_e32 v105, 0xffff0000, v212
	v_pk_add_f32 v[56:57], v[56:57], v[104:105]
	v_lshlrev_b32_e32 v104, 16, v211
	v_and_b32_e32 v105, 0xffff0000, v211
	v_pk_add_f32 v[62:63], v[62:63], v[104:105]
	v_lshlrev_b32_e32 v104, 16, v213
	v_and_b32_e32 v105, 0xffff0000, v213
	v_pk_add_f32 v[58:59], v[58:59], v[104:105]
	v_lshlrev_b32_e32 v104, 16, v218
	v_and_b32_e32 v105, 0xffff0000, v218
	v_pk_add_f32 v[52:53], v[52:53], v[104:105]
	v_lshlrev_b32_e32 v104, 16, v220
	v_and_b32_e32 v105, 0xffff0000, v220
	v_pk_add_f32 v[104:105], v[44:45], v[104:105]
	v_lshlrev_b32_e32 v44, 16, v219
	v_and_b32_e32 v45, 0xffff0000, v219
	v_pk_add_f32 v[54:55], v[54:55], v[44:45]
	v_lshlrev_b32_e32 v44, 16, v221
	v_and_b32_e32 v45, 0xffff0000, v221
	v_pk_add_f32 v[106:107], v[46:47], v[44:45]
	v_lshlrev_b32_e32 v44, 16, v226
	v_and_b32_e32 v45, 0xffff0000, v226
	v_pk_add_f32 v[44:45], v[48:49], v[44:45]
	v_lshlrev_b32_e32 v48, 16, v229
	v_and_b32_e32 v49, 0xffff0000, v229
	v_pk_add_f32 v[42:43], v[42:43], v[48:49]
	v_lshlrev_b32_e32 v48, 16, v234
	v_and_b32_e32 v49, 0xffff0000, v234
	v_pk_add_f32 v[36:37], v[36:37], v[48:49]
	v_lshlrev_b32_e32 v48, 16, v236
	v_and_b32_e32 v49, 0xffff0000, v236
	v_lshlrev_b32_e32 v46, 16, v228
	v_and_b32_e32 v47, 0xffff0000, v228
	v_pk_add_f32 v[48:49], v[28:29], v[48:49]
	v_lshlrev_b32_e32 v28, 16, v235
	v_and_b32_e32 v29, 0xffff0000, v235
	v_pk_add_f32 v[40:41], v[40:41], v[46:47]
	v_lshlrev_b32_e32 v46, 16, v227
	v_and_b32_e32 v47, 0xffff0000, v227
	v_pk_add_f32 v[38:39], v[38:39], v[28:29]
	v_lshlrev_b32_e32 v28, 16, v237
	v_and_b32_e32 v29, 0xffff0000, v237
	v_pk_add_f32 v[46:47], v[50:51], v[46:47]
	v_pk_add_f32 v[50:51], v[30:31], v[28:29]
	v_lshlrev_b32_e32 v28, 16, v238
	v_and_b32_e32 v29, 0xffff0000, v238
	v_lshlrev_b32_e32 v180, 16, v64
	v_and_b32_e32 v181, 0xffff0000, v64
	v_pk_add_f32 v[28:29], v[32:33], v[28:29]
	v_lshlrev_b32_e32 v32, 16, v241
	v_and_b32_e32 v33, 0xffff0000, v241
	v_pk_add_f32 v[4:5], v[4:5], v[180:181]
	v_lshlrev_b32_e32 v180, 16, v66
	v_and_b32_e32 v181, 0xffff0000, v66
	v_pk_add_f32 v[26:27], v[26:27], v[32:33]
	v_lshlrev_b32_e32 v32, 16, v242
	v_and_b32_e32 v33, 0xffff0000, v242
	v_pk_add_f32 v[0:1], v[0:1], v[180:181]
	v_lshl_add_u64 v[180:181], s[30:31], 0, v[182:183]
	v_cvt_pk_bf16_f32 v112, v60, v61
	v_cvt_pk_bf16_f32 v113, v62, v63
	v_cvt_pk_bf16_f32 v114, v56, v57
	v_cvt_pk_bf16_f32 v115, v58, v59
	v_pk_add_f32 v[20:21], v[20:21], v[32:33]
	v_lshlrev_b32_e32 v32, 16, v244
	v_and_b32_e32 v33, 0xffff0000, v244
	v_lshl_add_u64 v[180:181], v[180:181], 0, v[170:171]
	v_cvt_pk_bf16_f32 v116, v52, v53
	v_cvt_pk_bf16_f32 v117, v54, v55
	v_cvt_pk_bf16_f32 v118, v104, v105
	v_cvt_pk_bf16_f32 v119, v106, v107
	v_lshlrev_b32_e32 v30, 16, v240
	v_and_b32_e32 v31, 0xffff0000, v240
	v_pk_add_f32 v[32:33], v[12:13], v[32:33]
	v_lshlrev_b32_e32 v12, 16, v243
	v_and_b32_e32 v13, 0xffff0000, v243
	global_store_dwordx4 v[180:181], v[112:115], off
	global_store_dwordx4 v[180:181], v[116:119], off offset:256
	v_cvt_pk_bf16_f32 v146, v44, v45
	v_lshl_add_u64 v[112:113], s[30:31], 0, v[132:133]
	v_cvt_pk_bf16_f32 v147, v46, v47
	v_cvt_pk_bf16_f32 v148, v40, v41
	v_cvt_pk_bf16_f32 v149, v42, v43
	v_pk_add_f32 v[24:25], v[24:25], v[30:31]
	v_lshlrev_b32_e32 v30, 16, v239
	v_and_b32_e32 v31, 0xffff0000, v239
	v_pk_add_f32 v[22:23], v[22:23], v[12:13]
	v_lshlrev_b32_e32 v12, 16, v245
	v_and_b32_e32 v13, 0xffff0000, v245
	v_lshl_add_u64 v[112:113], v[112:113], 0, v[170:171]
	v_cvt_pk_bf16_f32 v172, v36, v37
	v_cvt_pk_bf16_f32 v173, v38, v39
	v_cvt_pk_bf16_f32 v174, v48, v49
	v_cvt_pk_bf16_f32 v175, v50, v51
	v_pk_add_f32 v[30:31], v[34:35], v[30:31]
	v_pk_add_f32 v[34:35], v[14:15], v[12:13]
	v_lshlrev_b32_e32 v12, 16, v246
	v_and_b32_e32 v13, 0xffff0000, v246
	v_lshlrev_b32_e32 v14, 16, v248
	v_and_b32_e32 v15, 0xffff0000, v248
	global_store_dwordx4 v[112:113], v[146:149], off
	global_store_dwordx4 v[112:113], v[172:175], off offset:256
	v_lshl_add_u64 v[112:113], s[30:31], 0, v[134:135]
	v_cvt_pk_bf16_f32 v176, v28, v29
	v_cvt_pk_bf16_f32 v177, v30, v31
	v_cvt_pk_bf16_f32 v178, v24, v25
	v_cvt_pk_bf16_f32 v179, v26, v27
	v_pk_add_f32 v[12:13], v[16:17], v[12:13]
	v_pk_add_f32 v[8:9], v[8:9], v[14:15]
	v_lshlrev_b32_e32 v14, 16, v247
	v_and_b32_e32 v15, 0xffff0000, v247
	v_lshlrev_b32_e32 v16, 16, v249
	v_and_b32_e32 v17, 0xffff0000, v249
	v_lshlrev_b32_e32 v64, 16, v65
	v_and_b32_e32 v65, 0xffff0000, v65
	v_lshl_add_u64 v[112:113], v[112:113], 0, v[170:171]
	v_cvt_pk_bf16_f32 v194, v20, v21
	v_cvt_pk_bf16_f32 v195, v22, v23
	v_cvt_pk_bf16_f32 v196, v32, v33
	v_cvt_pk_bf16_f32 v197, v34, v35
	v_pk_add_f32 v[14:15], v[18:19], v[14:15]
	v_pk_add_f32 v[10:11], v[10:11], v[16:17]
	v_pk_add_f32 v[6:7], v[6:7], v[64:65]
	v_lshlrev_b32_e32 v64, 16, v67
	v_and_b32_e32 v65, 0xffff0000, v67
	global_store_dwordx4 v[112:113], v[176:179], off
	global_store_dwordx4 v[112:113], v[194:197], off offset:256
	v_lshl_add_u64 v[112:113], s[30:31], 0, v[184:185]
	v_cvt_pk_bf16_f32 v16, v12, v13
	v_cvt_pk_bf16_f32 v17, v14, v15
	v_cvt_pk_bf16_f32 v18, v8, v9
	v_cvt_pk_bf16_f32 v19, v10, v11
	v_pk_add_f32 v[2:3], v[2:3], v[64:65]
	v_lshl_add_u64 v[112:113], v[112:113], 0, v[170:171]
	v_cvt_pk_bf16_f32 v64, v4, v5
	v_cvt_pk_bf16_f32 v65, v6, v7
	v_cvt_pk_bf16_f32 v66, v0, v1
	v_cvt_pk_bf16_f32 v67, v2, v3
	global_store_dwordx4 v[112:113], v[16:19], off
	global_store_dwordx4 v[112:113], v[64:67], off offset:256
	s_lshl_b32 s10, s81, 2
	v_and_b32_e32 v17, 64, v188
	v_xor_b32_e32 v16, 16, v188
	v_add_u32_e32 v17, 64, v17
	v_cmp_lt_i32_e32 vcc, v16, v17
	v_xor_b32_e32 v18, 32, v188
	s_ashr_i32 s11, s10, 31
	v_cndmask_b32_e32 v16, v188, v16, vcc
	v_lshlrev_b32_e32 v16, 2, v16
	v_mov_b32_e32 v132, v209
	v_cmp_lt_i32_e32 vcc, v18, v17
	s_lshl_b64 s[10:11], s[10:11], 2
	s_add_u32 s50, s75, s10
	v_cndmask_b32_e32 v17, v188, v18, vcc
	v_lshlrev_b32_e32 v17, 2, v17
	s_addc_u32 s51, s80, s11
	v_pk_mul_f32 v[18:19], v[120:121], v[120:121]
	v_pk_mul_f32 v[64:65], v[122:123], v[122:123]
	v_add_f32_e32 v18, v18, v19
	v_add_f32_e32 v18, v64, v18
	v_pk_mul_f32 v[66:67], v[108:109], v[108:109]
	v_add_f32_e32 v18, v65, v18
	v_add_f32_e32 v18, v66, v18
	v_pk_mul_f32 v[108:109], v[110:111], v[110:111]
	v_add_f32_e32 v18, v67, v18
	v_add_f32_e32 v18, v108, v18
	v_pk_mul_f32 v[100:101], v[100:101], v[100:101]
	v_add_f32_e32 v18, v109, v18
	v_add_f32_e32 v18, v100, v18
	v_pk_mul_f32 v[102:103], v[102:103], v[102:103]
	v_add_f32_e32 v18, v101, v18
	v_add_f32_e32 v18, v102, v18
	v_pk_mul_f32 v[110:111], v[124:125], v[124:125]
	v_add_f32_e32 v18, v103, v18
	v_add_f32_e32 v18, v110, v18
	v_pk_mul_f32 v[112:113], v[126:127], v[126:127]
	v_add_f32_e32 v18, v111, v18
	v_add_f32_e32 v18, v112, v18
	v_add_f32_e32 v18, v113, v18
	v_mov_b32_e32 v133, v18
	v_pk_mul_f32 v[18:19], v[92:93], v[92:93]
	v_pk_mul_f32 v[64:65], v[94:95], v[94:95]
	v_add_f32_e32 v18, v18, v19
	v_add_f32_e32 v18, v64, v18
	v_pk_mul_f32 v[66:67], v[88:89], v[88:89]
	v_add_f32_e32 v18, v65, v18
	v_add_f32_e32 v18, v66, v18
	v_pk_mul_f32 v[88:89], v[90:91], v[90:91]
	v_add_f32_e32 v18, v67, v18
	v_add_f32_e32 v18, v88, v18
	v_pk_mul_f32 v[90:91], v[96:97], v[96:97]
	v_add_f32_e32 v18, v89, v18
	v_add_f32_e32 v18, v90, v18
	v_pk_mul_f32 v[92:93], v[136:137], v[136:137]
	v_add_f32_e32 v18, v91, v18
	v_add_f32_e32 v18, v92, v18
	v_pk_mul_f32 v[94:95], v[98:99], v[98:99]
	v_add_f32_e32 v18, v93, v18
	v_add_f32_e32 v18, v94, v18
	v_pk_mul_f32 v[96:97], v[138:139], v[138:139]
	v_add_f32_e32 v18, v95, v18
	v_add_f32_e32 v18, v96, v18
	v_add_f32_e32 v18, v97, v18
	v_mov_b32_e32 v134, v18
	v_pk_mul_f32 v[18:19], v[74:75], v[74:75]
	v_pk_mul_f32 v[210:211], v[60:61], v[60:61]
	v_pk_mul_f32 v[64:65], v[80:81], v[80:81]
	v_pk_mul_f32 v[60:61], v[62:63], v[62:63]
	v_add_f32_e32 v18, v18, v19
	v_add_f32_e32 v210, v210, v211
	v_add_f32_e32 v18, v64, v18
	v_add_f32_e32 v210, v60, v210
	v_pk_mul_f32 v[66:67], v[78:79], v[78:79]
	v_pk_mul_f32 v[56:57], v[56:57], v[56:57]
	v_add_f32_e32 v18, v65, v18
	v_add_f32_e32 v210, v61, v210
	v_add_f32_e32 v18, v66, v18
	v_add_f32_e32 v210, v56, v210
	v_pk_mul_f32 v[74:75], v[82:83], v[82:83]
	v_pk_mul_f32 v[58:59], v[58:59], v[58:59]
	v_add_f32_e32 v18, v67, v18
	v_add_f32_e32 v210, v57, v210
	v_add_f32_e32 v18, v74, v18
	v_add_f32_e32 v210, v58, v210
	v_pk_mul_f32 v[78:79], v[84:85], v[84:85]
	v_pk_mul_f32 v[52:53], v[52:53], v[52:53]
	v_add_f32_e32 v18, v75, v18
	v_add_f32_e32 v210, v59, v210
	v_add_f32_e32 v18, v78, v18
	v_add_f32_e32 v210, v52, v210
	v_pk_mul_f32 v[80:81], v[128:129], v[128:129]
	v_pk_mul_f32 v[54:55], v[54:55], v[54:55]
	v_add_f32_e32 v18, v79, v18
	v_add_f32_e32 v210, v53, v210
	v_add_f32_e32 v18, v80, v18
	v_add_f32_e32 v210, v54, v210
	v_pk_mul_f32 v[82:83], v[86:87], v[86:87]
	v_pk_mul_f32 v[62:63], v[104:105], v[104:105]
	v_add_f32_e32 v18, v81, v18
	v_add_f32_e32 v210, v55, v210
	v_add_f32_e32 v18, v82, v18
	v_add_f32_e32 v210, v62, v210
	v_pk_mul_f32 v[84:85], v[130:131], v[130:131]
	v_pk_mul_f32 v[212:213], v[106:107], v[106:107]
	v_add_f32_e32 v18, v83, v18
	v_add_f32_e32 v210, v63, v210
	v_add_f32_e32 v18, v84, v18
	v_add_f32_e32 v210, v212, v210
	v_add_f32_e32 v18, v85, v18
	v_add_f32_e32 v210, v213, v210
	v_mov_b32_e32 v135, v18
	v_mov_b32_e32 v146, v210
	v_pk_mul_f32 v[18:19], v[44:45], v[44:45]
	v_pk_mul_f32 v[210:211], v[28:29], v[28:29]
	v_pk_mul_f32 v[44:45], v[46:47], v[46:47]
	v_pk_mul_f32 v[28:29], v[30:31], v[30:31]
	v_add_f32_e32 v18, v18, v19
	v_add_f32_e32 v210, v210, v211
	v_add_f32_e32 v18, v44, v18
	v_add_f32_e32 v210, v28, v210
	v_pk_mul_f32 v[40:41], v[40:41], v[40:41]
	v_pk_mul_f32 v[24:25], v[24:25], v[24:25]
	v_add_f32_e32 v18, v45, v18
	v_add_f32_e32 v210, v29, v210
	v_add_f32_e32 v18, v40, v18
	v_add_f32_e32 v210, v24, v210
	v_pk_mul_f32 v[42:43], v[42:43], v[42:43]
	v_pk_mul_f32 v[26:27], v[26:27], v[26:27]
	v_add_f32_e32 v18, v41, v18
	v_add_f32_e32 v210, v25, v210
	v_add_f32_e32 v18, v42, v18
	v_add_f32_e32 v210, v26, v210
	v_pk_mul_f32 v[36:37], v[36:37], v[36:37]
	v_pk_mul_f32 v[20:21], v[20:21], v[20:21]
	v_add_f32_e32 v18, v43, v18
	v_add_f32_e32 v210, v27, v210
	v_add_f32_e32 v18, v36, v18
	v_add_f32_e32 v210, v20, v210
	v_pk_mul_f32 v[38:39], v[38:39], v[38:39]
	v_pk_mul_f32 v[22:23], v[22:23], v[22:23]
	v_add_f32_e32 v18, v37, v18
	v_add_f32_e32 v210, v21, v210
	v_add_f32_e32 v18, v38, v18
	v_add_f32_e32 v210, v22, v210
	v_pk_mul_f32 v[46:47], v[48:49], v[48:49]
	v_pk_mul_f32 v[30:31], v[32:33], v[32:33]
	v_add_f32_e32 v18, v39, v18
	v_add_f32_e32 v210, v23, v210
	v_add_f32_e32 v18, v46, v18
	v_add_f32_e32 v210, v30, v210
	v_pk_mul_f32 v[48:49], v[50:51], v[50:51]
	v_pk_mul_f32 v[32:33], v[34:35], v[34:35]
	v_add_f32_e32 v18, v47, v18
	v_add_f32_e32 v210, v31, v210
	v_add_f32_e32 v18, v48, v18
	v_add_f32_e32 v210, v32, v210
	v_add_f32_e32 v18, v49, v18
	v_add_f32_e32 v210, v33, v210
	v_mov_b32_e32 v147, v18
	v_mov_b32_e32 v148, v210
	v_pk_mul_f32 v[12:13], v[12:13], v[12:13]
	v_pk_mul_f32 v[14:15], v[14:15], v[14:15]
	v_add_f32_e32 v12, v12, v13
	v_add_f32_e32 v12, v14, v12
	v_pk_mul_f32 v[8:9], v[8:9], v[8:9]
	v_add_f32_e32 v12, v15, v12
	v_add_f32_e32 v8, v8, v12
	v_pk_mul_f32 v[10:11], v[10:11], v[10:11]
	v_add_f32_e32 v8, v9, v8
	v_add_f32_e32 v8, v10, v8
	v_pk_mul_f32 v[4:5], v[4:5], v[4:5]
	v_add_f32_e32 v8, v11, v8
	v_add_f32_e32 v4, v4, v8
	v_pk_mul_f32 v[6:7], v[6:7], v[6:7]
	v_add_f32_e32 v4, v5, v4
	v_add_f32_e32 v4, v6, v4
	v_pk_mul_f32 v[0:1], v[0:1], v[0:1]
	v_add_f32_e32 v4, v7, v4
	v_add_f32_e32 v0, v0, v4
	v_pk_mul_f32 v[2:3], v[2:3], v[2:3]
	v_add_f32_e32 v0, v1, v0
	v_add_f32_e32 v0, v2, v0
	v_add_f32_e32 v0, v3, v0
	v_mov_b32_e32 v149, v0
	ds_bpermute_b32 v172, v16, v132
	ds_bpermute_b32 v173, v16, v133
	ds_bpermute_b32 v174, v16, v134
	ds_bpermute_b32 v175, v16, v135
	ds_bpermute_b32 v180, v16, v146
	ds_bpermute_b32 v181, v16, v147
	ds_bpermute_b32 v182, v16, v148
	ds_bpermute_b32 v183, v16, v149
	s_waitcnt lgkmcnt(0)
	v_add_f32_e32 v132, v132, v172
	v_add_f32_e32 v133, v133, v173
	v_add_f32_e32 v134, v134, v174
	v_add_f32_e32 v135, v135, v175
	v_add_f32_e32 v146, v146, v180
	v_add_f32_e32 v147, v147, v181
	v_add_f32_e32 v148, v148, v182
	v_add_f32_e32 v149, v149, v183
	ds_bpermute_b32 v172, v17, v132
	ds_bpermute_b32 v173, v17, v133
	ds_bpermute_b32 v174, v17, v134
	ds_bpermute_b32 v175, v17, v135
	ds_bpermute_b32 v180, v17, v146
	ds_bpermute_b32 v181, v17, v147
	ds_bpermute_b32 v182, v17, v148
	ds_bpermute_b32 v183, v17, v149
	s_and_saveexec_b64 s[52:53], s[42:43]
	s_cbranch_execz .LBB0_240
	s_waitcnt lgkmcnt(0)
	v_add_f32_e32 v132, v132, v172
	v_lshlrev_b64 v[18:19], 6, v[168:169]
	v_lshl_add_u64 v[18:19], s[50:51], 0, v[18:19]
	global_store_dword v[18:19], v132, off
	v_add_f32_e32 v133, v133, v173
	v_lshlrev_b64 v[18:19], 6, v[166:167]
	v_lshl_add_u64 v[18:19], s[50:51], 0, v[18:19]
	global_store_dword v[18:19], v133, off
	v_add_f32_e32 v134, v134, v174
	v_lshlrev_b64 v[18:19], 6, v[164:165]
	v_lshl_add_u64 v[18:19], s[50:51], 0, v[18:19]
	global_store_dword v[18:19], v134, off
	v_add_f32_e32 v135, v135, v175
	v_lshlrev_b64 v[18:19], 6, v[162:163]
	v_lshl_add_u64 v[18:19], s[50:51], 0, v[18:19]
	global_store_dword v[18:19], v135, off
	v_add_f32_e32 v146, v146, v180
	v_lshlrev_b64 v[18:19], 6, v[76:77]
	v_lshl_add_u64 v[18:19], s[50:51], 0, v[18:19]
	global_store_dword v[18:19], v146, off
	v_add_f32_e32 v147, v147, v181
	v_lshlrev_b64 v[18:19], 6, v[72:73]
	v_lshl_add_u64 v[18:19], s[50:51], 0, v[18:19]
	global_store_dword v[18:19], v147, off
	v_add_f32_e32 v148, v148, v182
	v_lshlrev_b64 v[18:19], 6, v[70:71]
	v_lshl_add_u64 v[18:19], s[50:51], 0, v[18:19]
	global_store_dword v[18:19], v148, off
	v_add_f32_e32 v149, v149, v183
	v_lshlrev_b64 v[18:19], 6, v[68:69]
	v_lshl_add_u64 v[18:19], s[50:51], 0, v[18:19]
	global_store_dword v[18:19], v149, off
	s_branch .LBB0_240

.LBB0_294:
	s_add_u32 s10, s48, 0x100
	s_addc_u32 s11, s49, 0
	s_ashr_i32 s31, s30, 31
	s_lshl_b64 s[38:39], s[30:31], 19
	s_add_u32 s46, s33, s38
	s_addc_u32 s47, s41, s39
	s_and_b64 s[38:39], s[44:45], exec
	s_cselect_b32 s12, s47, s5
	s_cselect_b32 s29, s46, s4
	s_ashr_i32 s35, s34, 31
	s_lshl_b64 s[38:39], s[34:35], 19
	s_add_u32 s38, s54, s38
	s_addc_u32 s39, s55, s39
	s_and_b64 s[50:51], s[44:45], exec
	s_cselect_b32 s31, s39, s49
	s_cselect_b32 s35, s38, s48
	s_add_u32 s48, s4, 0x40080
	s_addc_u32 s49, s5, 0
	v_lshl_add_u64 v[150:151], s[48:49], 0, v[136:137]
	v_lshl_add_u64 v[152:153], s[48:49], 0, v[138:139]
	s_mov_b32 s75, -2
	s_mov_b64 s[48:49], 0
	s_add_u32 s6, s4, s48
	s_addc_u32 s19, s5, s49
	s_add_u32 s6, s6, 0x100
	s_addc_u32 s19, s19, 0
	s_add_u32 s23, s10, s48
	s_addc_u32 s50, s11, s49
	s_add_i32 s80, 0, 0x10000
	v_add_u32_e32 v166, s80, v154
	ds_read_b128 v[146:149], v166
	ds_read_b128 v[158:161], v166 offset:1024
	ds_read_b128 v[162:165], v166 offset:2048
	ds_read_b128 v[166:169], v166 offset:3072
	s_cmpk_eq_i32 s48, 0x700
	s_cselect_b32 s53, s12, s19
	s_cselect_b32 s52, s29, s6
	s_cselect_b32 s51, s31, s50
	s_cselect_b32 s50, s35, s23
	v_lshl_add_u64 v[218:219], v[150:151], 0, s[48:49]
	s_add_i32 m0, s58, 0xc000
	ds_read_b128 v[170:173], v157
	ds_read_b128 v[174:177], v157 offset:1024
	ds_read_b128 v[178:181], v157 offset:2048
	ds_read_b128 v[182:185], v157 offset:3072
	ds_read_b128 v[194:197], v157 offset:4096
	ds_read_b128 v[206:209], v157 offset:5120
	ds_read_b128 v[210:213], v157 offset:6144
	ds_read_b128 v[214:217], v157 offset:7168
	global_load_lds_dwordx4 v[218:219], off
	v_lshl_add_u64 v[218:219], v[152:153], 0, s[48:49]
	s_add_i32 m0, s58, 0xe000
	s_nop 0
	global_load_lds_dwordx4 v[218:219], off
	s_add_i32 s6, 0, 0x14000
	v_add_u32_e32 v192, s6, v154
	ds_read_b128 v[218:221], v192
	ds_read_b128 v[222:225], v192 offset:1024
	ds_read_b128 v[226:229], v192 offset:2048
	ds_read_b128 v[230:233], v192 offset:3072
	s_setprio 0
	s_waitcnt vmcnt(24)
	s_cmp_lg_u32 s100, 0
	s_cbranch_scc1 .Lm4ap_295
	s_waitcnt vmcnt(8)

.LBB0_295:
	s_add_u32 s6, s4, s48
	s_addc_u32 s19, s5, s49
	s_add_u32 s6, s6, 0x100
	s_addc_u32 s19, s19, 0
	s_add_u32 s23, s10, s48
	s_addc_u32 s50, s11, s49
	s_add_i32 s80, 0, 0x10000
	v_add_u32_e32 v166, s80, v154
	ds_read_b128 v[146:149], v166
	ds_read_b128 v[158:161], v166 offset:1024
	ds_read_b128 v[162:165], v166 offset:2048
	ds_read_b128 v[166:169], v166 offset:3072
	s_cmpk_eq_i32 s48, 0x700
	s_cselect_b32 s53, s12, s19
	s_cselect_b32 s52, s29, s6
	s_cselect_b32 s51, s31, s50
	s_cselect_b32 s50, s35, s23
	v_lshl_add_u64 v[218:219], v[150:151], 0, s[48:49]
	s_add_i32 m0, s58, 0xc000
	ds_read_b128 v[170:173], v157
	ds_read_b128 v[174:177], v157 offset:1024
	ds_read_b128 v[178:181], v157 offset:2048
	ds_read_b128 v[182:185], v157 offset:3072
	ds_read_b128 v[194:197], v157 offset:4096
	ds_read_b128 v[206:209], v157 offset:5120
	ds_read_b128 v[210:213], v157 offset:6144
	ds_read_b128 v[214:217], v157 offset:7168
	global_load_lds_dwordx4 v[218:219], off
	v_lshl_add_u64 v[218:219], v[152:153], 0, s[48:49]
	s_add_i32 m0, s58, 0xe000
	s_nop 0
	global_load_lds_dwordx4 v[218:219], off
	s_add_i32 s6, 0, 0x14000
	v_add_u32_e32 v192, s6, v154
	ds_read_b128 v[218:221], v192
	ds_read_b128 v[222:225], v192 offset:1024
	ds_read_b128 v[226:229], v192 offset:2048
	ds_read_b128 v[230:233], v192 offset:3072
	s_nop 0
	s_waitcnt vmcnt(8)
	s_waitcnt lgkmcnt(0)
	s_barrier
	v_mfma_f32_16x16x32_bf16 v[124:127], v[146:149], v[170:173], v[124:127]
	v_mfma_f32_16x16x32_bf16 v[120:123], v[162:165], v[170:173], v[120:123]
	v_mfma_f32_16x16x32_bf16 v[116:119], v[146:149], v[178:181], v[116:119]
	v_mfma_f32_16x16x32_bf16 v[112:115], v[162:165], v[178:181], v[112:115]
	v_mfma_f32_16x16x32_bf16 v[108:111], v[146:149], v[194:197], v[108:111]
	v_mfma_f32_16x16x32_bf16 v[104:107], v[162:165], v[194:197], v[104:107]
	v_mfma_f32_16x16x32_bf16 v[100:103], v[146:149], v[210:213], v[100:103]
	v_mfma_f32_16x16x32_bf16 v[96:99], v[162:165], v[210:213], v[96:99]
	v_mfma_f32_16x16x32_bf16 v[124:127], v[158:161], v[174:177], v[124:127]
	v_mfma_f32_16x16x32_bf16 v[120:123], v[166:169], v[174:177], v[120:123]
	v_mfma_f32_16x16x32_bf16 v[116:119], v[158:161], v[182:185], v[116:119]
	v_mfma_f32_16x16x32_bf16 v[112:115], v[166:169], v[182:185], v[112:115]
	v_mfma_f32_16x16x32_bf16 v[108:111], v[158:161], v[206:209], v[108:111]
	v_mfma_f32_16x16x32_bf16 v[104:107], v[166:169], v[206:209], v[104:107]
	v_mfma_f32_16x16x32_bf16 v[100:103], v[158:161], v[214:217], v[100:103]
	v_mfma_f32_16x16x32_bf16 v[96:99], v[166:169], v[214:217], v[96:99]
	v_mfma_f32_16x16x32_bf16 v[92:95], v[218:221], v[170:173], v[92:95]
	v_mfma_f32_16x16x32_bf16 v[88:91], v[226:229], v[170:173], v[88:91]
	v_mfma_f32_16x16x32_bf16 v[84:87], v[218:221], v[178:181], v[84:87]
	v_mfma_f32_16x16x32_bf16 v[80:83], v[226:229], v[178:181], v[80:83]
	v_mfma_f32_16x16x32_bf16 v[76:79], v[218:221], v[194:197], v[76:79]
	v_mfma_f32_16x16x32_bf16 v[72:75], v[226:229], v[194:197], v[72:75]
	v_mfma_f32_16x16x32_bf16 v[68:71], v[218:221], v[210:213], v[68:71]
	v_mfma_f32_16x16x32_bf16 v[64:67], v[226:229], v[210:213], v[64:67]
	v_mfma_f32_16x16x32_bf16 v[92:95], v[222:225], v[174:177], v[92:95]
	v_mfma_f32_16x16x32_bf16 v[88:91], v[230:233], v[174:177], v[88:91]
	v_mfma_f32_16x16x32_bf16 v[84:87], v[222:225], v[182:185], v[84:87]
	v_mfma_f32_16x16x32_bf16 v[80:83], v[230:233], v[182:185], v[80:83]
	v_mfma_f32_16x16x32_bf16 v[76:79], v[222:225], v[206:209], v[76:79]
	v_mfma_f32_16x16x32_bf16 v[72:75], v[230:233], v[206:209], v[72:75]
	v_mfma_f32_16x16x32_bf16 v[68:71], v[222:225], v[214:217], v[68:71]
	v_mfma_f32_16x16x32_bf16 v[64:67], v[230:233], v[214:217], v[64:67]
	s_barrier
	s_add_i32 s19, s80, s57
	v_lshl_add_u64 v[234:235], s[50:51], 0, v[140:141]
	s_mov_b32 m0, s19
	s_nop 0
	global_load_lds_dwordx4 v[234:235], off
	v_lshl_add_u64 v[236:237], s[50:51], 0, v[132:133]
	s_add_i32 m0, s19, 0x2000
	s_nop 0
	global_load_lds_dwordx4 v[236:237], off
	s_mov_b32 m0, s58
	v_lshl_add_u64 v[238:239], s[52:53], 0, v[128:129]
	ds_read_b128 v[170:173], v157 offset:16384
	ds_read_b128 v[174:177], v157 offset:17408
	ds_read_b128 v[178:181], v157 offset:18432
	ds_read_b128 v[182:185], v157 offset:19456
	ds_read_b128 v[194:197], v157 offset:20480
	ds_read_b128 v[206:209], v157 offset:21504
	ds_read_b128 v[210:213], v157 offset:22528
	ds_read_b128 v[214:217], v157 offset:23552
	global_load_lds_dwordx4 v[238:239], off
	v_lshl_add_u64 v[240:241], s[52:53], 0, v[130:131]
	s_mov_b32 m0, s59
	s_nop 0
	global_load_lds_dwordx4 v[240:241], off
	s_add_u32 s80, s50, 0x40000
	s_addc_u32 s81, s51, 0
	s_add_i32 s6, s6, s57
	v_lshl_add_u64 v[250:251], s[80:81], 0, v[140:141]
	s_mov_b32 m0, s6
	s_nop 0
	global_load_lds_dwordx4 v[250:251], off
	v_lshl_add_u64 v[250:251], s[80:81], 0, v[132:133]
	s_add_i32 m0, s6, 0x2000
	s_nop 0
	global_load_lds_dwordx4 v[250:251], off
	s_waitcnt vmcnt(8)
	s_waitcnt lgkmcnt(0)
	s_barrier
	v_mfma_f32_16x16x32_bf16 v[60:63], v[146:149], v[170:173], v[60:63]
	v_mfma_f32_16x16x32_bf16 v[56:59], v[162:165], v[170:173], v[56:59]
	v_mfma_f32_16x16x32_bf16 v[52:55], v[146:149], v[178:181], v[52:55]
	v_mfma_f32_16x16x32_bf16 v[48:51], v[162:165], v[178:181], v[48:51]
	v_mfma_f32_16x16x32_bf16 v[44:47], v[146:149], v[194:197], v[44:47]
	v_mfma_f32_16x16x32_bf16 v[40:43], v[162:165], v[194:197], v[40:43]
	v_mfma_f32_16x16x32_bf16 v[36:39], v[146:149], v[210:213], v[36:39]
	v_mfma_f32_16x16x32_bf16 v[32:35], v[162:165], v[210:213], v[32:35]
	v_mfma_f32_16x16x32_bf16 v[60:63], v[158:161], v[174:177], v[60:63]
	v_mfma_f32_16x16x32_bf16 v[56:59], v[166:169], v[174:177], v[56:59]
	v_mfma_f32_16x16x32_bf16 v[52:55], v[158:161], v[182:185], v[52:55]
	v_mfma_f32_16x16x32_bf16 v[48:51], v[166:169], v[182:185], v[48:51]
	v_mfma_f32_16x16x32_bf16 v[44:47], v[158:161], v[206:209], v[44:47]
	v_mfma_f32_16x16x32_bf16 v[40:43], v[166:169], v[206:209], v[40:43]
	v_mfma_f32_16x16x32_bf16 v[36:39], v[158:161], v[214:217], v[36:39]
	v_mfma_f32_16x16x32_bf16 v[32:35], v[166:169], v[214:217], v[32:35]
	v_mfma_f32_16x16x32_bf16 v[28:31], v[218:221], v[170:173], v[28:31]
	v_mfma_f32_16x16x32_bf16 v[24:27], v[226:229], v[170:173], v[24:27]
	v_mfma_f32_16x16x32_bf16 v[20:23], v[218:221], v[178:181], v[20:23]
	v_mfma_f32_16x16x32_bf16 v[16:19], v[226:229], v[178:181], v[16:19]
	v_mfma_f32_16x16x32_bf16 v[12:15], v[218:221], v[194:197], v[12:15]
	v_mfma_f32_16x16x32_bf16 v[8:11], v[226:229], v[194:197], v[8:11]
	v_mfma_f32_16x16x32_bf16 v[4:7], v[218:221], v[210:213], v[4:7]
	v_mfma_f32_16x16x32_bf16 v[0:3], v[226:229], v[210:213], v[0:3]
	v_mfma_f32_16x16x32_bf16 v[28:31], v[222:225], v[174:177], v[28:31]
	v_mfma_f32_16x16x32_bf16 v[24:27], v[230:233], v[174:177], v[24:27]
	v_mfma_f32_16x16x32_bf16 v[20:23], v[222:225], v[182:185], v[20:23]
	v_mfma_f32_16x16x32_bf16 v[16:19], v[230:233], v[182:185], v[16:19]
	v_mfma_f32_16x16x32_bf16 v[12:15], v[222:225], v[206:209], v[12:15]
	v_mfma_f32_16x16x32_bf16 v[8:11], v[230:233], v[206:209], v[8:11]
	v_mfma_f32_16x16x32_bf16 v[4:7], v[222:225], v[214:217], v[4:7]
	v_mfma_f32_16x16x32_bf16 v[0:3], v[230:233], v[214:217], v[0:3]
	s_barrier
	s_add_i32 s6, 0, 0x18000
	v_add_u32_e32 v166, s6, v154
	ds_read_b128 v[146:149], v166
	ds_read_b128 v[158:161], v166 offset:1024
	ds_read_b128 v[162:165], v166 offset:2048
	ds_read_b128 v[166:169], v166 offset:3072
	s_add_u32 s52, s52, 0x40000
	s_addc_u32 s53, s53, 0
	s_mov_b32 m0, s68
	v_lshl_add_u64 v[218:219], s[52:53], 0, v[128:129]
	ds_read_b128 v[170:173], v157 offset:32768
	ds_read_b128 v[174:177], v157 offset:33792
	ds_read_b128 v[178:181], v157 offset:34816
	ds_read_b128 v[182:185], v157 offset:35840
	ds_read_b128 v[194:197], v157 offset:36864
	ds_read_b128 v[206:209], v157 offset:37888
	ds_read_b128 v[210:213], v157 offset:38912
	ds_read_b128 v[214:217], v157 offset:39936
	global_load_lds_dwordx4 v[218:219], off
	v_lshl_add_u64 v[218:219], s[52:53], 0, v[130:131]
	s_mov_b32 m0, s69
	s_nop 0
	global_load_lds_dwordx4 v[218:219], off
	s_add_i32 s19, 0, 0x1c000
	v_add_u32_e32 v192, s19, v154
	ds_read_b128 v[218:221], v192
	ds_read_b128 v[222:225], v192 offset:1024
	ds_read_b128 v[226:229], v192 offset:2048
	ds_read_b128 v[230:233], v192 offset:3072
	s_waitcnt vmcnt(8)
	s_waitcnt lgkmcnt(0)
	s_barrier
	v_mfma_f32_16x16x32_bf16 v[124:127], v[146:149], v[170:173], v[124:127]
	v_mfma_f32_16x16x32_bf16 v[120:123], v[162:165], v[170:173], v[120:123]
	v_mfma_f32_16x16x32_bf16 v[116:119], v[146:149], v[178:181], v[116:119]
	v_mfma_f32_16x16x32_bf16 v[112:115], v[162:165], v[178:181], v[112:115]
	v_mfma_f32_16x16x32_bf16 v[108:111], v[146:149], v[194:197], v[108:111]
	v_mfma_f32_16x16x32_bf16 v[104:107], v[162:165], v[194:197], v[104:107]
	v_mfma_f32_16x16x32_bf16 v[100:103], v[146:149], v[210:213], v[100:103]
	v_mfma_f32_16x16x32_bf16 v[96:99], v[162:165], v[210:213], v[96:99]
	v_mfma_f32_16x16x32_bf16 v[124:127], v[158:161], v[174:177], v[124:127]
	v_mfma_f32_16x16x32_bf16 v[120:123], v[166:169], v[174:177], v[120:123]
	v_mfma_f32_16x16x32_bf16 v[116:119], v[158:161], v[182:185], v[116:119]
	v_mfma_f32_16x16x32_bf16 v[112:115], v[166:169], v[182:185], v[112:115]
	v_mfma_f32_16x16x32_bf16 v[108:111], v[158:161], v[206:209], v[108:111]
	v_mfma_f32_16x16x32_bf16 v[104:107], v[166:169], v[206:209], v[104:107]
	v_mfma_f32_16x16x32_bf16 v[100:103], v[158:161], v[214:217], v[100:103]
	v_mfma_f32_16x16x32_bf16 v[96:99], v[166:169], v[214:217], v[96:99]
	v_mfma_f32_16x16x32_bf16 v[92:95], v[218:221], v[170:173], v[92:95]
	v_mfma_f32_16x16x32_bf16 v[88:91], v[226:229], v[170:173], v[88:91]
	v_mfma_f32_16x16x32_bf16 v[84:87], v[218:221], v[178:181], v[84:87]
	v_mfma_f32_16x16x32_bf16 v[80:83], v[226:229], v[178:181], v[80:83]
	v_mfma_f32_16x16x32_bf16 v[76:79], v[218:221], v[194:197], v[76:79]
	v_mfma_f32_16x16x32_bf16 v[72:75], v[226:229], v[194:197], v[72:75]
	v_mfma_f32_16x16x32_bf16 v[68:71], v[218:221], v[210:213], v[68:71]
	v_mfma_f32_16x16x32_bf16 v[64:67], v[226:229], v[210:213], v[64:67]
	v_mfma_f32_16x16x32_bf16 v[92:95], v[222:225], v[174:177], v[92:95]
	v_mfma_f32_16x16x32_bf16 v[88:91], v[230:233], v[174:177], v[88:91]
	v_mfma_f32_16x16x32_bf16 v[84:87], v[222:225], v[182:185], v[84:87]
	v_mfma_f32_16x16x32_bf16 v[80:83], v[230:233], v[182:185], v[80:83]
	v_mfma_f32_16x16x32_bf16 v[76:79], v[222:225], v[206:209], v[76:79]
	v_mfma_f32_16x16x32_bf16 v[72:75], v[230:233], v[206:209], v[72:75]
	v_mfma_f32_16x16x32_bf16 v[68:71], v[222:225], v[214:217], v[68:71]
	v_mfma_f32_16x16x32_bf16 v[64:67], v[230:233], v[214:217], v[64:67]
	s_barrier
	s_add_i32 s6, s6, s57
	v_lshl_add_u64 v[234:235], v[234:235], 0, s[36:37]
	s_mov_b32 m0, s6
	s_nop 0
	global_load_lds_dwordx4 v[234:235], off
	v_lshl_add_u64 v[234:235], v[236:237], 0, s[36:37]
	s_add_i32 m0, s6, 0x2000
	s_nop 0
	global_load_lds_dwordx4 v[234:235], off
	s_mov_b32 m0, s70
	v_lshl_add_u64 v[234:235], v[238:239], 0, s[36:37]
	ds_read_b128 v[170:173], v157 offset:49152
	ds_read_b128 v[174:177], v157 offset:50176
	ds_read_b128 v[178:181], v157 offset:51200
	ds_read_b128 v[182:185], v157 offset:52224
	ds_read_b128 v[194:197], v157 offset:53248
	ds_read_b128 v[206:209], v157 offset:54272
	ds_read_b128 v[210:213], v157 offset:55296
	ds_read_b128 v[214:217], v157 offset:56320
	global_load_lds_dwordx4 v[234:235], off
	v_lshl_add_u64 v[234:235], v[240:241], 0, s[36:37]
	s_mov_b32 m0, s71
	s_nop 0
	global_load_lds_dwordx4 v[234:235], off
	s_add_u32 s50, s50, 0x40080
	s_addc_u32 s51, s51, 0
	s_add_i32 s6, s19, s57
	v_lshl_add_u64 v[250:251], s[50:51], 0, v[140:141]
	s_mov_b32 m0, s6
	s_nop 0
	global_load_lds_dwordx4 v[250:251], off
	v_lshl_add_u64 v[250:251], s[50:51], 0, v[132:133]
	s_add_i32 m0, s6, 0x2000
	s_nop 0
	global_load_lds_dwordx4 v[250:251], off
	s_add_i32 s75, s75, 2
	s_add_u32 s48, s48, 0x100
	s_addc_u32 s49, s49, 0
	s_cmp_gt_u32 s75, 13
	s_nop 0
	s_waitcnt vmcnt(8)
	s_waitcnt lgkmcnt(0)
	s_barrier
	v_mfma_f32_16x16x32_bf16 v[60:63], v[146:149], v[170:173], v[60:63]
	v_mfma_f32_16x16x32_bf16 v[56:59], v[162:165], v[170:173], v[56:59]
	v_mfma_f32_16x16x32_bf16 v[52:55], v[146:149], v[178:181], v[52:55]
	v_mfma_f32_16x16x32_bf16 v[48:51], v[162:165], v[178:181], v[48:51]
	v_mfma_f32_16x16x32_bf16 v[44:47], v[146:149], v[194:197], v[44:47]
	v_mfma_f32_16x16x32_bf16 v[40:43], v[162:165], v[194:197], v[40:43]
	v_mfma_f32_16x16x32_bf16 v[36:39], v[146:149], v[210:213], v[36:39]
	v_mfma_f32_16x16x32_bf16 v[32:35], v[162:165], v[210:213], v[32:35]
	v_mfma_f32_16x16x32_bf16 v[60:63], v[158:161], v[174:177], v[60:63]
	v_mfma_f32_16x16x32_bf16 v[56:59], v[166:169], v[174:177], v[56:59]
	v_mfma_f32_16x16x32_bf16 v[52:55], v[158:161], v[182:185], v[52:55]
	v_mfma_f32_16x16x32_bf16 v[48:51], v[166:169], v[182:185], v[48:51]
	v_mfma_f32_16x16x32_bf16 v[44:47], v[158:161], v[206:209], v[44:47]
	v_mfma_f32_16x16x32_bf16 v[40:43], v[166:169], v[206:209], v[40:43]
	v_mfma_f32_16x16x32_bf16 v[36:39], v[158:161], v[214:217], v[36:39]
	v_mfma_f32_16x16x32_bf16 v[32:35], v[166:169], v[214:217], v[32:35]
	v_mfma_f32_16x16x32_bf16 v[28:31], v[218:221], v[170:173], v[28:31]
	v_mfma_f32_16x16x32_bf16 v[24:27], v[226:229], v[170:173], v[24:27]
	v_mfma_f32_16x16x32_bf16 v[20:23], v[218:221], v[178:181], v[20:23]
	v_mfma_f32_16x16x32_bf16 v[16:19], v[226:229], v[178:181], v[16:19]
	v_mfma_f32_16x16x32_bf16 v[12:15], v[218:221], v[194:197], v[12:15]
	v_mfma_f32_16x16x32_bf16 v[8:11], v[226:229], v[194:197], v[8:11]
	v_mfma_f32_16x16x32_bf16 v[4:7], v[218:221], v[210:213], v[4:7]
	v_mfma_f32_16x16x32_bf16 v[0:3], v[226:229], v[210:213], v[0:3]
	v_mfma_f32_16x16x32_bf16 v[28:31], v[222:225], v[174:177], v[28:31]
	v_mfma_f32_16x16x32_bf16 v[24:27], v[230:233], v[174:177], v[24:27]
	v_mfma_f32_16x16x32_bf16 v[20:23], v[222:225], v[182:185], v[20:23]
	v_mfma_f32_16x16x32_bf16 v[16:19], v[230:233], v[182:185], v[16:19]
	v_mfma_f32_16x16x32_bf16 v[12:15], v[222:225], v[206:209], v[12:15]
	v_mfma_f32_16x16x32_bf16 v[8:11], v[230:233], v[206:209], v[8:11]
	v_mfma_f32_16x16x32_bf16 v[4:7], v[222:225], v[214:217], v[4:7]
	v_mfma_f32_16x16x32_bf16 v[0:3], v[230:233], v[214:217], v[0:3]
	s_barrier
	s_cbranch_scc0 .LBB0_295
	s_mov_b32 s100, 1
	s_setprio 1
	s_add_u32 s48, s10, 0xffffff00
	v_lshl_add_u32 v166, s73, 10, v155
	s_addc_u32 s49, s11, -1
	s_ashr_i32 s29, s28, 31
	v_lshl_or_b32 v146, s72, 8, v156
	ds_read2_b32 v[158:159], v166 offset1:16
	s_lshl_b64 s[10:11], s[28:29], 8
	v_ashrrev_i32_e32 v147, 31, v146
	v_lshl_add_u64 v[148:149], s[10:11], 0, v[134:135]
	v_lshl_add_u64 v[146:147], v[146:147], 1, s[26:27]
	v_mad_u64_u32 v[150:151], s[10:11], v148, s13, v[146:147]
	v_mov_b32_e32 v146, v151
	v_mad_u64_u32 v[152:153], s[10:11], v149, s13, v[146:147]
	s_waitcnt lgkmcnt(0)
	v_pk_mul_f32 v[148:149], v[126:127], v[158:159] op_sel_hi:[1,0]
	v_pk_mul_f32 v[146:147], v[124:125], v[158:159] op_sel_hi:[1,0]
	v_pk_mul_f32 v[160:161], v[122:123], v[158:159] op_sel_hi:[1,0]
	v_pk_mul_f32 v[162:163], v[120:121], v[158:159] op_sel_hi:[1,0]
	v_mov_b32_e32 v151, v152
	v_cvt_pk_bf16_f32 v146, v146, v147
	v_cvt_pk_bf16_f32 v147, v148, v149
	v_cvt_pk_bf16_f32 v148, v162, v163
	v_cvt_pk_bf16_f32 v149, v160, v161
	global_store_dwordx4 v[150:151], v[146:149], off
	v_pk_mul_f32 v[160:161], v[90:91], v[158:159] op_sel_hi:[1,0]
	v_pk_mul_f32 v[162:163], v[88:89], v[158:159] op_sel_hi:[1,0]
	v_pk_mul_f32 v[148:149], v[94:95], v[158:159] op_sel_hi:[1,0]
	v_pk_mul_f32 v[146:147], v[92:93], v[158:159] op_sel_hi:[1,0]
	v_mov_b32_e32 v158, v159
	v_cvt_pk_bf16_f32 v146, v146, v147
	v_cvt_pk_bf16_f32 v147, v148, v149
	v_cvt_pk_bf16_f32 v148, v162, v163
	v_cvt_pk_bf16_f32 v149, v160, v161
	global_store_dwordx4 v[150:151], v[146:149], off offset:256
	v_pk_mul_f32 v[160:161], v[114:115], v[158:159] op_sel_hi:[1,0]
	s_mov_b32 s6, 0x1e000
	v_pk_mul_f32 v[148:149], v[118:119], v[158:159] op_sel_hi:[1,0]
	v_pk_mul_f32 v[146:147], v[116:117], v[158:159] op_sel_hi:[1,0]
	ds_read2_b32 v[164:165], v166 offset0:32 offset1:48
	v_pk_mul_f32 v[162:163], v[112:113], v[158:159] op_sel_hi:[1,0]
	v_cvt_pk_bf16_f32 v146, v146, v147
	v_cvt_pk_bf16_f32 v147, v148, v149
	v_cvt_pk_bf16_f32 v149, v160, v161
	v_add_co_u32_e32 v160, vcc, s6, v150
	v_cvt_pk_bf16_f32 v148, v162, v163
	s_nop 0
	v_addc_co_u32_e32 v161, vcc, 0, v152, vcc
	global_store_dwordx4 v[160:161], v[146:149], off
	v_pk_mul_f32 v[162:163], v[82:83], v[158:159] op_sel_hi:[1,0]
	s_mov_b32 s6, 0x3c000
	v_pk_mul_f32 v[148:149], v[86:87], v[158:159] op_sel_hi:[1,0]
	v_pk_mul_f32 v[146:147], v[84:85], v[158:159] op_sel_hi:[1,0]
	v_pk_mul_f32 v[158:159], v[80:81], v[158:159] op_sel_hi:[1,0]
	v_cvt_pk_bf16_f32 v146, v146, v147
	v_cvt_pk_bf16_f32 v147, v148, v149
	v_cvt_pk_bf16_f32 v148, v158, v159
	v_cvt_pk_bf16_f32 v149, v162, v163
	global_store_dwordx4 v[160:161], v[146:149], off offset:256
	s_waitcnt lgkmcnt(0)
	v_pk_mul_f32 v[158:159], v[106:107], v[164:165] op_sel_hi:[1,0]
	v_pk_mul_f32 v[160:161], v[104:105], v[164:165] op_sel_hi:[1,0]
	v_pk_mul_f32 v[148:149], v[110:111], v[164:165] op_sel_hi:[1,0]
	v_pk_mul_f32 v[146:147], v[108:109], v[164:165] op_sel_hi:[1,0]
	v_pk_mul_f32 v[162:163], v[72:73], v[164:165] op_sel_hi:[1,0]
	v_cvt_pk_bf16_f32 v146, v146, v147
	v_cvt_pk_bf16_f32 v147, v148, v149
	v_cvt_pk_bf16_f32 v149, v158, v159
	v_add_co_u32_e32 v158, vcc, s6, v150
	v_cvt_pk_bf16_f32 v148, v160, v161
	s_nop 0
	v_addc_co_u32_e32 v159, vcc, 0, v152, vcc
	global_store_dwordx4 v[158:159], v[146:149], off
	v_pk_mul_f32 v[160:161], v[74:75], v[164:165] op_sel_hi:[1,0]
	s_mov_b32 s6, 0x5a000
	v_pk_mul_f32 v[148:149], v[78:79], v[164:165] op_sel_hi:[1,0]
	v_pk_mul_f32 v[146:147], v[76:77], v[164:165] op_sel_hi:[1,0]
	s_nop 0
	v_cvt_pk_bf16_f32 v146, v146, v147
	v_cvt_pk_bf16_f32 v147, v148, v149
	v_cvt_pk_bf16_f32 v148, v162, v163
	v_cvt_pk_bf16_f32 v149, v160, v161
	global_store_dwordx4 v[158:159], v[146:149], off offset:256
	v_mov_b32_e32 v158, v165
	v_pk_mul_f32 v[160:161], v[98:99], v[158:159] op_sel_hi:[1,0]
	v_pk_mul_f32 v[148:149], v[102:103], v[158:159] op_sel_hi:[1,0]
	v_pk_mul_f32 v[146:147], v[100:101], v[158:159] op_sel_hi:[1,0]
	ds_read2_b32 v[164:165], v166 offset0:128 offset1:144
	v_pk_mul_f32 v[162:163], v[96:97], v[158:159] op_sel_hi:[1,0]
	v_cvt_pk_bf16_f32 v146, v146, v147
	v_cvt_pk_bf16_f32 v147, v148, v149
	v_cvt_pk_bf16_f32 v149, v160, v161
	v_add_co_u32_e32 v160, vcc, s6, v150
	v_cvt_pk_bf16_f32 v148, v162, v163
	s_nop 0
	v_addc_co_u32_e32 v161, vcc, 0, v152, vcc
	global_store_dwordx4 v[160:161], v[146:149], off
	v_pk_mul_f32 v[162:163], v[66:67], v[158:159] op_sel_hi:[1,0]
	s_mov_b32 s6, 0xf0000
	v_pk_mul_f32 v[148:149], v[70:71], v[158:159] op_sel_hi:[1,0]
	v_pk_mul_f32 v[146:147], v[68:69], v[158:159] op_sel_hi:[1,0]
	v_pk_mul_f32 v[158:159], v[64:65], v[158:159] op_sel_hi:[1,0]
	v_cvt_pk_bf16_f32 v146, v146, v147
	v_cvt_pk_bf16_f32 v147, v148, v149
	v_cvt_pk_bf16_f32 v148, v158, v159
	v_cvt_pk_bf16_f32 v149, v162, v163
	global_store_dwordx4 v[160:161], v[146:149], off offset:256
	s_waitcnt lgkmcnt(0)
	v_pk_mul_f32 v[158:159], v[58:59], v[164:165] op_sel_hi:[1,0]
	v_pk_mul_f32 v[160:161], v[56:57], v[164:165] op_sel_hi:[1,0]
	v_pk_mul_f32 v[148:149], v[62:63], v[164:165] op_sel_hi:[1,0]
	v_pk_mul_f32 v[146:147], v[60:61], v[164:165] op_sel_hi:[1,0]
	v_pk_mul_f32 v[162:163], v[24:25], v[164:165] op_sel_hi:[1,0]
	v_cvt_pk_bf16_f32 v146, v146, v147
	v_cvt_pk_bf16_f32 v147, v148, v149
	v_cvt_pk_bf16_f32 v149, v158, v159
	v_add_co_u32_e32 v158, vcc, s6, v150
	v_cvt_pk_bf16_f32 v148, v160, v161
	s_nop 0
	v_addc_co_u32_e32 v159, vcc, 0, v152, vcc
	global_store_dwordx4 v[158:159], v[146:149], off
	v_pk_mul_f32 v[160:161], v[26:27], v[164:165] op_sel_hi:[1,0]
	s_mov_b32 s6, 0x10e000
	v_pk_mul_f32 v[148:149], v[30:31], v[164:165] op_sel_hi:[1,0]
	v_pk_mul_f32 v[146:147], v[28:29], v[164:165] op_sel_hi:[1,0]
	s_nop 0
	v_cvt_pk_bf16_f32 v146, v146, v147
	v_cvt_pk_bf16_f32 v147, v148, v149
	v_cvt_pk_bf16_f32 v148, v162, v163
	v_cvt_pk_bf16_f32 v149, v160, v161
	global_store_dwordx4 v[158:159], v[146:149], off offset:256
	v_mov_b32_e32 v158, v165
	v_pk_mul_f32 v[160:161], v[50:51], v[158:159] op_sel_hi:[1,0]
	v_pk_mul_f32 v[148:149], v[54:55], v[158:159] op_sel_hi:[1,0]
	v_pk_mul_f32 v[146:147], v[52:53], v[158:159] op_sel_hi:[1,0]
	ds_read2_b32 v[164:165], v166 offset0:160 offset1:176
	v_pk_mul_f32 v[162:163], v[48:49], v[158:159] op_sel_hi:[1,0]
	v_cvt_pk_bf16_f32 v146, v146, v147
	v_cvt_pk_bf16_f32 v147, v148, v149
	v_cvt_pk_bf16_f32 v149, v160, v161
	v_add_co_u32_e32 v160, vcc, s6, v150
	v_cvt_pk_bf16_f32 v148, v162, v163
	s_nop 0
	v_addc_co_u32_e32 v161, vcc, 0, v152, vcc
	global_store_dwordx4 v[160:161], v[146:149], off
	v_pk_mul_f32 v[162:163], v[18:19], v[158:159] op_sel_hi:[1,0]
	s_mov_b32 s6, 0x12c000
	v_pk_mul_f32 v[148:149], v[22:23], v[158:159] op_sel_hi:[1,0]
	v_pk_mul_f32 v[146:147], v[20:21], v[158:159] op_sel_hi:[1,0]
	v_pk_mul_f32 v[158:159], v[16:17], v[158:159] op_sel_hi:[1,0]
	v_cvt_pk_bf16_f32 v146, v146, v147
	v_cvt_pk_bf16_f32 v147, v148, v149
	v_cvt_pk_bf16_f32 v148, v158, v159
	v_cvt_pk_bf16_f32 v149, v162, v163
	global_store_dwordx4 v[160:161], v[146:149], off offset:256
	s_waitcnt lgkmcnt(0)
	v_pk_mul_f32 v[158:159], v[42:43], v[164:165] op_sel_hi:[1,0]
	v_pk_mul_f32 v[160:161], v[40:41], v[164:165] op_sel_hi:[1,0]
	v_pk_mul_f32 v[148:149], v[46:47], v[164:165] op_sel_hi:[1,0]
	v_pk_mul_f32 v[146:147], v[44:45], v[164:165] op_sel_hi:[1,0]
	v_pk_mul_f32 v[162:163], v[8:9], v[164:165] op_sel_hi:[1,0]
	v_cvt_pk_bf16_f32 v146, v146, v147
	v_cvt_pk_bf16_f32 v147, v148, v149
	v_cvt_pk_bf16_f32 v149, v158, v159
	v_add_co_u32_e32 v158, vcc, s6, v150
	v_cvt_pk_bf16_f32 v148, v160, v161
	s_nop 0
	v_addc_co_u32_e32 v159, vcc, 0, v152, vcc
	global_store_dwordx4 v[158:159], v[146:149], off
	v_pk_mul_f32 v[160:161], v[10:11], v[164:165] op_sel_hi:[1,0]
	s_mov_b32 s6, 0x14a000
	v_pk_mul_f32 v[148:149], v[14:15], v[164:165] op_sel_hi:[1,0]
	v_pk_mul_f32 v[146:147], v[12:13], v[164:165] op_sel_hi:[1,0]
	v_add_co_u32_e32 v150, vcc, s6, v150
	v_cvt_pk_bf16_f32 v146, v146, v147
	v_cvt_pk_bf16_f32 v147, v148, v149
	v_cvt_pk_bf16_f32 v148, v162, v163
	v_cvt_pk_bf16_f32 v149, v160, v161
	global_store_dwordx4 v[158:159], v[146:149], off offset:256
	v_mov_b32_e32 v158, v165
	v_pk_mul_f32 v[160:161], v[34:35], v[158:159] op_sel_hi:[1,0]
	v_pk_mul_f32 v[148:149], v[38:39], v[158:159] op_sel_hi:[1,0]
	v_pk_mul_f32 v[146:147], v[36:37], v[158:159] op_sel_hi:[1,0]
	v_pk_mul_f32 v[162:163], v[32:33], v[158:159] op_sel_hi:[1,0]
	v_cvt_pk_bf16_f32 v146, v146, v147
	v_cvt_pk_bf16_f32 v147, v148, v149
	v_cvt_pk_bf16_f32 v148, v162, v163
	v_cvt_pk_bf16_f32 v149, v160, v161
	v_addc_co_u32_e32 v151, vcc, 0, v152, vcc
	global_store_dwordx4 v[150:151], v[146:149], off
	v_pk_mul_f32 v[152:153], v[2:3], v[158:159] op_sel_hi:[1,0]
	s_andn2_b64 vcc, exec, s[44:45]
	v_pk_mul_f32 v[148:149], v[6:7], v[158:159] op_sel_hi:[1,0]
	v_pk_mul_f32 v[146:147], v[4:5], v[158:159] op_sel_hi:[1,0]
	v_pk_mul_f32 v[158:159], v[0:1], v[158:159] op_sel_hi:[1,0]
	v_cvt_pk_bf16_f32 v146, v146, v147
	v_cvt_pk_bf16_f32 v147, v148, v149
	v_cvt_pk_bf16_f32 v148, v158, v159
	v_cvt_pk_bf16_f32 v149, v152, v153
	global_store_dwordx4 v[150:151], v[146:149], off offset:256
	s_cbranch_vccz .LBB0_291
	s_mov_b64 s[38:39], s[48:49]
	s_andn2_b64 vcc, exec, s[42:43]
	s_mov_b64 s[48:49], s[38:39]
	s_cbranch_vccnz .LBB0_292

.LBB0_314:
	s_add_u32 s11, s48, 0x100
	s_addc_u32 s12, s49, 0
	s_ashr_i32 s31, s30, 31
	s_lshl_b64 s[42:43], s[30:31], 19
	s_add_u32 s46, s33, s42
	s_addc_u32 s47, s41, s43
	s_and_b64 s[42:43], s[44:45], exec
	s_cselect_b32 s29, s47, s5
	s_cselect_b32 s31, s46, s4
	s_ashr_i32 s35, s34, 31
	s_lshl_b64 s[42:43], s[34:35], 19
	s_add_u32 s42, s54, s42
	s_addc_u32 s43, s55, s43
	s_and_b64 s[50:51], s[44:45], exec
	s_cselect_b32 s35, s43, s49
	s_cselect_b32 s74, s42, s48
	s_add_u32 s48, s4, 0x40080
	s_addc_u32 s49, s5, 0
	v_lshl_add_u64 v[150:151], s[48:49], 0, v[136:137]
	v_lshl_add_u64 v[152:153], s[48:49], 0, v[138:139]
	s_mov_b32 s75, -2
	s_mov_b64 s[48:49], 0
	s_add_u32 s6, s4, s48
	s_addc_u32 s19, s5, s49
	s_add_u32 s6, s6, 0x100
	s_addc_u32 s19, s19, 0
	s_add_u32 s23, s11, s48
	s_addc_u32 s50, s12, s49
	s_add_i32 s80, 0, 0x10000
	v_add_u32_e32 v157, s80, v154
	ds_read_b128 v[146:149], v157
	ds_read_b128 v[158:161], v157 offset:1024
	ds_read_b128 v[162:165], v157 offset:2048
	ds_read_b128 v[166:169], v157 offset:3072
	s_cmpk_eq_i32 s48, 0x700
	s_cselect_b32 s53, s29, s19
	s_cselect_b32 s52, s31, s6
	s_cselect_b32 s51, s35, s50
	s_cselect_b32 s50, s74, s23
	v_lshl_add_u64 v[218:219], v[150:151], 0, s[48:49]
	s_add_i32 m0, s58, 0xc000
	ds_read_b128 v[170:173], v156
	ds_read_b128 v[174:177], v156 offset:1024
	ds_read_b128 v[178:181], v156 offset:2048
	ds_read_b128 v[182:185], v156 offset:3072
	ds_read_b128 v[194:197], v156 offset:4096
	ds_read_b128 v[206:209], v156 offset:5120
	ds_read_b128 v[210:213], v156 offset:6144
	ds_read_b128 v[214:217], v156 offset:7168
	global_load_lds_dwordx4 v[218:219], off
	v_lshl_add_u64 v[218:219], v[152:153], 0, s[48:49]
	s_add_i32 m0, s58, 0xe000
	s_nop 0
	global_load_lds_dwordx4 v[218:219], off
	s_add_i32 s6, 0, 0x14000
	v_add_u32_e32 v157, s6, v154
	ds_read_b128 v[218:221], v157
	ds_read_b128 v[222:225], v157 offset:1024
	ds_read_b128 v[226:229], v157 offset:2048
	ds_read_b128 v[230:233], v157 offset:3072
	s_setprio 0
	s_waitcnt vmcnt(24)
	s_cmp_lg_u32 s100, 0
	s_cbranch_scc1 .Lm4ap_315
	s_waitcnt vmcnt(8)

.LBB0_315:
	s_add_u32 s6, s4, s48
	s_addc_u32 s19, s5, s49
	s_add_u32 s6, s6, 0x100
	s_addc_u32 s19, s19, 0
	s_add_u32 s23, s11, s48
	s_addc_u32 s50, s12, s49
	s_add_i32 s80, 0, 0x10000
	v_add_u32_e32 v157, s80, v154
	ds_read_b128 v[146:149], v157
	ds_read_b128 v[158:161], v157 offset:1024
	ds_read_b128 v[162:165], v157 offset:2048
	ds_read_b128 v[166:169], v157 offset:3072
	s_cmpk_eq_i32 s48, 0x700
	s_cselect_b32 s53, s29, s19
	s_cselect_b32 s52, s31, s6
	s_cselect_b32 s51, s35, s50
	s_cselect_b32 s50, s74, s23
	v_lshl_add_u64 v[218:219], v[150:151], 0, s[48:49]
	s_add_i32 m0, s58, 0xc000
	ds_read_b128 v[170:173], v156
	ds_read_b128 v[174:177], v156 offset:1024
	ds_read_b128 v[178:181], v156 offset:2048
	ds_read_b128 v[182:185], v156 offset:3072
	ds_read_b128 v[194:197], v156 offset:4096
	ds_read_b128 v[206:209], v156 offset:5120
	ds_read_b128 v[210:213], v156 offset:6144
	ds_read_b128 v[214:217], v156 offset:7168
	global_load_lds_dwordx4 v[218:219], off
	v_lshl_add_u64 v[218:219], v[152:153], 0, s[48:49]
	s_add_i32 m0, s58, 0xe000
	s_nop 0
	global_load_lds_dwordx4 v[218:219], off
	s_add_i32 s6, 0, 0x14000
	v_add_u32_e32 v157, s6, v154
	ds_read_b128 v[218:221], v157
	ds_read_b128 v[222:225], v157 offset:1024
	ds_read_b128 v[226:229], v157 offset:2048
	ds_read_b128 v[230:233], v157 offset:3072
	s_nop 0
	s_waitcnt vmcnt(8)
	s_waitcnt lgkmcnt(0)
	s_barrier
	v_mfma_f32_16x16x32_bf16 v[124:127], v[146:149], v[170:173], v[124:127]
	v_mfma_f32_16x16x32_bf16 v[120:123], v[162:165], v[170:173], v[120:123]
	v_mfma_f32_16x16x32_bf16 v[116:119], v[146:149], v[178:181], v[116:119]
	v_mfma_f32_16x16x32_bf16 v[112:115], v[162:165], v[178:181], v[112:115]
	v_mfma_f32_16x16x32_bf16 v[108:111], v[146:149], v[194:197], v[108:111]
	v_mfma_f32_16x16x32_bf16 v[104:107], v[162:165], v[194:197], v[104:107]
	v_mfma_f32_16x16x32_bf16 v[100:103], v[146:149], v[210:213], v[100:103]
	v_mfma_f32_16x16x32_bf16 v[96:99], v[162:165], v[210:213], v[96:99]
	v_mfma_f32_16x16x32_bf16 v[124:127], v[158:161], v[174:177], v[124:127]
	v_mfma_f32_16x16x32_bf16 v[120:123], v[166:169], v[174:177], v[120:123]
	v_mfma_f32_16x16x32_bf16 v[116:119], v[158:161], v[182:185], v[116:119]
	v_mfma_f32_16x16x32_bf16 v[112:115], v[166:169], v[182:185], v[112:115]
	v_mfma_f32_16x16x32_bf16 v[108:111], v[158:161], v[206:209], v[108:111]
	v_mfma_f32_16x16x32_bf16 v[104:107], v[166:169], v[206:209], v[104:107]
	v_mfma_f32_16x16x32_bf16 v[100:103], v[158:161], v[214:217], v[100:103]
	v_mfma_f32_16x16x32_bf16 v[96:99], v[166:169], v[214:217], v[96:99]
	v_mfma_f32_16x16x32_bf16 v[92:95], v[218:221], v[170:173], v[92:95]
	v_mfma_f32_16x16x32_bf16 v[88:91], v[226:229], v[170:173], v[88:91]
	v_mfma_f32_16x16x32_bf16 v[84:87], v[218:221], v[178:181], v[84:87]
	v_mfma_f32_16x16x32_bf16 v[80:83], v[226:229], v[178:181], v[80:83]
	v_mfma_f32_16x16x32_bf16 v[76:79], v[218:221], v[194:197], v[76:79]
	v_mfma_f32_16x16x32_bf16 v[72:75], v[226:229], v[194:197], v[72:75]
	v_mfma_f32_16x16x32_bf16 v[68:71], v[218:221], v[210:213], v[68:71]
	v_mfma_f32_16x16x32_bf16 v[64:67], v[226:229], v[210:213], v[64:67]
	v_mfma_f32_16x16x32_bf16 v[92:95], v[222:225], v[174:177], v[92:95]
	v_mfma_f32_16x16x32_bf16 v[88:91], v[230:233], v[174:177], v[88:91]
	v_mfma_f32_16x16x32_bf16 v[84:87], v[222:225], v[182:185], v[84:87]
	v_mfma_f32_16x16x32_bf16 v[80:83], v[230:233], v[182:185], v[80:83]
	v_mfma_f32_16x16x32_bf16 v[76:79], v[222:225], v[206:209], v[76:79]
	v_mfma_f32_16x16x32_bf16 v[72:75], v[230:233], v[206:209], v[72:75]
	v_mfma_f32_16x16x32_bf16 v[68:71], v[222:225], v[214:217], v[68:71]
	v_mfma_f32_16x16x32_bf16 v[64:67], v[230:233], v[214:217], v[64:67]
	s_barrier
	s_add_i32 s19, s80, s57
	v_lshl_add_u64 v[234:235], s[50:51], 0, v[140:141]
	s_mov_b32 m0, s19
	s_nop 0
	global_load_lds_dwordx4 v[234:235], off
	v_lshl_add_u64 v[236:237], s[50:51], 0, v[132:133]
	s_add_i32 m0, s19, 0x2000
	s_nop 0
	global_load_lds_dwordx4 v[236:237], off
	s_mov_b32 m0, s58
	v_lshl_add_u64 v[238:239], s[52:53], 0, v[128:129]
	ds_read_b128 v[170:173], v156 offset:16384
	ds_read_b128 v[174:177], v156 offset:17408
	ds_read_b128 v[178:181], v156 offset:18432
	ds_read_b128 v[182:185], v156 offset:19456
	ds_read_b128 v[194:197], v156 offset:20480
	ds_read_b128 v[206:209], v156 offset:21504
	ds_read_b128 v[210:213], v156 offset:22528
	ds_read_b128 v[214:217], v156 offset:23552
	global_load_lds_dwordx4 v[238:239], off
	v_lshl_add_u64 v[240:241], s[52:53], 0, v[130:131]
	s_mov_b32 m0, s59
	s_nop 0
	global_load_lds_dwordx4 v[240:241], off
	s_add_u32 s80, s50, 0x40000
	s_addc_u32 s81, s51, 0
	s_add_i32 s6, s6, s57
	v_lshl_add_u64 v[250:251], s[80:81], 0, v[140:141]
	s_mov_b32 m0, s6
	s_nop 0
	global_load_lds_dwordx4 v[250:251], off
	v_lshl_add_u64 v[250:251], s[80:81], 0, v[132:133]
	s_add_i32 m0, s6, 0x2000
	s_nop 0
	global_load_lds_dwordx4 v[250:251], off
	s_waitcnt vmcnt(8)
	s_waitcnt lgkmcnt(0)
	s_barrier
	v_mfma_f32_16x16x32_bf16 v[60:63], v[146:149], v[170:173], v[60:63]
	v_mfma_f32_16x16x32_bf16 v[56:59], v[162:165], v[170:173], v[56:59]
	v_mfma_f32_16x16x32_bf16 v[52:55], v[146:149], v[178:181], v[52:55]
	v_mfma_f32_16x16x32_bf16 v[48:51], v[162:165], v[178:181], v[48:51]
	v_mfma_f32_16x16x32_bf16 v[44:47], v[146:149], v[194:197], v[44:47]
	v_mfma_f32_16x16x32_bf16 v[40:43], v[162:165], v[194:197], v[40:43]
	v_mfma_f32_16x16x32_bf16 v[36:39], v[146:149], v[210:213], v[36:39]
	v_mfma_f32_16x16x32_bf16 v[32:35], v[162:165], v[210:213], v[32:35]
	v_mfma_f32_16x16x32_bf16 v[60:63], v[158:161], v[174:177], v[60:63]
	v_mfma_f32_16x16x32_bf16 v[56:59], v[166:169], v[174:177], v[56:59]
	v_mfma_f32_16x16x32_bf16 v[52:55], v[158:161], v[182:185], v[52:55]
	v_mfma_f32_16x16x32_bf16 v[48:51], v[166:169], v[182:185], v[48:51]
	v_mfma_f32_16x16x32_bf16 v[44:47], v[158:161], v[206:209], v[44:47]
	v_mfma_f32_16x16x32_bf16 v[40:43], v[166:169], v[206:209], v[40:43]
	v_mfma_f32_16x16x32_bf16 v[36:39], v[158:161], v[214:217], v[36:39]
	v_mfma_f32_16x16x32_bf16 v[32:35], v[166:169], v[214:217], v[32:35]
	v_mfma_f32_16x16x32_bf16 v[28:31], v[218:221], v[170:173], v[28:31]
	v_mfma_f32_16x16x32_bf16 v[24:27], v[226:229], v[170:173], v[24:27]
	v_mfma_f32_16x16x32_bf16 v[20:23], v[218:221], v[178:181], v[20:23]
	v_mfma_f32_16x16x32_bf16 v[16:19], v[226:229], v[178:181], v[16:19]
	v_mfma_f32_16x16x32_bf16 v[12:15], v[218:221], v[194:197], v[12:15]
	v_mfma_f32_16x16x32_bf16 v[8:11], v[226:229], v[194:197], v[8:11]
	v_mfma_f32_16x16x32_bf16 v[4:7], v[218:221], v[210:213], v[4:7]
	v_mfma_f32_16x16x32_bf16 v[0:3], v[226:229], v[210:213], v[0:3]
	v_mfma_f32_16x16x32_bf16 v[28:31], v[222:225], v[174:177], v[28:31]
	v_mfma_f32_16x16x32_bf16 v[24:27], v[230:233], v[174:177], v[24:27]
	v_mfma_f32_16x16x32_bf16 v[20:23], v[222:225], v[182:185], v[20:23]
	v_mfma_f32_16x16x32_bf16 v[16:19], v[230:233], v[182:185], v[16:19]
	v_mfma_f32_16x16x32_bf16 v[12:15], v[222:225], v[206:209], v[12:15]
	v_mfma_f32_16x16x32_bf16 v[8:11], v[230:233], v[206:209], v[8:11]
	v_mfma_f32_16x16x32_bf16 v[4:7], v[222:225], v[214:217], v[4:7]
	v_mfma_f32_16x16x32_bf16 v[0:3], v[230:233], v[214:217], v[0:3]
	s_barrier
	s_add_i32 s6, 0, 0x18000
	v_add_u32_e32 v157, s6, v154
	ds_read_b128 v[146:149], v157
	ds_read_b128 v[158:161], v157 offset:1024
	ds_read_b128 v[162:165], v157 offset:2048
	ds_read_b128 v[166:169], v157 offset:3072
	s_add_u32 s52, s52, 0x40000
	s_addc_u32 s53, s53, 0
	s_mov_b32 m0, s68
	v_lshl_add_u64 v[218:219], s[52:53], 0, v[128:129]
	ds_read_b128 v[170:173], v156 offset:32768
	ds_read_b128 v[174:177], v156 offset:33792
	ds_read_b128 v[178:181], v156 offset:34816
	ds_read_b128 v[182:185], v156 offset:35840
	ds_read_b128 v[194:197], v156 offset:36864
	ds_read_b128 v[206:209], v156 offset:37888
	ds_read_b128 v[210:213], v156 offset:38912
	ds_read_b128 v[214:217], v156 offset:39936
	global_load_lds_dwordx4 v[218:219], off
	v_lshl_add_u64 v[218:219], s[52:53], 0, v[130:131]
	s_mov_b32 m0, s69
	s_nop 0
	global_load_lds_dwordx4 v[218:219], off
	s_add_i32 s19, 0, 0x1c000
	v_add_u32_e32 v157, s19, v154
	ds_read_b128 v[218:221], v157
	ds_read_b128 v[222:225], v157 offset:1024
	ds_read_b128 v[226:229], v157 offset:2048
	ds_read_b128 v[230:233], v157 offset:3072
	s_waitcnt vmcnt(8)
	s_waitcnt lgkmcnt(0)
	s_barrier
	v_mfma_f32_16x16x32_bf16 v[124:127], v[146:149], v[170:173], v[124:127]
	v_mfma_f32_16x16x32_bf16 v[120:123], v[162:165], v[170:173], v[120:123]
	v_mfma_f32_16x16x32_bf16 v[116:119], v[146:149], v[178:181], v[116:119]
	v_mfma_f32_16x16x32_bf16 v[112:115], v[162:165], v[178:181], v[112:115]
	v_mfma_f32_16x16x32_bf16 v[108:111], v[146:149], v[194:197], v[108:111]
	v_mfma_f32_16x16x32_bf16 v[104:107], v[162:165], v[194:197], v[104:107]
	v_mfma_f32_16x16x32_bf16 v[100:103], v[146:149], v[210:213], v[100:103]
	v_mfma_f32_16x16x32_bf16 v[96:99], v[162:165], v[210:213], v[96:99]
	v_mfma_f32_16x16x32_bf16 v[124:127], v[158:161], v[174:177], v[124:127]
	v_mfma_f32_16x16x32_bf16 v[120:123], v[166:169], v[174:177], v[120:123]
	v_mfma_f32_16x16x32_bf16 v[116:119], v[158:161], v[182:185], v[116:119]
	v_mfma_f32_16x16x32_bf16 v[112:115], v[166:169], v[182:185], v[112:115]
	v_mfma_f32_16x16x32_bf16 v[108:111], v[158:161], v[206:209], v[108:111]
	v_mfma_f32_16x16x32_bf16 v[104:107], v[166:169], v[206:209], v[104:107]
	v_mfma_f32_16x16x32_bf16 v[100:103], v[158:161], v[214:217], v[100:103]
	v_mfma_f32_16x16x32_bf16 v[96:99], v[166:169], v[214:217], v[96:99]
	v_mfma_f32_16x16x32_bf16 v[92:95], v[218:221], v[170:173], v[92:95]
	v_mfma_f32_16x16x32_bf16 v[88:91], v[226:229], v[170:173], v[88:91]
	v_mfma_f32_16x16x32_bf16 v[84:87], v[218:221], v[178:181], v[84:87]
	v_mfma_f32_16x16x32_bf16 v[80:83], v[226:229], v[178:181], v[80:83]
	v_mfma_f32_16x16x32_bf16 v[76:79], v[218:221], v[194:197], v[76:79]
	v_mfma_f32_16x16x32_bf16 v[72:75], v[226:229], v[194:197], v[72:75]
	v_mfma_f32_16x16x32_bf16 v[68:71], v[218:221], v[210:213], v[68:71]
	v_mfma_f32_16x16x32_bf16 v[64:67], v[226:229], v[210:213], v[64:67]
	v_mfma_f32_16x16x32_bf16 v[92:95], v[222:225], v[174:177], v[92:95]
	v_mfma_f32_16x16x32_bf16 v[88:91], v[230:233], v[174:177], v[88:91]
	v_mfma_f32_16x16x32_bf16 v[84:87], v[222:225], v[182:185], v[84:87]
	v_mfma_f32_16x16x32_bf16 v[80:83], v[230:233], v[182:185], v[80:83]
	v_mfma_f32_16x16x32_bf16 v[76:79], v[222:225], v[206:209], v[76:79]
	v_mfma_f32_16x16x32_bf16 v[72:75], v[230:233], v[206:209], v[72:75]
	v_mfma_f32_16x16x32_bf16 v[68:71], v[222:225], v[214:217], v[68:71]
	v_mfma_f32_16x16x32_bf16 v[64:67], v[230:233], v[214:217], v[64:67]
	s_barrier
	s_add_i32 s6, s6, s57
	v_lshl_add_u64 v[234:235], v[234:235], 0, s[36:37]
	s_mov_b32 m0, s6
	s_nop 0
	global_load_lds_dwordx4 v[234:235], off
	v_lshl_add_u64 v[234:235], v[236:237], 0, s[36:37]
	s_add_i32 m0, s6, 0x2000
	s_nop 0
	global_load_lds_dwordx4 v[234:235], off
	s_mov_b32 m0, s71
	v_lshl_add_u64 v[234:235], v[238:239], 0, s[36:37]
	ds_read_b128 v[170:173], v156 offset:49152
	ds_read_b128 v[174:177], v156 offset:50176
	ds_read_b128 v[178:181], v156 offset:51200
	ds_read_b128 v[182:185], v156 offset:52224
	ds_read_b128 v[194:197], v156 offset:53248
	ds_read_b128 v[206:209], v156 offset:54272
	ds_read_b128 v[210:213], v156 offset:55296
	ds_read_b128 v[214:217], v156 offset:56320
	global_load_lds_dwordx4 v[234:235], off
	v_lshl_add_u64 v[234:235], v[240:241], 0, s[36:37]
	s_mov_b32 m0, s72
	s_nop 0
	global_load_lds_dwordx4 v[234:235], off
	s_add_u32 s50, s50, 0x40080
	s_addc_u32 s51, s51, 0
	s_add_i32 s6, s19, s57
	v_lshl_add_u64 v[250:251], s[50:51], 0, v[140:141]
	s_mov_b32 m0, s6
	s_nop 0
	global_load_lds_dwordx4 v[250:251], off
	v_lshl_add_u64 v[250:251], s[50:51], 0, v[132:133]
	s_add_i32 m0, s6, 0x2000
	s_nop 0
	global_load_lds_dwordx4 v[250:251], off
	s_add_i32 s75, s75, 2
	s_add_u32 s48, s48, 0x100
	s_addc_u32 s49, s49, 0
	s_cmp_gt_u32 s75, 13
	s_nop 0
	s_waitcnt vmcnt(8)
	s_waitcnt lgkmcnt(0)
	s_barrier
	v_mfma_f32_16x16x32_bf16 v[60:63], v[146:149], v[170:173], v[60:63]
	v_mfma_f32_16x16x32_bf16 v[56:59], v[162:165], v[170:173], v[56:59]
	v_mfma_f32_16x16x32_bf16 v[52:55], v[146:149], v[178:181], v[52:55]
	v_mfma_f32_16x16x32_bf16 v[48:51], v[162:165], v[178:181], v[48:51]
	v_mfma_f32_16x16x32_bf16 v[44:47], v[146:149], v[194:197], v[44:47]
	v_mfma_f32_16x16x32_bf16 v[40:43], v[162:165], v[194:197], v[40:43]
	v_mfma_f32_16x16x32_bf16 v[36:39], v[146:149], v[210:213], v[36:39]
	v_mfma_f32_16x16x32_bf16 v[32:35], v[162:165], v[210:213], v[32:35]
	v_mfma_f32_16x16x32_bf16 v[60:63], v[158:161], v[174:177], v[60:63]
	v_mfma_f32_16x16x32_bf16 v[56:59], v[166:169], v[174:177], v[56:59]
	v_mfma_f32_16x16x32_bf16 v[52:55], v[158:161], v[182:185], v[52:55]
	v_mfma_f32_16x16x32_bf16 v[48:51], v[166:169], v[182:185], v[48:51]
	v_mfma_f32_16x16x32_bf16 v[44:47], v[158:161], v[206:209], v[44:47]
	v_mfma_f32_16x16x32_bf16 v[40:43], v[166:169], v[206:209], v[40:43]
	v_mfma_f32_16x16x32_bf16 v[36:39], v[158:161], v[214:217], v[36:39]
	v_mfma_f32_16x16x32_bf16 v[32:35], v[166:169], v[214:217], v[32:35]
	v_mfma_f32_16x16x32_bf16 v[28:31], v[218:221], v[170:173], v[28:31]
	v_mfma_f32_16x16x32_bf16 v[24:27], v[226:229], v[170:173], v[24:27]
	v_mfma_f32_16x16x32_bf16 v[20:23], v[218:221], v[178:181], v[20:23]
	v_mfma_f32_16x16x32_bf16 v[16:19], v[226:229], v[178:181], v[16:19]
	v_mfma_f32_16x16x32_bf16 v[12:15], v[218:221], v[194:197], v[12:15]
	v_mfma_f32_16x16x32_bf16 v[8:11], v[226:229], v[194:197], v[8:11]
	v_mfma_f32_16x16x32_bf16 v[4:7], v[218:221], v[210:213], v[4:7]
	v_mfma_f32_16x16x32_bf16 v[0:3], v[226:229], v[210:213], v[0:3]
	v_mfma_f32_16x16x32_bf16 v[28:31], v[222:225], v[174:177], v[28:31]
	v_mfma_f32_16x16x32_bf16 v[24:27], v[230:233], v[174:177], v[24:27]
	v_mfma_f32_16x16x32_bf16 v[20:23], v[222:225], v[182:185], v[20:23]
	v_mfma_f32_16x16x32_bf16 v[16:19], v[230:233], v[182:185], v[16:19]
	v_mfma_f32_16x16x32_bf16 v[12:15], v[222:225], v[206:209], v[12:15]
	v_mfma_f32_16x16x32_bf16 v[8:11], v[230:233], v[206:209], v[8:11]
	v_mfma_f32_16x16x32_bf16 v[4:7], v[222:225], v[214:217], v[4:7]
	v_mfma_f32_16x16x32_bf16 v[0:3], v[230:233], v[214:217], v[0:3]
	s_barrier
	s_cbranch_scc0 .LBB0_315
	s_mov_b32 s100, 1
	s_setprio 1
	s_add_u32 s48, s11, 0xffffff00
	v_lshl_or_b32 v146, s70, 8, v155
	s_addc_u32 s49, s12, -1
	s_ashr_i32 s29, s28, 31
	v_ashrrev_i32_e32 v147, 31, v146
	v_lshl_add_u64 v[146:147], v[146:147], 1, s[26:27]
	s_lshl_b64 s[50:51], s[28:29], 20
	v_lshl_add_u64 v[146:147], v[146:147], 0, s[50:51]
	v_lshl_add_u64 v[150:151], v[146:147], 0, v[134:135]
	v_cvt_pk_bf16_f32 v146, v124, v125
	v_cvt_pk_bf16_f32 v147, v126, v127
	v_cvt_pk_bf16_f32 v148, v120, v121
	v_cvt_pk_bf16_f32 v149, v122, v123
	global_store_dwordx4 v[150:151], v[146:149], off
	v_add_co_u32_e32 v152, vcc, s66, v150
	s_nop 0
	v_cvt_pk_bf16_f32 v146, v92, v93
	v_cvt_pk_bf16_f32 v147, v94, v95
	v_cvt_pk_bf16_f32 v148, v88, v89
	v_cvt_pk_bf16_f32 v149, v90, v91
	global_store_dwordx4 v[150:151], v[146:149], off offset:256
	v_addc_co_u32_e32 v153, vcc, 0, v151, vcc
	s_nop 0
	v_cvt_pk_bf16_f32 v146, v116, v117
	v_cvt_pk_bf16_f32 v147, v118, v119
	v_cvt_pk_bf16_f32 v148, v112, v113
	v_cvt_pk_bf16_f32 v149, v114, v115
	global_store_dwordx4 v[152:153], v[146:149], off
	s_mov_b32 s6, 0x20000
	s_nop 0
	v_cvt_pk_bf16_f32 v146, v84, v85
	v_cvt_pk_bf16_f32 v147, v86, v87
	v_cvt_pk_bf16_f32 v148, v80, v81
	v_cvt_pk_bf16_f32 v149, v82, v83
	global_store_dwordx4 v[152:153], v[146:149], off offset:256
	v_add_co_u32_e32 v152, vcc, s6, v150
	s_nop 0
	v_cvt_pk_bf16_f32 v146, v108, v109
	v_cvt_pk_bf16_f32 v147, v110, v111
	v_cvt_pk_bf16_f32 v148, v104, v105
	v_cvt_pk_bf16_f32 v149, v106, v107
	v_addc_co_u32_e32 v153, vcc, 0, v151, vcc
	global_store_dwordx4 v[152:153], v[146:149], off
	s_mov_b32 s6, 0x30000
	s_nop 0
	v_cvt_pk_bf16_f32 v146, v76, v77
	v_cvt_pk_bf16_f32 v147, v78, v79
	v_cvt_pk_bf16_f32 v148, v72, v73
	v_cvt_pk_bf16_f32 v149, v74, v75
	global_store_dwordx4 v[152:153], v[146:149], off offset:256
	v_add_co_u32_e32 v152, vcc, s6, v150
	s_nop 0
	v_cvt_pk_bf16_f32 v146, v100, v101
	v_cvt_pk_bf16_f32 v147, v102, v103
	v_cvt_pk_bf16_f32 v148, v96, v97
	v_cvt_pk_bf16_f32 v149, v98, v99
	v_addc_co_u32_e32 v153, vcc, 0, v151, vcc
	global_store_dwordx4 v[152:153], v[146:149], off
	s_mov_b32 s6, 0x80000
	s_nop 0
	v_cvt_pk_bf16_f32 v146, v68, v69
	v_cvt_pk_bf16_f32 v147, v70, v71
	v_cvt_pk_bf16_f32 v148, v64, v65
	v_cvt_pk_bf16_f32 v149, v66, v67
	global_store_dwordx4 v[152:153], v[146:149], off offset:256
	v_add_co_u32_e32 v152, vcc, s6, v150
	s_nop 0
	v_cvt_pk_bf16_f32 v146, v60, v61
	v_cvt_pk_bf16_f32 v147, v62, v63
	v_cvt_pk_bf16_f32 v148, v56, v57
	v_cvt_pk_bf16_f32 v149, v58, v59
	v_addc_co_u32_e32 v153, vcc, 0, v151, vcc
	global_store_dwordx4 v[152:153], v[146:149], off
	s_mov_b32 s6, 0x90000
	s_nop 0
	v_cvt_pk_bf16_f32 v146, v28, v29
	v_cvt_pk_bf16_f32 v147, v30, v31
	v_cvt_pk_bf16_f32 v148, v24, v25
	v_cvt_pk_bf16_f32 v149, v26, v27
	global_store_dwordx4 v[152:153], v[146:149], off offset:256
	v_add_co_u32_e32 v152, vcc, s6, v150
	s_nop 0
	v_cvt_pk_bf16_f32 v146, v52, v53
	v_cvt_pk_bf16_f32 v147, v54, v55
	v_cvt_pk_bf16_f32 v148, v48, v49
	v_cvt_pk_bf16_f32 v149, v50, v51
	v_addc_co_u32_e32 v153, vcc, 0, v151, vcc
	global_store_dwordx4 v[152:153], v[146:149], off
	s_mov_b32 s6, 0xa0000
	s_nop 0
	v_cvt_pk_bf16_f32 v146, v20, v21
	v_cvt_pk_bf16_f32 v147, v22, v23
	v_cvt_pk_bf16_f32 v148, v16, v17
	v_cvt_pk_bf16_f32 v149, v18, v19
	global_store_dwordx4 v[152:153], v[146:149], off offset:256
	v_add_co_u32_e32 v152, vcc, s6, v150
	s_nop 0
	v_cvt_pk_bf16_f32 v146, v44, v45
	v_cvt_pk_bf16_f32 v147, v46, v47
	v_cvt_pk_bf16_f32 v148, v40, v41
	v_cvt_pk_bf16_f32 v149, v42, v43
	v_addc_co_u32_e32 v153, vcc, 0, v151, vcc
	s_mov_b32 s6, 0xb0000
	global_store_dwordx4 v[152:153], v[146:149], off
	v_add_co_u32_e32 v150, vcc, s6, v150
	s_nop 0
	v_cvt_pk_bf16_f32 v146, v12, v13
	v_cvt_pk_bf16_f32 v147, v14, v15
	v_cvt_pk_bf16_f32 v148, v8, v9
	v_cvt_pk_bf16_f32 v149, v10, v11
	global_store_dwordx4 v[152:153], v[146:149], off offset:256
	v_addc_co_u32_e32 v151, vcc, 0, v151, vcc
	s_nop 0
	v_cvt_pk_bf16_f32 v146, v36, v37
	v_cvt_pk_bf16_f32 v147, v38, v39
	v_cvt_pk_bf16_f32 v148, v32, v33
	v_cvt_pk_bf16_f32 v149, v34, v35
	global_store_dwordx4 v[150:151], v[146:149], off
	s_andn2_b64 vcc, exec, s[44:45]
	s_nop 0
	v_cvt_pk_bf16_f32 v146, v4, v5
	v_cvt_pk_bf16_f32 v147, v6, v7
	v_cvt_pk_bf16_f32 v148, v0, v1
	v_cvt_pk_bf16_f32 v149, v2, v3
	global_store_dwordx4 v[150:151], v[146:149], off offset:256
	s_cbranch_vccz .LBB0_307
	s_mov_b64 s[42:43], s[48:49]
	s_andn2_b64 vcc, exec, s[38:39]
	s_mov_b64 s[48:49], s[42:43]
	s_cbranch_vccnz .LBB0_308

.LBB0_341:
	s_add_u32 s46, s50, 0x100
	s_addc_u32 s47, s51, 0
	s_add_i32 s6, 0, 0x10000
	v_add_u32_e32 v146, s6, v206
	ds_read_b128 v[128:131], v146
	ds_read_b128 v[132:135], v146 offset:1024
	ds_read_b128 v[136:139], v146 offset:2048
	ds_read_b128 v[146:149], v146 offset:3072
	s_cmp_eq_u32 s12, 40
	s_cselect_b32 s53, s31, s47
	s_cselect_b32 s52, s30, s46
	s_cselect_b32 s49, s35, s11
	s_cselect_b32 s48, s34, s10
	v_lshl_add_u64 v[214:215], s[50:51], 0, v[158:159]
	s_add_i32 m0, s58, 0xc000
	ds_read_b128 v[162:165], v208
	ds_read_b128 v[166:169], v208 offset:1024
	ds_read_b128 v[170:173], v208 offset:2048
	ds_read_b128 v[174:177], v208 offset:3072
	ds_read_b128 v[178:181], v208 offset:4096
	ds_read_b128 v[182:185], v208 offset:5120
	ds_read_b128 v[194:197], v208 offset:6144
	ds_read_b128 v[210:213], v208 offset:7168
	global_load_lds_dwordx4 v[214:215], off
	v_lshl_add_u64 v[214:215], s[50:51], 0, v[160:161]
	s_add_i32 m0, s58, 0xe000
	s_nop 0
	global_load_lds_dwordx4 v[214:215], off
	s_add_i32 s19, 0, 0x14000
	v_add_u32_e32 v192, s19, v206
	ds_read_b128 v[214:217], v192
	ds_read_b128 v[218:221], v192 offset:1024
	ds_read_b128 v[222:225], v192 offset:2048
	ds_read_b128 v[226:229], v192 offset:3072
	s_nop 0
	s_waitcnt vmcnt(8)
	s_waitcnt lgkmcnt(0)
	s_barrier
	v_mfma_f32_16x16x32_bf16 v[124:127], v[128:131], v[162:165], v[124:127]
	v_mfma_f32_16x16x32_bf16 v[120:123], v[136:139], v[162:165], v[120:123]
	v_mfma_f32_16x16x32_bf16 v[108:111], v[128:131], v[170:173], v[108:111]
	v_mfma_f32_16x16x32_bf16 v[104:107], v[136:139], v[170:173], v[104:107]
	v_mfma_f32_16x16x32_bf16 v[96:99], v[128:131], v[178:181], v[96:99]
	v_mfma_f32_16x16x32_bf16 v[88:91], v[136:139], v[178:181], v[88:91]
	v_mfma_f32_16x16x32_bf16 v[84:87], v[128:131], v[194:197], v[84:87]
	v_mfma_f32_16x16x32_bf16 v[80:83], v[136:139], v[194:197], v[80:83]
	v_mfma_f32_16x16x32_bf16 v[124:127], v[132:135], v[166:169], v[124:127]
	v_mfma_f32_16x16x32_bf16 v[120:123], v[146:149], v[166:169], v[120:123]
	v_mfma_f32_16x16x32_bf16 v[108:111], v[132:135], v[174:177], v[108:111]
	v_mfma_f32_16x16x32_bf16 v[104:107], v[146:149], v[174:177], v[104:107]
	v_mfma_f32_16x16x32_bf16 v[96:99], v[132:135], v[182:185], v[96:99]
	v_mfma_f32_16x16x32_bf16 v[88:91], v[146:149], v[182:185], v[88:91]
	v_mfma_f32_16x16x32_bf16 v[84:87], v[132:135], v[210:213], v[84:87]
	v_mfma_f32_16x16x32_bf16 v[80:83], v[146:149], v[210:213], v[80:83]
	v_mfma_f32_16x16x32_bf16 v[116:119], v[214:217], v[162:165], v[116:119]
	v_mfma_f32_16x16x32_bf16 v[112:115], v[222:225], v[162:165], v[112:115]
	v_mfma_f32_16x16x32_bf16 v[100:103], v[214:217], v[170:173], v[100:103]
	v_mfma_f32_16x16x32_bf16 v[92:95], v[222:225], v[170:173], v[92:95]
	v_mfma_f32_16x16x32_bf16 v[76:79], v[214:217], v[178:181], v[76:79]
	v_mfma_f32_16x16x32_bf16 v[72:75], v[222:225], v[178:181], v[72:75]
	v_mfma_f32_16x16x32_bf16 v[68:71], v[214:217], v[194:197], v[68:71]
	v_mfma_f32_16x16x32_bf16 v[64:67], v[222:225], v[194:197], v[64:67]
	v_mfma_f32_16x16x32_bf16 v[116:119], v[218:221], v[166:169], v[116:119]
	v_mfma_f32_16x16x32_bf16 v[112:115], v[226:229], v[166:169], v[112:115]
	v_mfma_f32_16x16x32_bf16 v[100:103], v[218:221], v[174:177], v[100:103]
	v_mfma_f32_16x16x32_bf16 v[92:95], v[226:229], v[174:177], v[92:95]
	v_mfma_f32_16x16x32_bf16 v[76:79], v[218:221], v[182:185], v[76:79]
	v_mfma_f32_16x16x32_bf16 v[72:75], v[226:229], v[182:185], v[72:75]
	v_mfma_f32_16x16x32_bf16 v[68:71], v[218:221], v[210:213], v[68:71]
	v_mfma_f32_16x16x32_bf16 v[64:67], v[226:229], v[210:213], v[64:67]
	s_barrier
	s_add_i32 s6, s6, s57
	v_lshl_add_u64 v[230:231], s[48:49], 0, v[140:141]
	s_mov_b32 m0, s6
	s_nop 0
	global_load_lds_dwordx4 v[230:231], off
	v_lshl_add_u64 v[232:233], s[48:49], 0, v[150:151]
	s_add_i32 m0, s6, 0x2000
	s_nop 0
	global_load_lds_dwordx4 v[232:233], off
	s_mov_b32 m0, s58
	v_lshl_add_u64 v[234:235], s[52:53], 0, v[154:155]
	ds_read_b128 v[162:165], v208 offset:16384
	ds_read_b128 v[166:169], v208 offset:17408
	ds_read_b128 v[170:173], v208 offset:18432
	ds_read_b128 v[174:177], v208 offset:19456
	ds_read_b128 v[178:181], v208 offset:20480
	ds_read_b128 v[182:185], v208 offset:21504
	ds_read_b128 v[194:197], v208 offset:22528
	ds_read_b128 v[210:213], v208 offset:23552
	global_load_lds_dwordx4 v[234:235], off
	v_lshl_add_u64 v[236:237], s[52:53], 0, v[152:153]
	s_mov_b32 m0, s59
	s_nop 0
	global_load_lds_dwordx4 v[236:237], off
	s_add_u32 s50, s48, 0xb0000
	s_addc_u32 s51, s49, 0
	s_add_i32 s6, s19, s57
	v_lshl_add_u64 v[250:251], s[50:51], 0, v[140:141]
	s_mov_b32 m0, s6
	s_nop 0
	global_load_lds_dwordx4 v[250:251], off
	v_lshl_add_u64 v[250:251], s[50:51], 0, v[150:151]
	s_add_i32 m0, s6, 0x2000
	s_nop 0
	global_load_lds_dwordx4 v[250:251], off
	s_waitcnt vmcnt(8)
	s_waitcnt lgkmcnt(0)
	s_barrier
	v_mfma_f32_16x16x32_bf16 v[60:63], v[128:131], v[162:165], v[60:63]
	v_mfma_f32_16x16x32_bf16 v[56:59], v[136:139], v[162:165], v[56:59]
	v_mfma_f32_16x16x32_bf16 v[48:51], v[128:131], v[170:173], v[48:51]
	v_mfma_f32_16x16x32_bf16 v[40:43], v[136:139], v[170:173], v[40:43]
	v_mfma_f32_16x16x32_bf16 v[32:35], v[128:131], v[178:181], v[32:35]
	v_mfma_f32_16x16x32_bf16 v[24:27], v[136:139], v[178:181], v[24:27]
	v_mfma_f32_16x16x32_bf16 v[16:19], v[128:131], v[194:197], v[16:19]
	v_mfma_f32_16x16x32_bf16 v[8:11], v[136:139], v[194:197], v[8:11]
	v_mfma_f32_16x16x32_bf16 v[60:63], v[132:135], v[166:169], v[60:63]
	v_mfma_f32_16x16x32_bf16 v[56:59], v[146:149], v[166:169], v[56:59]
	v_mfma_f32_16x16x32_bf16 v[48:51], v[132:135], v[174:177], v[48:51]
	v_mfma_f32_16x16x32_bf16 v[40:43], v[146:149], v[174:177], v[40:43]
	v_mfma_f32_16x16x32_bf16 v[32:35], v[132:135], v[182:185], v[32:35]
	v_mfma_f32_16x16x32_bf16 v[24:27], v[146:149], v[182:185], v[24:27]
	v_mfma_f32_16x16x32_bf16 v[16:19], v[132:135], v[210:213], v[16:19]
	v_mfma_f32_16x16x32_bf16 v[8:11], v[146:149], v[210:213], v[8:11]
	v_mfma_f32_16x16x32_bf16 v[52:55], v[214:217], v[162:165], v[52:55]
	v_mfma_f32_16x16x32_bf16 v[44:47], v[222:225], v[162:165], v[44:47]
	v_mfma_f32_16x16x32_bf16 v[36:39], v[214:217], v[170:173], v[36:39]
	v_mfma_f32_16x16x32_bf16 v[28:31], v[222:225], v[170:173], v[28:31]
	v_mfma_f32_16x16x32_bf16 v[20:23], v[214:217], v[178:181], v[20:23]
	v_mfma_f32_16x16x32_bf16 v[12:15], v[222:225], v[178:181], v[12:15]
	v_mfma_f32_16x16x32_bf16 v[4:7], v[214:217], v[194:197], v[4:7]
	v_mfma_f32_16x16x32_bf16 v[0:3], v[222:225], v[194:197], v[0:3]
	v_mfma_f32_16x16x32_bf16 v[52:55], v[218:221], v[166:169], v[52:55]
	v_mfma_f32_16x16x32_bf16 v[44:47], v[226:229], v[166:169], v[44:47]
	v_mfma_f32_16x16x32_bf16 v[36:39], v[218:221], v[174:177], v[36:39]
	v_mfma_f32_16x16x32_bf16 v[28:31], v[226:229], v[174:177], v[28:31]
	v_mfma_f32_16x16x32_bf16 v[20:23], v[218:221], v[182:185], v[20:23]
	v_mfma_f32_16x16x32_bf16 v[12:15], v[226:229], v[182:185], v[12:15]
	v_mfma_f32_16x16x32_bf16 v[4:7], v[218:221], v[210:213], v[4:7]
	v_mfma_f32_16x16x32_bf16 v[0:3], v[226:229], v[210:213], v[0:3]
	s_barrier
	s_add_i32 s6, 0, 0x18000
	v_add_u32_e32 v146, s6, v206
	ds_read_b128 v[128:131], v146
	ds_read_b128 v[132:135], v146 offset:1024
	ds_read_b128 v[136:139], v146 offset:2048
	ds_read_b128 v[146:149], v146 offset:3072
	s_add_u32 s50, s52, 0xb0000
	s_addc_u32 s51, s53, 0
	s_mov_b32 m0, s68
	v_lshl_add_u64 v[214:215], s[50:51], 0, v[154:155]
	ds_read_b128 v[162:165], v208 offset:32768
	ds_read_b128 v[166:169], v208 offset:33792
	ds_read_b128 v[170:173], v208 offset:34816
	ds_read_b128 v[174:177], v208 offset:35840
	ds_read_b128 v[178:181], v208 offset:36864
	ds_read_b128 v[182:185], v208 offset:37888
	ds_read_b128 v[194:197], v208 offset:38912
	ds_read_b128 v[210:213], v208 offset:39936
	global_load_lds_dwordx4 v[214:215], off
	v_lshl_add_u64 v[214:215], s[50:51], 0, v[152:153]
	s_mov_b32 m0, s69
	s_nop 0
	global_load_lds_dwordx4 v[214:215], off
	s_add_i32 s19, 0, 0x1c000
	v_add_u32_e32 v192, s19, v206
	ds_read_b128 v[214:217], v192
	ds_read_b128 v[218:221], v192 offset:1024
	ds_read_b128 v[222:225], v192 offset:2048
	ds_read_b128 v[226:229], v192 offset:3072
	s_waitcnt vmcnt(8)
	s_waitcnt lgkmcnt(0)
	s_barrier
	v_mfma_f32_16x16x32_bf16 v[124:127], v[128:131], v[162:165], v[124:127]
	v_mfma_f32_16x16x32_bf16 v[120:123], v[136:139], v[162:165], v[120:123]
	v_mfma_f32_16x16x32_bf16 v[108:111], v[128:131], v[170:173], v[108:111]
	v_mfma_f32_16x16x32_bf16 v[104:107], v[136:139], v[170:173], v[104:107]
	v_mfma_f32_16x16x32_bf16 v[96:99], v[128:131], v[178:181], v[96:99]
	v_mfma_f32_16x16x32_bf16 v[88:91], v[136:139], v[178:181], v[88:91]
	v_mfma_f32_16x16x32_bf16 v[84:87], v[128:131], v[194:197], v[84:87]
	v_mfma_f32_16x16x32_bf16 v[80:83], v[136:139], v[194:197], v[80:83]
	v_mfma_f32_16x16x32_bf16 v[124:127], v[132:135], v[166:169], v[124:127]
	v_mfma_f32_16x16x32_bf16 v[120:123], v[146:149], v[166:169], v[120:123]
	v_mfma_f32_16x16x32_bf16 v[108:111], v[132:135], v[174:177], v[108:111]
	v_mfma_f32_16x16x32_bf16 v[104:107], v[146:149], v[174:177], v[104:107]
	v_mfma_f32_16x16x32_bf16 v[96:99], v[132:135], v[182:185], v[96:99]
	v_mfma_f32_16x16x32_bf16 v[88:91], v[146:149], v[182:185], v[88:91]
	v_mfma_f32_16x16x32_bf16 v[84:87], v[132:135], v[210:213], v[84:87]
	v_mfma_f32_16x16x32_bf16 v[80:83], v[146:149], v[210:213], v[80:83]
	v_mfma_f32_16x16x32_bf16 v[116:119], v[214:217], v[162:165], v[116:119]
	v_mfma_f32_16x16x32_bf16 v[112:115], v[222:225], v[162:165], v[112:115]
	v_mfma_f32_16x16x32_bf16 v[100:103], v[214:217], v[170:173], v[100:103]
	v_mfma_f32_16x16x32_bf16 v[92:95], v[222:225], v[170:173], v[92:95]
	v_mfma_f32_16x16x32_bf16 v[76:79], v[214:217], v[178:181], v[76:79]
	v_mfma_f32_16x16x32_bf16 v[72:75], v[222:225], v[178:181], v[72:75]
	v_mfma_f32_16x16x32_bf16 v[68:71], v[214:217], v[194:197], v[68:71]
	v_mfma_f32_16x16x32_bf16 v[64:67], v[222:225], v[194:197], v[64:67]
	v_mfma_f32_16x16x32_bf16 v[116:119], v[218:221], v[166:169], v[116:119]
	v_mfma_f32_16x16x32_bf16 v[112:115], v[226:229], v[166:169], v[112:115]
	v_mfma_f32_16x16x32_bf16 v[100:103], v[218:221], v[174:177], v[100:103]
	v_mfma_f32_16x16x32_bf16 v[92:95], v[226:229], v[174:177], v[92:95]
	v_mfma_f32_16x16x32_bf16 v[76:79], v[218:221], v[182:185], v[76:79]
	v_mfma_f32_16x16x32_bf16 v[72:75], v[226:229], v[182:185], v[72:75]
	v_mfma_f32_16x16x32_bf16 v[68:71], v[218:221], v[210:213], v[68:71]
	v_mfma_f32_16x16x32_bf16 v[64:67], v[226:229], v[210:213], v[64:67]
	s_barrier
	s_add_i32 s6, s6, s57
	v_lshl_add_u64 v[230:231], v[230:231], 0, s[36:37]
	s_mov_b32 m0, s6
	s_nop 0
	global_load_lds_dwordx4 v[230:231], off
	v_lshl_add_u64 v[230:231], v[232:233], 0, s[36:37]
	s_add_i32 m0, s6, 0x2000
	s_nop 0
	global_load_lds_dwordx4 v[230:231], off
	s_mov_b32 m0, s70
	v_lshl_add_u64 v[230:231], v[234:235], 0, s[36:37]
	ds_read_b128 v[162:165], v208 offset:49152
	ds_read_b128 v[166:169], v208 offset:50176
	ds_read_b128 v[170:173], v208 offset:51200
	ds_read_b128 v[174:177], v208 offset:52224
	ds_read_b128 v[178:181], v208 offset:53248
	ds_read_b128 v[182:185], v208 offset:54272
	ds_read_b128 v[194:197], v208 offset:55296
	ds_read_b128 v[210:213], v208 offset:56320
	global_load_lds_dwordx4 v[230:231], off
	v_lshl_add_u64 v[230:231], v[236:237], 0, s[36:37]
	s_mov_b32 m0, s71
	s_nop 0
	global_load_lds_dwordx4 v[230:231], off
	s_add_u32 s48, s48, 0xb0080
	s_addc_u32 s49, s49, 0
	s_add_i32 s6, s19, s57
	v_lshl_add_u64 v[250:251], s[48:49], 0, v[140:141]
	s_mov_b32 m0, s6
	s_nop 0
	global_load_lds_dwordx4 v[250:251], off
	v_lshl_add_u64 v[250:251], s[48:49], 0, v[150:151]
	s_add_i32 m0, s6, 0x2000
	s_nop 0
	global_load_lds_dwordx4 v[250:251], off
	s_add_i32 s12, s12, 2
	s_add_u32 s10, s10, 0x100
	s_addc_u32 s11, s11, 0
	s_cmp_gt_u32 s12, 41
	s_mov_b64 s[50:51], s[46:47]
	s_waitcnt vmcnt(8)
	s_waitcnt lgkmcnt(0)
	s_barrier
	v_mfma_f32_16x16x32_bf16 v[60:63], v[128:131], v[162:165], v[60:63]
	v_mfma_f32_16x16x32_bf16 v[56:59], v[136:139], v[162:165], v[56:59]
	v_mfma_f32_16x16x32_bf16 v[48:51], v[128:131], v[170:173], v[48:51]
	v_mfma_f32_16x16x32_bf16 v[40:43], v[136:139], v[170:173], v[40:43]
	v_mfma_f32_16x16x32_bf16 v[32:35], v[128:131], v[178:181], v[32:35]
	v_mfma_f32_16x16x32_bf16 v[24:27], v[136:139], v[178:181], v[24:27]
	v_mfma_f32_16x16x32_bf16 v[16:19], v[128:131], v[194:197], v[16:19]
	v_mfma_f32_16x16x32_bf16 v[8:11], v[136:139], v[194:197], v[8:11]
	v_mfma_f32_16x16x32_bf16 v[60:63], v[132:135], v[166:169], v[60:63]
	v_mfma_f32_16x16x32_bf16 v[56:59], v[146:149], v[166:169], v[56:59]
	v_mfma_f32_16x16x32_bf16 v[48:51], v[132:135], v[174:177], v[48:51]
	v_mfma_f32_16x16x32_bf16 v[40:43], v[146:149], v[174:177], v[40:43]
	v_mfma_f32_16x16x32_bf16 v[32:35], v[132:135], v[182:185], v[32:35]
	v_mfma_f32_16x16x32_bf16 v[24:27], v[146:149], v[182:185], v[24:27]
	v_mfma_f32_16x16x32_bf16 v[16:19], v[132:135], v[210:213], v[16:19]
	v_mfma_f32_16x16x32_bf16 v[8:11], v[146:149], v[210:213], v[8:11]
	v_mfma_f32_16x16x32_bf16 v[52:55], v[214:217], v[162:165], v[52:55]
	v_mfma_f32_16x16x32_bf16 v[44:47], v[222:225], v[162:165], v[44:47]
	v_mfma_f32_16x16x32_bf16 v[36:39], v[214:217], v[170:173], v[36:39]
	v_mfma_f32_16x16x32_bf16 v[28:31], v[222:225], v[170:173], v[28:31]
	v_mfma_f32_16x16x32_bf16 v[20:23], v[214:217], v[178:181], v[20:23]
	v_mfma_f32_16x16x32_bf16 v[12:15], v[222:225], v[178:181], v[12:15]
	v_mfma_f32_16x16x32_bf16 v[4:7], v[214:217], v[194:197], v[4:7]
	v_mfma_f32_16x16x32_bf16 v[0:3], v[222:225], v[194:197], v[0:3]
	v_mfma_f32_16x16x32_bf16 v[52:55], v[218:221], v[166:169], v[52:55]
	v_mfma_f32_16x16x32_bf16 v[44:47], v[226:229], v[166:169], v[44:47]
	v_mfma_f32_16x16x32_bf16 v[36:39], v[218:221], v[174:177], v[36:39]
	v_mfma_f32_16x16x32_bf16 v[28:31], v[226:229], v[174:177], v[28:31]
	v_mfma_f32_16x16x32_bf16 v[20:23], v[218:221], v[182:185], v[20:23]
	v_mfma_f32_16x16x32_bf16 v[12:15], v[226:229], v[182:185], v[12:15]
	v_mfma_f32_16x16x32_bf16 v[4:7], v[218:221], v[210:213], v[4:7]
	v_mfma_f32_16x16x32_bf16 v[0:3], v[226:229], v[210:213], v[0:3]
	s_barrier
	s_cbranch_scc0 .LBB0_341
	s_mov_b32 s100, 1
	s_setprio 1
	s_ashr_i32 s39, s38, 31
	v_lshl_or_b32 v128, s81, 8, v207
	s_lshl_b64 s[10:11], s[38:39], 8
	v_ashrrev_i32_e32 v129, 31, v128
	v_lshl_add_u64 v[168:169], s[10:11], 0, v[156:157]
	v_lshlrev_b64 v[170:171], 1, v[128:129]
	v_lshl_add_u64 v[174:175], s[26:27], 0, v[170:171]
	v_lshlrev_b64 v[172:173], 11, v[168:169]
	v_lshl_add_u64 v[128:129], v[174:175], 0, v[172:173]
	global_load_dwordx4 v[182:185], v[128:129], off
	global_load_dwordx4 v[210:213], v[128:129], off offset:256
	v_or_b32_e32 v166, 16, v168
	v_mov_b32_e32 v167, v169
	v_lshlrev_b64 v[176:177], 11, v[166:167]
	v_lshl_add_u64 v[128:129], v[174:175], 0, v[176:177]
	global_load_dwordx4 v[214:217], v[128:129], off
	global_load_dwordx4 v[218:221], v[128:129], off offset:256
	v_or_b32_e32 v164, 32, v168
	v_mov_b32_e32 v165, v169
	v_or_b32_e32 v162, 48, v168
	v_mov_b32_e32 v163, v169
	v_lshlrev_b64 v[180:181], 11, v[164:165]
	v_lshlrev_b64 v[178:179], 11, v[162:163]
	v_lshl_add_u64 v[128:129], v[174:175], 0, v[180:181]
	v_lshl_add_u64 v[130:131], v[174:175], 0, v[178:179]
	global_load_dwordx4 v[222:225], v[128:129], off
	global_load_dwordx4 v[136:139], v[128:129], off offset:256
	global_load_dwordx4 v[132:135], v[130:131], off
	s_nop 0
	global_load_dwordx4 v[128:131], v[130:131], off offset:256
	s_mov_b64 s[10:11], 0x90
	v_lshl_add_u64 v[172:173], s[28:29], 0, v[172:173]
	v_lshl_add_u64 v[172:173], v[172:173], 0, v[170:171]
	s_waitcnt vmcnt(0)
	v_lshlrev_b32_e32 v146, 16, v182
	v_and_b32_e32 v147, 0xffff0000, v182
	v_lshlrev_b32_e32 v148, 16, v184
	v_and_b32_e32 v149, 0xffff0000, v184
	v_lshlrev_b32_e32 v182, 16, v183
	v_and_b32_e32 v183, 0xffff0000, v183
	v_lshlrev_b32_e32 v194, 16, v210
	v_and_b32_e32 v195, 0xffff0000, v210
	v_lshlrev_b32_e32 v196, 16, v212
	v_and_b32_e32 v197, 0xffff0000, v212
	v_lshlrev_b32_e32 v210, 16, v211
	v_and_b32_e32 v211, 0xffff0000, v211
	v_lshlrev_b32_e32 v212, 16, v213
	v_and_b32_e32 v213, 0xffff0000, v213
	v_pk_fma_f32 v[124:125], v[124:125], 0.5, v[146:147] op_sel_hi:[1,0,1]
	v_pk_fma_f32 v[120:121], v[120:121], 0.5, v[148:149] op_sel_hi:[1,0,1]
	v_pk_fma_f32 v[126:127], v[126:127], 0.5, v[182:183] op_sel_hi:[1,0,1]
	v_pk_fma_f32 v[116:117], v[116:117], 0.5, v[194:195] op_sel_hi:[1,0,1]
	v_pk_fma_f32 v[146:147], v[112:113], 0.5, v[196:197] op_sel_hi:[1,0,1]
	v_pk_fma_f32 v[118:119], v[118:119], 0.5, v[210:211] op_sel_hi:[1,0,1]
	v_pk_fma_f32 v[148:149], v[114:115], 0.5, v[212:213] op_sel_hi:[1,0,1]
	v_pk_mul_f32 v[212:213], v[124:125], v[124:125]
	v_lshlrev_b32_e32 v182, 16, v214
	v_and_b32_e32 v183, 0xffff0000, v214
	v_lshlrev_b32_e32 v194, 16, v215
	v_and_b32_e32 v195, 0xffff0000, v215
	v_pk_mul_f32 v[214:215], v[126:127], v[126:127]
	v_cvt_pk_bf16_f32 v112, v124, v125
	v_cvt_pk_bf16_f32 v113, v126, v127
	v_pk_mul_f32 v[124:125], v[116:117], v[116:117]
	v_pk_mul_f32 v[126:127], v[118:119], v[118:119]
	v_pk_mul_f32 v[228:229], v[146:147], v[146:147]
	v_cvt_pk_bf16_f32 v116, v116, v117
	v_cvt_pk_bf16_f32 v117, v118, v119
	v_cvt_pk_bf16_f32 v118, v146, v147
	v_add_f32_e32 v146, v212, v213
	v_lshlrev_b32_e32 v184, 16, v185
	v_and_b32_e32 v185, 0xffff0000, v185
	v_add_f32_e32 v146, v214, v146
	v_pk_fma_f32 v[122:123], v[122:123], 0.5, v[184:185] op_sel_hi:[1,0,1]
	v_lshlrev_b32_e32 v184, 16, v216
	v_and_b32_e32 v185, 0xffff0000, v216
	v_lshlrev_b32_e32 v196, 16, v217
	v_and_b32_e32 v197, 0xffff0000, v217
	v_pk_mul_f32 v[216:217], v[120:121], v[120:121]
	v_add_f32_e32 v146, v215, v146
	v_add_f32_e32 v146, v216, v146
	v_pk_mul_f32 v[226:227], v[122:123], v[122:123]
	v_add_f32_e32 v146, v217, v146
	v_add_f32_e32 v146, v226, v146
	v_add_f32_e32 v146, v227, v146
	v_add_f32_e32 v124, v124, v146
	v_add_f32_e32 v124, v125, v124
	v_add_f32_e32 v124, v126, v124
	v_add_f32_e32 v124, v127, v124
	v_add_f32_e32 v124, v228, v124
	v_pk_mul_f32 v[230:231], v[148:149], v[148:149]
	v_add_f32_e32 v124, v229, v124
	v_add_f32_e32 v124, v230, v124
	v_add_f32_e32 v209, v231, v124
	v_lshlrev_b32_e32 v124, 16, v220
	v_and_b32_e32 v125, 0xffff0000, v220
	v_pk_fma_f32 v[124:125], v[92:93], 0.5, v[124:125] op_sel_hi:[1,0,1]
	v_lshlrev_b32_e32 v92, 16, v219
	v_and_b32_e32 v93, 0xffff0000, v219
	v_pk_fma_f32 v[102:103], v[102:103], 0.5, v[92:93] op_sel_hi:[1,0,1]
	v_lshlrev_b32_e32 v92, 16, v221
	v_and_b32_e32 v93, 0xffff0000, v221
	v_pk_fma_f32 v[126:127], v[94:95], 0.5, v[92:93] op_sel_hi:[1,0,1]
	v_lshlrev_b32_e32 v92, 16, v222
	v_and_b32_e32 v93, 0xffff0000, v222
	v_pk_fma_f32 v[92:93], v[96:97], 0.5, v[92:93] op_sel_hi:[1,0,1]
	v_lshlrev_b32_e32 v96, 16, v225
	v_and_b32_e32 v97, 0xffff0000, v225
	v_lshlrev_b32_e32 v94, 16, v224
	v_and_b32_e32 v95, 0xffff0000, v224
	v_pk_fma_f32 v[90:91], v[90:91], 0.5, v[96:97] op_sel_hi:[1,0,1]
	v_lshlrev_b32_e32 v96, 16, v136
	v_and_b32_e32 v97, 0xffff0000, v136
	v_pk_fma_f32 v[88:89], v[88:89], 0.5, v[94:95] op_sel_hi:[1,0,1]
	v_lshlrev_b32_e32 v94, 16, v223
	v_and_b32_e32 v95, 0xffff0000, v223
	v_pk_fma_f32 v[96:97], v[76:77], 0.5, v[96:97] op_sel_hi:[1,0,1]
	v_lshl_add_u64 v[76:77], v[168:169], 0, s[36:37]
	v_cvt_pk_bf16_f32 v114, v120, v121
	v_pk_fma_f32 v[120:121], v[108:109], 0.5, v[182:183] op_sel_hi:[1,0,1]
	v_pk_fma_f32 v[94:95], v[98:99], 0.5, v[94:95] op_sel_hi:[1,0,1]
	v_lshlrev_b64 v[182:183], 11, v[76:77]
	v_lshlrev_b32_e32 v98, 16, v138
	v_and_b32_e32 v99, 0xffff0000, v138
	v_lshl_add_u64 v[146:147], v[174:175], 0, v[182:183]
	v_pk_fma_f32 v[98:99], v[72:73], 0.5, v[98:99] op_sel_hi:[1,0,1]
	v_lshlrev_b32_e32 v72, 16, v137
	v_and_b32_e32 v73, 0xffff0000, v137
	v_lshlrev_b32_e32 v210, 16, v218
	v_and_b32_e32 v211, 0xffff0000, v218
	global_load_dwordx4 v[218:221], v[146:147], off
	global_load_dwordx4 v[226:229], v[146:147], off offset:256
	v_pk_fma_f32 v[136:137], v[78:79], 0.5, v[72:73] op_sel_hi:[1,0,1]
	v_lshlrev_b32_e32 v72, 16, v139
	v_and_b32_e32 v73, 0xffff0000, v139
	v_pk_fma_f32 v[138:139], v[74:75], 0.5, v[72:73] op_sel_hi:[1,0,1]
	v_lshlrev_b32_e32 v72, 16, v132
	v_and_b32_e32 v73, 0xffff0000, v132
	v_pk_fma_f32 v[74:75], v[84:85], 0.5, v[72:73] op_sel_hi:[1,0,1]
	v_lshlrev_b32_e32 v72, 16, v134
	v_and_b32_e32 v73, 0xffff0000, v134
	v_pk_fma_f32 v[78:79], v[80:81], 0.5, v[72:73] op_sel_hi:[1,0,1]
	v_lshlrev_b32_e32 v72, 16, v133
	v_and_b32_e32 v73, 0xffff0000, v133
	v_pk_fma_f32 v[80:81], v[86:87], 0.5, v[72:73] op_sel_hi:[1,0,1]
	v_lshlrev_b32_e32 v72, 16, v135
	v_and_b32_e32 v73, 0xffff0000, v135
	v_pk_fma_f32 v[82:83], v[82:83], 0.5, v[72:73] op_sel_hi:[1,0,1]
	v_lshl_add_u64 v[72:73], v[168:169], 0, s[10:11]
	v_lshlrev_b64 v[132:133], 11, v[72:73]
	v_lshl_add_u64 v[134:135], v[174:175], 0, v[132:133]
	global_load_dwordx4 v[234:237], v[134:135], off
	global_load_dwordx4 v[242:245], v[134:135], off offset:256
	v_lshlrev_b32_e32 v84, 16, v128
	v_and_b32_e32 v85, 0xffff0000, v128
	v_pk_fma_f32 v[84:85], v[68:69], 0.5, v[84:85] op_sel_hi:[1,0,1]
	v_lshlrev_b32_e32 v68, 16, v130
	v_and_b32_e32 v69, 0xffff0000, v130
	v_pk_fma_f32 v[86:87], v[64:65], 0.5, v[68:69] op_sel_hi:[1,0,1]
	v_lshlrev_b32_e32 v64, 16, v129
	v_and_b32_e32 v65, 0xffff0000, v129
	s_mov_b64 s[10:11], 0xa0
	v_pk_fma_f32 v[128:129], v[70:71], 0.5, v[64:65] op_sel_hi:[1,0,1]
	v_lshl_add_u64 v[70:71], v[168:169], 0, s[10:11]
	v_lshlrev_b32_e32 v64, 16, v131
	v_and_b32_e32 v65, 0xffff0000, v131
	v_lshlrev_b64 v[134:135], 11, v[70:71]
	v_pk_fma_f32 v[130:131], v[66:67], 0.5, v[64:65] op_sel_hi:[1,0,1]
	v_lshl_add_u64 v[64:65], v[174:175], 0, v[134:135]
	v_cvt_pk_bf16_f32 v115, v122, v123
	v_pk_fma_f32 v[122:123], v[110:111], 0.5, v[194:195] op_sel_hi:[1,0,1]
	v_pk_fma_f32 v[110:111], v[106:107], 0.5, v[196:197] op_sel_hi:[1,0,1]
	global_load_dwordx4 v[246:249], v[64:65], off
	global_load_dwordx4 v[194:197], v[64:65], off offset:256
	s_mov_b64 s[10:11], 0xb0
	v_lshl_add_u64 v[68:69], v[168:169], 0, s[10:11]
	v_pk_fma_f32 v[108:109], v[104:105], 0.5, v[184:185] op_sel_hi:[1,0,1]
	v_lshlrev_b64 v[184:185], 11, v[68:69]
	v_lshl_add_u64 v[64:65], v[174:175], 0, v[184:185]
	v_cvt_pk_bf16_f32 v119, v148, v149
	global_load_dwordx4 v[146:149], v[64:65], off
	s_nop 0
	global_load_dwordx4 v[64:67], v[64:65], off offset:256
	global_store_dwordx4 v[172:173], v[112:115], off
	global_store_dwordx4 v[172:173], v[116:119], off offset:256
	v_cvt_pk_bf16_f32 v104, v120, v121
	v_lshl_add_u64 v[112:113], s[28:29], 0, v[176:177]
	v_cvt_pk_bf16_f32 v105, v122, v123
	v_cvt_pk_bf16_f32 v106, v108, v109
	v_cvt_pk_bf16_f32 v107, v110, v111
	v_pk_fma_f32 v[100:101], v[100:101], 0.5, v[210:211] op_sel_hi:[1,0,1]
	v_lshl_add_u64 v[112:113], v[112:113], 0, v[170:171]
	v_cvt_pk_bf16_f32 v210, v100, v101
	v_cvt_pk_bf16_f32 v211, v102, v103
	v_cvt_pk_bf16_f32 v212, v124, v125
	v_cvt_pk_bf16_f32 v213, v126, v127
	global_store_dwordx4 v[112:113], v[104:107], off
	global_store_dwordx4 v[112:113], v[210:213], off offset:256
	v_cvt_pk_bf16_f32 v214, v92, v93
	v_lshl_add_u64 v[104:105], s[28:29], 0, v[180:181]
	v_cvt_pk_bf16_f32 v215, v94, v95
	v_cvt_pk_bf16_f32 v216, v88, v89
	v_cvt_pk_bf16_f32 v217, v90, v91
	v_lshl_add_u64 v[104:105], v[104:105], 0, v[170:171]
	v_cvt_pk_bf16_f32 v222, v96, v97
	v_cvt_pk_bf16_f32 v223, v136, v137
	v_cvt_pk_bf16_f32 v224, v98, v99
	v_cvt_pk_bf16_f32 v225, v138, v139
	global_store_dwordx4 v[104:105], v[214:217], off
	global_store_dwordx4 v[104:105], v[222:225], off offset:256
	v_lshl_add_u64 v[104:105], s[28:29], 0, v[178:179]
	v_cvt_pk_bf16_f32 v230, v74, v75
	v_cvt_pk_bf16_f32 v231, v80, v81
	v_cvt_pk_bf16_f32 v232, v78, v79
	v_cvt_pk_bf16_f32 v233, v82, v83
	v_lshl_add_u64 v[104:105], v[104:105], 0, v[170:171]
	v_cvt_pk_bf16_f32 v238, v84, v85
	v_cvt_pk_bf16_f32 v239, v128, v129
	v_cvt_pk_bf16_f32 v240, v86, v87
	v_cvt_pk_bf16_f32 v241, v130, v131
	global_store_dwordx4 v[104:105], v[230:233], off
	global_store_dwordx4 v[104:105], v[238:241], off offset:256
	s_waitcnt vmcnt(8)
	v_lshlrev_b32_e32 v104, 16, v218
	v_and_b32_e32 v105, 0xffff0000, v218
	v_pk_fma_f32 v[60:61], v[60:61], 0.5, v[104:105] op_sel_hi:[1,0,1]
	v_lshlrev_b32_e32 v104, 16, v220
	v_and_b32_e32 v105, 0xffff0000, v220
	v_pk_fma_f32 v[56:57], v[56:57], 0.5, v[104:105] op_sel_hi:[1,0,1]
	v_lshlrev_b32_e32 v104, 16, v219
	v_and_b32_e32 v105, 0xffff0000, v219
	v_pk_fma_f32 v[62:63], v[62:63], 0.5, v[104:105] op_sel_hi:[1,0,1]
	v_lshlrev_b32_e32 v104, 16, v221
	v_and_b32_e32 v105, 0xffff0000, v221
	v_pk_fma_f32 v[58:59], v[58:59], 0.5, v[104:105] op_sel_hi:[1,0,1]
	v_lshlrev_b32_e32 v104, 16, v226
	v_and_b32_e32 v105, 0xffff0000, v226
	v_pk_fma_f32 v[52:53], v[52:53], 0.5, v[104:105] op_sel_hi:[1,0,1]
	v_lshlrev_b32_e32 v104, 16, v228
	v_and_b32_e32 v105, 0xffff0000, v228
	v_pk_fma_f32 v[104:105], v[44:45], 0.5, v[104:105] op_sel_hi:[1,0,1]
	v_lshlrev_b32_e32 v44, 16, v227
	v_and_b32_e32 v45, 0xffff0000, v227
	v_pk_fma_f32 v[54:55], v[54:55], 0.5, v[44:45] op_sel_hi:[1,0,1]
	v_lshlrev_b32_e32 v44, 16, v229
	v_and_b32_e32 v45, 0xffff0000, v229
	v_pk_fma_f32 v[106:107], v[46:47], 0.5, v[44:45] op_sel_hi:[1,0,1]
	v_lshlrev_b32_e32 v44, 16, v234
	v_and_b32_e32 v45, 0xffff0000, v234
	v_pk_fma_f32 v[44:45], v[48:49], 0.5, v[44:45] op_sel_hi:[1,0,1]
	v_lshlrev_b32_e32 v48, 16, v237
	v_and_b32_e32 v49, 0xffff0000, v237
	v_pk_fma_f32 v[42:43], v[42:43], 0.5, v[48:49] op_sel_hi:[1,0,1]
	v_lshlrev_b32_e32 v48, 16, v242
	v_and_b32_e32 v49, 0xffff0000, v242
	v_pk_fma_f32 v[36:37], v[36:37], 0.5, v[48:49] op_sel_hi:[1,0,1]
	v_lshlrev_b32_e32 v48, 16, v244
	v_and_b32_e32 v49, 0xffff0000, v244
	v_lshlrev_b32_e32 v46, 16, v236
	v_and_b32_e32 v47, 0xffff0000, v236
	v_pk_fma_f32 v[48:49], v[28:29], 0.5, v[48:49] op_sel_hi:[1,0,1]
	v_lshlrev_b32_e32 v28, 16, v243
	v_and_b32_e32 v29, 0xffff0000, v243
	v_pk_fma_f32 v[40:41], v[40:41], 0.5, v[46:47] op_sel_hi:[1,0,1]
	v_lshlrev_b32_e32 v46, 16, v235
	v_and_b32_e32 v47, 0xffff0000, v235
	v_pk_fma_f32 v[38:39], v[38:39], 0.5, v[28:29] op_sel_hi:[1,0,1]
	v_lshlrev_b32_e32 v28, 16, v245
	v_and_b32_e32 v29, 0xffff0000, v245
	v_pk_fma_f32 v[46:47], v[50:51], 0.5, v[46:47] op_sel_hi:[1,0,1]
	v_pk_fma_f32 v[50:51], v[30:31], 0.5, v[28:29] op_sel_hi:[1,0,1]
	v_lshlrev_b32_e32 v28, 16, v246
	v_and_b32_e32 v29, 0xffff0000, v246
	v_pk_fma_f32 v[28:29], v[32:33], 0.5, v[28:29] op_sel_hi:[1,0,1]
	v_lshlrev_b32_e32 v32, 16, v249
	v_and_b32_e32 v33, 0xffff0000, v249
	v_pk_fma_f32 v[26:27], v[26:27], 0.5, v[32:33] op_sel_hi:[1,0,1]
	v_lshlrev_b32_e32 v32, 16, v194
	v_and_b32_e32 v33, 0xffff0000, v194
	v_pk_fma_f32 v[20:21], v[20:21], 0.5, v[32:33] op_sel_hi:[1,0,1]
	v_lshlrev_b32_e32 v32, 16, v196
	v_and_b32_e32 v33, 0xffff0000, v196
	v_lshlrev_b32_e32 v30, 16, v248
	v_and_b32_e32 v31, 0xffff0000, v248
	v_pk_fma_f32 v[32:33], v[12:13], 0.5, v[32:33] op_sel_hi:[1,0,1]
	v_lshlrev_b32_e32 v12, 16, v195
	v_and_b32_e32 v13, 0xffff0000, v195
	v_pk_fma_f32 v[24:25], v[24:25], 0.5, v[30:31] op_sel_hi:[1,0,1]
	v_lshlrev_b32_e32 v30, 16, v247
	v_and_b32_e32 v31, 0xffff0000, v247
	v_pk_fma_f32 v[22:23], v[22:23], 0.5, v[12:13] op_sel_hi:[1,0,1]
	v_lshlrev_b32_e32 v12, 16, v197
	v_and_b32_e32 v13, 0xffff0000, v197
	v_pk_fma_f32 v[30:31], v[34:35], 0.5, v[30:31] op_sel_hi:[1,0,1]
	v_pk_fma_f32 v[34:35], v[14:15], 0.5, v[12:13] op_sel_hi:[1,0,1]
	v_lshlrev_b32_e32 v14, 16, v148
	v_and_b32_e32 v15, 0xffff0000, v148
	v_lshlrev_b32_e32 v12, 16, v146
	v_and_b32_e32 v13, 0xffff0000, v146
	v_pk_fma_f32 v[8:9], v[8:9], 0.5, v[14:15] op_sel_hi:[1,0,1]
	v_lshlrev_b32_e32 v14, 16, v147
	v_and_b32_e32 v15, 0xffff0000, v147
	v_lshlrev_b32_e32 v146, 16, v64
	v_and_b32_e32 v147, 0xffff0000, v64
	v_pk_fma_f32 v[4:5], v[4:5], 0.5, v[146:147] op_sel_hi:[1,0,1]
	v_lshlrev_b32_e32 v146, 16, v66
	v_and_b32_e32 v147, 0xffff0000, v66
	v_pk_fma_f32 v[0:1], v[0:1], 0.5, v[146:147] op_sel_hi:[1,0,1]
	v_lshl_add_u64 v[146:147], s[28:29], 0, v[182:183]
	v_cvt_pk_bf16_f32 v112, v60, v61
	v_cvt_pk_bf16_f32 v113, v62, v63
	v_cvt_pk_bf16_f32 v114, v56, v57
	v_cvt_pk_bf16_f32 v115, v58, v59
	v_lshl_add_u64 v[146:147], v[146:147], 0, v[170:171]
	v_cvt_pk_bf16_f32 v116, v52, v53
	v_cvt_pk_bf16_f32 v117, v54, v55
	v_cvt_pk_bf16_f32 v118, v104, v105
	v_cvt_pk_bf16_f32 v119, v106, v107
	global_store_dwordx4 v[146:147], v[112:115], off
	global_store_dwordx4 v[146:147], v[116:119], off offset:256
	v_cvt_pk_bf16_f32 v172, v44, v45
	v_lshl_add_u64 v[112:113], s[28:29], 0, v[132:133]
	v_cvt_pk_bf16_f32 v173, v46, v47
	v_cvt_pk_bf16_f32 v174, v40, v41
	v_cvt_pk_bf16_f32 v175, v42, v43
	v_lshl_add_u64 v[112:113], v[112:113], 0, v[170:171]
	v_cvt_pk_bf16_f32 v176, v36, v37
	v_cvt_pk_bf16_f32 v177, v38, v39
	v_cvt_pk_bf16_f32 v178, v48, v49
	v_cvt_pk_bf16_f32 v179, v50, v51
	global_store_dwordx4 v[112:113], v[172:175], off
	global_store_dwordx4 v[112:113], v[176:179], off offset:256
	v_lshl_add_u64 v[112:113], s[28:29], 0, v[134:135]
	v_cvt_pk_bf16_f32 v210, v28, v29
	v_cvt_pk_bf16_f32 v211, v30, v31
	v_cvt_pk_bf16_f32 v212, v24, v25
	v_cvt_pk_bf16_f32 v213, v26, v27
	v_pk_fma_f32 v[12:13], v[16:17], 0.5, v[12:13] op_sel_hi:[1,0,1]
	v_lshlrev_b32_e32 v16, 16, v149
	v_and_b32_e32 v17, 0xffff0000, v149
	v_lshlrev_b32_e32 v64, 16, v65
	v_and_b32_e32 v65, 0xffff0000, v65
	v_lshl_add_u64 v[112:113], v[112:113], 0, v[170:171]
	v_cvt_pk_bf16_f32 v194, v20, v21
	v_cvt_pk_bf16_f32 v195, v22, v23
	v_cvt_pk_bf16_f32 v196, v32, v33
	v_cvt_pk_bf16_f32 v197, v34, v35
	v_pk_fma_f32 v[14:15], v[18:19], 0.5, v[14:15] op_sel_hi:[1,0,1]
	v_pk_fma_f32 v[10:11], v[10:11], 0.5, v[16:17] op_sel_hi:[1,0,1]
	v_pk_fma_f32 v[6:7], v[6:7], 0.5, v[64:65] op_sel_hi:[1,0,1]
	v_lshlrev_b32_e32 v64, 16, v67
	v_and_b32_e32 v65, 0xffff0000, v67
	global_store_dwordx4 v[112:113], v[210:213], off
	global_store_dwordx4 v[112:113], v[194:197], off offset:256
	v_lshl_add_u64 v[112:113], s[28:29], 0, v[184:185]
	v_cvt_pk_bf16_f32 v16, v12, v13
	v_cvt_pk_bf16_f32 v17, v14, v15
	v_cvt_pk_bf16_f32 v18, v8, v9
	v_cvt_pk_bf16_f32 v19, v10, v11
	v_pk_fma_f32 v[2:3], v[2:3], 0.5, v[64:65] op_sel_hi:[1,0,1]
	v_lshl_add_u64 v[112:113], v[112:113], 0, v[170:171]
	v_cvt_pk_bf16_f32 v64, v4, v5
	v_cvt_pk_bf16_f32 v65, v6, v7
	v_cvt_pk_bf16_f32 v66, v0, v1
	v_cvt_pk_bf16_f32 v67, v2, v3
	global_store_dwordx4 v[112:113], v[16:19], off
	global_store_dwordx4 v[112:113], v[64:67], off offset:256
	s_lshl_b32 s10, s81, 2
	v_and_b32_e32 v17, 64, v188
	v_xor_b32_e32 v16, 16, v188
	v_add_u32_e32 v17, 64, v17
	v_cmp_lt_i32_e32 vcc, v16, v17
	v_xor_b32_e32 v18, 32, v188
	s_ashr_i32 s11, s10, 31
	v_cndmask_b32_e32 v16, v188, v16, vcc
	v_lshlrev_b32_e32 v16, 2, v16
	v_mov_b32_e32 v132, v209
	v_cmp_lt_i32_e32 vcc, v18, v17
	s_lshl_b64 s[10:11], s[10:11], 2
	s_add_u32 s38, s73, s10
	v_cndmask_b32_e32 v17, v188, v18, vcc
	v_lshlrev_b32_e32 v17, 2, v17
	s_addc_u32 s39, s74, s11
	v_pk_mul_f32 v[18:19], v[120:121], v[120:121]
	v_pk_mul_f32 v[64:65], v[122:123], v[122:123]
	v_add_f32_e32 v18, v18, v19
	v_add_f32_e32 v18, v64, v18
	v_pk_mul_f32 v[66:67], v[108:109], v[108:109]
	v_add_f32_e32 v18, v65, v18
	v_add_f32_e32 v18, v66, v18
	v_pk_mul_f32 v[108:109], v[110:111], v[110:111]
	v_add_f32_e32 v18, v67, v18
	v_add_f32_e32 v18, v108, v18
	v_pk_mul_f32 v[100:101], v[100:101], v[100:101]
	v_add_f32_e32 v18, v109, v18
	v_add_f32_e32 v18, v100, v18
	v_pk_mul_f32 v[102:103], v[102:103], v[102:103]
	v_add_f32_e32 v18, v101, v18
	v_add_f32_e32 v18, v102, v18
	v_pk_mul_f32 v[110:111], v[124:125], v[124:125]
	v_add_f32_e32 v18, v103, v18
	v_add_f32_e32 v18, v110, v18
	v_pk_mul_f32 v[112:113], v[126:127], v[126:127]
	v_add_f32_e32 v18, v111, v18
	v_add_f32_e32 v18, v112, v18
	v_add_f32_e32 v18, v113, v18
	v_mov_b32_e32 v133, v18
	v_pk_mul_f32 v[18:19], v[92:93], v[92:93]
	v_pk_mul_f32 v[64:65], v[94:95], v[94:95]
	v_add_f32_e32 v18, v18, v19
	v_add_f32_e32 v18, v64, v18
	v_pk_mul_f32 v[66:67], v[88:89], v[88:89]
	v_add_f32_e32 v18, v65, v18
	v_add_f32_e32 v18, v66, v18
	v_pk_mul_f32 v[88:89], v[90:91], v[90:91]
	v_add_f32_e32 v18, v67, v18
	v_add_f32_e32 v18, v88, v18
	v_pk_mul_f32 v[90:91], v[96:97], v[96:97]
	v_add_f32_e32 v18, v89, v18
	v_add_f32_e32 v18, v90, v18
	v_pk_mul_f32 v[92:93], v[136:137], v[136:137]
	v_add_f32_e32 v18, v91, v18
	v_add_f32_e32 v18, v92, v18
	v_pk_mul_f32 v[94:95], v[98:99], v[98:99]
	v_add_f32_e32 v18, v93, v18
	v_add_f32_e32 v18, v94, v18
	v_pk_mul_f32 v[96:97], v[138:139], v[138:139]
	v_add_f32_e32 v18, v95, v18
	v_add_f32_e32 v18, v96, v18
	v_add_f32_e32 v18, v97, v18
	v_mov_b32_e32 v134, v18
	v_pk_mul_f32 v[18:19], v[74:75], v[74:75]
	v_pk_mul_f32 v[180:181], v[60:61], v[60:61]
	v_pk_mul_f32 v[64:65], v[80:81], v[80:81]
	v_pk_mul_f32 v[60:61], v[62:63], v[62:63]
	v_add_f32_e32 v18, v18, v19
	v_add_f32_e32 v180, v180, v181
	v_add_f32_e32 v18, v64, v18
	v_add_f32_e32 v180, v60, v180
	v_pk_mul_f32 v[66:67], v[78:79], v[78:79]
	v_pk_mul_f32 v[56:57], v[56:57], v[56:57]
	v_add_f32_e32 v18, v65, v18
	v_add_f32_e32 v180, v61, v180
	v_add_f32_e32 v18, v66, v18
	v_add_f32_e32 v180, v56, v180
	v_pk_mul_f32 v[74:75], v[82:83], v[82:83]
	v_pk_mul_f32 v[58:59], v[58:59], v[58:59]
	v_add_f32_e32 v18, v67, v18
	v_add_f32_e32 v180, v57, v180
	v_add_f32_e32 v18, v74, v18
	v_add_f32_e32 v180, v58, v180
	v_pk_mul_f32 v[78:79], v[84:85], v[84:85]
	v_pk_mul_f32 v[52:53], v[52:53], v[52:53]
	v_add_f32_e32 v18, v75, v18
	v_add_f32_e32 v180, v59, v180
	v_add_f32_e32 v18, v78, v18
	v_add_f32_e32 v180, v52, v180
	v_pk_mul_f32 v[80:81], v[128:129], v[128:129]
	v_pk_mul_f32 v[54:55], v[54:55], v[54:55]
	v_add_f32_e32 v18, v79, v18
	v_add_f32_e32 v180, v53, v180
	v_add_f32_e32 v18, v80, v18
	v_add_f32_e32 v180, v54, v180
	v_pk_mul_f32 v[82:83], v[86:87], v[86:87]
	v_pk_mul_f32 v[62:63], v[104:105], v[104:105]
	v_add_f32_e32 v18, v81, v18
	v_add_f32_e32 v180, v55, v180
	v_add_f32_e32 v18, v82, v18
	v_add_f32_e32 v180, v62, v180
	v_pk_mul_f32 v[84:85], v[130:131], v[130:131]
	v_pk_mul_f32 v[182:183], v[106:107], v[106:107]
	v_add_f32_e32 v18, v83, v18
	v_add_f32_e32 v180, v63, v180
	v_add_f32_e32 v18, v84, v18
	v_add_f32_e32 v180, v182, v180
	v_add_f32_e32 v18, v85, v18
	v_add_f32_e32 v180, v183, v180
	v_mov_b32_e32 v135, v18
	v_mov_b32_e32 v146, v180
	v_pk_mul_f32 v[18:19], v[44:45], v[44:45]
	v_pk_mul_f32 v[180:181], v[28:29], v[28:29]
	v_pk_mul_f32 v[44:45], v[46:47], v[46:47]
	v_pk_mul_f32 v[28:29], v[30:31], v[30:31]
	v_add_f32_e32 v18, v18, v19
	v_add_f32_e32 v180, v180, v181
	v_add_f32_e32 v18, v44, v18
	v_add_f32_e32 v180, v28, v180
	v_pk_mul_f32 v[40:41], v[40:41], v[40:41]
	v_pk_mul_f32 v[24:25], v[24:25], v[24:25]
	v_add_f32_e32 v18, v45, v18
	v_add_f32_e32 v180, v29, v180
	v_add_f32_e32 v18, v40, v18
	v_add_f32_e32 v180, v24, v180
	v_pk_mul_f32 v[42:43], v[42:43], v[42:43]
	v_pk_mul_f32 v[26:27], v[26:27], v[26:27]
	v_add_f32_e32 v18, v41, v18
	v_add_f32_e32 v180, v25, v180
	v_add_f32_e32 v18, v42, v18
	v_add_f32_e32 v180, v26, v180
	v_pk_mul_f32 v[36:37], v[36:37], v[36:37]
	v_pk_mul_f32 v[20:21], v[20:21], v[20:21]
	v_add_f32_e32 v18, v43, v18
	v_add_f32_e32 v180, v27, v180
	v_add_f32_e32 v18, v36, v18
	v_add_f32_e32 v180, v20, v180
	v_pk_mul_f32 v[38:39], v[38:39], v[38:39]
	v_pk_mul_f32 v[22:23], v[22:23], v[22:23]
	v_add_f32_e32 v18, v37, v18
	v_add_f32_e32 v180, v21, v180
	v_add_f32_e32 v18, v38, v18
	v_add_f32_e32 v180, v22, v180
	v_pk_mul_f32 v[46:47], v[48:49], v[48:49]
	v_pk_mul_f32 v[30:31], v[32:33], v[32:33]
	v_add_f32_e32 v18, v39, v18
	v_add_f32_e32 v180, v23, v180
	v_add_f32_e32 v18, v46, v18
	v_add_f32_e32 v180, v30, v180
	v_pk_mul_f32 v[48:49], v[50:51], v[50:51]
	v_pk_mul_f32 v[32:33], v[34:35], v[34:35]
	v_add_f32_e32 v18, v47, v18
	v_add_f32_e32 v180, v31, v180
	v_add_f32_e32 v18, v48, v18
	v_add_f32_e32 v180, v32, v180
	v_add_f32_e32 v18, v49, v18
	v_add_f32_e32 v180, v33, v180
	v_mov_b32_e32 v147, v18
	v_mov_b32_e32 v148, v180
	v_pk_mul_f32 v[12:13], v[12:13], v[12:13]
	v_pk_mul_f32 v[14:15], v[14:15], v[14:15]
	v_add_f32_e32 v12, v12, v13
	v_add_f32_e32 v12, v14, v12
	v_pk_mul_f32 v[8:9], v[8:9], v[8:9]
	v_add_f32_e32 v12, v15, v12
	v_add_f32_e32 v8, v8, v12
	v_pk_mul_f32 v[10:11], v[10:11], v[10:11]
	v_add_f32_e32 v8, v9, v8
	v_add_f32_e32 v8, v10, v8
	v_pk_mul_f32 v[4:5], v[4:5], v[4:5]
	v_add_f32_e32 v8, v11, v8
	v_add_f32_e32 v4, v4, v8
	v_pk_mul_f32 v[6:7], v[6:7], v[6:7]
	v_add_f32_e32 v4, v5, v4
	v_add_f32_e32 v4, v6, v4
	v_pk_mul_f32 v[0:1], v[0:1], v[0:1]
	v_add_f32_e32 v4, v7, v4
	v_add_f32_e32 v0, v0, v4
	v_pk_mul_f32 v[2:3], v[2:3], v[2:3]
	v_add_f32_e32 v0, v1, v0
	v_add_f32_e32 v0, v2, v0
	v_add_f32_e32 v0, v3, v0
	v_mov_b32_e32 v149, v0
	ds_bpermute_b32 v172, v16, v132
	ds_bpermute_b32 v173, v16, v133
	ds_bpermute_b32 v174, v16, v134
	ds_bpermute_b32 v175, v16, v135
	ds_bpermute_b32 v176, v16, v146
	ds_bpermute_b32 v177, v16, v147
	ds_bpermute_b32 v178, v16, v148
	ds_bpermute_b32 v179, v16, v149
	s_waitcnt lgkmcnt(0)
	v_add_f32_e32 v132, v132, v172
	v_add_f32_e32 v133, v133, v173
	v_add_f32_e32 v134, v134, v174
	v_add_f32_e32 v135, v135, v175
	v_add_f32_e32 v146, v146, v176
	v_add_f32_e32 v147, v147, v177
	v_add_f32_e32 v148, v148, v178
	v_add_f32_e32 v149, v149, v179
	ds_bpermute_b32 v172, v17, v132
	ds_bpermute_b32 v173, v17, v133
	ds_bpermute_b32 v174, v17, v134
	ds_bpermute_b32 v175, v17, v135
	ds_bpermute_b32 v176, v17, v146
	ds_bpermute_b32 v177, v17, v147
	ds_bpermute_b32 v178, v17, v148
	ds_bpermute_b32 v179, v17, v149
	s_and_saveexec_b64 s[46:47], s[42:43]
	s_cbranch_execz .LBB0_329
	s_waitcnt lgkmcnt(0)
	v_add_f32_e32 v132, v132, v172
	v_lshlrev_b64 v[18:19], 6, v[168:169]
	v_lshl_add_u64 v[18:19], s[38:39], 0, v[18:19]
	global_store_dword v[18:19], v132, off
	v_add_f32_e32 v133, v133, v173
	v_lshlrev_b64 v[18:19], 6, v[166:167]
	v_lshl_add_u64 v[18:19], s[38:39], 0, v[18:19]
	global_store_dword v[18:19], v133, off
	v_add_f32_e32 v134, v134, v174
	v_lshlrev_b64 v[18:19], 6, v[164:165]
	v_lshl_add_u64 v[18:19], s[38:39], 0, v[18:19]
	global_store_dword v[18:19], v134, off
	v_add_f32_e32 v135, v135, v175
	v_lshlrev_b64 v[18:19], 6, v[162:163]
	v_lshl_add_u64 v[18:19], s[38:39], 0, v[18:19]
	global_store_dword v[18:19], v135, off
	v_add_f32_e32 v146, v146, v176
	v_lshlrev_b64 v[18:19], 6, v[76:77]
	v_lshl_add_u64 v[18:19], s[38:39], 0, v[18:19]
	global_store_dword v[18:19], v146, off
	v_add_f32_e32 v147, v147, v177
	v_lshlrev_b64 v[18:19], 6, v[72:73]
	v_lshl_add_u64 v[18:19], s[38:39], 0, v[18:19]
	global_store_dword v[18:19], v147, off
	v_add_f32_e32 v148, v148, v178
	v_lshlrev_b64 v[18:19], 6, v[70:71]
	v_lshl_add_u64 v[18:19], s[38:39], 0, v[18:19]
	global_store_dword v[18:19], v148, off
	v_add_f32_e32 v149, v149, v179
	v_lshlrev_b64 v[18:19], 6, v[68:69]
	v_lshl_add_u64 v[18:19], s[38:39], 0, v[18:19]
	global_store_dword v[18:19], v149, off
	s_branch .LBB0_329

.LBB0_385:
	s_add_u32 s10, s52, 0x100
	s_addc_u32 s11, s53, 0
	s_ashr_i32 s39, s38, 31
	s_lshl_b64 s[48:49], s[38:39], 19
	s_add_u32 s50, s33, s48
	s_addc_u32 s51, s41, s49
	s_and_b64 s[48:49], s[44:45], exec
	s_cselect_b32 s12, s51, s29
	s_cselect_b32 s35, s50, s28
	s_ashr_i32 s47, s46, 31
	s_lshl_b64 s[48:49], s[46:47], 19
	s_add_u32 s48, s26, s48
	s_addc_u32 s49, s27, s49
	s_and_b64 s[54:55], s[44:45], exec
	s_cselect_b32 s39, s49, s53
	s_cselect_b32 s47, s48, s52
	s_add_u32 s52, s28, 0x40080
	s_addc_u32 s53, s29, 0
	v_lshl_add_u64 v[150:151], s[52:53], 0, v[136:137]
	v_lshl_add_u64 v[152:153], s[52:53], 0, v[138:139]
	s_mov_b32 s81, -2
	s_mov_b64 s[52:53], 0
	s_add_u32 s6, s28, s52
	s_addc_u32 s19, s29, s53
	s_add_u32 s6, s6, 0x100
	s_addc_u32 s19, s19, 0
	s_add_u32 s23, s10, s52
	s_addc_u32 s54, s11, s53
	s_add_i32 s82, 0, 0x10000
	v_add_u32_e32 v146, s82, v154
	ds_read_b128 v[158:161], v146
	ds_read_b128 v[162:165], v146 offset:1024
	ds_read_b128 v[166:169], v146 offset:2048
	ds_read_b128 v[170:173], v146 offset:3072
	s_cmpk_eq_i32 s52, 0x700
	s_cselect_b32 s59, s12, s19
	s_cselect_b32 s58, s35, s6
	s_cselect_b32 s55, s39, s54
	s_cselect_b32 s54, s47, s23
	v_lshl_add_u64 v[146:147], v[150:151], 0, s[52:53]
	s_add_i32 m0, s68, 0xc000
	ds_read_b128 v[174:177], v157
	ds_read_b128 v[178:181], v157 offset:1024
	ds_read_b128 v[182:185], v157 offset:2048
	ds_read_b128 v[206:209], v157 offset:3072
	ds_read_b128 v[210:213], v157 offset:4096
	ds_read_b128 v[214:217], v157 offset:5120
	ds_read_b128 v[218:221], v157 offset:6144
	ds_read_b128 v[222:225], v157 offset:7168
	global_load_lds_dwordx4 v[146:147], off
	v_lshl_add_u64 v[146:147], v[152:153], 0, s[52:53]
	s_add_i32 m0, s68, 0xe000
	s_nop 0
	global_load_lds_dwordx4 v[146:147], off
	s_add_i32 s6, 0, 0x14000
	v_add_u32_e32 v146, s6, v154
	ds_read_b128 v[226:229], v146
	ds_read_b128 v[230:233], v146 offset:1024
	ds_read_b128 v[234:237], v146 offset:2048
	ds_read_b128 v[238:241], v146 offset:3072
	s_setprio 0
	s_waitcnt vmcnt(16)
	s_cmp_lg_u32 s100, 0
	s_cbranch_scc1 .Lm4ap_386
	s_waitcnt vmcnt(8)

.LBB0_386:
	s_add_u32 s6, s28, s52
	s_addc_u32 s19, s29, s53
	s_add_u32 s6, s6, 0x100
	s_addc_u32 s19, s19, 0
	s_add_u32 s23, s10, s52
	s_addc_u32 s54, s11, s53
	s_add_i32 s82, 0, 0x10000
	v_add_u32_e32 v146, s82, v154
	ds_read_b128 v[158:161], v146
	ds_read_b128 v[162:165], v146 offset:1024
	ds_read_b128 v[166:169], v146 offset:2048
	ds_read_b128 v[170:173], v146 offset:3072
	s_cmpk_eq_i32 s52, 0x700
	s_cselect_b32 s59, s12, s19
	s_cselect_b32 s58, s35, s6
	s_cselect_b32 s55, s39, s54
	s_cselect_b32 s54, s47, s23
	v_lshl_add_u64 v[146:147], v[150:151], 0, s[52:53]
	s_add_i32 m0, s68, 0xc000
	ds_read_b128 v[174:177], v157
	ds_read_b128 v[178:181], v157 offset:1024
	ds_read_b128 v[182:185], v157 offset:2048
	ds_read_b128 v[206:209], v157 offset:3072
	ds_read_b128 v[210:213], v157 offset:4096
	ds_read_b128 v[214:217], v157 offset:5120
	ds_read_b128 v[218:221], v157 offset:6144
	ds_read_b128 v[222:225], v157 offset:7168
	global_load_lds_dwordx4 v[146:147], off
	v_lshl_add_u64 v[146:147], v[152:153], 0, s[52:53]
	s_add_i32 m0, s68, 0xe000
	s_nop 0
	global_load_lds_dwordx4 v[146:147], off
	s_add_i32 s6, 0, 0x14000
	v_add_u32_e32 v146, s6, v154
	ds_read_b128 v[226:229], v146
	ds_read_b128 v[230:233], v146 offset:1024
	ds_read_b128 v[234:237], v146 offset:2048
	ds_read_b128 v[238:241], v146 offset:3072
	s_nop 0
	s_waitcnt vmcnt(8)
	s_waitcnt lgkmcnt(0)
	s_barrier
	v_mfma_f32_16x16x32_bf16 v[124:127], v[158:161], v[174:177], v[124:127]
	v_mfma_f32_16x16x32_bf16 v[120:123], v[166:169], v[174:177], v[120:123]
	v_mfma_f32_16x16x32_bf16 v[116:119], v[158:161], v[182:185], v[116:119]
	v_mfma_f32_16x16x32_bf16 v[112:115], v[166:169], v[182:185], v[112:115]
	v_mfma_f32_16x16x32_bf16 v[108:111], v[158:161], v[210:213], v[108:111]
	v_mfma_f32_16x16x32_bf16 v[104:107], v[166:169], v[210:213], v[104:107]
	v_mfma_f32_16x16x32_bf16 v[100:103], v[158:161], v[218:221], v[100:103]
	v_mfma_f32_16x16x32_bf16 v[96:99], v[166:169], v[218:221], v[96:99]
	v_mfma_f32_16x16x32_bf16 v[124:127], v[162:165], v[178:181], v[124:127]
	v_mfma_f32_16x16x32_bf16 v[120:123], v[170:173], v[178:181], v[120:123]
	v_mfma_f32_16x16x32_bf16 v[116:119], v[162:165], v[206:209], v[116:119]
	v_mfma_f32_16x16x32_bf16 v[112:115], v[170:173], v[206:209], v[112:115]
	v_mfma_f32_16x16x32_bf16 v[108:111], v[162:165], v[214:217], v[108:111]
	v_mfma_f32_16x16x32_bf16 v[104:107], v[170:173], v[214:217], v[104:107]
	v_mfma_f32_16x16x32_bf16 v[100:103], v[162:165], v[222:225], v[100:103]
	v_mfma_f32_16x16x32_bf16 v[96:99], v[170:173], v[222:225], v[96:99]
	v_mfma_f32_16x16x32_bf16 v[92:95], v[226:229], v[174:177], v[92:95]
	v_mfma_f32_16x16x32_bf16 v[88:91], v[234:237], v[174:177], v[88:91]
	v_mfma_f32_16x16x32_bf16 v[84:87], v[226:229], v[182:185], v[84:87]
	v_mfma_f32_16x16x32_bf16 v[80:83], v[234:237], v[182:185], v[80:83]
	v_mfma_f32_16x16x32_bf16 v[76:79], v[226:229], v[210:213], v[76:79]
	v_mfma_f32_16x16x32_bf16 v[72:75], v[234:237], v[210:213], v[72:75]
	v_mfma_f32_16x16x32_bf16 v[68:71], v[226:229], v[218:221], v[68:71]
	v_mfma_f32_16x16x32_bf16 v[64:67], v[234:237], v[218:221], v[64:67]
	v_mfma_f32_16x16x32_bf16 v[92:95], v[230:233], v[178:181], v[92:95]
	v_mfma_f32_16x16x32_bf16 v[88:91], v[238:241], v[178:181], v[88:91]
	v_mfma_f32_16x16x32_bf16 v[84:87], v[230:233], v[206:209], v[84:87]
	v_mfma_f32_16x16x32_bf16 v[80:83], v[238:241], v[206:209], v[80:83]
	v_mfma_f32_16x16x32_bf16 v[76:79], v[230:233], v[214:217], v[76:79]
	v_mfma_f32_16x16x32_bf16 v[72:75], v[238:241], v[214:217], v[72:75]
	v_mfma_f32_16x16x32_bf16 v[68:71], v[230:233], v[222:225], v[68:71]
	v_mfma_f32_16x16x32_bf16 v[64:67], v[238:241], v[222:225], v[64:67]
	s_barrier
	s_add_i32 s19, s82, s57
	v_lshl_add_u64 v[146:147], s[54:55], 0, v[140:141]
	s_mov_b32 m0, s19
	v_lshl_add_u64 v[148:149], s[54:55], 0, v[132:133]
	global_load_lds_dwordx4 v[146:147], off
	s_add_i32 m0, s19, 0x2000
	s_nop 0
	global_load_lds_dwordx4 v[148:149], off
	s_mov_b32 m0, s68
	v_lshl_add_u64 v[194:195], s[58:59], 0, v[128:129]
	ds_read_b128 v[174:177], v157 offset:16384
	ds_read_b128 v[178:181], v157 offset:17408
	ds_read_b128 v[182:185], v157 offset:18432
	ds_read_b128 v[206:209], v157 offset:19456
	ds_read_b128 v[210:213], v157 offset:20480
	ds_read_b128 v[214:217], v157 offset:21504
	ds_read_b128 v[218:221], v157 offset:22528
	ds_read_b128 v[222:225], v157 offset:23552
	global_load_lds_dwordx4 v[194:195], off
	v_lshl_add_u64 v[196:197], s[58:59], 0, v[130:131]
	s_mov_b32 m0, s69
	s_nop 0
	global_load_lds_dwordx4 v[196:197], off
	s_add_u32 s82, s54, 0x40000
	s_addc_u32 s83, s55, 0
	s_add_i32 s6, s6, s57
	v_lshl_add_u64 v[250:251], s[82:83], 0, v[140:141]
	s_mov_b32 m0, s6
	s_nop 0
	global_load_lds_dwordx4 v[250:251], off
	v_lshl_add_u64 v[250:251], s[82:83], 0, v[132:133]
	s_add_i32 m0, s6, 0x2000
	s_nop 0
	global_load_lds_dwordx4 v[250:251], off
	s_nop 0
	s_waitcnt vmcnt(8)
	s_waitcnt lgkmcnt(0)
	s_barrier
	v_mfma_f32_16x16x32_bf16 v[60:63], v[158:161], v[174:177], v[60:63]
	v_mfma_f32_16x16x32_bf16 v[56:59], v[166:169], v[174:177], v[56:59]
	v_mfma_f32_16x16x32_bf16 v[52:55], v[158:161], v[182:185], v[52:55]
	v_mfma_f32_16x16x32_bf16 v[48:51], v[166:169], v[182:185], v[48:51]
	v_mfma_f32_16x16x32_bf16 v[44:47], v[158:161], v[210:213], v[44:47]
	v_mfma_f32_16x16x32_bf16 v[40:43], v[166:169], v[210:213], v[40:43]
	v_mfma_f32_16x16x32_bf16 v[36:39], v[158:161], v[218:221], v[36:39]
	v_mfma_f32_16x16x32_bf16 v[32:35], v[166:169], v[218:221], v[32:35]
	v_mfma_f32_16x16x32_bf16 v[60:63], v[162:165], v[178:181], v[60:63]
	v_mfma_f32_16x16x32_bf16 v[56:59], v[170:173], v[178:181], v[56:59]
	v_mfma_f32_16x16x32_bf16 v[52:55], v[162:165], v[206:209], v[52:55]
	v_mfma_f32_16x16x32_bf16 v[48:51], v[170:173], v[206:209], v[48:51]
	v_mfma_f32_16x16x32_bf16 v[44:47], v[162:165], v[214:217], v[44:47]
	v_mfma_f32_16x16x32_bf16 v[40:43], v[170:173], v[214:217], v[40:43]
	v_mfma_f32_16x16x32_bf16 v[36:39], v[162:165], v[222:225], v[36:39]
	v_mfma_f32_16x16x32_bf16 v[32:35], v[170:173], v[222:225], v[32:35]
	v_mfma_f32_16x16x32_bf16 v[28:31], v[226:229], v[174:177], v[28:31]
	v_mfma_f32_16x16x32_bf16 v[24:27], v[234:237], v[174:177], v[24:27]
	v_mfma_f32_16x16x32_bf16 v[20:23], v[226:229], v[182:185], v[20:23]
	v_mfma_f32_16x16x32_bf16 v[16:19], v[234:237], v[182:185], v[16:19]
	v_mfma_f32_16x16x32_bf16 v[12:15], v[226:229], v[210:213], v[12:15]
	v_mfma_f32_16x16x32_bf16 v[8:11], v[234:237], v[210:213], v[8:11]
	v_mfma_f32_16x16x32_bf16 v[4:7], v[226:229], v[218:221], v[4:7]
	v_mfma_f32_16x16x32_bf16 v[0:3], v[234:237], v[218:221], v[0:3]
	v_mfma_f32_16x16x32_bf16 v[28:31], v[230:233], v[178:181], v[28:31]
	v_mfma_f32_16x16x32_bf16 v[24:27], v[238:241], v[178:181], v[24:27]
	v_mfma_f32_16x16x32_bf16 v[20:23], v[230:233], v[206:209], v[20:23]
	v_mfma_f32_16x16x32_bf16 v[16:19], v[238:241], v[206:209], v[16:19]
	v_mfma_f32_16x16x32_bf16 v[12:15], v[230:233], v[214:217], v[12:15]
	v_mfma_f32_16x16x32_bf16 v[8:11], v[238:241], v[214:217], v[8:11]
	v_mfma_f32_16x16x32_bf16 v[4:7], v[230:233], v[222:225], v[4:7]
	v_mfma_f32_16x16x32_bf16 v[0:3], v[238:241], v[222:225], v[0:3]
	s_barrier
	s_add_i32 s6, 0, 0x18000
	v_add_u32_e32 v170, s6, v154
	ds_read_b128 v[158:161], v170
	ds_read_b128 v[162:165], v170 offset:1024
	ds_read_b128 v[166:169], v170 offset:2048
	ds_read_b128 v[170:173], v170 offset:3072
	s_add_u32 s58, s58, 0x40000
	s_addc_u32 s59, s59, 0
	s_mov_b32 m0, s70
	v_lshl_add_u64 v[226:227], s[58:59], 0, v[128:129]
	ds_read_b128 v[174:177], v157 offset:32768
	ds_read_b128 v[178:181], v157 offset:33792
	ds_read_b128 v[182:185], v157 offset:34816
	ds_read_b128 v[206:209], v157 offset:35840
	ds_read_b128 v[210:213], v157 offset:36864
	ds_read_b128 v[214:217], v157 offset:37888
	ds_read_b128 v[218:221], v157 offset:38912
	ds_read_b128 v[222:225], v157 offset:39936
	global_load_lds_dwordx4 v[226:227], off
	v_lshl_add_u64 v[226:227], s[58:59], 0, v[130:131]
	s_mov_b32 m0, s71
	s_nop 0
	global_load_lds_dwordx4 v[226:227], off
	s_add_i32 s19, 0, 0x1c000
	v_add_u32_e32 v192, s19, v154
	ds_read_b128 v[226:229], v192
	ds_read_b128 v[230:233], v192 offset:1024
	ds_read_b128 v[234:237], v192 offset:2048
	ds_read_b128 v[238:241], v192 offset:3072
	s_waitcnt vmcnt(8)
	s_waitcnt lgkmcnt(0)
	s_barrier
	v_mfma_f32_16x16x32_bf16 v[124:127], v[158:161], v[174:177], v[124:127]
	v_mfma_f32_16x16x32_bf16 v[120:123], v[166:169], v[174:177], v[120:123]
	v_mfma_f32_16x16x32_bf16 v[116:119], v[158:161], v[182:185], v[116:119]
	v_mfma_f32_16x16x32_bf16 v[112:115], v[166:169], v[182:185], v[112:115]
	v_mfma_f32_16x16x32_bf16 v[108:111], v[158:161], v[210:213], v[108:111]
	v_mfma_f32_16x16x32_bf16 v[104:107], v[166:169], v[210:213], v[104:107]
	v_mfma_f32_16x16x32_bf16 v[100:103], v[158:161], v[218:221], v[100:103]
	v_mfma_f32_16x16x32_bf16 v[96:99], v[166:169], v[218:221], v[96:99]
	v_mfma_f32_16x16x32_bf16 v[124:127], v[162:165], v[178:181], v[124:127]
	v_mfma_f32_16x16x32_bf16 v[120:123], v[170:173], v[178:181], v[120:123]
	v_mfma_f32_16x16x32_bf16 v[116:119], v[162:165], v[206:209], v[116:119]
	v_mfma_f32_16x16x32_bf16 v[112:115], v[170:173], v[206:209], v[112:115]
	v_mfma_f32_16x16x32_bf16 v[108:111], v[162:165], v[214:217], v[108:111]
	v_mfma_f32_16x16x32_bf16 v[104:107], v[170:173], v[214:217], v[104:107]
	v_mfma_f32_16x16x32_bf16 v[100:103], v[162:165], v[222:225], v[100:103]
	v_mfma_f32_16x16x32_bf16 v[96:99], v[170:173], v[222:225], v[96:99]
	v_mfma_f32_16x16x32_bf16 v[92:95], v[226:229], v[174:177], v[92:95]
	v_mfma_f32_16x16x32_bf16 v[88:91], v[234:237], v[174:177], v[88:91]
	v_mfma_f32_16x16x32_bf16 v[84:87], v[226:229], v[182:185], v[84:87]
	v_mfma_f32_16x16x32_bf16 v[80:83], v[234:237], v[182:185], v[80:83]
	v_mfma_f32_16x16x32_bf16 v[76:79], v[226:229], v[210:213], v[76:79]
	v_mfma_f32_16x16x32_bf16 v[72:75], v[234:237], v[210:213], v[72:75]
	v_mfma_f32_16x16x32_bf16 v[68:71], v[226:229], v[218:221], v[68:71]
	v_mfma_f32_16x16x32_bf16 v[64:67], v[234:237], v[218:221], v[64:67]
	v_mfma_f32_16x16x32_bf16 v[92:95], v[230:233], v[178:181], v[92:95]
	v_mfma_f32_16x16x32_bf16 v[88:91], v[238:241], v[178:181], v[88:91]
	v_mfma_f32_16x16x32_bf16 v[84:87], v[230:233], v[206:209], v[84:87]
	v_mfma_f32_16x16x32_bf16 v[80:83], v[238:241], v[206:209], v[80:83]
	v_mfma_f32_16x16x32_bf16 v[76:79], v[230:233], v[214:217], v[76:79]
	v_mfma_f32_16x16x32_bf16 v[72:75], v[238:241], v[214:217], v[72:75]
	v_mfma_f32_16x16x32_bf16 v[68:71], v[230:233], v[222:225], v[68:71]
	v_mfma_f32_16x16x32_bf16 v[64:67], v[238:241], v[222:225], v[64:67]
	s_barrier
	s_add_i32 s6, s6, s57
	v_lshl_add_u64 v[146:147], v[146:147], 0, s[36:37]
	s_mov_b32 m0, s6
	s_nop 0
	global_load_lds_dwordx4 v[146:147], off
	v_lshl_add_u64 v[146:147], v[148:149], 0, s[36:37]
	s_add_i32 m0, s6, 0x2000
	s_nop 0
	global_load_lds_dwordx4 v[146:147], off
	s_mov_b32 m0, s72
	v_lshl_add_u64 v[146:147], v[194:195], 0, s[36:37]
	ds_read_b128 v[174:177], v157 offset:49152
	ds_read_b128 v[178:181], v157 offset:50176
	ds_read_b128 v[182:185], v157 offset:51200
	ds_read_b128 v[206:209], v157 offset:52224
	ds_read_b128 v[210:213], v157 offset:53248
	ds_read_b128 v[214:217], v157 offset:54272
	ds_read_b128 v[218:221], v157 offset:55296
	ds_read_b128 v[222:225], v157 offset:56320
	global_load_lds_dwordx4 v[146:147], off
	v_lshl_add_u64 v[146:147], v[196:197], 0, s[36:37]
	s_mov_b32 m0, s73
	s_nop 0
	global_load_lds_dwordx4 v[146:147], off
	s_add_u32 s54, s54, 0x40080
	s_addc_u32 s55, s55, 0
	s_add_i32 s6, s19, s57
	v_lshl_add_u64 v[146:147], s[54:55], 0, v[140:141]
	s_mov_b32 m0, s6
	s_nop 0
	global_load_lds_dwordx4 v[146:147], off
	v_lshl_add_u64 v[146:147], s[54:55], 0, v[132:133]
	s_add_i32 m0, s6, 0x2000
	s_nop 0
	global_load_lds_dwordx4 v[146:147], off
	s_add_i32 s81, s81, 2
	s_add_u32 s52, s52, 0x100
	s_addc_u32 s53, s53, 0
	s_cmp_gt_u32 s81, 13
	s_nop 0
	s_waitcnt vmcnt(8)
	s_waitcnt lgkmcnt(0)
	s_barrier
	v_mfma_f32_16x16x32_bf16 v[60:63], v[158:161], v[174:177], v[60:63]
	v_mfma_f32_16x16x32_bf16 v[56:59], v[166:169], v[174:177], v[56:59]
	v_mfma_f32_16x16x32_bf16 v[52:55], v[158:161], v[182:185], v[52:55]
	v_mfma_f32_16x16x32_bf16 v[48:51], v[166:169], v[182:185], v[48:51]
	v_mfma_f32_16x16x32_bf16 v[44:47], v[158:161], v[210:213], v[44:47]
	v_mfma_f32_16x16x32_bf16 v[40:43], v[166:169], v[210:213], v[40:43]
	v_mfma_f32_16x16x32_bf16 v[36:39], v[158:161], v[218:221], v[36:39]
	v_mfma_f32_16x16x32_bf16 v[32:35], v[166:169], v[218:221], v[32:35]
	v_mfma_f32_16x16x32_bf16 v[60:63], v[162:165], v[178:181], v[60:63]
	v_mfma_f32_16x16x32_bf16 v[56:59], v[170:173], v[178:181], v[56:59]
	v_mfma_f32_16x16x32_bf16 v[52:55], v[162:165], v[206:209], v[52:55]
	v_mfma_f32_16x16x32_bf16 v[48:51], v[170:173], v[206:209], v[48:51]
	v_mfma_f32_16x16x32_bf16 v[44:47], v[162:165], v[214:217], v[44:47]
	v_mfma_f32_16x16x32_bf16 v[40:43], v[170:173], v[214:217], v[40:43]
	v_mfma_f32_16x16x32_bf16 v[36:39], v[162:165], v[222:225], v[36:39]
	v_mfma_f32_16x16x32_bf16 v[32:35], v[170:173], v[222:225], v[32:35]
	v_mfma_f32_16x16x32_bf16 v[28:31], v[226:229], v[174:177], v[28:31]
	v_mfma_f32_16x16x32_bf16 v[24:27], v[234:237], v[174:177], v[24:27]
	v_mfma_f32_16x16x32_bf16 v[20:23], v[226:229], v[182:185], v[20:23]
	v_mfma_f32_16x16x32_bf16 v[16:19], v[234:237], v[182:185], v[16:19]
	v_mfma_f32_16x16x32_bf16 v[12:15], v[226:229], v[210:213], v[12:15]
	v_mfma_f32_16x16x32_bf16 v[8:11], v[234:237], v[210:213], v[8:11]
	v_mfma_f32_16x16x32_bf16 v[4:7], v[226:229], v[218:221], v[4:7]
	v_mfma_f32_16x16x32_bf16 v[0:3], v[234:237], v[218:221], v[0:3]
	v_mfma_f32_16x16x32_bf16 v[28:31], v[230:233], v[178:181], v[28:31]
	v_mfma_f32_16x16x32_bf16 v[24:27], v[238:241], v[178:181], v[24:27]
	v_mfma_f32_16x16x32_bf16 v[20:23], v[230:233], v[206:209], v[20:23]
	v_mfma_f32_16x16x32_bf16 v[16:19], v[238:241], v[206:209], v[16:19]
	v_mfma_f32_16x16x32_bf16 v[12:15], v[230:233], v[214:217], v[12:15]
	v_mfma_f32_16x16x32_bf16 v[8:11], v[238:241], v[214:217], v[8:11]
	v_mfma_f32_16x16x32_bf16 v[4:7], v[230:233], v[222:225], v[4:7]
	v_mfma_f32_16x16x32_bf16 v[0:3], v[238:241], v[222:225], v[0:3]
	s_barrier
	s_cbranch_scc0 .LBB0_386
	s_mov_b32 s100, 1
	s_setprio 1
	v_lshl_add_u32 v158, s75, 10, v155
	ds_read2_b32 v[146:147], v158 offset1:16
	ds_read2_b32 v[208:209], v158 offset0:32 offset1:48
	ds_read2_b32 v[210:211], v158 offset0:128 offset1:144
	ds_read2_b32 v[212:213], v158 offset0:160 offset1:176
	s_add_u32 s52, s10, 0xffffff00
	s_addc_u32 s53, s11, -1
	s_ashr_i32 s35, s34, 31
	s_lshl_b64 s[10:11], s[34:35], 8
	s_waitcnt lgkmcnt(0)
	v_mul_f32_e32 v184, 0xbfb8aa3b, v146
	v_mul_f32_e32 v206, v146, v146
	v_pk_mul_f32 v[168:169], v[124:125], v[184:185] op_sel_hi:[1,0]
	v_pk_mul_f32 v[170:171], v[126:127], v[184:185] op_sel_hi:[1,0]
	v_pk_mul_f32 v[172:173], v[120:121], v[184:185] op_sel_hi:[1,0]
	v_pk_mul_f32 v[174:175], v[122:123], v[184:185] op_sel_hi:[1,0]
	v_exp_f32_e32 v168, v168
	v_exp_f32_e32 v169, v169
	v_exp_f32_e32 v170, v170
	v_exp_f32_e32 v171, v171
	v_exp_f32_e32 v172, v172
	v_exp_f32_e32 v173, v173
	v_exp_f32_e32 v174, v174
	v_exp_f32_e32 v175, v175
	v_pk_mul_f32 v[176:177], v[124:125], v[92:93]
	v_pk_mul_f32 v[178:179], v[126:127], v[94:95]
	v_pk_mul_f32 v[180:181], v[120:121], v[88:89]
	v_pk_mul_f32 v[182:183], v[122:123], v[90:91]
	v_pk_add_f32 v[168:169], v[168:169], 1.0 op_sel_hi:[1,0]
	v_pk_add_f32 v[170:171], v[170:171], 1.0 op_sel_hi:[1,0]
	v_pk_add_f32 v[172:173], v[172:173], 1.0 op_sel_hi:[1,0]
	v_pk_add_f32 v[174:175], v[174:175], 1.0 op_sel_hi:[1,0]
	v_rcp_f32_e32 v168, v168
	v_rcp_f32_e32 v169, v169
	v_rcp_f32_e32 v170, v170
	v_rcp_f32_e32 v171, v171
	v_rcp_f32_e32 v172, v172
	v_rcp_f32_e32 v173, v173
	v_rcp_f32_e32 v174, v174
	v_rcp_f32_e32 v175, v175
	v_pk_mul_f32 v[176:177], v[176:177], v[206:207] op_sel_hi:[1,0]
	v_pk_mul_f32 v[178:179], v[178:179], v[206:207] op_sel_hi:[1,0]
	v_pk_mul_f32 v[180:181], v[180:181], v[206:207] op_sel_hi:[1,0]
	v_pk_mul_f32 v[182:183], v[182:183], v[206:207] op_sel_hi:[1,0]
	v_pk_mul_f32 v[176:177], v[176:177], v[168:169]
	v_pk_mul_f32 v[178:179], v[178:179], v[170:171]
	v_pk_mul_f32 v[180:181], v[180:181], v[172:173]
	v_pk_mul_f32 v[182:183], v[182:183], v[174:175]
	v_cvt_pk_bf16_f32 v160, v176, v177
	v_cvt_pk_bf16_f32 v161, v178, v179
	v_cvt_pk_bf16_f32 v162, v180, v181
	v_cvt_pk_bf16_f32 v163, v182, v183
	v_lshl_add_u64 v[152:153], v[134:135], 0, s[10:11]
	s_movk_i32 s6, 0x1600
	v_lshl_or_b32 v150, s74, 7, v156
	v_ashrrev_i32_e32 v151, 31, v150
	s_nop 1
	v_mov_b64_e32 v[148:149], s[30:31]
	v_mad_u64_u32 v[148:149], s[10:11], v152, s6, v[148:149]
	v_mov_b32_e32 v146, v149
	v_mad_u64_u32 v[152:153], s[10:11], v153, s6, v[146:147]
	v_mov_b32_e32 v149, v152
	v_mov_b32_e32 v146, v147
	v_lshl_add_u64 v[150:151], v[150:151], 1, v[148:149]
	global_store_dwordx4 v[150:151], v[160:163], off
	v_mul_f32_e32 v184, 0xbfb8aa3b, v146
	v_mul_f32_e32 v206, v146, v146
	v_pk_mul_f32 v[168:169], v[116:117], v[184:185] op_sel_hi:[1,0]
	v_pk_mul_f32 v[170:171], v[118:119], v[184:185] op_sel_hi:[1,0]
	v_pk_mul_f32 v[172:173], v[112:113], v[184:185] op_sel_hi:[1,0]
	v_pk_mul_f32 v[174:175], v[114:115], v[184:185] op_sel_hi:[1,0]
	v_exp_f32_e32 v168, v168
	v_exp_f32_e32 v169, v169
	v_exp_f32_e32 v170, v170
	v_exp_f32_e32 v171, v171
	v_exp_f32_e32 v172, v172
	v_exp_f32_e32 v173, v173
	v_exp_f32_e32 v174, v174
	v_exp_f32_e32 v175, v175
	v_pk_mul_f32 v[176:177], v[116:117], v[84:85]
	v_pk_mul_f32 v[178:179], v[118:119], v[86:87]
	v_pk_mul_f32 v[180:181], v[112:113], v[80:81]
	v_pk_mul_f32 v[182:183], v[114:115], v[82:83]
	v_pk_add_f32 v[168:169], v[168:169], 1.0 op_sel_hi:[1,0]
	v_pk_add_f32 v[170:171], v[170:171], 1.0 op_sel_hi:[1,0]
	v_pk_add_f32 v[172:173], v[172:173], 1.0 op_sel_hi:[1,0]
	v_pk_add_f32 v[174:175], v[174:175], 1.0 op_sel_hi:[1,0]
	v_rcp_f32_e32 v168, v168
	v_rcp_f32_e32 v169, v169
	v_rcp_f32_e32 v170, v170
	v_rcp_f32_e32 v171, v171
	v_rcp_f32_e32 v172, v172
	v_rcp_f32_e32 v173, v173
	v_rcp_f32_e32 v174, v174
	v_rcp_f32_e32 v175, v175
	v_pk_mul_f32 v[176:177], v[176:177], v[206:207] op_sel_hi:[1,0]
	v_pk_mul_f32 v[178:179], v[178:179], v[206:207] op_sel_hi:[1,0]
	v_pk_mul_f32 v[180:181], v[180:181], v[206:207] op_sel_hi:[1,0]
	v_pk_mul_f32 v[182:183], v[182:183], v[206:207] op_sel_hi:[1,0]
	v_pk_mul_f32 v[176:177], v[176:177], v[168:169]
	v_pk_mul_f32 v[178:179], v[178:179], v[170:171]
	v_pk_mul_f32 v[180:181], v[180:181], v[172:173]
	v_pk_mul_f32 v[182:183], v[182:183], v[174:175]
	v_cvt_pk_bf16_f32 v160, v176, v177
	v_cvt_pk_bf16_f32 v161, v178, v179
	v_cvt_pk_bf16_f32 v162, v180, v181
	v_cvt_pk_bf16_f32 v163, v182, v183
	s_mov_b32 s6, 0x16000
	s_nop 1
	v_add_co_u32_e32 v146, vcc, s6, v150
	s_nop 0
	v_addc_co_u32_e32 v147, vcc, 0, v151, vcc
	global_store_dwordx4 v[146:147], v[160:163], off
	v_mov_b32_e32 v146, v208
	v_mov_b32_e32 v147, v209
	s_mov_b32 s6, 0x2c000
	s_waitcnt lgkmcnt(0)
	v_mul_f32_e32 v184, 0xbfb8aa3b, v146
	v_mul_f32_e32 v206, v146, v146
	v_pk_mul_f32 v[168:169], v[108:109], v[184:185] op_sel_hi:[1,0]
	v_pk_mul_f32 v[170:171], v[110:111], v[184:185] op_sel_hi:[1,0]
	v_pk_mul_f32 v[172:173], v[104:105], v[184:185] op_sel_hi:[1,0]
	v_pk_mul_f32 v[174:175], v[106:107], v[184:185] op_sel_hi:[1,0]
	v_exp_f32_e32 v168, v168
	v_exp_f32_e32 v169, v169
	v_exp_f32_e32 v170, v170
	v_exp_f32_e32 v171, v171
	v_exp_f32_e32 v172, v172
	v_exp_f32_e32 v173, v173
	v_exp_f32_e32 v174, v174
	v_exp_f32_e32 v175, v175
	v_pk_mul_f32 v[176:177], v[108:109], v[76:77]
	v_pk_mul_f32 v[178:179], v[110:111], v[78:79]
	v_pk_mul_f32 v[180:181], v[104:105], v[72:73]
	v_pk_mul_f32 v[182:183], v[106:107], v[74:75]
	v_pk_add_f32 v[168:169], v[168:169], 1.0 op_sel_hi:[1,0]
	v_pk_add_f32 v[170:171], v[170:171], 1.0 op_sel_hi:[1,0]
	v_pk_add_f32 v[172:173], v[172:173], 1.0 op_sel_hi:[1,0]
	v_pk_add_f32 v[174:175], v[174:175], 1.0 op_sel_hi:[1,0]
	v_rcp_f32_e32 v168, v168
	v_rcp_f32_e32 v169, v169
	v_rcp_f32_e32 v170, v170
	v_rcp_f32_e32 v171, v171
	v_rcp_f32_e32 v172, v172
	v_rcp_f32_e32 v173, v173
	v_rcp_f32_e32 v174, v174
	v_rcp_f32_e32 v175, v175
	v_pk_mul_f32 v[176:177], v[176:177], v[206:207] op_sel_hi:[1,0]
	v_pk_mul_f32 v[178:179], v[178:179], v[206:207] op_sel_hi:[1,0]
	v_pk_mul_f32 v[180:181], v[180:181], v[206:207] op_sel_hi:[1,0]
	v_pk_mul_f32 v[182:183], v[182:183], v[206:207] op_sel_hi:[1,0]
	v_pk_mul_f32 v[176:177], v[176:177], v[168:169]
	v_pk_mul_f32 v[178:179], v[178:179], v[170:171]
	v_pk_mul_f32 v[180:181], v[180:181], v[172:173]
	v_pk_mul_f32 v[182:183], v[182:183], v[174:175]
	v_cvt_pk_bf16_f32 v160, v176, v177
	v_cvt_pk_bf16_f32 v161, v178, v179
	v_cvt_pk_bf16_f32 v162, v180, v181
	v_cvt_pk_bf16_f32 v163, v182, v183
	s_nop 1
	v_mov_b32_e32 v146, v147
	v_add_co_u32_e32 v148, vcc, s6, v150
	v_addc_co_u32_e32 v149, vcc, 0, v151, vcc
	global_store_dwordx4 v[148:149], v[160:163], off
	v_mul_f32_e32 v184, 0xbfb8aa3b, v146
	v_mul_f32_e32 v206, v146, v146
	v_pk_mul_f32 v[168:169], v[100:101], v[184:185] op_sel_hi:[1,0]
	v_pk_mul_f32 v[170:171], v[102:103], v[184:185] op_sel_hi:[1,0]
	v_pk_mul_f32 v[172:173], v[96:97], v[184:185] op_sel_hi:[1,0]
	v_pk_mul_f32 v[174:175], v[98:99], v[184:185] op_sel_hi:[1,0]
	v_exp_f32_e32 v168, v168
	v_exp_f32_e32 v169, v169
	v_exp_f32_e32 v170, v170
	v_exp_f32_e32 v171, v171
	v_exp_f32_e32 v172, v172
	v_exp_f32_e32 v173, v173
	v_exp_f32_e32 v174, v174
	v_exp_f32_e32 v175, v175
	v_pk_mul_f32 v[176:177], v[100:101], v[68:69]
	v_pk_mul_f32 v[178:179], v[102:103], v[70:71]
	v_pk_mul_f32 v[180:181], v[96:97], v[64:65]
	v_pk_mul_f32 v[182:183], v[98:99], v[66:67]
	v_pk_add_f32 v[168:169], v[168:169], 1.0 op_sel_hi:[1,0]
	v_pk_add_f32 v[170:171], v[170:171], 1.0 op_sel_hi:[1,0]
	v_pk_add_f32 v[172:173], v[172:173], 1.0 op_sel_hi:[1,0]
	v_pk_add_f32 v[174:175], v[174:175], 1.0 op_sel_hi:[1,0]
	v_rcp_f32_e32 v168, v168
	v_rcp_f32_e32 v169, v169
	v_rcp_f32_e32 v170, v170
	v_rcp_f32_e32 v171, v171
	v_rcp_f32_e32 v172, v172
	v_rcp_f32_e32 v173, v173
	v_rcp_f32_e32 v174, v174
	v_rcp_f32_e32 v175, v175
	v_pk_mul_f32 v[176:177], v[176:177], v[206:207] op_sel_hi:[1,0]
	v_pk_mul_f32 v[178:179], v[178:179], v[206:207] op_sel_hi:[1,0]
	v_pk_mul_f32 v[180:181], v[180:181], v[206:207] op_sel_hi:[1,0]
	v_pk_mul_f32 v[182:183], v[182:183], v[206:207] op_sel_hi:[1,0]
	v_pk_mul_f32 v[176:177], v[176:177], v[168:169]
	v_pk_mul_f32 v[178:179], v[178:179], v[170:171]
	v_pk_mul_f32 v[180:181], v[180:181], v[172:173]
	v_pk_mul_f32 v[182:183], v[182:183], v[174:175]
	v_cvt_pk_bf16_f32 v160, v176, v177
	v_cvt_pk_bf16_f32 v161, v178, v179
	v_cvt_pk_bf16_f32 v162, v180, v181
	v_cvt_pk_bf16_f32 v163, v182, v183
	s_mov_b32 s6, 0x42000
	s_nop 1
	v_add_co_u32_e32 v146, vcc, s6, v150
	s_nop 0
	v_addc_co_u32_e32 v147, vcc, 0, v151, vcc
	global_store_dwordx4 v[146:147], v[160:163], off
	v_mov_b32_e32 v146, v210
	v_mov_b32_e32 v147, v211
	s_mov_b32 s6, 0xb0000
	s_waitcnt lgkmcnt(0)
	v_mul_f32_e32 v184, 0xbfb8aa3b, v146
	v_mul_f32_e32 v206, v146, v146
	v_pk_mul_f32 v[168:169], v[60:61], v[184:185] op_sel_hi:[1,0]
	v_pk_mul_f32 v[170:171], v[62:63], v[184:185] op_sel_hi:[1,0]
	v_pk_mul_f32 v[172:173], v[56:57], v[184:185] op_sel_hi:[1,0]
	v_pk_mul_f32 v[174:175], v[58:59], v[184:185] op_sel_hi:[1,0]
	v_exp_f32_e32 v168, v168
	v_exp_f32_e32 v169, v169
	v_exp_f32_e32 v170, v170
	v_exp_f32_e32 v171, v171
	v_exp_f32_e32 v172, v172
	v_exp_f32_e32 v173, v173
	v_exp_f32_e32 v174, v174
	v_exp_f32_e32 v175, v175
	v_pk_mul_f32 v[176:177], v[60:61], v[28:29]
	v_pk_mul_f32 v[178:179], v[62:63], v[30:31]
	v_pk_mul_f32 v[180:181], v[56:57], v[24:25]
	v_pk_mul_f32 v[182:183], v[58:59], v[26:27]
	v_pk_add_f32 v[168:169], v[168:169], 1.0 op_sel_hi:[1,0]
	v_pk_add_f32 v[170:171], v[170:171], 1.0 op_sel_hi:[1,0]
	v_pk_add_f32 v[172:173], v[172:173], 1.0 op_sel_hi:[1,0]
	v_pk_add_f32 v[174:175], v[174:175], 1.0 op_sel_hi:[1,0]
	v_rcp_f32_e32 v168, v168
	v_rcp_f32_e32 v169, v169
	v_rcp_f32_e32 v170, v170
	v_rcp_f32_e32 v171, v171
	v_rcp_f32_e32 v172, v172
	v_rcp_f32_e32 v173, v173
	v_rcp_f32_e32 v174, v174
	v_rcp_f32_e32 v175, v175
	v_pk_mul_f32 v[176:177], v[176:177], v[206:207] op_sel_hi:[1,0]
	v_pk_mul_f32 v[178:179], v[178:179], v[206:207] op_sel_hi:[1,0]
	v_pk_mul_f32 v[180:181], v[180:181], v[206:207] op_sel_hi:[1,0]
	v_pk_mul_f32 v[182:183], v[182:183], v[206:207] op_sel_hi:[1,0]
	v_pk_mul_f32 v[176:177], v[176:177], v[168:169]
	v_pk_mul_f32 v[178:179], v[178:179], v[170:171]
	v_pk_mul_f32 v[180:181], v[180:181], v[172:173]
	v_pk_mul_f32 v[182:183], v[182:183], v[174:175]
	v_cvt_pk_bf16_f32 v160, v176, v177
	v_cvt_pk_bf16_f32 v161, v178, v179
	v_cvt_pk_bf16_f32 v162, v180, v181
	v_cvt_pk_bf16_f32 v163, v182, v183
	s_nop 1
	v_mov_b32_e32 v146, v147
	v_add_co_u32_e32 v148, vcc, s6, v150
	v_addc_co_u32_e32 v149, vcc, 0, v151, vcc
	global_store_dwordx4 v[148:149], v[160:163], off
	v_mul_f32_e32 v184, 0xbfb8aa3b, v146
	v_mul_f32_e32 v206, v146, v146
	v_pk_mul_f32 v[168:169], v[52:53], v[184:185] op_sel_hi:[1,0]
	v_pk_mul_f32 v[170:171], v[54:55], v[184:185] op_sel_hi:[1,0]
	v_pk_mul_f32 v[172:173], v[48:49], v[184:185] op_sel_hi:[1,0]
	v_pk_mul_f32 v[174:175], v[50:51], v[184:185] op_sel_hi:[1,0]
	v_exp_f32_e32 v168, v168
	v_exp_f32_e32 v169, v169
	v_exp_f32_e32 v170, v170
	v_exp_f32_e32 v171, v171
	v_exp_f32_e32 v172, v172
	v_exp_f32_e32 v173, v173
	v_exp_f32_e32 v174, v174
	v_exp_f32_e32 v175, v175
	v_pk_mul_f32 v[176:177], v[52:53], v[20:21]
	v_pk_mul_f32 v[178:179], v[54:55], v[22:23]
	v_pk_mul_f32 v[180:181], v[48:49], v[16:17]
	v_pk_mul_f32 v[182:183], v[50:51], v[18:19]
	v_pk_add_f32 v[168:169], v[168:169], 1.0 op_sel_hi:[1,0]
	v_pk_add_f32 v[170:171], v[170:171], 1.0 op_sel_hi:[1,0]
	v_pk_add_f32 v[172:173], v[172:173], 1.0 op_sel_hi:[1,0]
	v_pk_add_f32 v[174:175], v[174:175], 1.0 op_sel_hi:[1,0]
	v_rcp_f32_e32 v168, v168
	v_rcp_f32_e32 v169, v169
	v_rcp_f32_e32 v170, v170
	v_rcp_f32_e32 v171, v171
	v_rcp_f32_e32 v172, v172
	v_rcp_f32_e32 v173, v173
	v_rcp_f32_e32 v174, v174
	v_rcp_f32_e32 v175, v175
	v_pk_mul_f32 v[176:177], v[176:177], v[206:207] op_sel_hi:[1,0]
	v_pk_mul_f32 v[178:179], v[178:179], v[206:207] op_sel_hi:[1,0]
	v_pk_mul_f32 v[180:181], v[180:181], v[206:207] op_sel_hi:[1,0]
	v_pk_mul_f32 v[182:183], v[182:183], v[206:207] op_sel_hi:[1,0]
	v_pk_mul_f32 v[176:177], v[176:177], v[168:169]
	v_pk_mul_f32 v[178:179], v[178:179], v[170:171]
	v_pk_mul_f32 v[180:181], v[180:181], v[172:173]
	v_pk_mul_f32 v[182:183], v[182:183], v[174:175]
	v_cvt_pk_bf16_f32 v160, v176, v177
	v_cvt_pk_bf16_f32 v161, v178, v179
	v_cvt_pk_bf16_f32 v162, v180, v181
	v_cvt_pk_bf16_f32 v163, v182, v183
	s_mov_b32 s6, 0xc6000
	s_nop 1
	v_add_co_u32_e32 v146, vcc, s6, v150
	s_nop 0
	v_addc_co_u32_e32 v147, vcc, 0, v151, vcc
	global_store_dwordx4 v[146:147], v[160:163], off
	v_mov_b32_e32 v146, v212
	v_mov_b32_e32 v147, v213
	s_mov_b32 s6, 0xdc000
	s_waitcnt lgkmcnt(0)
	v_mul_f32_e32 v184, 0xbfb8aa3b, v146
	v_mul_f32_e32 v206, v146, v146
	v_pk_mul_f32 v[168:169], v[44:45], v[184:185] op_sel_hi:[1,0]
	v_pk_mul_f32 v[170:171], v[46:47], v[184:185] op_sel_hi:[1,0]
	v_pk_mul_f32 v[172:173], v[40:41], v[184:185] op_sel_hi:[1,0]
	v_pk_mul_f32 v[174:175], v[42:43], v[184:185] op_sel_hi:[1,0]
	v_exp_f32_e32 v168, v168
	v_exp_f32_e32 v169, v169
	v_exp_f32_e32 v170, v170
	v_exp_f32_e32 v171, v171
	v_exp_f32_e32 v172, v172
	v_exp_f32_e32 v173, v173
	v_exp_f32_e32 v174, v174
	v_exp_f32_e32 v175, v175
	v_pk_mul_f32 v[176:177], v[44:45], v[12:13]
	v_pk_mul_f32 v[178:179], v[46:47], v[14:15]
	v_pk_mul_f32 v[180:181], v[40:41], v[8:9]
	v_pk_mul_f32 v[182:183], v[42:43], v[10:11]
	v_pk_add_f32 v[168:169], v[168:169], 1.0 op_sel_hi:[1,0]
	v_pk_add_f32 v[170:171], v[170:171], 1.0 op_sel_hi:[1,0]
	v_pk_add_f32 v[172:173], v[172:173], 1.0 op_sel_hi:[1,0]
	v_pk_add_f32 v[174:175], v[174:175], 1.0 op_sel_hi:[1,0]
	v_rcp_f32_e32 v168, v168
	v_rcp_f32_e32 v169, v169
	v_rcp_f32_e32 v170, v170
	v_rcp_f32_e32 v171, v171
	v_rcp_f32_e32 v172, v172
	v_rcp_f32_e32 v173, v173
	v_rcp_f32_e32 v174, v174
	v_rcp_f32_e32 v175, v175
	v_pk_mul_f32 v[176:177], v[176:177], v[206:207] op_sel_hi:[1,0]
	v_pk_mul_f32 v[178:179], v[178:179], v[206:207] op_sel_hi:[1,0]
	v_pk_mul_f32 v[180:181], v[180:181], v[206:207] op_sel_hi:[1,0]
	v_pk_mul_f32 v[182:183], v[182:183], v[206:207] op_sel_hi:[1,0]
	v_pk_mul_f32 v[176:177], v[176:177], v[168:169]
	v_pk_mul_f32 v[178:179], v[178:179], v[170:171]
	v_pk_mul_f32 v[180:181], v[180:181], v[172:173]
	v_pk_mul_f32 v[182:183], v[182:183], v[174:175]
	v_cvt_pk_bf16_f32 v158, v176, v177
	v_cvt_pk_bf16_f32 v159, v178, v179
	v_cvt_pk_bf16_f32 v160, v180, v181
	v_cvt_pk_bf16_f32 v161, v182, v183
	s_nop 1
	v_mov_b32_e32 v146, v147
	v_add_co_u32_e32 v148, vcc, s6, v150
	v_addc_co_u32_e32 v149, vcc, 0, v151, vcc
	global_store_dwordx4 v[148:149], v[158:161], off
	v_mul_f32_e32 v184, 0xbfb8aa3b, v146
	v_mul_f32_e32 v206, v146, v146
	v_pk_mul_f32 v[168:169], v[36:37], v[184:185] op_sel_hi:[1,0]
	v_pk_mul_f32 v[170:171], v[38:39], v[184:185] op_sel_hi:[1,0]
	v_pk_mul_f32 v[172:173], v[32:33], v[184:185] op_sel_hi:[1,0]
	v_pk_mul_f32 v[174:175], v[34:35], v[184:185] op_sel_hi:[1,0]
	v_exp_f32_e32 v168, v168
	v_exp_f32_e32 v169, v169
	v_exp_f32_e32 v170, v170
	v_exp_f32_e32 v171, v171
	v_exp_f32_e32 v172, v172
	v_exp_f32_e32 v173, v173
	v_exp_f32_e32 v174, v174
	v_exp_f32_e32 v175, v175
	v_pk_mul_f32 v[176:177], v[36:37], v[4:5]
	v_pk_mul_f32 v[178:179], v[38:39], v[6:7]
	v_pk_mul_f32 v[180:181], v[32:33], v[0:1]
	v_pk_mul_f32 v[182:183], v[34:35], v[2:3]
	v_pk_add_f32 v[168:169], v[168:169], 1.0 op_sel_hi:[1,0]
	v_pk_add_f32 v[170:171], v[170:171], 1.0 op_sel_hi:[1,0]
	v_pk_add_f32 v[172:173], v[172:173], 1.0 op_sel_hi:[1,0]
	v_pk_add_f32 v[174:175], v[174:175], 1.0 op_sel_hi:[1,0]
	v_rcp_f32_e32 v168, v168
	v_rcp_f32_e32 v169, v169
	v_rcp_f32_e32 v170, v170
	v_rcp_f32_e32 v171, v171
	v_rcp_f32_e32 v172, v172
	v_rcp_f32_e32 v173, v173
	v_rcp_f32_e32 v174, v174
	v_rcp_f32_e32 v175, v175
	v_pk_mul_f32 v[176:177], v[176:177], v[206:207] op_sel_hi:[1,0]
	v_pk_mul_f32 v[178:179], v[178:179], v[206:207] op_sel_hi:[1,0]
	v_pk_mul_f32 v[180:181], v[180:181], v[206:207] op_sel_hi:[1,0]
	v_pk_mul_f32 v[182:183], v[182:183], v[206:207] op_sel_hi:[1,0]
	v_pk_mul_f32 v[176:177], v[176:177], v[168:169]
	v_pk_mul_f32 v[178:179], v[178:179], v[170:171]
	v_pk_mul_f32 v[180:181], v[180:181], v[172:173]
	v_pk_mul_f32 v[182:183], v[182:183], v[174:175]
	v_cvt_pk_bf16_f32 v158, v176, v177
	v_cvt_pk_bf16_f32 v159, v178, v179
	v_cvt_pk_bf16_f32 v160, v180, v181
	v_cvt_pk_bf16_f32 v161, v182, v183
	s_nop 1
	v_add_co_u32_e32 v146, vcc, 0xf2000, v150
	s_nop 0
	v_addc_co_u32_e32 v147, vcc, 0, v151, vcc
	s_andn2_b64 vcc, exec, s[44:45]
	global_store_dwordx4 v[146:147], v[158:161], off
	s_cbranch_vccz .LBB0_382
	s_mov_b64 s[48:49], s[52:53]
	s_andn2_b64 vcc, exec, s[42:43]
	s_mov_b64 s[52:53], s[48:49]
	s_cbranch_vccnz .LBB0_383
